# MFMA order per compute segment: accumulate chains of two, the B fragment kept across four consecutive chains (all four A row blocks), across both column halves
# speedup vs baseline: 1.0049x; 1.0048x over previous
.LBB0_74:
	s_ashr_i32 s27, s26, 31
	s_lshl_b64 s[28:29], s[26:27], 19
	s_add_u32 s28, s3, s28
	s_addc_u32 s29, s35, s29
	s_and_b64 s[30:31], s[4:5], exec
	s_cselect_b32 s27, s29, s49
	s_cselect_b32 s68, s28, s48
	s_ashr_i32 s23, s22, 31
	s_lshl_b64 s[30:31], s[22:23], 19
	s_add_u32 s30, s50, s30
	s_addc_u32 s31, s51, s31
	s_and_b64 s[70:71], s[4:5], exec
	s_cselect_b32 s69, s31, s47
	s_cselect_b32 s70, s30, s46
	s_lshl_b32 s23, s44, 8
	v_add_u32_e32 v0, s23, v148
	s_add_u32 s71, s46, 0x100
	v_ashrrev_i32_e32 v1, 31, v0
	s_addc_u32 s74, s47, 0
	v_lshl_add_u64 v[144:145], v[0:1], 4, s[12:13]
	s_add_u32 s44, s48, 0x40080
	s_addc_u32 s45, s49, 0
	s_mov_b32 s75, -2
	s_mov_b64 s[46:47], 0
	s_cmp_eq_u32 s59, 1
	s_cbranch_scc1 .Lfa_0
	v_add_u32_e32 v153, s64, v147
	ds_read_b128 v[160:163], v153
	v_xor_b32_e32 v253, 64, v153
	ds_read_b128 v[164:167], v253
	ds_read_b128 v[168:171], v153 offset:2048
	ds_read_b128 v[172:175], v253 offset:2048
	v_add_u32_e32 v153, s65, v147
	ds_read_b128 v[176:179], v153
	v_xor_b32_e32 v253, 64, v153
	ds_read_b128 v[180:183], v253
	ds_read_b128 v[186:189], v153 offset:2048
	ds_read_b128 v[190:193], v253 offset:2048
	s_add_u32 s48, s44, 0xfffc0080
	s_addc_u32 s49, s45, -1
	s_and_b64 s[46:47], s[46:47], exec
	s_cselect_b32 s49, s27, s49
	s_cselect_b32 s48, s68, s48
	s_cselect_b32 s47, s69, s74
	s_cselect_b32 s46, s70, s71
	v_lshl_add_u64 v[154:155], s[44:45], 0, v[138:139]
	s_add_i32 m0, s55, 0xc000
	ds_read_b128 v[194:197], v150
	v_xor_b32_e32 v253, 64, v150
	ds_read_b128 v[198:201], v253
	ds_read_b128 v[202:205], v150 offset:2048
	ds_read_b128 v[206:209], v253 offset:2048
	ds_read_b128 v[210:213], v150 offset:4096
	ds_read_b128 v[214:217], v253 offset:4096
	ds_read_b128 v[218:221], v150 offset:6144
	ds_read_b128 v[222:225], v253 offset:6144
	global_load_lds_dwordx4 v[154:155], off
	v_lshl_add_u64 v[154:155], s[44:45], 0, v[136:137]
	s_add_i32 m0, s55, 0xe000
	s_nop 0
	global_load_lds_dwordx4 v[154:155], off
	s_waitcnt vmcnt(16)
	s_waitcnt lgkmcnt(0)
	s_setprio 1
	s_barrier
	v_mfma_f32_16x16x32_bf16 v[124:127], v[160:163], v[194:197], 0
	v_mfma_f32_16x16x32_bf16 v[116:119], v[168:171], v[194:197], 0
	v_mfma_f32_16x16x32_bf16 v[108:111], v[160:163], v[202:205], 0
	v_mfma_f32_16x16x32_bf16 v[100:103], v[168:171], v[202:205], 0
	v_mfma_f32_16x16x32_bf16 v[92:95], v[160:163], v[210:213], 0
	v_mfma_f32_16x16x32_bf16 v[84:87], v[168:171], v[210:213], 0
	v_mfma_f32_16x16x32_bf16 v[76:79], v[160:163], v[218:221], 0
	v_mfma_f32_16x16x32_bf16 v[68:71], v[168:171], v[218:221], 0
	v_mfma_f32_16x16x32_bf16 v[124:127], v[164:167], v[198:201], v[124:127]
	v_mfma_f32_16x16x32_bf16 v[116:119], v[172:175], v[198:201], v[116:119]
	v_mfma_f32_16x16x32_bf16 v[108:111], v[164:167], v[206:209], v[108:111]
	v_mfma_f32_16x16x32_bf16 v[100:103], v[172:175], v[206:209], v[100:103]
	v_mfma_f32_16x16x32_bf16 v[92:95], v[164:167], v[214:217], v[92:95]
	v_mfma_f32_16x16x32_bf16 v[84:87], v[172:175], v[214:217], v[84:87]
	v_mfma_f32_16x16x32_bf16 v[76:79], v[164:167], v[222:225], v[76:79]
	v_mfma_f32_16x16x32_bf16 v[68:71], v[172:175], v[222:225], v[68:71]
	s_setprio 0
	s_setprio 1
	v_mfma_f32_16x16x32_bf16 v[120:123], v[176:179], v[194:197], 0
	v_mfma_f32_16x16x32_bf16 v[112:115], v[186:189], v[194:197], 0
	v_mfma_f32_16x16x32_bf16 v[104:107], v[176:179], v[202:205], 0
	v_mfma_f32_16x16x32_bf16 v[96:99], v[186:189], v[202:205], 0
	v_mfma_f32_16x16x32_bf16 v[88:91], v[176:179], v[210:213], 0
	v_mfma_f32_16x16x32_bf16 v[80:83], v[186:189], v[210:213], 0
	v_mfma_f32_16x16x32_bf16 v[72:75], v[176:179], v[218:221], 0
	v_mfma_f32_16x16x32_bf16 v[64:67], v[186:189], v[218:221], 0
	v_mfma_f32_16x16x32_bf16 v[120:123], v[180:183], v[198:201], v[120:123]
	v_mfma_f32_16x16x32_bf16 v[112:115], v[190:193], v[198:201], v[112:115]
	v_mfma_f32_16x16x32_bf16 v[104:107], v[180:183], v[206:209], v[104:107]
	v_mfma_f32_16x16x32_bf16 v[96:99], v[190:193], v[206:209], v[96:99]
	v_mfma_f32_16x16x32_bf16 v[88:91], v[180:183], v[214:217], v[88:91]
	v_mfma_f32_16x16x32_bf16 v[80:83], v[190:193], v[214:217], v[80:83]
	v_mfma_f32_16x16x32_bf16 v[72:75], v[180:183], v[222:225], v[72:75]
	v_mfma_f32_16x16x32_bf16 v[64:67], v[190:193], v[222:225], v[64:67]
	s_barrier
	s_setprio 0
	s_add_i32 s76, s64, s52
	v_lshl_add_u64 v[154:155], s[46:47], 0, v[132:133]
	s_mov_b32 m0, s76
	ds_read_b128 v[194:197], v150 offset:16384
	v_xor_b32_e32 v253, 64, v150
	ds_read_b128 v[198:201], v253 offset:16384
	ds_read_b128 v[202:205], v150 offset:18432
	ds_read_b128 v[206:209], v253 offset:18432
	ds_read_b128 v[210:213], v150 offset:20480
	ds_read_b128 v[214:217], v253 offset:20480
	ds_read_b128 v[218:221], v150 offset:22528
	ds_read_b128 v[222:225], v253 offset:22528
	global_load_lds_dwordx4 v[154:155], off
	s_add_i32 m0, s76, 0x2000
	s_add_u32 s76, s46, 0x40000
	v_lshl_add_u64 v[226:227], s[46:47], 0, v[128:129]
	s_addc_u32 s77, s47, 0
	s_add_i32 s78, s65, s52
	global_load_lds_dwordx4 v[226:227], off
	v_lshl_add_u64 v[228:229], s[76:77], 0, v[132:133]
	s_mov_b32 m0, s78
	v_lshl_add_u64 v[230:231], s[48:49], 0, v[130:131]
	global_load_lds_dwordx4 v[228:229], off
	v_lshl_add_u64 v[228:229], s[76:77], 0, v[128:129]
	s_add_i32 m0, s78, 0x2000
	s_nop 0
	global_load_lds_dwordx4 v[228:229], off
	v_lshl_add_u64 v[228:229], s[48:49], 0, v[134:135]
	s_mov_b32 m0, s55
	s_nop 0
	global_load_lds_dwordx4 v[228:229], off
	s_mov_b32 m0, s56
	s_nop 0
	global_load_lds_dwordx4 v[230:231], off
	s_waitcnt vmcnt(16)
	s_waitcnt lgkmcnt(0)
	s_setprio 1
	s_barrier
	v_mfma_f32_16x16x32_bf16 v[60:63], v[160:163], v[194:197], 0
	v_mfma_f32_16x16x32_bf16 v[52:55], v[168:171], v[194:197], 0
	v_mfma_f32_16x16x32_bf16 v[44:47], v[160:163], v[202:205], 0
	v_mfma_f32_16x16x32_bf16 v[36:39], v[168:171], v[202:205], 0
	v_mfma_f32_16x16x32_bf16 v[28:31], v[160:163], v[210:213], 0
	v_mfma_f32_16x16x32_bf16 v[20:23], v[168:171], v[210:213], 0
	v_mfma_f32_16x16x32_bf16 v[12:15], v[160:163], v[218:221], 0
	v_mfma_f32_16x16x32_bf16 v[4:7], v[168:171], v[218:221], 0
	v_mfma_f32_16x16x32_bf16 v[60:63], v[164:167], v[198:201], v[60:63]
	v_mfma_f32_16x16x32_bf16 v[52:55], v[172:175], v[198:201], v[52:55]
	v_mfma_f32_16x16x32_bf16 v[44:47], v[164:167], v[206:209], v[44:47]
	v_mfma_f32_16x16x32_bf16 v[36:39], v[172:175], v[206:209], v[36:39]
	v_mfma_f32_16x16x32_bf16 v[28:31], v[164:167], v[214:217], v[28:31]
	v_mfma_f32_16x16x32_bf16 v[20:23], v[172:175], v[214:217], v[20:23]
	v_mfma_f32_16x16x32_bf16 v[12:15], v[164:167], v[222:225], v[12:15]
	v_mfma_f32_16x16x32_bf16 v[4:7], v[172:175], v[222:225], v[4:7]
	s_setprio 0
	s_setprio 1
	v_mfma_f32_16x16x32_bf16 v[56:59], v[176:179], v[194:197], 0
	v_mfma_f32_16x16x32_bf16 v[48:51], v[186:189], v[194:197], 0
	v_mfma_f32_16x16x32_bf16 v[40:43], v[176:179], v[202:205], 0
	v_mfma_f32_16x16x32_bf16 v[32:35], v[186:189], v[202:205], 0
	v_mfma_f32_16x16x32_bf16 v[24:27], v[176:179], v[210:213], 0
	v_mfma_f32_16x16x32_bf16 v[16:19], v[186:189], v[210:213], 0
	v_mfma_f32_16x16x32_bf16 v[8:11], v[176:179], v[218:221], 0
	v_mfma_f32_16x16x32_bf16 v[0:3], v[186:189], v[218:221], 0
	v_mfma_f32_16x16x32_bf16 v[56:59], v[180:183], v[198:201], v[56:59]
	v_mfma_f32_16x16x32_bf16 v[48:51], v[190:193], v[198:201], v[48:51]
	v_mfma_f32_16x16x32_bf16 v[40:43], v[180:183], v[206:209], v[40:43]
	v_mfma_f32_16x16x32_bf16 v[32:35], v[190:193], v[206:209], v[32:35]
	v_mfma_f32_16x16x32_bf16 v[24:27], v[180:183], v[214:217], v[24:27]
	v_mfma_f32_16x16x32_bf16 v[16:19], v[190:193], v[214:217], v[16:19]
	v_mfma_f32_16x16x32_bf16 v[8:11], v[180:183], v[222:225], v[8:11]
	v_mfma_f32_16x16x32_bf16 v[0:3], v[190:193], v[222:225], v[0:3]
	s_barrier
	s_setprio 0
	s_add_i32 s76, 0, 0x18000
	v_add_u32_e32 v153, s76, v147
	s_add_i32 s77, 0, 0x1c000
	ds_read_b128 v[160:163], v153
	v_xor_b32_e32 v253, 64, v153
	ds_read_b128 v[164:167], v253
	ds_read_b128 v[168:171], v153 offset:2048
	ds_read_b128 v[172:175], v253 offset:2048
	v_add_u32_e32 v153, s77, v147
	ds_read_b128 v[176:179], v153
	v_xor_b32_e32 v253, 64, v153
	ds_read_b128 v[180:183], v253
	ds_read_b128 v[186:189], v153 offset:2048
	ds_read_b128 v[190:193], v253 offset:2048
	s_add_u32 s48, s48, 0x40000
	s_addc_u32 s49, s49, 0
	s_mov_b32 m0, s57
	v_lshl_add_u64 v[232:233], s[48:49], 0, v[134:135]
	ds_read_b128 v[194:197], v150 offset:32768
	v_xor_b32_e32 v253, 64, v150
	ds_read_b128 v[198:201], v253 offset:32768
	ds_read_b128 v[202:205], v150 offset:34816
	ds_read_b128 v[206:209], v253 offset:34816
	ds_read_b128 v[210:213], v150 offset:36864
	ds_read_b128 v[214:217], v253 offset:36864
	ds_read_b128 v[218:221], v150 offset:38912
	ds_read_b128 v[222:225], v253 offset:38912
	global_load_lds_dwordx4 v[232:233], off
	v_lshl_add_u64 v[232:233], s[48:49], 0, v[130:131]
	s_mov_b32 m0, s58
	s_nop 0
	global_load_lds_dwordx4 v[232:233], off
	s_waitcnt vmcnt(8)
	s_waitcnt lgkmcnt(0)
	s_setprio 1
	s_barrier
	v_mfma_f32_16x16x32_bf16 v[124:127], v[160:163], v[194:197], v[124:127]
	v_mfma_f32_16x16x32_bf16 v[124:127], v[164:167], v[198:201], v[124:127]
	v_mfma_f32_16x16x32_bf16 v[108:111], v[164:167], v[206:209], v[108:111]
	v_mfma_f32_16x16x32_bf16 v[108:111], v[160:163], v[202:205], v[108:111]
	v_mfma_f32_16x16x32_bf16 v[92:95], v[160:163], v[210:213], v[92:95]
	v_mfma_f32_16x16x32_bf16 v[92:95], v[164:167], v[214:217], v[92:95]
	v_mfma_f32_16x16x32_bf16 v[76:79], v[164:167], v[222:225], v[76:79]
	v_mfma_f32_16x16x32_bf16 v[76:79], v[160:163], v[218:221], v[76:79]
	v_mfma_f32_16x16x32_bf16 v[68:71], v[168:171], v[218:221], v[68:71]
	v_mfma_f32_16x16x32_bf16 v[68:71], v[172:175], v[222:225], v[68:71]
	v_mfma_f32_16x16x32_bf16 v[84:87], v[172:175], v[214:217], v[84:87]
	v_mfma_f32_16x16x32_bf16 v[84:87], v[168:171], v[210:213], v[84:87]
	v_mfma_f32_16x16x32_bf16 v[100:103], v[168:171], v[202:205], v[100:103]
	v_mfma_f32_16x16x32_bf16 v[100:103], v[172:175], v[206:209], v[100:103]
	v_mfma_f32_16x16x32_bf16 v[116:119], v[172:175], v[198:201], v[116:119]
	v_mfma_f32_16x16x32_bf16 v[116:119], v[168:171], v[194:197], v[116:119]
	s_setprio 0
	s_setprio 1
	v_mfma_f32_16x16x32_bf16 v[112:115], v[186:189], v[194:197], v[112:115]
	v_mfma_f32_16x16x32_bf16 v[112:115], v[190:193], v[198:201], v[112:115]
	v_mfma_f32_16x16x32_bf16 v[96:99], v[190:193], v[206:209], v[96:99]
	v_mfma_f32_16x16x32_bf16 v[96:99], v[186:189], v[202:205], v[96:99]
	v_mfma_f32_16x16x32_bf16 v[80:83], v[186:189], v[210:213], v[80:83]
	v_mfma_f32_16x16x32_bf16 v[80:83], v[190:193], v[214:217], v[80:83]
	v_mfma_f32_16x16x32_bf16 v[64:67], v[190:193], v[222:225], v[64:67]
	v_mfma_f32_16x16x32_bf16 v[64:67], v[186:189], v[218:221], v[64:67]
	v_mfma_f32_16x16x32_bf16 v[72:75], v[176:179], v[218:221], v[72:75]
	v_mfma_f32_16x16x32_bf16 v[72:75], v[180:183], v[222:225], v[72:75]
	v_mfma_f32_16x16x32_bf16 v[88:91], v[180:183], v[214:217], v[88:91]
	v_mfma_f32_16x16x32_bf16 v[88:91], v[176:179], v[210:213], v[88:91]
	v_mfma_f32_16x16x32_bf16 v[104:107], v[176:179], v[202:205], v[104:107]
	v_mfma_f32_16x16x32_bf16 v[104:107], v[180:183], v[206:209], v[104:107]
	v_mfma_f32_16x16x32_bf16 v[120:123], v[180:183], v[198:201], v[120:123]
	v_mfma_f32_16x16x32_bf16 v[120:123], v[176:179], v[194:197], v[120:123]
	s_barrier
	s_setprio 0
	s_add_i32 s48, s76, s52
	v_lshl_add_u64 v[154:155], v[154:155], 0, s[14:15]
	s_mov_b32 m0, s48
	ds_read_b128 v[194:197], v150 offset:49152
	v_xor_b32_e32 v253, 64, v150
	ds_read_b128 v[198:201], v253 offset:49152
	ds_read_b128 v[202:205], v150 offset:51200
	ds_read_b128 v[206:209], v253 offset:51200
	ds_read_b128 v[210:213], v150 offset:53248
	ds_read_b128 v[214:217], v253 offset:53248
	ds_read_b128 v[218:221], v150 offset:55296
	ds_read_b128 v[222:225], v253 offset:55296
	global_load_lds_dwordx4 v[154:155], off
	s_add_i32 m0, s48, 0x2000
	s_add_u32 s46, s46, 0x40080
	v_lshl_add_u64 v[154:155], v[226:227], 0, s[14:15]
	s_addc_u32 s47, s47, 0
	s_add_i32 s48, s77, s52
	global_load_lds_dwordx4 v[154:155], off
	v_lshl_add_u64 v[154:155], s[46:47], 0, v[132:133]
	s_mov_b32 m0, s48
	s_nop 0
	global_load_lds_dwordx4 v[154:155], off
	v_lshl_add_u64 v[154:155], s[46:47], 0, v[128:129]
	s_add_i32 m0, s48, 0x2000
	s_nop 0
	global_load_lds_dwordx4 v[154:155], off
	v_lshl_add_u64 v[154:155], v[228:229], 0, s[14:15]
	s_mov_b32 m0, s60
	s_nop 0
	global_load_lds_dwordx4 v[154:155], off
	v_lshl_add_u64 v[154:155], v[230:231], 0, s[14:15]
	s_mov_b32 m0, s61
	s_nop 0
	global_load_lds_dwordx4 v[154:155], off
	s_waitcnt vmcnt(8)
	s_waitcnt lgkmcnt(0)
	s_setprio 1
	s_barrier
	v_mfma_f32_16x16x32_bf16 v[60:63], v[160:163], v[194:197], v[60:63]
	v_mfma_f32_16x16x32_bf16 v[60:63], v[164:167], v[198:201], v[60:63]
	v_mfma_f32_16x16x32_bf16 v[44:47], v[164:167], v[206:209], v[44:47]
	v_mfma_f32_16x16x32_bf16 v[44:47], v[160:163], v[202:205], v[44:47]
	v_mfma_f32_16x16x32_bf16 v[28:31], v[160:163], v[210:213], v[28:31]
	v_mfma_f32_16x16x32_bf16 v[28:31], v[164:167], v[214:217], v[28:31]
	v_mfma_f32_16x16x32_bf16 v[12:15], v[164:167], v[222:225], v[12:15]
	v_mfma_f32_16x16x32_bf16 v[12:15], v[160:163], v[218:221], v[12:15]
	v_mfma_f32_16x16x32_bf16 v[4:7], v[168:171], v[218:221], v[4:7]
	v_mfma_f32_16x16x32_bf16 v[4:7], v[172:175], v[222:225], v[4:7]
	v_mfma_f32_16x16x32_bf16 v[20:23], v[172:175], v[214:217], v[20:23]
	v_mfma_f32_16x16x32_bf16 v[20:23], v[168:171], v[210:213], v[20:23]
	v_mfma_f32_16x16x32_bf16 v[36:39], v[168:171], v[202:205], v[36:39]
	v_mfma_f32_16x16x32_bf16 v[36:39], v[172:175], v[206:209], v[36:39]
	v_mfma_f32_16x16x32_bf16 v[52:55], v[172:175], v[198:201], v[52:55]
	v_mfma_f32_16x16x32_bf16 v[52:55], v[168:171], v[194:197], v[52:55]
	s_setprio 0
	s_setprio 1
	v_mfma_f32_16x16x32_bf16 v[48:51], v[186:189], v[194:197], v[48:51]
	v_mfma_f32_16x16x32_bf16 v[48:51], v[190:193], v[198:201], v[48:51]
	v_mfma_f32_16x16x32_bf16 v[32:35], v[190:193], v[206:209], v[32:35]
	v_mfma_f32_16x16x32_bf16 v[32:35], v[186:189], v[202:205], v[32:35]
	v_mfma_f32_16x16x32_bf16 v[16:19], v[186:189], v[210:213], v[16:19]
	v_mfma_f32_16x16x32_bf16 v[16:19], v[190:193], v[214:217], v[16:19]
	v_mfma_f32_16x16x32_bf16 v[0:3], v[190:193], v[222:225], v[0:3]
	v_mfma_f32_16x16x32_bf16 v[0:3], v[186:189], v[218:221], v[0:3]
	v_mfma_f32_16x16x32_bf16 v[8:11], v[176:179], v[218:221], v[8:11]
	v_mfma_f32_16x16x32_bf16 v[8:11], v[180:183], v[222:225], v[8:11]
	v_mfma_f32_16x16x32_bf16 v[24:27], v[180:183], v[214:217], v[24:27]
	v_mfma_f32_16x16x32_bf16 v[24:27], v[176:179], v[210:213], v[24:27]
	v_mfma_f32_16x16x32_bf16 v[40:43], v[176:179], v[202:205], v[40:43]
	v_mfma_f32_16x16x32_bf16 v[40:43], v[180:183], v[206:209], v[40:43]
	v_mfma_f32_16x16x32_bf16 v[56:59], v[180:183], v[198:201], v[56:59]
	v_mfma_f32_16x16x32_bf16 v[56:59], v[176:179], v[194:197], v[56:59]
	s_barrier
	s_setprio 0
	s_add_i32 s75, s75, 2
	s_add_u32 s71, s71, 0x100
	s_addc_u32 s74, s74, 0
	s_add_u32 s44, s44, 0x100
	s_addc_u32 s45, s45, 0
	s_branch .LBB0_76
.Lfa_0:
	v_add_u32_e32 v153, s64, v147
	ds_read_b128 v[160:163], v153
	v_xor_b32_e32 v253, 64, v153
	ds_read_b128 v[164:167], v253
	ds_read_b128 v[168:171], v153 offset:2048
	ds_read_b128 v[172:175], v253 offset:2048
	v_add_u32_e32 v153, s65, v147
	ds_read_b128 v[176:179], v153
	v_xor_b32_e32 v253, 64, v153
	ds_read_b128 v[180:183], v253
	ds_read_b128 v[186:189], v153 offset:2048
	ds_read_b128 v[190:193], v253 offset:2048
	s_add_u32 s48, s44, 0xfffc0080
	s_addc_u32 s49, s45, -1
	s_and_b64 s[46:47], s[46:47], exec
	s_cselect_b32 s49, s27, s49
	s_cselect_b32 s48, s68, s48
	s_cselect_b32 s47, s69, s74
	s_cselect_b32 s46, s70, s71
	v_lshl_add_u64 v[154:155], s[44:45], 0, v[138:139]
	s_add_i32 m0, s55, 0xc000
	ds_read_b128 v[194:197], v150
	v_xor_b32_e32 v253, 64, v150
	ds_read_b128 v[198:201], v253
	ds_read_b128 v[202:205], v150 offset:2048
	ds_read_b128 v[206:209], v253 offset:2048
	ds_read_b128 v[210:213], v150 offset:4096
	ds_read_b128 v[214:217], v253 offset:4096
	ds_read_b128 v[218:221], v150 offset:6144
	ds_read_b128 v[222:225], v253 offset:6144
	global_load_lds_dwordx4 v[154:155], off
	v_lshl_add_u64 v[154:155], s[44:45], 0, v[136:137]
	s_add_i32 m0, s55, 0xe000
	s_nop 0
	global_load_lds_dwordx4 v[154:155], off
	s_waitcnt vmcnt(8)
	s_waitcnt lgkmcnt(0)
	s_setprio 1
	s_barrier
	v_mfma_f32_16x16x32_bf16 v[124:127], v[160:163], v[194:197], 0
	v_mfma_f32_16x16x32_bf16 v[116:119], v[168:171], v[194:197], 0
	v_mfma_f32_16x16x32_bf16 v[108:111], v[160:163], v[202:205], 0
	v_mfma_f32_16x16x32_bf16 v[100:103], v[168:171], v[202:205], 0
	v_mfma_f32_16x16x32_bf16 v[92:95], v[160:163], v[210:213], 0
	v_mfma_f32_16x16x32_bf16 v[84:87], v[168:171], v[210:213], 0
	v_mfma_f32_16x16x32_bf16 v[76:79], v[160:163], v[218:221], 0
	v_mfma_f32_16x16x32_bf16 v[68:71], v[168:171], v[218:221], 0
	v_mfma_f32_16x16x32_bf16 v[124:127], v[164:167], v[198:201], v[124:127]
	v_mfma_f32_16x16x32_bf16 v[116:119], v[172:175], v[198:201], v[116:119]
	v_mfma_f32_16x16x32_bf16 v[108:111], v[164:167], v[206:209], v[108:111]
	v_mfma_f32_16x16x32_bf16 v[100:103], v[172:175], v[206:209], v[100:103]
	v_mfma_f32_16x16x32_bf16 v[92:95], v[164:167], v[214:217], v[92:95]
	v_mfma_f32_16x16x32_bf16 v[84:87], v[172:175], v[214:217], v[84:87]
	v_mfma_f32_16x16x32_bf16 v[76:79], v[164:167], v[222:225], v[76:79]
	v_mfma_f32_16x16x32_bf16 v[68:71], v[172:175], v[222:225], v[68:71]
	s_setprio 0
	s_setprio 1
	v_mfma_f32_16x16x32_bf16 v[120:123], v[176:179], v[194:197], 0
	v_mfma_f32_16x16x32_bf16 v[112:115], v[186:189], v[194:197], 0
	v_mfma_f32_16x16x32_bf16 v[104:107], v[176:179], v[202:205], 0
	v_mfma_f32_16x16x32_bf16 v[96:99], v[186:189], v[202:205], 0
	v_mfma_f32_16x16x32_bf16 v[88:91], v[176:179], v[210:213], 0
	v_mfma_f32_16x16x32_bf16 v[80:83], v[186:189], v[210:213], 0
	v_mfma_f32_16x16x32_bf16 v[72:75], v[176:179], v[218:221], 0
	v_mfma_f32_16x16x32_bf16 v[64:67], v[186:189], v[218:221], 0
	v_mfma_f32_16x16x32_bf16 v[120:123], v[180:183], v[198:201], v[120:123]
	v_mfma_f32_16x16x32_bf16 v[112:115], v[190:193], v[198:201], v[112:115]
	v_mfma_f32_16x16x32_bf16 v[104:107], v[180:183], v[206:209], v[104:107]
	v_mfma_f32_16x16x32_bf16 v[96:99], v[190:193], v[206:209], v[96:99]
	v_mfma_f32_16x16x32_bf16 v[88:91], v[180:183], v[214:217], v[88:91]
	v_mfma_f32_16x16x32_bf16 v[80:83], v[190:193], v[214:217], v[80:83]
	v_mfma_f32_16x16x32_bf16 v[72:75], v[180:183], v[222:225], v[72:75]
	v_mfma_f32_16x16x32_bf16 v[64:67], v[190:193], v[222:225], v[64:67]
	s_barrier
	s_setprio 0
	s_add_i32 s76, s64, s52
	v_lshl_add_u64 v[154:155], s[46:47], 0, v[132:133]
	s_mov_b32 m0, s76
	ds_read_b128 v[194:197], v150 offset:16384
	v_xor_b32_e32 v253, 64, v150
	ds_read_b128 v[198:201], v253 offset:16384
	ds_read_b128 v[202:205], v150 offset:18432
	ds_read_b128 v[206:209], v253 offset:18432
	ds_read_b128 v[210:213], v150 offset:20480
	ds_read_b128 v[214:217], v253 offset:20480
	ds_read_b128 v[218:221], v150 offset:22528
	ds_read_b128 v[222:225], v253 offset:22528
	global_load_lds_dwordx4 v[154:155], off
	s_add_i32 m0, s76, 0x2000
	s_add_u32 s76, s46, 0x40000
	v_lshl_add_u64 v[226:227], s[46:47], 0, v[128:129]
	s_addc_u32 s77, s47, 0
	s_add_i32 s78, s65, s52
	global_load_lds_dwordx4 v[226:227], off
	v_lshl_add_u64 v[228:229], s[76:77], 0, v[132:133]
	s_mov_b32 m0, s78
	v_lshl_add_u64 v[230:231], s[48:49], 0, v[130:131]
	global_load_lds_dwordx4 v[228:229], off
	v_lshl_add_u64 v[228:229], s[76:77], 0, v[128:129]
	s_add_i32 m0, s78, 0x2000
	s_nop 0
	global_load_lds_dwordx4 v[228:229], off
	v_lshl_add_u64 v[228:229], s[48:49], 0, v[134:135]
	s_mov_b32 m0, s55
	s_nop 0
	global_load_lds_dwordx4 v[228:229], off
	s_mov_b32 m0, s56
	s_nop 0
	global_load_lds_dwordx4 v[230:231], off
	s_waitcnt vmcnt(8)
	s_waitcnt lgkmcnt(0)
	s_setprio 1
	s_barrier
	v_mfma_f32_16x16x32_bf16 v[60:63], v[160:163], v[194:197], 0
	v_mfma_f32_16x16x32_bf16 v[52:55], v[168:171], v[194:197], 0
	v_mfma_f32_16x16x32_bf16 v[44:47], v[160:163], v[202:205], 0
	v_mfma_f32_16x16x32_bf16 v[36:39], v[168:171], v[202:205], 0
	v_mfma_f32_16x16x32_bf16 v[28:31], v[160:163], v[210:213], 0
	v_mfma_f32_16x16x32_bf16 v[20:23], v[168:171], v[210:213], 0
	v_mfma_f32_16x16x32_bf16 v[12:15], v[160:163], v[218:221], 0
	v_mfma_f32_16x16x32_bf16 v[4:7], v[168:171], v[218:221], 0
	v_mfma_f32_16x16x32_bf16 v[60:63], v[164:167], v[198:201], v[60:63]
	v_mfma_f32_16x16x32_bf16 v[52:55], v[172:175], v[198:201], v[52:55]
	v_mfma_f32_16x16x32_bf16 v[44:47], v[164:167], v[206:209], v[44:47]
	v_mfma_f32_16x16x32_bf16 v[36:39], v[172:175], v[206:209], v[36:39]
	v_mfma_f32_16x16x32_bf16 v[28:31], v[164:167], v[214:217], v[28:31]
	v_mfma_f32_16x16x32_bf16 v[20:23], v[172:175], v[214:217], v[20:23]
	v_mfma_f32_16x16x32_bf16 v[12:15], v[164:167], v[222:225], v[12:15]
	v_mfma_f32_16x16x32_bf16 v[4:7], v[172:175], v[222:225], v[4:7]
	s_setprio 0
	s_setprio 1
	v_mfma_f32_16x16x32_bf16 v[56:59], v[176:179], v[194:197], 0
	v_mfma_f32_16x16x32_bf16 v[48:51], v[186:189], v[194:197], 0
	v_mfma_f32_16x16x32_bf16 v[40:43], v[176:179], v[202:205], 0
	v_mfma_f32_16x16x32_bf16 v[32:35], v[186:189], v[202:205], 0
	v_mfma_f32_16x16x32_bf16 v[24:27], v[176:179], v[210:213], 0
	v_mfma_f32_16x16x32_bf16 v[16:19], v[186:189], v[210:213], 0
	v_mfma_f32_16x16x32_bf16 v[8:11], v[176:179], v[218:221], 0
	v_mfma_f32_16x16x32_bf16 v[0:3], v[186:189], v[218:221], 0
	v_mfma_f32_16x16x32_bf16 v[56:59], v[180:183], v[198:201], v[56:59]
	v_mfma_f32_16x16x32_bf16 v[48:51], v[190:193], v[198:201], v[48:51]
	v_mfma_f32_16x16x32_bf16 v[40:43], v[180:183], v[206:209], v[40:43]
	v_mfma_f32_16x16x32_bf16 v[32:35], v[190:193], v[206:209], v[32:35]
	v_mfma_f32_16x16x32_bf16 v[24:27], v[180:183], v[214:217], v[24:27]
	v_mfma_f32_16x16x32_bf16 v[16:19], v[190:193], v[214:217], v[16:19]
	v_mfma_f32_16x16x32_bf16 v[8:11], v[180:183], v[222:225], v[8:11]
	v_mfma_f32_16x16x32_bf16 v[0:3], v[190:193], v[222:225], v[0:3]
	s_barrier
	s_setprio 0
	s_add_i32 s76, 0, 0x18000
	v_add_u32_e32 v153, s76, v147
	s_add_i32 s77, 0, 0x1c000
	ds_read_b128 v[160:163], v153
	v_xor_b32_e32 v253, 64, v153
	ds_read_b128 v[164:167], v253
	ds_read_b128 v[168:171], v153 offset:2048
	ds_read_b128 v[172:175], v253 offset:2048
	v_add_u32_e32 v153, s77, v147
	ds_read_b128 v[176:179], v153
	v_xor_b32_e32 v253, 64, v153
	ds_read_b128 v[180:183], v253
	ds_read_b128 v[186:189], v153 offset:2048
	ds_read_b128 v[190:193], v253 offset:2048
	s_add_u32 s48, s48, 0x40000
	s_addc_u32 s49, s49, 0
	s_mov_b32 m0, s57
	v_lshl_add_u64 v[232:233], s[48:49], 0, v[134:135]
	ds_read_b128 v[194:197], v150 offset:32768
	v_xor_b32_e32 v253, 64, v150
	ds_read_b128 v[198:201], v253 offset:32768
	ds_read_b128 v[202:205], v150 offset:34816
	ds_read_b128 v[206:209], v253 offset:34816
	ds_read_b128 v[210:213], v150 offset:36864
	ds_read_b128 v[214:217], v253 offset:36864
	ds_read_b128 v[218:221], v150 offset:38912
	ds_read_b128 v[222:225], v253 offset:38912
	global_load_lds_dwordx4 v[232:233], off
	v_lshl_add_u64 v[232:233], s[48:49], 0, v[130:131]
	s_mov_b32 m0, s58
	s_nop 0
	global_load_lds_dwordx4 v[232:233], off
	s_waitcnt vmcnt(8)
	s_waitcnt lgkmcnt(0)
	s_setprio 1
	s_barrier
	v_mfma_f32_16x16x32_bf16 v[124:127], v[160:163], v[194:197], v[124:127]
	v_mfma_f32_16x16x32_bf16 v[124:127], v[164:167], v[198:201], v[124:127]
	v_mfma_f32_16x16x32_bf16 v[108:111], v[164:167], v[206:209], v[108:111]
	v_mfma_f32_16x16x32_bf16 v[108:111], v[160:163], v[202:205], v[108:111]
	v_mfma_f32_16x16x32_bf16 v[92:95], v[160:163], v[210:213], v[92:95]
	v_mfma_f32_16x16x32_bf16 v[92:95], v[164:167], v[214:217], v[92:95]
	v_mfma_f32_16x16x32_bf16 v[76:79], v[164:167], v[222:225], v[76:79]
	v_mfma_f32_16x16x32_bf16 v[76:79], v[160:163], v[218:221], v[76:79]
	v_mfma_f32_16x16x32_bf16 v[68:71], v[168:171], v[218:221], v[68:71]
	v_mfma_f32_16x16x32_bf16 v[68:71], v[172:175], v[222:225], v[68:71]
	v_mfma_f32_16x16x32_bf16 v[84:87], v[172:175], v[214:217], v[84:87]
	v_mfma_f32_16x16x32_bf16 v[84:87], v[168:171], v[210:213], v[84:87]
	v_mfma_f32_16x16x32_bf16 v[100:103], v[168:171], v[202:205], v[100:103]
	v_mfma_f32_16x16x32_bf16 v[100:103], v[172:175], v[206:209], v[100:103]
	v_mfma_f32_16x16x32_bf16 v[116:119], v[172:175], v[198:201], v[116:119]
	v_mfma_f32_16x16x32_bf16 v[116:119], v[168:171], v[194:197], v[116:119]
	s_setprio 0
	s_setprio 1
	v_mfma_f32_16x16x32_bf16 v[112:115], v[186:189], v[194:197], v[112:115]
	v_mfma_f32_16x16x32_bf16 v[112:115], v[190:193], v[198:201], v[112:115]
	v_mfma_f32_16x16x32_bf16 v[96:99], v[190:193], v[206:209], v[96:99]
	v_mfma_f32_16x16x32_bf16 v[96:99], v[186:189], v[202:205], v[96:99]
	v_mfma_f32_16x16x32_bf16 v[80:83], v[186:189], v[210:213], v[80:83]
	v_mfma_f32_16x16x32_bf16 v[80:83], v[190:193], v[214:217], v[80:83]
	v_mfma_f32_16x16x32_bf16 v[64:67], v[190:193], v[222:225], v[64:67]
	v_mfma_f32_16x16x32_bf16 v[64:67], v[186:189], v[218:221], v[64:67]
	v_mfma_f32_16x16x32_bf16 v[72:75], v[176:179], v[218:221], v[72:75]
	v_mfma_f32_16x16x32_bf16 v[72:75], v[180:183], v[222:225], v[72:75]
	v_mfma_f32_16x16x32_bf16 v[88:91], v[180:183], v[214:217], v[88:91]
	v_mfma_f32_16x16x32_bf16 v[88:91], v[176:179], v[210:213], v[88:91]
	v_mfma_f32_16x16x32_bf16 v[104:107], v[176:179], v[202:205], v[104:107]
	v_mfma_f32_16x16x32_bf16 v[104:107], v[180:183], v[206:209], v[104:107]
	v_mfma_f32_16x16x32_bf16 v[120:123], v[180:183], v[198:201], v[120:123]
	v_mfma_f32_16x16x32_bf16 v[120:123], v[176:179], v[194:197], v[120:123]
	s_barrier
	s_setprio 0
	s_add_i32 s48, s76, s52
	v_lshl_add_u64 v[154:155], v[154:155], 0, s[14:15]
	s_mov_b32 m0, s48
	ds_read_b128 v[194:197], v150 offset:49152
	v_xor_b32_e32 v253, 64, v150
	ds_read_b128 v[198:201], v253 offset:49152
	ds_read_b128 v[202:205], v150 offset:51200
	ds_read_b128 v[206:209], v253 offset:51200
	ds_read_b128 v[210:213], v150 offset:53248
	ds_read_b128 v[214:217], v253 offset:53248
	ds_read_b128 v[218:221], v150 offset:55296
	ds_read_b128 v[222:225], v253 offset:55296
	global_load_lds_dwordx4 v[154:155], off
	s_add_i32 m0, s48, 0x2000
	s_add_u32 s46, s46, 0x40080
	v_lshl_add_u64 v[154:155], v[226:227], 0, s[14:15]
	s_addc_u32 s47, s47, 0
	s_add_i32 s48, s77, s52
	global_load_lds_dwordx4 v[154:155], off
	v_lshl_add_u64 v[154:155], s[46:47], 0, v[132:133]
	s_mov_b32 m0, s48
	s_nop 0
	global_load_lds_dwordx4 v[154:155], off
	v_lshl_add_u64 v[154:155], s[46:47], 0, v[128:129]
	s_add_i32 m0, s48, 0x2000
	s_nop 0
	global_load_lds_dwordx4 v[154:155], off
	v_lshl_add_u64 v[154:155], v[228:229], 0, s[14:15]
	s_mov_b32 m0, s60
	s_nop 0
	global_load_lds_dwordx4 v[154:155], off
	v_lshl_add_u64 v[154:155], v[230:231], 0, s[14:15]
	s_mov_b32 m0, s61
	s_nop 0
	global_load_lds_dwordx4 v[154:155], off
	s_waitcnt vmcnt(8)
	s_waitcnt lgkmcnt(0)
	s_setprio 1
	s_barrier
	v_mfma_f32_16x16x32_bf16 v[60:63], v[160:163], v[194:197], v[60:63]
	v_mfma_f32_16x16x32_bf16 v[60:63], v[164:167], v[198:201], v[60:63]
	v_mfma_f32_16x16x32_bf16 v[44:47], v[164:167], v[206:209], v[44:47]
	v_mfma_f32_16x16x32_bf16 v[44:47], v[160:163], v[202:205], v[44:47]
	v_mfma_f32_16x16x32_bf16 v[28:31], v[160:163], v[210:213], v[28:31]
	v_mfma_f32_16x16x32_bf16 v[28:31], v[164:167], v[214:217], v[28:31]
	v_mfma_f32_16x16x32_bf16 v[12:15], v[164:167], v[222:225], v[12:15]
	v_mfma_f32_16x16x32_bf16 v[12:15], v[160:163], v[218:221], v[12:15]
	v_mfma_f32_16x16x32_bf16 v[4:7], v[168:171], v[218:221], v[4:7]
	v_mfma_f32_16x16x32_bf16 v[4:7], v[172:175], v[222:225], v[4:7]
	v_mfma_f32_16x16x32_bf16 v[20:23], v[172:175], v[214:217], v[20:23]
	v_mfma_f32_16x16x32_bf16 v[20:23], v[168:171], v[210:213], v[20:23]
	v_mfma_f32_16x16x32_bf16 v[36:39], v[168:171], v[202:205], v[36:39]
	v_mfma_f32_16x16x32_bf16 v[36:39], v[172:175], v[206:209], v[36:39]
	v_mfma_f32_16x16x32_bf16 v[52:55], v[172:175], v[198:201], v[52:55]
	v_mfma_f32_16x16x32_bf16 v[52:55], v[168:171], v[194:197], v[52:55]
	s_setprio 0
	s_setprio 1
	v_mfma_f32_16x16x32_bf16 v[48:51], v[186:189], v[194:197], v[48:51]
	v_mfma_f32_16x16x32_bf16 v[48:51], v[190:193], v[198:201], v[48:51]
	v_mfma_f32_16x16x32_bf16 v[32:35], v[190:193], v[206:209], v[32:35]
	v_mfma_f32_16x16x32_bf16 v[32:35], v[186:189], v[202:205], v[32:35]
	v_mfma_f32_16x16x32_bf16 v[16:19], v[186:189], v[210:213], v[16:19]
	v_mfma_f32_16x16x32_bf16 v[16:19], v[190:193], v[214:217], v[16:19]
	v_mfma_f32_16x16x32_bf16 v[0:3], v[190:193], v[222:225], v[0:3]
	v_mfma_f32_16x16x32_bf16 v[0:3], v[186:189], v[218:221], v[0:3]
	v_mfma_f32_16x16x32_bf16 v[8:11], v[176:179], v[218:221], v[8:11]
	v_mfma_f32_16x16x32_bf16 v[8:11], v[180:183], v[222:225], v[8:11]
	v_mfma_f32_16x16x32_bf16 v[24:27], v[180:183], v[214:217], v[24:27]
	v_mfma_f32_16x16x32_bf16 v[24:27], v[176:179], v[210:213], v[24:27]
	v_mfma_f32_16x16x32_bf16 v[40:43], v[176:179], v[202:205], v[40:43]
	v_mfma_f32_16x16x32_bf16 v[40:43], v[180:183], v[206:209], v[40:43]
	v_mfma_f32_16x16x32_bf16 v[56:59], v[180:183], v[198:201], v[56:59]
	v_mfma_f32_16x16x32_bf16 v[56:59], v[176:179], v[194:197], v[56:59]
	s_barrier
	s_setprio 0
	s_add_i32 s75, s75, 2
	s_add_u32 s71, s71, 0x100
	s_addc_u32 s74, s74, 0
	s_add_u32 s44, s44, 0x100
	s_addc_u32 s45, s45, 0
	s_branch .LBB0_76
.LBB0_75:
	v_add_u32_e32 v153, s64, v147
	ds_read_b128 v[160:163], v153
	v_xor_b32_e32 v253, 64, v153
	ds_read_b128 v[164:167], v253
	ds_read_b128 v[168:171], v153 offset:2048
	ds_read_b128 v[172:175], v253 offset:2048
	v_add_u32_e32 v153, s65, v147
	ds_read_b128 v[176:179], v153
	v_xor_b32_e32 v253, 64, v153
	ds_read_b128 v[180:183], v253
	ds_read_b128 v[186:189], v153 offset:2048
	ds_read_b128 v[190:193], v253 offset:2048
	s_add_u32 s48, s44, 0xfffc0080
	s_addc_u32 s49, s45, -1
	s_and_b64 s[46:47], s[46:47], exec
	s_cselect_b32 s49, s27, s49
	s_cselect_b32 s48, s68, s48
	s_cselect_b32 s47, s69, s74
	s_cselect_b32 s46, s70, s71
	v_lshl_add_u64 v[154:155], s[44:45], 0, v[138:139]
	s_add_i32 m0, s55, 0xc000
	ds_read_b128 v[194:197], v150
	v_xor_b32_e32 v253, 64, v150
	ds_read_b128 v[198:201], v253
	ds_read_b128 v[202:205], v150 offset:2048
	ds_read_b128 v[206:209], v253 offset:2048
	ds_read_b128 v[210:213], v150 offset:4096
	ds_read_b128 v[214:217], v253 offset:4096
	ds_read_b128 v[218:221], v150 offset:6144
	ds_read_b128 v[222:225], v253 offset:6144
	global_load_lds_dwordx4 v[154:155], off
	v_lshl_add_u64 v[154:155], s[44:45], 0, v[136:137]
	s_add_i32 m0, s55, 0xe000
	s_nop 0
	global_load_lds_dwordx4 v[154:155], off
	s_waitcnt vmcnt(8)
	s_waitcnt lgkmcnt(0)
	s_setprio 1
	s_barrier
	v_mfma_f32_16x16x32_bf16 v[124:127], v[160:163], v[194:197], v[124:127]
	v_mfma_f32_16x16x32_bf16 v[124:127], v[164:167], v[198:201], v[124:127]
	v_mfma_f32_16x16x32_bf16 v[108:111], v[164:167], v[206:209], v[108:111]
	v_mfma_f32_16x16x32_bf16 v[108:111], v[160:163], v[202:205], v[108:111]
	v_mfma_f32_16x16x32_bf16 v[92:95], v[160:163], v[210:213], v[92:95]
	v_mfma_f32_16x16x32_bf16 v[92:95], v[164:167], v[214:217], v[92:95]
	v_mfma_f32_16x16x32_bf16 v[76:79], v[164:167], v[222:225], v[76:79]
	v_mfma_f32_16x16x32_bf16 v[76:79], v[160:163], v[218:221], v[76:79]
	v_mfma_f32_16x16x32_bf16 v[68:71], v[168:171], v[218:221], v[68:71]
	v_mfma_f32_16x16x32_bf16 v[68:71], v[172:175], v[222:225], v[68:71]
	v_mfma_f32_16x16x32_bf16 v[84:87], v[172:175], v[214:217], v[84:87]
	v_mfma_f32_16x16x32_bf16 v[84:87], v[168:171], v[210:213], v[84:87]
	v_mfma_f32_16x16x32_bf16 v[100:103], v[168:171], v[202:205], v[100:103]
	v_mfma_f32_16x16x32_bf16 v[100:103], v[172:175], v[206:209], v[100:103]
	v_mfma_f32_16x16x32_bf16 v[116:119], v[172:175], v[198:201], v[116:119]
	v_mfma_f32_16x16x32_bf16 v[116:119], v[168:171], v[194:197], v[116:119]
	s_setprio 0
	s_setprio 1
	v_mfma_f32_16x16x32_bf16 v[112:115], v[186:189], v[194:197], v[112:115]
	v_mfma_f32_16x16x32_bf16 v[112:115], v[190:193], v[198:201], v[112:115]
	v_mfma_f32_16x16x32_bf16 v[96:99], v[190:193], v[206:209], v[96:99]
	v_mfma_f32_16x16x32_bf16 v[96:99], v[186:189], v[202:205], v[96:99]
	v_mfma_f32_16x16x32_bf16 v[80:83], v[186:189], v[210:213], v[80:83]
	v_mfma_f32_16x16x32_bf16 v[80:83], v[190:193], v[214:217], v[80:83]
	v_mfma_f32_16x16x32_bf16 v[64:67], v[190:193], v[222:225], v[64:67]
	v_mfma_f32_16x16x32_bf16 v[64:67], v[186:189], v[218:221], v[64:67]
	v_mfma_f32_16x16x32_bf16 v[72:75], v[176:179], v[218:221], v[72:75]
	v_mfma_f32_16x16x32_bf16 v[72:75], v[180:183], v[222:225], v[72:75]
	v_mfma_f32_16x16x32_bf16 v[88:91], v[180:183], v[214:217], v[88:91]
	v_mfma_f32_16x16x32_bf16 v[88:91], v[176:179], v[210:213], v[88:91]
	v_mfma_f32_16x16x32_bf16 v[104:107], v[176:179], v[202:205], v[104:107]
	v_mfma_f32_16x16x32_bf16 v[104:107], v[180:183], v[206:209], v[104:107]
	v_mfma_f32_16x16x32_bf16 v[120:123], v[180:183], v[198:201], v[120:123]
	v_mfma_f32_16x16x32_bf16 v[120:123], v[176:179], v[194:197], v[120:123]
	s_barrier
	s_setprio 0
	s_add_i32 s76, s64, s52
	v_lshl_add_u64 v[154:155], s[46:47], 0, v[132:133]
	s_mov_b32 m0, s76
	ds_read_b128 v[194:197], v150 offset:16384
	v_xor_b32_e32 v253, 64, v150
	ds_read_b128 v[198:201], v253 offset:16384
	ds_read_b128 v[202:205], v150 offset:18432
	ds_read_b128 v[206:209], v253 offset:18432
	ds_read_b128 v[210:213], v150 offset:20480
	ds_read_b128 v[214:217], v253 offset:20480
	ds_read_b128 v[218:221], v150 offset:22528
	ds_read_b128 v[222:225], v253 offset:22528
	global_load_lds_dwordx4 v[154:155], off
	s_add_i32 m0, s76, 0x2000
	s_add_u32 s76, s46, 0x40000
	v_lshl_add_u64 v[226:227], s[46:47], 0, v[128:129]
	s_addc_u32 s77, s47, 0
	s_add_i32 s78, s65, s52
	global_load_lds_dwordx4 v[226:227], off
	v_lshl_add_u64 v[228:229], s[76:77], 0, v[132:133]
	s_mov_b32 m0, s78
	v_lshl_add_u64 v[230:231], s[48:49], 0, v[130:131]
	global_load_lds_dwordx4 v[228:229], off
	v_lshl_add_u64 v[228:229], s[76:77], 0, v[128:129]
	s_add_i32 m0, s78, 0x2000
	s_nop 0
	global_load_lds_dwordx4 v[228:229], off
	v_lshl_add_u64 v[228:229], s[48:49], 0, v[134:135]
	s_mov_b32 m0, s55
	s_nop 0
	global_load_lds_dwordx4 v[228:229], off
	s_mov_b32 m0, s56
	s_nop 0
	global_load_lds_dwordx4 v[230:231], off
	s_waitcnt vmcnt(8)
	s_waitcnt lgkmcnt(0)
	s_setprio 1
	s_barrier
	v_mfma_f32_16x16x32_bf16 v[60:63], v[160:163], v[194:197], v[60:63]
	v_mfma_f32_16x16x32_bf16 v[60:63], v[164:167], v[198:201], v[60:63]
	v_mfma_f32_16x16x32_bf16 v[44:47], v[164:167], v[206:209], v[44:47]
	v_mfma_f32_16x16x32_bf16 v[44:47], v[160:163], v[202:205], v[44:47]
	v_mfma_f32_16x16x32_bf16 v[28:31], v[160:163], v[210:213], v[28:31]
	v_mfma_f32_16x16x32_bf16 v[28:31], v[164:167], v[214:217], v[28:31]
	v_mfma_f32_16x16x32_bf16 v[12:15], v[164:167], v[222:225], v[12:15]
	v_mfma_f32_16x16x32_bf16 v[12:15], v[160:163], v[218:221], v[12:15]
	v_mfma_f32_16x16x32_bf16 v[4:7], v[168:171], v[218:221], v[4:7]
	v_mfma_f32_16x16x32_bf16 v[4:7], v[172:175], v[222:225], v[4:7]
	v_mfma_f32_16x16x32_bf16 v[20:23], v[172:175], v[214:217], v[20:23]
	v_mfma_f32_16x16x32_bf16 v[20:23], v[168:171], v[210:213], v[20:23]
	v_mfma_f32_16x16x32_bf16 v[36:39], v[168:171], v[202:205], v[36:39]
	v_mfma_f32_16x16x32_bf16 v[36:39], v[172:175], v[206:209], v[36:39]
	v_mfma_f32_16x16x32_bf16 v[52:55], v[172:175], v[198:201], v[52:55]
	v_mfma_f32_16x16x32_bf16 v[52:55], v[168:171], v[194:197], v[52:55]
	s_setprio 0
	s_setprio 1
	v_mfma_f32_16x16x32_bf16 v[48:51], v[186:189], v[194:197], v[48:51]
	v_mfma_f32_16x16x32_bf16 v[48:51], v[190:193], v[198:201], v[48:51]
	v_mfma_f32_16x16x32_bf16 v[32:35], v[190:193], v[206:209], v[32:35]
	v_mfma_f32_16x16x32_bf16 v[32:35], v[186:189], v[202:205], v[32:35]
	v_mfma_f32_16x16x32_bf16 v[16:19], v[186:189], v[210:213], v[16:19]
	v_mfma_f32_16x16x32_bf16 v[16:19], v[190:193], v[214:217], v[16:19]
	v_mfma_f32_16x16x32_bf16 v[0:3], v[190:193], v[222:225], v[0:3]
	v_mfma_f32_16x16x32_bf16 v[0:3], v[186:189], v[218:221], v[0:3]
	v_mfma_f32_16x16x32_bf16 v[8:11], v[176:179], v[218:221], v[8:11]
	v_mfma_f32_16x16x32_bf16 v[8:11], v[180:183], v[222:225], v[8:11]
	v_mfma_f32_16x16x32_bf16 v[24:27], v[180:183], v[214:217], v[24:27]
	v_mfma_f32_16x16x32_bf16 v[24:27], v[176:179], v[210:213], v[24:27]
	v_mfma_f32_16x16x32_bf16 v[40:43], v[176:179], v[202:205], v[40:43]
	v_mfma_f32_16x16x32_bf16 v[40:43], v[180:183], v[206:209], v[40:43]
	v_mfma_f32_16x16x32_bf16 v[56:59], v[180:183], v[198:201], v[56:59]
	v_mfma_f32_16x16x32_bf16 v[56:59], v[176:179], v[194:197], v[56:59]
	s_barrier
	s_setprio 0
	s_add_i32 s76, 0, 0x18000
	v_add_u32_e32 v153, s76, v147
	s_add_i32 s77, 0, 0x1c000
	ds_read_b128 v[160:163], v153
	v_xor_b32_e32 v253, 64, v153
	ds_read_b128 v[164:167], v253
	ds_read_b128 v[168:171], v153 offset:2048
	ds_read_b128 v[172:175], v253 offset:2048
	v_add_u32_e32 v153, s77, v147
	ds_read_b128 v[176:179], v153
	v_xor_b32_e32 v253, 64, v153
	ds_read_b128 v[180:183], v253
	ds_read_b128 v[186:189], v153 offset:2048
	ds_read_b128 v[190:193], v253 offset:2048
	s_add_u32 s48, s48, 0x40000
	s_addc_u32 s49, s49, 0
	s_mov_b32 m0, s57
	v_lshl_add_u64 v[232:233], s[48:49], 0, v[134:135]
	ds_read_b128 v[194:197], v150 offset:32768
	v_xor_b32_e32 v253, 64, v150
	ds_read_b128 v[198:201], v253 offset:32768
	ds_read_b128 v[202:205], v150 offset:34816
	ds_read_b128 v[206:209], v253 offset:34816
	ds_read_b128 v[210:213], v150 offset:36864
	ds_read_b128 v[214:217], v253 offset:36864
	ds_read_b128 v[218:221], v150 offset:38912
	ds_read_b128 v[222:225], v253 offset:38912
	global_load_lds_dwordx4 v[232:233], off
	v_lshl_add_u64 v[232:233], s[48:49], 0, v[130:131]
	s_mov_b32 m0, s58
	s_nop 0
	global_load_lds_dwordx4 v[232:233], off
	s_waitcnt vmcnt(8)
	s_waitcnt lgkmcnt(0)
	s_setprio 1
	s_barrier
	v_mfma_f32_16x16x32_bf16 v[124:127], v[160:163], v[194:197], v[124:127]
	v_mfma_f32_16x16x32_bf16 v[124:127], v[164:167], v[198:201], v[124:127]
	v_mfma_f32_16x16x32_bf16 v[108:111], v[164:167], v[206:209], v[108:111]
	v_mfma_f32_16x16x32_bf16 v[108:111], v[160:163], v[202:205], v[108:111]
	v_mfma_f32_16x16x32_bf16 v[92:95], v[160:163], v[210:213], v[92:95]
	v_mfma_f32_16x16x32_bf16 v[92:95], v[164:167], v[214:217], v[92:95]
	v_mfma_f32_16x16x32_bf16 v[76:79], v[164:167], v[222:225], v[76:79]
	v_mfma_f32_16x16x32_bf16 v[76:79], v[160:163], v[218:221], v[76:79]
	v_mfma_f32_16x16x32_bf16 v[68:71], v[168:171], v[218:221], v[68:71]
	v_mfma_f32_16x16x32_bf16 v[68:71], v[172:175], v[222:225], v[68:71]
	v_mfma_f32_16x16x32_bf16 v[84:87], v[172:175], v[214:217], v[84:87]
	v_mfma_f32_16x16x32_bf16 v[84:87], v[168:171], v[210:213], v[84:87]
	v_mfma_f32_16x16x32_bf16 v[100:103], v[168:171], v[202:205], v[100:103]
	v_mfma_f32_16x16x32_bf16 v[100:103], v[172:175], v[206:209], v[100:103]
	v_mfma_f32_16x16x32_bf16 v[116:119], v[172:175], v[198:201], v[116:119]
	v_mfma_f32_16x16x32_bf16 v[116:119], v[168:171], v[194:197], v[116:119]
	s_setprio 0
	s_setprio 1
	v_mfma_f32_16x16x32_bf16 v[112:115], v[186:189], v[194:197], v[112:115]
	v_mfma_f32_16x16x32_bf16 v[112:115], v[190:193], v[198:201], v[112:115]
	v_mfma_f32_16x16x32_bf16 v[96:99], v[190:193], v[206:209], v[96:99]
	v_mfma_f32_16x16x32_bf16 v[96:99], v[186:189], v[202:205], v[96:99]
	v_mfma_f32_16x16x32_bf16 v[80:83], v[186:189], v[210:213], v[80:83]
	v_mfma_f32_16x16x32_bf16 v[80:83], v[190:193], v[214:217], v[80:83]
	v_mfma_f32_16x16x32_bf16 v[64:67], v[190:193], v[222:225], v[64:67]
	v_mfma_f32_16x16x32_bf16 v[64:67], v[186:189], v[218:221], v[64:67]
	v_mfma_f32_16x16x32_bf16 v[72:75], v[176:179], v[218:221], v[72:75]
	v_mfma_f32_16x16x32_bf16 v[72:75], v[180:183], v[222:225], v[72:75]
	v_mfma_f32_16x16x32_bf16 v[88:91], v[180:183], v[214:217], v[88:91]
	v_mfma_f32_16x16x32_bf16 v[88:91], v[176:179], v[210:213], v[88:91]
	v_mfma_f32_16x16x32_bf16 v[104:107], v[176:179], v[202:205], v[104:107]
	v_mfma_f32_16x16x32_bf16 v[104:107], v[180:183], v[206:209], v[104:107]
	v_mfma_f32_16x16x32_bf16 v[120:123], v[180:183], v[198:201], v[120:123]
	v_mfma_f32_16x16x32_bf16 v[120:123], v[176:179], v[194:197], v[120:123]
	s_barrier
	s_setprio 0
	s_add_i32 s48, s76, s52
	v_lshl_add_u64 v[154:155], v[154:155], 0, s[14:15]
	s_mov_b32 m0, s48
	ds_read_b128 v[194:197], v150 offset:49152
	v_xor_b32_e32 v253, 64, v150
	ds_read_b128 v[198:201], v253 offset:49152
	ds_read_b128 v[202:205], v150 offset:51200
	ds_read_b128 v[206:209], v253 offset:51200
	ds_read_b128 v[210:213], v150 offset:53248
	ds_read_b128 v[214:217], v253 offset:53248
	ds_read_b128 v[218:221], v150 offset:55296
	ds_read_b128 v[222:225], v253 offset:55296
	global_load_lds_dwordx4 v[154:155], off
	s_add_i32 m0, s48, 0x2000
	s_add_u32 s46, s46, 0x40080
	v_lshl_add_u64 v[154:155], v[226:227], 0, s[14:15]
	s_addc_u32 s47, s47, 0
	s_add_i32 s48, s77, s52
	global_load_lds_dwordx4 v[154:155], off
	v_lshl_add_u64 v[154:155], s[46:47], 0, v[132:133]
	s_mov_b32 m0, s48
	s_nop 0
	global_load_lds_dwordx4 v[154:155], off
	v_lshl_add_u64 v[154:155], s[46:47], 0, v[128:129]
	s_add_i32 m0, s48, 0x2000
	s_nop 0
	global_load_lds_dwordx4 v[154:155], off
	v_lshl_add_u64 v[154:155], v[228:229], 0, s[14:15]
	s_mov_b32 m0, s60
	s_nop 0
	global_load_lds_dwordx4 v[154:155], off
	v_lshl_add_u64 v[154:155], v[230:231], 0, s[14:15]
	s_mov_b32 m0, s61
	s_nop 0
	global_load_lds_dwordx4 v[154:155], off
	s_waitcnt vmcnt(8)
	s_waitcnt lgkmcnt(0)
	s_setprio 1
	s_barrier
	v_mfma_f32_16x16x32_bf16 v[60:63], v[160:163], v[194:197], v[60:63]
	v_mfma_f32_16x16x32_bf16 v[60:63], v[164:167], v[198:201], v[60:63]
	v_mfma_f32_16x16x32_bf16 v[44:47], v[164:167], v[206:209], v[44:47]
	v_mfma_f32_16x16x32_bf16 v[44:47], v[160:163], v[202:205], v[44:47]
	v_mfma_f32_16x16x32_bf16 v[28:31], v[160:163], v[210:213], v[28:31]
	v_mfma_f32_16x16x32_bf16 v[28:31], v[164:167], v[214:217], v[28:31]
	v_mfma_f32_16x16x32_bf16 v[12:15], v[164:167], v[222:225], v[12:15]
	v_mfma_f32_16x16x32_bf16 v[12:15], v[160:163], v[218:221], v[12:15]
	v_mfma_f32_16x16x32_bf16 v[4:7], v[168:171], v[218:221], v[4:7]
	v_mfma_f32_16x16x32_bf16 v[4:7], v[172:175], v[222:225], v[4:7]
	v_mfma_f32_16x16x32_bf16 v[20:23], v[172:175], v[214:217], v[20:23]
	v_mfma_f32_16x16x32_bf16 v[20:23], v[168:171], v[210:213], v[20:23]
	v_mfma_f32_16x16x32_bf16 v[36:39], v[168:171], v[202:205], v[36:39]
	v_mfma_f32_16x16x32_bf16 v[36:39], v[172:175], v[206:209], v[36:39]
	v_mfma_f32_16x16x32_bf16 v[52:55], v[172:175], v[198:201], v[52:55]
	v_mfma_f32_16x16x32_bf16 v[52:55], v[168:171], v[194:197], v[52:55]
	s_setprio 0
	s_setprio 1
	v_mfma_f32_16x16x32_bf16 v[48:51], v[186:189], v[194:197], v[48:51]
	v_mfma_f32_16x16x32_bf16 v[48:51], v[190:193], v[198:201], v[48:51]
	v_mfma_f32_16x16x32_bf16 v[32:35], v[190:193], v[206:209], v[32:35]
	v_mfma_f32_16x16x32_bf16 v[32:35], v[186:189], v[202:205], v[32:35]
	v_mfma_f32_16x16x32_bf16 v[16:19], v[186:189], v[210:213], v[16:19]
	v_mfma_f32_16x16x32_bf16 v[16:19], v[190:193], v[214:217], v[16:19]
	v_mfma_f32_16x16x32_bf16 v[0:3], v[190:193], v[222:225], v[0:3]
	v_mfma_f32_16x16x32_bf16 v[0:3], v[186:189], v[218:221], v[0:3]
	v_mfma_f32_16x16x32_bf16 v[8:11], v[176:179], v[218:221], v[8:11]
	v_mfma_f32_16x16x32_bf16 v[8:11], v[180:183], v[222:225], v[8:11]
	v_mfma_f32_16x16x32_bf16 v[24:27], v[180:183], v[214:217], v[24:27]
	v_mfma_f32_16x16x32_bf16 v[24:27], v[176:179], v[210:213], v[24:27]
	v_mfma_f32_16x16x32_bf16 v[40:43], v[176:179], v[202:205], v[40:43]
	v_mfma_f32_16x16x32_bf16 v[40:43], v[180:183], v[206:209], v[40:43]
	v_mfma_f32_16x16x32_bf16 v[56:59], v[180:183], v[198:201], v[56:59]
	v_mfma_f32_16x16x32_bf16 v[56:59], v[176:179], v[194:197], v[56:59]
	s_barrier
	s_setprio 0
	s_add_i32 s75, s75, 2
	s_add_u32 s71, s71, 0x100
	s_addc_u32 s74, s74, 0
	s_add_u32 s44, s44, 0x100
	s_addc_u32 s45, s45, 0
	s_cmp_gt_u32 s75, 13
	s_cbranch_scc1 .LBB0_78

.Llast_0:
	v_add_u32_e32 v153, s64, v147
	ds_read_b128 v[160:163], v153
	v_xor_b32_e32 v253, 64, v153
	ds_read_b128 v[164:167], v253
	ds_read_b128 v[168:171], v153 offset:2048
	ds_read_b128 v[172:175], v253 offset:2048
	v_add_u32_e32 v153, s65, v147
	ds_read_b128 v[176:179], v153
	v_xor_b32_e32 v253, 64, v153
	ds_read_b128 v[180:183], v253
	ds_read_b128 v[186:189], v153 offset:2048
	ds_read_b128 v[190:193], v253 offset:2048
	s_add_u32 s48, s44, 0xfffc0080
	s_addc_u32 s49, s45, -1
	s_and_b64 s[46:47], s[46:47], exec
	s_cselect_b32 s49, s27, s49
	s_cselect_b32 s48, s68, s48
	s_cselect_b32 s47, s69, s74
	s_cselect_b32 s46, s70, s71
	v_lshl_add_u64 v[154:155], s[44:45], 0, v[138:139]
	s_add_i32 m0, s55, 0xc000
	ds_read_b128 v[194:197], v150
	v_xor_b32_e32 v253, 64, v150
	ds_read_b128 v[198:201], v253
	ds_read_b128 v[202:205], v150 offset:2048
	ds_read_b128 v[206:209], v253 offset:2048
	ds_read_b128 v[210:213], v150 offset:4096
	ds_read_b128 v[214:217], v253 offset:4096
	ds_read_b128 v[218:221], v150 offset:6144
	ds_read_b128 v[222:225], v253 offset:6144
	global_load_lds_dwordx4 v[154:155], off
	v_lshl_add_u64 v[154:155], s[44:45], 0, v[136:137]
	s_add_i32 m0, s55, 0xe000
	s_nop 0
	global_load_lds_dwordx4 v[154:155], off
	s_waitcnt vmcnt(8)
	s_waitcnt lgkmcnt(0)
	s_setprio 1
	s_barrier
	v_mfma_f32_16x16x32_bf16 v[124:127], v[160:163], v[194:197], v[124:127]
	v_mfma_f32_16x16x32_bf16 v[124:127], v[164:167], v[198:201], v[124:127]
	v_mfma_f32_16x16x32_bf16 v[108:111], v[164:167], v[206:209], v[108:111]
	v_mfma_f32_16x16x32_bf16 v[108:111], v[160:163], v[202:205], v[108:111]
	v_mfma_f32_16x16x32_bf16 v[92:95], v[160:163], v[210:213], v[92:95]
	v_mfma_f32_16x16x32_bf16 v[92:95], v[164:167], v[214:217], v[92:95]
	v_mfma_f32_16x16x32_bf16 v[76:79], v[164:167], v[222:225], v[76:79]
	v_mfma_f32_16x16x32_bf16 v[76:79], v[160:163], v[218:221], v[76:79]
	v_mfma_f32_16x16x32_bf16 v[68:71], v[168:171], v[218:221], v[68:71]
	v_mfma_f32_16x16x32_bf16 v[68:71], v[172:175], v[222:225], v[68:71]
	v_mfma_f32_16x16x32_bf16 v[84:87], v[172:175], v[214:217], v[84:87]
	v_mfma_f32_16x16x32_bf16 v[84:87], v[168:171], v[210:213], v[84:87]
	v_mfma_f32_16x16x32_bf16 v[100:103], v[168:171], v[202:205], v[100:103]
	v_mfma_f32_16x16x32_bf16 v[100:103], v[172:175], v[206:209], v[100:103]
	v_mfma_f32_16x16x32_bf16 v[116:119], v[172:175], v[198:201], v[116:119]
	v_mfma_f32_16x16x32_bf16 v[116:119], v[168:171], v[194:197], v[116:119]
	s_setprio 0
	s_setprio 1
	v_mfma_f32_16x16x32_bf16 v[112:115], v[186:189], v[194:197], v[112:115]
	v_mfma_f32_16x16x32_bf16 v[112:115], v[190:193], v[198:201], v[112:115]
	v_mfma_f32_16x16x32_bf16 v[96:99], v[190:193], v[206:209], v[96:99]
	v_mfma_f32_16x16x32_bf16 v[96:99], v[186:189], v[202:205], v[96:99]
	v_mfma_f32_16x16x32_bf16 v[80:83], v[186:189], v[210:213], v[80:83]
	v_mfma_f32_16x16x32_bf16 v[80:83], v[190:193], v[214:217], v[80:83]
	v_mfma_f32_16x16x32_bf16 v[64:67], v[190:193], v[222:225], v[64:67]
	v_mfma_f32_16x16x32_bf16 v[64:67], v[186:189], v[218:221], v[64:67]
	v_mfma_f32_16x16x32_bf16 v[72:75], v[176:179], v[218:221], v[72:75]
	v_mfma_f32_16x16x32_bf16 v[72:75], v[180:183], v[222:225], v[72:75]
	v_mfma_f32_16x16x32_bf16 v[88:91], v[180:183], v[214:217], v[88:91]
	v_mfma_f32_16x16x32_bf16 v[88:91], v[176:179], v[210:213], v[88:91]
	v_mfma_f32_16x16x32_bf16 v[104:107], v[176:179], v[202:205], v[104:107]
	v_mfma_f32_16x16x32_bf16 v[104:107], v[180:183], v[206:209], v[104:107]
	v_mfma_f32_16x16x32_bf16 v[120:123], v[180:183], v[198:201], v[120:123]
	v_mfma_f32_16x16x32_bf16 v[120:123], v[176:179], v[194:197], v[120:123]
	s_barrier
	s_setprio 0
	s_add_i32 s76, s64, s52
	v_lshl_add_u64 v[154:155], s[46:47], 0, v[132:133]
	s_mov_b32 m0, s76
	ds_read_b128 v[194:197], v150 offset:16384
	v_xor_b32_e32 v253, 64, v150
	ds_read_b128 v[198:201], v253 offset:16384
	ds_read_b128 v[202:205], v150 offset:18432
	ds_read_b128 v[206:209], v253 offset:18432
	ds_read_b128 v[210:213], v150 offset:20480
	ds_read_b128 v[214:217], v253 offset:20480
	ds_read_b128 v[218:221], v150 offset:22528
	ds_read_b128 v[222:225], v253 offset:22528
	global_load_lds_dwordx4 v[154:155], off
	s_add_i32 m0, s76, 0x2000
	s_add_u32 s76, s46, 0x40000
	v_lshl_add_u64 v[226:227], s[46:47], 0, v[128:129]
	s_addc_u32 s77, s47, 0
	s_add_i32 s78, s65, s52
	global_load_lds_dwordx4 v[226:227], off
	v_lshl_add_u64 v[228:229], s[76:77], 0, v[132:133]
	s_mov_b32 m0, s78
	v_lshl_add_u64 v[230:231], s[48:49], 0, v[130:131]
	global_load_lds_dwordx4 v[228:229], off
	v_lshl_add_u64 v[228:229], s[76:77], 0, v[128:129]
	s_add_i32 m0, s78, 0x2000
	s_nop 0
	global_load_lds_dwordx4 v[228:229], off
	v_lshl_add_u64 v[228:229], s[48:49], 0, v[134:135]
	s_mov_b32 m0, s55
	s_nop 0
	global_load_lds_dwordx4 v[228:229], off
	s_mov_b32 m0, s56
	s_nop 0
	global_load_lds_dwordx4 v[230:231], off
	s_waitcnt vmcnt(8)
	s_waitcnt lgkmcnt(0)
	s_setprio 1
	s_barrier
	v_mfma_f32_16x16x32_bf16 v[60:63], v[160:163], v[194:197], v[60:63]
	v_mfma_f32_16x16x32_bf16 v[60:63], v[164:167], v[198:201], v[60:63]
	v_mfma_f32_16x16x32_bf16 v[44:47], v[164:167], v[206:209], v[44:47]
	v_mfma_f32_16x16x32_bf16 v[44:47], v[160:163], v[202:205], v[44:47]
	v_mfma_f32_16x16x32_bf16 v[28:31], v[160:163], v[210:213], v[28:31]
	v_mfma_f32_16x16x32_bf16 v[28:31], v[164:167], v[214:217], v[28:31]
	v_mfma_f32_16x16x32_bf16 v[12:15], v[164:167], v[222:225], v[12:15]
	v_mfma_f32_16x16x32_bf16 v[12:15], v[160:163], v[218:221], v[12:15]
	v_mfma_f32_16x16x32_bf16 v[4:7], v[168:171], v[218:221], v[4:7]
	v_mfma_f32_16x16x32_bf16 v[4:7], v[172:175], v[222:225], v[4:7]
	v_mfma_f32_16x16x32_bf16 v[20:23], v[172:175], v[214:217], v[20:23]
	v_mfma_f32_16x16x32_bf16 v[20:23], v[168:171], v[210:213], v[20:23]
	v_mfma_f32_16x16x32_bf16 v[36:39], v[168:171], v[202:205], v[36:39]
	v_mfma_f32_16x16x32_bf16 v[36:39], v[172:175], v[206:209], v[36:39]
	v_mfma_f32_16x16x32_bf16 v[52:55], v[172:175], v[198:201], v[52:55]
	v_mfma_f32_16x16x32_bf16 v[52:55], v[168:171], v[194:197], v[52:55]
	s_setprio 0
	s_setprio 1
	v_mfma_f32_16x16x32_bf16 v[48:51], v[186:189], v[194:197], v[48:51]
	v_mfma_f32_16x16x32_bf16 v[48:51], v[190:193], v[198:201], v[48:51]
	v_mfma_f32_16x16x32_bf16 v[32:35], v[190:193], v[206:209], v[32:35]
	v_mfma_f32_16x16x32_bf16 v[32:35], v[186:189], v[202:205], v[32:35]
	v_mfma_f32_16x16x32_bf16 v[16:19], v[186:189], v[210:213], v[16:19]
	v_mfma_f32_16x16x32_bf16 v[16:19], v[190:193], v[214:217], v[16:19]
	v_mfma_f32_16x16x32_bf16 v[0:3], v[190:193], v[222:225], v[0:3]
	v_mfma_f32_16x16x32_bf16 v[0:3], v[186:189], v[218:221], v[0:3]
	v_mfma_f32_16x16x32_bf16 v[8:11], v[176:179], v[218:221], v[8:11]
	v_mfma_f32_16x16x32_bf16 v[8:11], v[180:183], v[222:225], v[8:11]
	v_mfma_f32_16x16x32_bf16 v[24:27], v[180:183], v[214:217], v[24:27]
	v_mfma_f32_16x16x32_bf16 v[24:27], v[176:179], v[210:213], v[24:27]
	v_mfma_f32_16x16x32_bf16 v[40:43], v[176:179], v[202:205], v[40:43]
	v_mfma_f32_16x16x32_bf16 v[40:43], v[180:183], v[206:209], v[40:43]
	v_mfma_f32_16x16x32_bf16 v[56:59], v[180:183], v[198:201], v[56:59]
	v_mfma_f32_16x16x32_bf16 v[56:59], v[176:179], v[194:197], v[56:59]
	s_barrier
	s_setprio 0
	s_add_i32 s76, 0, 0x18000
	v_add_u32_e32 v153, s76, v147
	s_add_i32 s77, 0, 0x1c000
	ds_read_b128 v[160:163], v153
	v_xor_b32_e32 v253, 64, v153
	ds_read_b128 v[164:167], v253
	ds_read_b128 v[168:171], v153 offset:2048
	ds_read_b128 v[172:175], v253 offset:2048
	v_add_u32_e32 v153, s77, v147
	ds_read_b128 v[176:179], v153
	v_xor_b32_e32 v253, 64, v153
	ds_read_b128 v[180:183], v253
	ds_read_b128 v[186:189], v153 offset:2048
	ds_read_b128 v[190:193], v253 offset:2048
	s_add_u32 s48, s48, 0x40000
	s_addc_u32 s49, s49, 0
	s_mov_b32 m0, s57
	v_lshl_add_u64 v[232:233], s[48:49], 0, v[134:135]
	ds_read_b128 v[194:197], v150 offset:32768
	v_xor_b32_e32 v253, 64, v150
	ds_read_b128 v[198:201], v253 offset:32768
	ds_read_b128 v[202:205], v150 offset:34816
	ds_read_b128 v[206:209], v253 offset:34816
	ds_read_b128 v[210:213], v150 offset:36864
	ds_read_b128 v[214:217], v253 offset:36864
	ds_read_b128 v[218:221], v150 offset:38912
	ds_read_b128 v[222:225], v253 offset:38912
	global_load_lds_dwordx4 v[232:233], off
	v_lshl_add_u64 v[232:233], s[48:49], 0, v[130:131]
	s_mov_b32 m0, s58
	s_nop 0
	global_load_lds_dwordx4 v[232:233], off
	s_waitcnt vmcnt(8)
	s_waitcnt lgkmcnt(0)
	s_setprio 1
	s_barrier
	v_mfma_f32_16x16x32_bf16 v[124:127], v[160:163], v[194:197], v[124:127]
	v_mfma_f32_16x16x32_bf16 v[124:127], v[164:167], v[198:201], v[124:127]
	v_mfma_f32_16x16x32_bf16 v[108:111], v[164:167], v[206:209], v[108:111]
	v_mfma_f32_16x16x32_bf16 v[108:111], v[160:163], v[202:205], v[108:111]
	v_mfma_f32_16x16x32_bf16 v[92:95], v[160:163], v[210:213], v[92:95]
	v_mfma_f32_16x16x32_bf16 v[92:95], v[164:167], v[214:217], v[92:95]
	v_mfma_f32_16x16x32_bf16 v[76:79], v[164:167], v[222:225], v[76:79]
	v_mfma_f32_16x16x32_bf16 v[76:79], v[160:163], v[218:221], v[76:79]
	v_mfma_f32_16x16x32_bf16 v[68:71], v[168:171], v[218:221], v[68:71]
	v_mfma_f32_16x16x32_bf16 v[68:71], v[172:175], v[222:225], v[68:71]
	v_mfma_f32_16x16x32_bf16 v[84:87], v[172:175], v[214:217], v[84:87]
	v_mfma_f32_16x16x32_bf16 v[84:87], v[168:171], v[210:213], v[84:87]
	v_mfma_f32_16x16x32_bf16 v[100:103], v[168:171], v[202:205], v[100:103]
	v_mfma_f32_16x16x32_bf16 v[100:103], v[172:175], v[206:209], v[100:103]
	v_mfma_f32_16x16x32_bf16 v[116:119], v[172:175], v[198:201], v[116:119]
	v_mfma_f32_16x16x32_bf16 v[116:119], v[168:171], v[194:197], v[116:119]
	s_setprio 0
	s_setprio 1
	v_mfma_f32_16x16x32_bf16 v[112:115], v[186:189], v[194:197], v[112:115]
	v_mfma_f32_16x16x32_bf16 v[112:115], v[190:193], v[198:201], v[112:115]
	v_mfma_f32_16x16x32_bf16 v[96:99], v[190:193], v[206:209], v[96:99]
	v_mfma_f32_16x16x32_bf16 v[96:99], v[186:189], v[202:205], v[96:99]
	v_mfma_f32_16x16x32_bf16 v[80:83], v[186:189], v[210:213], v[80:83]
	v_mfma_f32_16x16x32_bf16 v[80:83], v[190:193], v[214:217], v[80:83]
	v_mfma_f32_16x16x32_bf16 v[64:67], v[190:193], v[222:225], v[64:67]
	v_mfma_f32_16x16x32_bf16 v[64:67], v[186:189], v[218:221], v[64:67]
	v_mfma_f32_16x16x32_bf16 v[72:75], v[176:179], v[218:221], v[72:75]
	v_mfma_f32_16x16x32_bf16 v[72:75], v[180:183], v[222:225], v[72:75]
	v_mfma_f32_16x16x32_bf16 v[88:91], v[180:183], v[214:217], v[88:91]
	v_mfma_f32_16x16x32_bf16 v[88:91], v[176:179], v[210:213], v[88:91]
	v_mfma_f32_16x16x32_bf16 v[104:107], v[176:179], v[202:205], v[104:107]
	v_mfma_f32_16x16x32_bf16 v[104:107], v[180:183], v[206:209], v[104:107]
	v_mfma_f32_16x16x32_bf16 v[120:123], v[180:183], v[198:201], v[120:123]
	v_mfma_f32_16x16x32_bf16 v[120:123], v[176:179], v[194:197], v[120:123]
	s_barrier
	s_setprio 0
	v_add_u32_e32 v234, 0x21000, v151
	ds_read_b128 v[236:239], v234
	ds_read_b128 v[240:243], v234 offset:256
	ds_read_b128 v[244:247], v234 offset:512
	ds_read_b128 v[248:251], v234 offset:768
	v_add_u32_e32 v235, s23, v146
	v_mul_u32_u24_e32 v235, 0x1600, v235
	v_lshl_or_b32 v234, s67, 7, v149
	v_lshl_add_u32 v235, v234, 1, v235
	s_add_i32 s48, s76, s52
	v_lshl_add_u64 v[154:155], v[154:155], 0, s[14:15]
	s_mov_b32 m0, s48
	ds_read_b128 v[194:197], v150 offset:49152
	v_xor_b32_e32 v253, 64, v150
	ds_read_b128 v[198:201], v253 offset:49152
	ds_read_b128 v[202:205], v150 offset:51200
	ds_read_b128 v[206:209], v253 offset:51200
	ds_read_b128 v[210:213], v150 offset:53248
	ds_read_b128 v[214:217], v253 offset:53248
	ds_read_b128 v[218:221], v150 offset:55296
	ds_read_b128 v[222:225], v253 offset:55296
	global_load_lds_dwordx4 v[154:155], off
	s_add_i32 m0, s48, 0x2000
	s_add_u32 s46, s46, 0x40080
	v_lshl_add_u64 v[154:155], v[226:227], 0, s[14:15]
	s_addc_u32 s47, s47, 0
	s_add_i32 s48, s77, s52
	global_load_lds_dwordx4 v[154:155], off
	v_lshl_add_u64 v[154:155], s[46:47], 0, v[132:133]
	s_mov_b32 m0, s48
	s_nop 0
	global_load_lds_dwordx4 v[154:155], off
	v_lshl_add_u64 v[154:155], s[46:47], 0, v[128:129]
	s_add_i32 m0, s48, 0x2000
	s_nop 0
	global_load_lds_dwordx4 v[154:155], off
	v_lshl_add_u64 v[154:155], v[228:229], 0, s[14:15]
	s_mov_b32 m0, s60
	s_nop 0
	global_load_lds_dwordx4 v[154:155], off
	v_lshl_add_u64 v[154:155], v[230:231], 0, s[14:15]
	s_mov_b32 m0, s61
	s_nop 0
	global_load_lds_dwordx4 v[154:155], off
	s_waitcnt lgkmcnt(8)
	v_add_f32_e32 v236, v236, v237
	v_add_f32_e32 v238, v238, v239
	v_add_f32_e32 v240, v240, v241
	v_add_f32_e32 v242, v242, v243
	v_add_f32_e32 v244, v244, v245
	v_add_f32_e32 v246, v246, v247
	v_add_f32_e32 v248, v248, v249
	v_add_f32_e32 v250, v250, v251
	v_add_f32_e32 v236, v236, v238
	v_add_f32_e32 v240, v240, v242
	v_add_f32_e32 v244, v244, v246
	v_add_f32_e32 v248, v248, v250
	v_fmamk_f32 v236, v236, 0x3a800000, v152
	v_fmamk_f32 v240, v240, 0x3a800000, v152
	v_fmamk_f32 v244, v244, 0x3a800000, v152
	v_fmamk_f32 v248, v248, 0x3a800000, v152
	v_rsq_f32_e32 v236, v236
	v_rsq_f32_e32 v240, v240
	v_rsq_f32_e32 v244, v244
	v_rsq_f32_e32 v248, v248
	v_mul_f32_e32 v252, 0xbfb8aa3b, v236
	v_mul_f32_e32 v254, v236, v236
	v_rcp_f32_e32 v254, v254
	v_pk_mul_f32 v[120:121], v[124:125], v[120:121]
	v_pk_mul_f32 v[122:123], v[126:127], v[122:123]
	v_pk_mul_f32 v[112:113], v[116:117], v[112:113]
	v_pk_mul_f32 v[114:115], v[118:119], v[114:115]
	v_pk_mul_f32 v[124:125], v[124:125], v[252:253] op_sel_hi:[1,0]
	v_pk_mul_f32 v[126:127], v[126:127], v[252:253] op_sel_hi:[1,0]
	v_pk_mul_f32 v[116:117], v[116:117], v[252:253] op_sel_hi:[1,0]
	v_pk_mul_f32 v[118:119], v[118:119], v[252:253] op_sel_hi:[1,0]
	v_exp_f32_e32 v124, v124
	v_exp_f32_e32 v125, v125
	v_exp_f32_e32 v126, v126
	v_exp_f32_e32 v127, v127
	v_exp_f32_e32 v116, v116
	v_exp_f32_e32 v117, v117
	v_exp_f32_e32 v118, v118
	v_exp_f32_e32 v119, v119
	v_pk_fma_f32 v[124:125], v[124:125], v[254:255], v[254:255] op_sel_hi:[1,0,0]
	v_pk_fma_f32 v[126:127], v[126:127], v[254:255], v[254:255] op_sel_hi:[1,0,0]
	v_pk_fma_f32 v[116:117], v[116:117], v[254:255], v[254:255] op_sel_hi:[1,0,0]
	v_pk_fma_f32 v[118:119], v[118:119], v[254:255], v[254:255] op_sel_hi:[1,0,0]
	v_rcp_f32_e32 v124, v124
	v_rcp_f32_e32 v125, v125
	v_rcp_f32_e32 v126, v126
	v_rcp_f32_e32 v127, v127
	v_rcp_f32_e32 v116, v116
	v_rcp_f32_e32 v117, v117
	v_rcp_f32_e32 v118, v118
	v_rcp_f32_e32 v119, v119
	v_pk_mul_f32 v[120:121], v[120:121], v[124:125]
	v_pk_mul_f32 v[122:123], v[122:123], v[126:127]
	v_pk_mul_f32 v[112:113], v[112:113], v[116:117]
	v_pk_mul_f32 v[114:115], v[114:115], v[118:119]
	v_cvt_pk_bf16_f32 v120, v120, v121
	v_cvt_pk_bf16_f32 v121, v122, v123
	v_cvt_pk_bf16_f32 v122, v112, v113
	v_cvt_pk_bf16_f32 v123, v114, v115
	global_store_dwordx4 v235, v[120:123], s[10:11]
	v_add_u32_e32 v234, 0x16000, v235
	v_mul_f32_e32 v252, 0xbfb8aa3b, v240
	v_mul_f32_e32 v254, v240, v240
	v_rcp_f32_e32 v254, v254
	v_pk_mul_f32 v[104:105], v[108:109], v[104:105]
	v_pk_mul_f32 v[106:107], v[110:111], v[106:107]
	v_pk_mul_f32 v[96:97], v[100:101], v[96:97]
	v_pk_mul_f32 v[98:99], v[102:103], v[98:99]
	v_pk_mul_f32 v[108:109], v[108:109], v[252:253] op_sel_hi:[1,0]
	v_pk_mul_f32 v[110:111], v[110:111], v[252:253] op_sel_hi:[1,0]
	v_pk_mul_f32 v[100:101], v[100:101], v[252:253] op_sel_hi:[1,0]
	v_pk_mul_f32 v[102:103], v[102:103], v[252:253] op_sel_hi:[1,0]
	v_exp_f32_e32 v108, v108
	v_exp_f32_e32 v109, v109
	v_exp_f32_e32 v110, v110
	v_exp_f32_e32 v111, v111
	v_exp_f32_e32 v100, v100
	v_exp_f32_e32 v101, v101
	v_exp_f32_e32 v102, v102
	v_exp_f32_e32 v103, v103
	v_pk_fma_f32 v[108:109], v[108:109], v[254:255], v[254:255] op_sel_hi:[1,0,0]
	v_pk_fma_f32 v[110:111], v[110:111], v[254:255], v[254:255] op_sel_hi:[1,0,0]
	v_pk_fma_f32 v[100:101], v[100:101], v[254:255], v[254:255] op_sel_hi:[1,0,0]
	v_pk_fma_f32 v[102:103], v[102:103], v[254:255], v[254:255] op_sel_hi:[1,0,0]
	v_rcp_f32_e32 v108, v108
	v_rcp_f32_e32 v109, v109
	v_rcp_f32_e32 v110, v110
	v_rcp_f32_e32 v111, v111
	v_rcp_f32_e32 v100, v100
	v_rcp_f32_e32 v101, v101
	v_rcp_f32_e32 v102, v102
	v_rcp_f32_e32 v103, v103
	v_pk_mul_f32 v[104:105], v[104:105], v[108:109]
	v_pk_mul_f32 v[106:107], v[106:107], v[110:111]
	v_pk_mul_f32 v[96:97], v[96:97], v[100:101]
	v_pk_mul_f32 v[98:99], v[98:99], v[102:103]
	v_cvt_pk_bf16_f32 v104, v104, v105
	v_cvt_pk_bf16_f32 v105, v106, v107
	v_cvt_pk_bf16_f32 v106, v96, v97
	v_cvt_pk_bf16_f32 v107, v98, v99
	global_store_dwordx4 v234, v[104:107], s[10:11]
	v_add_u32_e32 v235, 0x16000, v234
	v_mul_f32_e32 v252, 0xbfb8aa3b, v244
	v_mul_f32_e32 v254, v244, v244
	v_rcp_f32_e32 v254, v254
	v_pk_mul_f32 v[88:89], v[92:93], v[88:89]
	v_pk_mul_f32 v[90:91], v[94:95], v[90:91]
	v_pk_mul_f32 v[80:81], v[84:85], v[80:81]
	v_pk_mul_f32 v[82:83], v[86:87], v[82:83]
	v_pk_mul_f32 v[92:93], v[92:93], v[252:253] op_sel_hi:[1,0]
	v_pk_mul_f32 v[94:95], v[94:95], v[252:253] op_sel_hi:[1,0]
	v_pk_mul_f32 v[84:85], v[84:85], v[252:253] op_sel_hi:[1,0]
	v_pk_mul_f32 v[86:87], v[86:87], v[252:253] op_sel_hi:[1,0]
	v_exp_f32_e32 v92, v92
	v_exp_f32_e32 v93, v93
	v_exp_f32_e32 v94, v94
	v_exp_f32_e32 v95, v95
	v_exp_f32_e32 v84, v84
	v_exp_f32_e32 v85, v85
	v_exp_f32_e32 v86, v86
	v_exp_f32_e32 v87, v87
	v_pk_fma_f32 v[92:93], v[92:93], v[254:255], v[254:255] op_sel_hi:[1,0,0]
	v_pk_fma_f32 v[94:95], v[94:95], v[254:255], v[254:255] op_sel_hi:[1,0,0]
	v_pk_fma_f32 v[84:85], v[84:85], v[254:255], v[254:255] op_sel_hi:[1,0,0]
	v_pk_fma_f32 v[86:87], v[86:87], v[254:255], v[254:255] op_sel_hi:[1,0,0]
	v_rcp_f32_e32 v92, v92
	v_rcp_f32_e32 v93, v93
	v_rcp_f32_e32 v94, v94
	v_rcp_f32_e32 v95, v95
	v_rcp_f32_e32 v84, v84
	v_rcp_f32_e32 v85, v85
	v_rcp_f32_e32 v86, v86
	v_rcp_f32_e32 v87, v87
	v_pk_mul_f32 v[88:89], v[88:89], v[92:93]
	v_pk_mul_f32 v[90:91], v[90:91], v[94:95]
	v_pk_mul_f32 v[80:81], v[80:81], v[84:85]
	v_pk_mul_f32 v[82:83], v[82:83], v[86:87]
	v_cvt_pk_bf16_f32 v88, v88, v89
	v_cvt_pk_bf16_f32 v89, v90, v91
	v_cvt_pk_bf16_f32 v90, v80, v81
	v_cvt_pk_bf16_f32 v91, v82, v83
	global_store_dwordx4 v235, v[88:91], s[10:11]
	v_add_u32_e32 v234, 0x16000, v235
	v_mul_f32_e32 v252, 0xbfb8aa3b, v248
	v_mul_f32_e32 v254, v248, v248
	v_rcp_f32_e32 v254, v254
	v_pk_mul_f32 v[72:73], v[76:77], v[72:73]
	v_pk_mul_f32 v[74:75], v[78:79], v[74:75]
	v_pk_mul_f32 v[64:65], v[68:69], v[64:65]
	v_pk_mul_f32 v[66:67], v[70:71], v[66:67]
	v_pk_mul_f32 v[76:77], v[76:77], v[252:253] op_sel_hi:[1,0]
	v_pk_mul_f32 v[78:79], v[78:79], v[252:253] op_sel_hi:[1,0]
	v_pk_mul_f32 v[68:69], v[68:69], v[252:253] op_sel_hi:[1,0]
	v_pk_mul_f32 v[70:71], v[70:71], v[252:253] op_sel_hi:[1,0]
	v_exp_f32_e32 v76, v76
	v_exp_f32_e32 v77, v77
	v_exp_f32_e32 v78, v78
	v_exp_f32_e32 v79, v79
	v_exp_f32_e32 v68, v68
	v_exp_f32_e32 v69, v69
	v_exp_f32_e32 v70, v70
	v_exp_f32_e32 v71, v71
	v_pk_fma_f32 v[76:77], v[76:77], v[254:255], v[254:255] op_sel_hi:[1,0,0]
	v_pk_fma_f32 v[78:79], v[78:79], v[254:255], v[254:255] op_sel_hi:[1,0,0]
	v_pk_fma_f32 v[68:69], v[68:69], v[254:255], v[254:255] op_sel_hi:[1,0,0]
	v_pk_fma_f32 v[70:71], v[70:71], v[254:255], v[254:255] op_sel_hi:[1,0,0]
	v_rcp_f32_e32 v76, v76
	v_rcp_f32_e32 v77, v77
	v_rcp_f32_e32 v78, v78
	v_rcp_f32_e32 v79, v79
	v_rcp_f32_e32 v68, v68
	v_rcp_f32_e32 v69, v69
	v_rcp_f32_e32 v70, v70
	v_rcp_f32_e32 v71, v71
	v_pk_mul_f32 v[72:73], v[72:73], v[76:77]
	v_pk_mul_f32 v[74:75], v[74:75], v[78:79]
	v_pk_mul_f32 v[64:65], v[64:65], v[68:69]
	v_pk_mul_f32 v[66:67], v[66:67], v[70:71]
	v_cvt_pk_bf16_f32 v72, v72, v73
	v_cvt_pk_bf16_f32 v73, v74, v75
	v_cvt_pk_bf16_f32 v74, v64, v65
	v_cvt_pk_bf16_f32 v75, v66, v67
	global_store_dwordx4 v234, v[72:75], s[10:11]
	s_waitcnt vmcnt(12)
	s_waitcnt lgkmcnt(0)
	s_setprio 1
	s_barrier
	v_mfma_f32_16x16x32_bf16 v[60:63], v[160:163], v[194:197], v[60:63]
	v_mfma_f32_16x16x32_bf16 v[60:63], v[164:167], v[198:201], v[60:63]
	v_mfma_f32_16x16x32_bf16 v[44:47], v[164:167], v[206:209], v[44:47]
	v_mfma_f32_16x16x32_bf16 v[44:47], v[160:163], v[202:205], v[44:47]
	v_mfma_f32_16x16x32_bf16 v[28:31], v[160:163], v[210:213], v[28:31]
	v_mfma_f32_16x16x32_bf16 v[28:31], v[164:167], v[214:217], v[28:31]
	v_mfma_f32_16x16x32_bf16 v[12:15], v[164:167], v[222:225], v[12:15]
	v_mfma_f32_16x16x32_bf16 v[12:15], v[160:163], v[218:221], v[12:15]
	v_mfma_f32_16x16x32_bf16 v[4:7], v[168:171], v[218:221], v[4:7]
	v_mfma_f32_16x16x32_bf16 v[4:7], v[172:175], v[222:225], v[4:7]
	v_mfma_f32_16x16x32_bf16 v[20:23], v[172:175], v[214:217], v[20:23]
	v_mfma_f32_16x16x32_bf16 v[20:23], v[168:171], v[210:213], v[20:23]
	v_mfma_f32_16x16x32_bf16 v[36:39], v[168:171], v[202:205], v[36:39]
	v_mfma_f32_16x16x32_bf16 v[36:39], v[172:175], v[206:209], v[36:39]
	v_mfma_f32_16x16x32_bf16 v[52:55], v[172:175], v[198:201], v[52:55]
	v_mfma_f32_16x16x32_bf16 v[52:55], v[168:171], v[194:197], v[52:55]
	s_setprio 0
	s_setprio 1
	v_mfma_f32_16x16x32_bf16 v[48:51], v[186:189], v[194:197], v[48:51]
	v_mfma_f32_16x16x32_bf16 v[48:51], v[190:193], v[198:201], v[48:51]
	v_mfma_f32_16x16x32_bf16 v[32:35], v[190:193], v[206:209], v[32:35]
	v_mfma_f32_16x16x32_bf16 v[32:35], v[186:189], v[202:205], v[32:35]
	v_mfma_f32_16x16x32_bf16 v[16:19], v[186:189], v[210:213], v[16:19]
	v_mfma_f32_16x16x32_bf16 v[16:19], v[190:193], v[214:217], v[16:19]
	v_mfma_f32_16x16x32_bf16 v[0:3], v[190:193], v[222:225], v[0:3]
	v_mfma_f32_16x16x32_bf16 v[0:3], v[186:189], v[218:221], v[0:3]
	v_mfma_f32_16x16x32_bf16 v[8:11], v[176:179], v[218:221], v[8:11]
	v_mfma_f32_16x16x32_bf16 v[8:11], v[180:183], v[222:225], v[8:11]
	v_mfma_f32_16x16x32_bf16 v[24:27], v[180:183], v[214:217], v[24:27]
	v_mfma_f32_16x16x32_bf16 v[24:27], v[176:179], v[210:213], v[24:27]
	v_mfma_f32_16x16x32_bf16 v[40:43], v[176:179], v[202:205], v[40:43]
	v_mfma_f32_16x16x32_bf16 v[40:43], v[180:183], v[206:209], v[40:43]
	v_mfma_f32_16x16x32_bf16 v[56:59], v[180:183], v[198:201], v[56:59]
	v_mfma_f32_16x16x32_bf16 v[56:59], v[176:179], v[194:197], v[56:59]
	s_barrier
	s_setprio 0
	s_add_i32 s75, s75, 2
	s_add_u32 s71, s71, 0x100
	s_addc_u32 s74, s74, 0
	s_add_u32 s44, s44, 0x100
	s_addc_u32 s45, s45, 0

.LBB0_158:
	s_add_u32 s81, s56, 0x100
	s_addc_u32 s82, s57, 0
	s_mov_b32 s83, -2
	s_waitcnt lgkmcnt(0)
	s_cmp_eq_u32 s70, 1
	s_cbranch_scc1 .Lfa_1
	ds_read_b128 v[128:131], v189
	v_xor_b32_e32 v253, 64, v189
	ds_read_b128 v[132:135], v253
	ds_read_b128 v[136:139], v189 offset:2048
	ds_read_b128 v[140:143], v253 offset:2048
	ds_read_b128 v[144:147], v190
	v_xor_b32_e32 v253, 64, v190
	ds_read_b128 v[148:151], v253
	ds_read_b128 v[172:175], v190 offset:2048
	ds_read_b128 v[176:179], v253 offset:2048
	s_add_u32 s56, s54, 0x100
	s_addc_u32 s57, s55, 0
	s_cmp_eq_u32 s83, 40
	s_cselect_b32 s61, s15, s57
	s_cselect_b32 s60, s14, s56
	s_cselect_b32 s59, s53, s82
	s_cselect_b32 s58, s52, s81
	v_lshl_add_u64 v[222:223], s[54:55], 0, v[166:167]
	s_add_i32 m0, s66, 0xc000
	ds_read_b128 v[180:183], v191
	v_xor_b32_e32 v253, 64, v191
	ds_read_b128 v[194:197], v253
	ds_read_b128 v[198:201], v191 offset:2048
	ds_read_b128 v[202:205], v253 offset:2048
	ds_read_b128 v[206:209], v191 offset:4096
	ds_read_b128 v[210:213], v253 offset:4096
	ds_read_b128 v[214:217], v191 offset:6144
	ds_read_b128 v[218:221], v253 offset:6144
	global_load_lds_dwordx4 v[222:223], off
	v_lshl_add_u64 v[222:223], s[54:55], 0, v[164:165]
	s_add_i32 m0, s66, 0xe000
	s_nop 0
	global_load_lds_dwordx4 v[222:223], off
	s_waitcnt vmcnt(24)
	s_waitcnt lgkmcnt(0)
	s_setprio 1
	s_barrier
	v_mfma_f32_16x16x32_bf16 v[124:127], v[128:131], v[180:183], 0
	v_mfma_f32_16x16x32_bf16 v[120:123], v[136:139], v[180:183], 0
	v_mfma_f32_16x16x32_bf16 v[108:111], v[128:131], v[198:201], 0
	v_mfma_f32_16x16x32_bf16 v[104:107], v[136:139], v[198:201], 0
	v_mfma_f32_16x16x32_bf16 v[92:95], v[128:131], v[206:209], 0
	v_mfma_f32_16x16x32_bf16 v[88:91], v[136:139], v[206:209], 0
	v_mfma_f32_16x16x32_bf16 v[76:79], v[128:131], v[214:217], 0
	v_mfma_f32_16x16x32_bf16 v[72:75], v[136:139], v[214:217], 0
	v_mfma_f32_16x16x32_bf16 v[124:127], v[132:135], v[194:197], v[124:127]
	v_mfma_f32_16x16x32_bf16 v[120:123], v[140:143], v[194:197], v[120:123]
	v_mfma_f32_16x16x32_bf16 v[108:111], v[132:135], v[202:205], v[108:111]
	v_mfma_f32_16x16x32_bf16 v[104:107], v[140:143], v[202:205], v[104:107]
	v_mfma_f32_16x16x32_bf16 v[92:95], v[132:135], v[210:213], v[92:95]
	v_mfma_f32_16x16x32_bf16 v[88:91], v[140:143], v[210:213], v[88:91]
	v_mfma_f32_16x16x32_bf16 v[76:79], v[132:135], v[218:221], v[76:79]
	v_mfma_f32_16x16x32_bf16 v[72:75], v[140:143], v[218:221], v[72:75]
	s_setprio 0
	s_setprio 1
	v_mfma_f32_16x16x32_bf16 v[116:119], v[144:147], v[180:183], 0
	v_mfma_f32_16x16x32_bf16 v[112:115], v[172:175], v[180:183], 0
	v_mfma_f32_16x16x32_bf16 v[100:103], v[144:147], v[198:201], 0
	v_mfma_f32_16x16x32_bf16 v[96:99], v[172:175], v[198:201], 0
	v_mfma_f32_16x16x32_bf16 v[84:87], v[144:147], v[206:209], 0
	v_mfma_f32_16x16x32_bf16 v[80:83], v[172:175], v[206:209], 0
	v_mfma_f32_16x16x32_bf16 v[68:71], v[144:147], v[214:217], 0
	v_mfma_f32_16x16x32_bf16 v[64:67], v[172:175], v[214:217], 0
	v_mfma_f32_16x16x32_bf16 v[116:119], v[148:151], v[194:197], v[116:119]
	v_mfma_f32_16x16x32_bf16 v[112:115], v[176:179], v[194:197], v[112:115]
	v_mfma_f32_16x16x32_bf16 v[100:103], v[148:151], v[202:205], v[100:103]
	v_mfma_f32_16x16x32_bf16 v[96:99], v[176:179], v[202:205], v[96:99]
	v_mfma_f32_16x16x32_bf16 v[84:87], v[148:151], v[210:213], v[84:87]
	v_mfma_f32_16x16x32_bf16 v[80:83], v[176:179], v[210:213], v[80:83]
	v_mfma_f32_16x16x32_bf16 v[68:71], v[148:151], v[218:221], v[68:71]
	v_mfma_f32_16x16x32_bf16 v[64:67], v[176:179], v[218:221], v[64:67]
	s_barrier
	s_setprio 0
	s_add_i32 s54, s77, s65
	v_lshl_add_u64 v[222:223], s[58:59], 0, v[154:155]
	s_mov_b32 m0, s54
	ds_read_b128 v[180:183], v191 offset:16384
	v_xor_b32_e32 v253, 64, v191
	ds_read_b128 v[194:197], v253 offset:16384
	ds_read_b128 v[198:201], v191 offset:18432
	ds_read_b128 v[202:205], v253 offset:18432
	ds_read_b128 v[206:209], v191 offset:20480
	ds_read_b128 v[210:213], v253 offset:20480
	ds_read_b128 v[214:217], v191 offset:22528
	ds_read_b128 v[218:221], v253 offset:22528
	global_load_lds_dwordx4 v[222:223], off
	s_add_i32 m0, s54, 0x2000
	s_add_u32 s54, s58, 0xb0000
	v_lshl_add_u64 v[224:225], s[58:59], 0, v[162:163]
	s_addc_u32 s55, s59, 0
	s_add_i32 s84, s78, s65
	global_load_lds_dwordx4 v[224:225], off
	v_lshl_add_u64 v[226:227], s[54:55], 0, v[154:155]
	s_mov_b32 m0, s84
	v_lshl_add_u64 v[228:229], s[60:61], 0, v[160:161]
	global_load_lds_dwordx4 v[226:227], off
	v_lshl_add_u64 v[226:227], s[54:55], 0, v[162:163]
	s_add_i32 m0, s84, 0x2000
	s_nop 0
	global_load_lds_dwordx4 v[226:227], off
	v_lshl_add_u64 v[226:227], s[60:61], 0, v[152:153]
	s_mov_b32 m0, s66
	s_nop 0
	global_load_lds_dwordx4 v[226:227], off
	s_mov_b32 m0, s67
	s_nop 0
	global_load_lds_dwordx4 v[228:229], off
	s_waitcnt vmcnt(24)
	s_waitcnt lgkmcnt(0)
	s_setprio 1
	s_barrier
	v_mfma_f32_16x16x32_bf16 v[60:63], v[128:131], v[180:183], 0
	v_mfma_f32_16x16x32_bf16 v[56:59], v[136:139], v[180:183], 0
	v_mfma_f32_16x16x32_bf16 v[44:47], v[128:131], v[198:201], 0
	v_mfma_f32_16x16x32_bf16 v[40:43], v[136:139], v[198:201], 0
	v_mfma_f32_16x16x32_bf16 v[28:31], v[128:131], v[206:209], 0
	v_mfma_f32_16x16x32_bf16 v[24:27], v[136:139], v[206:209], 0
	v_mfma_f32_16x16x32_bf16 v[12:15], v[128:131], v[214:217], 0
	v_mfma_f32_16x16x32_bf16 v[8:11], v[136:139], v[214:217], 0
	v_mfma_f32_16x16x32_bf16 v[60:63], v[132:135], v[194:197], v[60:63]
	v_mfma_f32_16x16x32_bf16 v[56:59], v[140:143], v[194:197], v[56:59]
	v_mfma_f32_16x16x32_bf16 v[44:47], v[132:135], v[202:205], v[44:47]
	v_mfma_f32_16x16x32_bf16 v[40:43], v[140:143], v[202:205], v[40:43]
	v_mfma_f32_16x16x32_bf16 v[28:31], v[132:135], v[210:213], v[28:31]
	v_mfma_f32_16x16x32_bf16 v[24:27], v[140:143], v[210:213], v[24:27]
	v_mfma_f32_16x16x32_bf16 v[12:15], v[132:135], v[218:221], v[12:15]
	v_mfma_f32_16x16x32_bf16 v[8:11], v[140:143], v[218:221], v[8:11]
	s_setprio 0
	s_setprio 1
	v_mfma_f32_16x16x32_bf16 v[52:55], v[144:147], v[180:183], 0
	v_mfma_f32_16x16x32_bf16 v[48:51], v[172:175], v[180:183], 0
	v_mfma_f32_16x16x32_bf16 v[36:39], v[144:147], v[198:201], 0
	v_mfma_f32_16x16x32_bf16 v[32:35], v[172:175], v[198:201], 0
	v_mfma_f32_16x16x32_bf16 v[20:23], v[144:147], v[206:209], 0
	v_mfma_f32_16x16x32_bf16 v[16:19], v[172:175], v[206:209], 0
	v_mfma_f32_16x16x32_bf16 v[4:7], v[144:147], v[214:217], 0
	v_mfma_f32_16x16x32_bf16 v[0:3], v[172:175], v[214:217], 0
	v_mfma_f32_16x16x32_bf16 v[52:55], v[148:151], v[194:197], v[52:55]
	v_mfma_f32_16x16x32_bf16 v[48:51], v[176:179], v[194:197], v[48:51]
	v_mfma_f32_16x16x32_bf16 v[36:39], v[148:151], v[202:205], v[36:39]
	v_mfma_f32_16x16x32_bf16 v[32:35], v[176:179], v[202:205], v[32:35]
	v_mfma_f32_16x16x32_bf16 v[20:23], v[148:151], v[210:213], v[20:23]
	v_mfma_f32_16x16x32_bf16 v[16:19], v[176:179], v[210:213], v[16:19]
	v_mfma_f32_16x16x32_bf16 v[4:7], v[148:151], v[218:221], v[4:7]
	v_mfma_f32_16x16x32_bf16 v[0:3], v[176:179], v[218:221], v[0:3]
	s_barrier
	s_setprio 0
	s_add_i32 s84, 0, 0x18000
	s_add_i32 s85, 0, 0x1c000
	v_add_u32_e32 v140, s84, v186
	v_add_u32_e32 v176, s85, v186
	ds_read_b128 v[128:131], v140
	v_xor_b32_e32 v253, 64, v140
	ds_read_b128 v[132:135], v253
	ds_read_b128 v[136:139], v140 offset:2048
	ds_read_b128 v[140:143], v253 offset:2048
	ds_read_b128 v[144:147], v176
	v_xor_b32_e32 v253, 64, v176
	ds_read_b128 v[148:151], v253
	ds_read_b128 v[172:175], v176 offset:2048
	ds_read_b128 v[176:179], v253 offset:2048
	s_add_u32 s54, s60, 0xb0000
	s_addc_u32 s55, s61, 0
	s_mov_b32 m0, s68
	v_lshl_add_u64 v[230:231], s[54:55], 0, v[152:153]
	ds_read_b128 v[180:183], v191 offset:32768
	v_xor_b32_e32 v253, 64, v191
	ds_read_b128 v[194:197], v253 offset:32768
	ds_read_b128 v[198:201], v191 offset:34816
	ds_read_b128 v[202:205], v253 offset:34816
	ds_read_b128 v[206:209], v191 offset:36864
	ds_read_b128 v[210:213], v253 offset:36864
	ds_read_b128 v[214:217], v191 offset:38912
	ds_read_b128 v[218:221], v253 offset:38912
	global_load_lds_dwordx4 v[230:231], off
	v_lshl_add_u64 v[230:231], s[54:55], 0, v[160:161]
	s_mov_b32 m0, s69
	s_nop 0
	global_load_lds_dwordx4 v[230:231], off
	s_waitcnt vmcnt(8)
	s_waitcnt lgkmcnt(0)
	s_setprio 1
	s_barrier
	v_mfma_f32_16x16x32_bf16 v[124:127], v[128:131], v[180:183], v[124:127]
	v_mfma_f32_16x16x32_bf16 v[124:127], v[132:135], v[194:197], v[124:127]
	v_mfma_f32_16x16x32_bf16 v[108:111], v[132:135], v[202:205], v[108:111]
	v_mfma_f32_16x16x32_bf16 v[108:111], v[128:131], v[198:201], v[108:111]
	v_mfma_f32_16x16x32_bf16 v[92:95], v[128:131], v[206:209], v[92:95]
	v_mfma_f32_16x16x32_bf16 v[92:95], v[132:135], v[210:213], v[92:95]
	v_mfma_f32_16x16x32_bf16 v[76:79], v[132:135], v[218:221], v[76:79]
	v_mfma_f32_16x16x32_bf16 v[76:79], v[128:131], v[214:217], v[76:79]
	v_mfma_f32_16x16x32_bf16 v[72:75], v[136:139], v[214:217], v[72:75]
	v_mfma_f32_16x16x32_bf16 v[72:75], v[140:143], v[218:221], v[72:75]
	v_mfma_f32_16x16x32_bf16 v[88:91], v[140:143], v[210:213], v[88:91]
	v_mfma_f32_16x16x32_bf16 v[88:91], v[136:139], v[206:209], v[88:91]
	v_mfma_f32_16x16x32_bf16 v[104:107], v[136:139], v[198:201], v[104:107]
	v_mfma_f32_16x16x32_bf16 v[104:107], v[140:143], v[202:205], v[104:107]
	v_mfma_f32_16x16x32_bf16 v[120:123], v[140:143], v[194:197], v[120:123]
	v_mfma_f32_16x16x32_bf16 v[120:123], v[136:139], v[180:183], v[120:123]
	s_setprio 0
	s_setprio 1
	v_mfma_f32_16x16x32_bf16 v[112:115], v[172:175], v[180:183], v[112:115]
	v_mfma_f32_16x16x32_bf16 v[112:115], v[176:179], v[194:197], v[112:115]
	v_mfma_f32_16x16x32_bf16 v[96:99], v[176:179], v[202:205], v[96:99]
	v_mfma_f32_16x16x32_bf16 v[96:99], v[172:175], v[198:201], v[96:99]
	v_mfma_f32_16x16x32_bf16 v[80:83], v[172:175], v[206:209], v[80:83]
	v_mfma_f32_16x16x32_bf16 v[80:83], v[176:179], v[210:213], v[80:83]
	v_mfma_f32_16x16x32_bf16 v[64:67], v[176:179], v[218:221], v[64:67]
	v_mfma_f32_16x16x32_bf16 v[64:67], v[172:175], v[214:217], v[64:67]
	v_mfma_f32_16x16x32_bf16 v[68:71], v[144:147], v[214:217], v[68:71]
	v_mfma_f32_16x16x32_bf16 v[68:71], v[148:151], v[218:221], v[68:71]
	v_mfma_f32_16x16x32_bf16 v[84:87], v[148:151], v[210:213], v[84:87]
	v_mfma_f32_16x16x32_bf16 v[84:87], v[144:147], v[206:209], v[84:87]
	v_mfma_f32_16x16x32_bf16 v[100:103], v[144:147], v[198:201], v[100:103]
	v_mfma_f32_16x16x32_bf16 v[100:103], v[148:151], v[202:205], v[100:103]
	v_mfma_f32_16x16x32_bf16 v[116:119], v[148:151], v[194:197], v[116:119]
	v_mfma_f32_16x16x32_bf16 v[116:119], v[144:147], v[180:183], v[116:119]
	s_barrier
	s_setprio 0
	s_add_i32 s54, s84, s65
	v_lshl_add_u64 v[222:223], v[222:223], 0, s[28:29]
	s_mov_b32 m0, s54
	ds_read_b128 v[180:183], v191 offset:49152
	v_xor_b32_e32 v253, 64, v191
	ds_read_b128 v[194:197], v253 offset:49152
	ds_read_b128 v[198:201], v191 offset:51200
	ds_read_b128 v[202:205], v253 offset:51200
	ds_read_b128 v[206:209], v191 offset:53248
	ds_read_b128 v[210:213], v253 offset:53248
	ds_read_b128 v[214:217], v191 offset:55296
	ds_read_b128 v[218:221], v253 offset:55296
	global_load_lds_dwordx4 v[222:223], off
	s_add_i32 m0, s54, 0x2000
	s_add_u32 s54, s58, 0xb0080
	v_lshl_add_u64 v[222:223], v[224:225], 0, s[28:29]
	s_addc_u32 s55, s59, 0
	s_add_i32 s58, s85, s65
	global_load_lds_dwordx4 v[222:223], off
	v_lshl_add_u64 v[222:223], s[54:55], 0, v[154:155]
	s_mov_b32 m0, s58
	s_nop 0
	global_load_lds_dwordx4 v[222:223], off
	v_lshl_add_u64 v[222:223], s[54:55], 0, v[162:163]
	s_add_i32 m0, s58, 0x2000
	s_nop 0
	global_load_lds_dwordx4 v[222:223], off
	v_lshl_add_u64 v[222:223], v[226:227], 0, s[28:29]
	s_mov_b32 m0, s3
	s_nop 0
	global_load_lds_dwordx4 v[222:223], off
	v_lshl_add_u64 v[222:223], v[228:229], 0, s[28:29]
	s_mov_b32 m0, s71
	s_nop 0
	global_load_lds_dwordx4 v[222:223], off
	s_waitcnt vmcnt(8)
	s_waitcnt lgkmcnt(0)
	s_setprio 1
	s_barrier
	v_mfma_f32_16x16x32_bf16 v[60:63], v[128:131], v[180:183], v[60:63]
	v_mfma_f32_16x16x32_bf16 v[60:63], v[132:135], v[194:197], v[60:63]
	v_mfma_f32_16x16x32_bf16 v[44:47], v[132:135], v[202:205], v[44:47]
	v_mfma_f32_16x16x32_bf16 v[44:47], v[128:131], v[198:201], v[44:47]
	v_mfma_f32_16x16x32_bf16 v[28:31], v[128:131], v[206:209], v[28:31]
	v_mfma_f32_16x16x32_bf16 v[28:31], v[132:135], v[210:213], v[28:31]
	v_mfma_f32_16x16x32_bf16 v[12:15], v[132:135], v[218:221], v[12:15]
	v_mfma_f32_16x16x32_bf16 v[12:15], v[128:131], v[214:217], v[12:15]
	v_mfma_f32_16x16x32_bf16 v[8:11], v[136:139], v[214:217], v[8:11]
	v_mfma_f32_16x16x32_bf16 v[8:11], v[140:143], v[218:221], v[8:11]
	v_mfma_f32_16x16x32_bf16 v[24:27], v[140:143], v[210:213], v[24:27]
	v_mfma_f32_16x16x32_bf16 v[24:27], v[136:139], v[206:209], v[24:27]
	v_mfma_f32_16x16x32_bf16 v[40:43], v[136:139], v[198:201], v[40:43]
	v_mfma_f32_16x16x32_bf16 v[40:43], v[140:143], v[202:205], v[40:43]
	v_mfma_f32_16x16x32_bf16 v[56:59], v[140:143], v[194:197], v[56:59]
	v_mfma_f32_16x16x32_bf16 v[56:59], v[136:139], v[180:183], v[56:59]
	s_setprio 0
	s_setprio 1
	v_mfma_f32_16x16x32_bf16 v[48:51], v[172:175], v[180:183], v[48:51]
	v_mfma_f32_16x16x32_bf16 v[48:51], v[176:179], v[194:197], v[48:51]
	v_mfma_f32_16x16x32_bf16 v[32:35], v[176:179], v[202:205], v[32:35]
	v_mfma_f32_16x16x32_bf16 v[32:35], v[172:175], v[198:201], v[32:35]
	v_mfma_f32_16x16x32_bf16 v[16:19], v[172:175], v[206:209], v[16:19]
	v_mfma_f32_16x16x32_bf16 v[16:19], v[176:179], v[210:213], v[16:19]
	v_mfma_f32_16x16x32_bf16 v[0:3], v[176:179], v[218:221], v[0:3]
	v_mfma_f32_16x16x32_bf16 v[0:3], v[172:175], v[214:217], v[0:3]
	v_mfma_f32_16x16x32_bf16 v[4:7], v[144:147], v[214:217], v[4:7]
	v_mfma_f32_16x16x32_bf16 v[4:7], v[148:151], v[218:221], v[4:7]
	v_mfma_f32_16x16x32_bf16 v[20:23], v[148:151], v[210:213], v[20:23]
	v_mfma_f32_16x16x32_bf16 v[20:23], v[144:147], v[206:209], v[20:23]
	v_mfma_f32_16x16x32_bf16 v[36:39], v[144:147], v[198:201], v[36:39]
	v_mfma_f32_16x16x32_bf16 v[36:39], v[148:151], v[202:205], v[36:39]
	v_mfma_f32_16x16x32_bf16 v[52:55], v[148:151], v[194:197], v[52:55]
	v_mfma_f32_16x16x32_bf16 v[52:55], v[144:147], v[180:183], v[52:55]
	s_barrier
	s_setprio 0
	s_add_i32 s83, s83, 2
	s_add_u32 s81, s81, 0x100
	s_addc_u32 s82, s82, 0
	s_cmp_gt_u32 s83, 41
	s_mov_b64 s[54:55], s[56:57]
	s_branch .LBB0_159
.Lfa_1:
	ds_read_b128 v[128:131], v189
	v_xor_b32_e32 v253, 64, v189
	ds_read_b128 v[132:135], v253
	ds_read_b128 v[136:139], v189 offset:2048
	ds_read_b128 v[140:143], v253 offset:2048
	ds_read_b128 v[144:147], v190
	v_xor_b32_e32 v253, 64, v190
	ds_read_b128 v[148:151], v253
	ds_read_b128 v[172:175], v190 offset:2048
	ds_read_b128 v[176:179], v253 offset:2048
	s_add_u32 s56, s54, 0x100
	s_addc_u32 s57, s55, 0
	s_cmp_eq_u32 s83, 40
	s_cselect_b32 s61, s15, s57
	s_cselect_b32 s60, s14, s56
	s_cselect_b32 s59, s53, s82
	s_cselect_b32 s58, s52, s81
	v_lshl_add_u64 v[222:223], s[54:55], 0, v[166:167]
	s_add_i32 m0, s66, 0xc000
	ds_read_b128 v[180:183], v191
	v_xor_b32_e32 v253, 64, v191
	ds_read_b128 v[194:197], v253
	ds_read_b128 v[198:201], v191 offset:2048
	ds_read_b128 v[202:205], v253 offset:2048
	ds_read_b128 v[206:209], v191 offset:4096
	ds_read_b128 v[210:213], v253 offset:4096
	ds_read_b128 v[214:217], v191 offset:6144
	ds_read_b128 v[218:221], v253 offset:6144
	global_load_lds_dwordx4 v[222:223], off
	v_lshl_add_u64 v[222:223], s[54:55], 0, v[164:165]
	s_add_i32 m0, s66, 0xe000
	s_nop 0
	global_load_lds_dwordx4 v[222:223], off
	s_waitcnt vmcnt(8)
	s_waitcnt lgkmcnt(0)
	s_setprio 1
	s_barrier
	v_mfma_f32_16x16x32_bf16 v[124:127], v[128:131], v[180:183], 0
	v_mfma_f32_16x16x32_bf16 v[120:123], v[136:139], v[180:183], 0
	v_mfma_f32_16x16x32_bf16 v[108:111], v[128:131], v[198:201], 0
	v_mfma_f32_16x16x32_bf16 v[104:107], v[136:139], v[198:201], 0
	v_mfma_f32_16x16x32_bf16 v[92:95], v[128:131], v[206:209], 0
	v_mfma_f32_16x16x32_bf16 v[88:91], v[136:139], v[206:209], 0
	v_mfma_f32_16x16x32_bf16 v[76:79], v[128:131], v[214:217], 0
	v_mfma_f32_16x16x32_bf16 v[72:75], v[136:139], v[214:217], 0
	v_mfma_f32_16x16x32_bf16 v[124:127], v[132:135], v[194:197], v[124:127]
	v_mfma_f32_16x16x32_bf16 v[120:123], v[140:143], v[194:197], v[120:123]
	v_mfma_f32_16x16x32_bf16 v[108:111], v[132:135], v[202:205], v[108:111]
	v_mfma_f32_16x16x32_bf16 v[104:107], v[140:143], v[202:205], v[104:107]
	v_mfma_f32_16x16x32_bf16 v[92:95], v[132:135], v[210:213], v[92:95]
	v_mfma_f32_16x16x32_bf16 v[88:91], v[140:143], v[210:213], v[88:91]
	v_mfma_f32_16x16x32_bf16 v[76:79], v[132:135], v[218:221], v[76:79]
	v_mfma_f32_16x16x32_bf16 v[72:75], v[140:143], v[218:221], v[72:75]
	s_setprio 0
	s_setprio 1
	v_mfma_f32_16x16x32_bf16 v[116:119], v[144:147], v[180:183], 0
	v_mfma_f32_16x16x32_bf16 v[112:115], v[172:175], v[180:183], 0
	v_mfma_f32_16x16x32_bf16 v[100:103], v[144:147], v[198:201], 0
	v_mfma_f32_16x16x32_bf16 v[96:99], v[172:175], v[198:201], 0
	v_mfma_f32_16x16x32_bf16 v[84:87], v[144:147], v[206:209], 0
	v_mfma_f32_16x16x32_bf16 v[80:83], v[172:175], v[206:209], 0
	v_mfma_f32_16x16x32_bf16 v[68:71], v[144:147], v[214:217], 0
	v_mfma_f32_16x16x32_bf16 v[64:67], v[172:175], v[214:217], 0
	v_mfma_f32_16x16x32_bf16 v[116:119], v[148:151], v[194:197], v[116:119]
	v_mfma_f32_16x16x32_bf16 v[112:115], v[176:179], v[194:197], v[112:115]
	v_mfma_f32_16x16x32_bf16 v[100:103], v[148:151], v[202:205], v[100:103]
	v_mfma_f32_16x16x32_bf16 v[96:99], v[176:179], v[202:205], v[96:99]
	v_mfma_f32_16x16x32_bf16 v[84:87], v[148:151], v[210:213], v[84:87]
	v_mfma_f32_16x16x32_bf16 v[80:83], v[176:179], v[210:213], v[80:83]
	v_mfma_f32_16x16x32_bf16 v[68:71], v[148:151], v[218:221], v[68:71]
	v_mfma_f32_16x16x32_bf16 v[64:67], v[176:179], v[218:221], v[64:67]
	s_barrier
	s_setprio 0
	s_add_i32 s54, s77, s65
	v_lshl_add_u64 v[222:223], s[58:59], 0, v[154:155]
	s_mov_b32 m0, s54
	ds_read_b128 v[180:183], v191 offset:16384
	v_xor_b32_e32 v253, 64, v191
	ds_read_b128 v[194:197], v253 offset:16384
	ds_read_b128 v[198:201], v191 offset:18432
	ds_read_b128 v[202:205], v253 offset:18432
	ds_read_b128 v[206:209], v191 offset:20480
	ds_read_b128 v[210:213], v253 offset:20480
	ds_read_b128 v[214:217], v191 offset:22528
	ds_read_b128 v[218:221], v253 offset:22528
	global_load_lds_dwordx4 v[222:223], off
	s_add_i32 m0, s54, 0x2000
	s_add_u32 s54, s58, 0xb0000
	v_lshl_add_u64 v[224:225], s[58:59], 0, v[162:163]
	s_addc_u32 s55, s59, 0
	s_add_i32 s84, s78, s65
	global_load_lds_dwordx4 v[224:225], off
	v_lshl_add_u64 v[226:227], s[54:55], 0, v[154:155]
	s_mov_b32 m0, s84
	v_lshl_add_u64 v[228:229], s[60:61], 0, v[160:161]
	global_load_lds_dwordx4 v[226:227], off
	v_lshl_add_u64 v[226:227], s[54:55], 0, v[162:163]
	s_add_i32 m0, s84, 0x2000
	s_nop 0
	global_load_lds_dwordx4 v[226:227], off
	v_lshl_add_u64 v[226:227], s[60:61], 0, v[152:153]
	s_mov_b32 m0, s66
	s_nop 0
	global_load_lds_dwordx4 v[226:227], off
	s_mov_b32 m0, s67
	s_nop 0
	global_load_lds_dwordx4 v[228:229], off
	s_waitcnt vmcnt(8)
	s_waitcnt lgkmcnt(0)
	s_setprio 1
	s_barrier
	v_mfma_f32_16x16x32_bf16 v[60:63], v[128:131], v[180:183], 0
	v_mfma_f32_16x16x32_bf16 v[56:59], v[136:139], v[180:183], 0
	v_mfma_f32_16x16x32_bf16 v[44:47], v[128:131], v[198:201], 0
	v_mfma_f32_16x16x32_bf16 v[40:43], v[136:139], v[198:201], 0
	v_mfma_f32_16x16x32_bf16 v[28:31], v[128:131], v[206:209], 0
	v_mfma_f32_16x16x32_bf16 v[24:27], v[136:139], v[206:209], 0
	v_mfma_f32_16x16x32_bf16 v[12:15], v[128:131], v[214:217], 0
	v_mfma_f32_16x16x32_bf16 v[8:11], v[136:139], v[214:217], 0
	v_mfma_f32_16x16x32_bf16 v[60:63], v[132:135], v[194:197], v[60:63]
	v_mfma_f32_16x16x32_bf16 v[56:59], v[140:143], v[194:197], v[56:59]
	v_mfma_f32_16x16x32_bf16 v[44:47], v[132:135], v[202:205], v[44:47]
	v_mfma_f32_16x16x32_bf16 v[40:43], v[140:143], v[202:205], v[40:43]
	v_mfma_f32_16x16x32_bf16 v[28:31], v[132:135], v[210:213], v[28:31]
	v_mfma_f32_16x16x32_bf16 v[24:27], v[140:143], v[210:213], v[24:27]
	v_mfma_f32_16x16x32_bf16 v[12:15], v[132:135], v[218:221], v[12:15]
	v_mfma_f32_16x16x32_bf16 v[8:11], v[140:143], v[218:221], v[8:11]
	s_setprio 0
	s_setprio 1
	v_mfma_f32_16x16x32_bf16 v[52:55], v[144:147], v[180:183], 0
	v_mfma_f32_16x16x32_bf16 v[48:51], v[172:175], v[180:183], 0
	v_mfma_f32_16x16x32_bf16 v[36:39], v[144:147], v[198:201], 0
	v_mfma_f32_16x16x32_bf16 v[32:35], v[172:175], v[198:201], 0
	v_mfma_f32_16x16x32_bf16 v[20:23], v[144:147], v[206:209], 0
	v_mfma_f32_16x16x32_bf16 v[16:19], v[172:175], v[206:209], 0
	v_mfma_f32_16x16x32_bf16 v[4:7], v[144:147], v[214:217], 0
	v_mfma_f32_16x16x32_bf16 v[0:3], v[172:175], v[214:217], 0
	v_mfma_f32_16x16x32_bf16 v[52:55], v[148:151], v[194:197], v[52:55]
	v_mfma_f32_16x16x32_bf16 v[48:51], v[176:179], v[194:197], v[48:51]
	v_mfma_f32_16x16x32_bf16 v[36:39], v[148:151], v[202:205], v[36:39]
	v_mfma_f32_16x16x32_bf16 v[32:35], v[176:179], v[202:205], v[32:35]
	v_mfma_f32_16x16x32_bf16 v[20:23], v[148:151], v[210:213], v[20:23]
	v_mfma_f32_16x16x32_bf16 v[16:19], v[176:179], v[210:213], v[16:19]
	v_mfma_f32_16x16x32_bf16 v[4:7], v[148:151], v[218:221], v[4:7]
	v_mfma_f32_16x16x32_bf16 v[0:3], v[176:179], v[218:221], v[0:3]
	s_barrier
	s_setprio 0
	s_add_i32 s84, 0, 0x18000
	s_add_i32 s85, 0, 0x1c000
	v_add_u32_e32 v140, s84, v186
	v_add_u32_e32 v176, s85, v186
	ds_read_b128 v[128:131], v140
	v_xor_b32_e32 v253, 64, v140
	ds_read_b128 v[132:135], v253
	ds_read_b128 v[136:139], v140 offset:2048
	ds_read_b128 v[140:143], v253 offset:2048
	ds_read_b128 v[144:147], v176
	v_xor_b32_e32 v253, 64, v176
	ds_read_b128 v[148:151], v253
	ds_read_b128 v[172:175], v176 offset:2048
	ds_read_b128 v[176:179], v253 offset:2048
	s_add_u32 s54, s60, 0xb0000
	s_addc_u32 s55, s61, 0
	s_mov_b32 m0, s68
	v_lshl_add_u64 v[230:231], s[54:55], 0, v[152:153]
	ds_read_b128 v[180:183], v191 offset:32768
	v_xor_b32_e32 v253, 64, v191
	ds_read_b128 v[194:197], v253 offset:32768
	ds_read_b128 v[198:201], v191 offset:34816
	ds_read_b128 v[202:205], v253 offset:34816
	ds_read_b128 v[206:209], v191 offset:36864
	ds_read_b128 v[210:213], v253 offset:36864
	ds_read_b128 v[214:217], v191 offset:38912
	ds_read_b128 v[218:221], v253 offset:38912
	global_load_lds_dwordx4 v[230:231], off
	v_lshl_add_u64 v[230:231], s[54:55], 0, v[160:161]
	s_mov_b32 m0, s69
	s_nop 0
	global_load_lds_dwordx4 v[230:231], off
	s_waitcnt vmcnt(8)
	s_waitcnt lgkmcnt(0)
	s_setprio 1
	s_barrier
	v_mfma_f32_16x16x32_bf16 v[124:127], v[128:131], v[180:183], v[124:127]
	v_mfma_f32_16x16x32_bf16 v[124:127], v[132:135], v[194:197], v[124:127]
	v_mfma_f32_16x16x32_bf16 v[108:111], v[132:135], v[202:205], v[108:111]
	v_mfma_f32_16x16x32_bf16 v[108:111], v[128:131], v[198:201], v[108:111]
	v_mfma_f32_16x16x32_bf16 v[92:95], v[128:131], v[206:209], v[92:95]
	v_mfma_f32_16x16x32_bf16 v[92:95], v[132:135], v[210:213], v[92:95]
	v_mfma_f32_16x16x32_bf16 v[76:79], v[132:135], v[218:221], v[76:79]
	v_mfma_f32_16x16x32_bf16 v[76:79], v[128:131], v[214:217], v[76:79]
	v_mfma_f32_16x16x32_bf16 v[72:75], v[136:139], v[214:217], v[72:75]
	v_mfma_f32_16x16x32_bf16 v[72:75], v[140:143], v[218:221], v[72:75]
	v_mfma_f32_16x16x32_bf16 v[88:91], v[140:143], v[210:213], v[88:91]
	v_mfma_f32_16x16x32_bf16 v[88:91], v[136:139], v[206:209], v[88:91]
	v_mfma_f32_16x16x32_bf16 v[104:107], v[136:139], v[198:201], v[104:107]
	v_mfma_f32_16x16x32_bf16 v[104:107], v[140:143], v[202:205], v[104:107]
	v_mfma_f32_16x16x32_bf16 v[120:123], v[140:143], v[194:197], v[120:123]
	v_mfma_f32_16x16x32_bf16 v[120:123], v[136:139], v[180:183], v[120:123]
	s_setprio 0
	s_setprio 1
	v_mfma_f32_16x16x32_bf16 v[112:115], v[172:175], v[180:183], v[112:115]
	v_mfma_f32_16x16x32_bf16 v[112:115], v[176:179], v[194:197], v[112:115]
	v_mfma_f32_16x16x32_bf16 v[96:99], v[176:179], v[202:205], v[96:99]
	v_mfma_f32_16x16x32_bf16 v[96:99], v[172:175], v[198:201], v[96:99]
	v_mfma_f32_16x16x32_bf16 v[80:83], v[172:175], v[206:209], v[80:83]
	v_mfma_f32_16x16x32_bf16 v[80:83], v[176:179], v[210:213], v[80:83]
	v_mfma_f32_16x16x32_bf16 v[64:67], v[176:179], v[218:221], v[64:67]
	v_mfma_f32_16x16x32_bf16 v[64:67], v[172:175], v[214:217], v[64:67]
	v_mfma_f32_16x16x32_bf16 v[68:71], v[144:147], v[214:217], v[68:71]
	v_mfma_f32_16x16x32_bf16 v[68:71], v[148:151], v[218:221], v[68:71]
	v_mfma_f32_16x16x32_bf16 v[84:87], v[148:151], v[210:213], v[84:87]
	v_mfma_f32_16x16x32_bf16 v[84:87], v[144:147], v[206:209], v[84:87]
	v_mfma_f32_16x16x32_bf16 v[100:103], v[144:147], v[198:201], v[100:103]
	v_mfma_f32_16x16x32_bf16 v[100:103], v[148:151], v[202:205], v[100:103]
	v_mfma_f32_16x16x32_bf16 v[116:119], v[148:151], v[194:197], v[116:119]
	v_mfma_f32_16x16x32_bf16 v[116:119], v[144:147], v[180:183], v[116:119]
	s_barrier
	s_setprio 0
	s_add_i32 s54, s84, s65
	v_lshl_add_u64 v[222:223], v[222:223], 0, s[28:29]
	s_mov_b32 m0, s54
	ds_read_b128 v[180:183], v191 offset:49152
	v_xor_b32_e32 v253, 64, v191
	ds_read_b128 v[194:197], v253 offset:49152
	ds_read_b128 v[198:201], v191 offset:51200
	ds_read_b128 v[202:205], v253 offset:51200
	ds_read_b128 v[206:209], v191 offset:53248
	ds_read_b128 v[210:213], v253 offset:53248
	ds_read_b128 v[214:217], v191 offset:55296
	ds_read_b128 v[218:221], v253 offset:55296
	global_load_lds_dwordx4 v[222:223], off
	s_add_i32 m0, s54, 0x2000
	s_add_u32 s54, s58, 0xb0080
	v_lshl_add_u64 v[222:223], v[224:225], 0, s[28:29]
	s_addc_u32 s55, s59, 0
	s_add_i32 s58, s85, s65
	global_load_lds_dwordx4 v[222:223], off
	v_lshl_add_u64 v[222:223], s[54:55], 0, v[154:155]
	s_mov_b32 m0, s58
	s_nop 0
	global_load_lds_dwordx4 v[222:223], off
	v_lshl_add_u64 v[222:223], s[54:55], 0, v[162:163]
	s_add_i32 m0, s58, 0x2000
	s_nop 0
	global_load_lds_dwordx4 v[222:223], off
	v_lshl_add_u64 v[222:223], v[226:227], 0, s[28:29]
	s_mov_b32 m0, s3
	s_nop 0
	global_load_lds_dwordx4 v[222:223], off
	v_lshl_add_u64 v[222:223], v[228:229], 0, s[28:29]
	s_mov_b32 m0, s71
	s_nop 0
	global_load_lds_dwordx4 v[222:223], off
	s_waitcnt vmcnt(8)
	s_waitcnt lgkmcnt(0)
	s_setprio 1
	s_barrier
	v_mfma_f32_16x16x32_bf16 v[60:63], v[128:131], v[180:183], v[60:63]
	v_mfma_f32_16x16x32_bf16 v[60:63], v[132:135], v[194:197], v[60:63]
	v_mfma_f32_16x16x32_bf16 v[44:47], v[132:135], v[202:205], v[44:47]
	v_mfma_f32_16x16x32_bf16 v[44:47], v[128:131], v[198:201], v[44:47]
	v_mfma_f32_16x16x32_bf16 v[28:31], v[128:131], v[206:209], v[28:31]
	v_mfma_f32_16x16x32_bf16 v[28:31], v[132:135], v[210:213], v[28:31]
	v_mfma_f32_16x16x32_bf16 v[12:15], v[132:135], v[218:221], v[12:15]
	v_mfma_f32_16x16x32_bf16 v[12:15], v[128:131], v[214:217], v[12:15]
	v_mfma_f32_16x16x32_bf16 v[8:11], v[136:139], v[214:217], v[8:11]
	v_mfma_f32_16x16x32_bf16 v[8:11], v[140:143], v[218:221], v[8:11]
	v_mfma_f32_16x16x32_bf16 v[24:27], v[140:143], v[210:213], v[24:27]
	v_mfma_f32_16x16x32_bf16 v[24:27], v[136:139], v[206:209], v[24:27]
	v_mfma_f32_16x16x32_bf16 v[40:43], v[136:139], v[198:201], v[40:43]
	v_mfma_f32_16x16x32_bf16 v[40:43], v[140:143], v[202:205], v[40:43]
	v_mfma_f32_16x16x32_bf16 v[56:59], v[140:143], v[194:197], v[56:59]
	v_mfma_f32_16x16x32_bf16 v[56:59], v[136:139], v[180:183], v[56:59]
	s_setprio 0
	s_setprio 1
	v_mfma_f32_16x16x32_bf16 v[48:51], v[172:175], v[180:183], v[48:51]
	v_mfma_f32_16x16x32_bf16 v[48:51], v[176:179], v[194:197], v[48:51]
	v_mfma_f32_16x16x32_bf16 v[32:35], v[176:179], v[202:205], v[32:35]
	v_mfma_f32_16x16x32_bf16 v[32:35], v[172:175], v[198:201], v[32:35]
	v_mfma_f32_16x16x32_bf16 v[16:19], v[172:175], v[206:209], v[16:19]
	v_mfma_f32_16x16x32_bf16 v[16:19], v[176:179], v[210:213], v[16:19]
	v_mfma_f32_16x16x32_bf16 v[0:3], v[176:179], v[218:221], v[0:3]
	v_mfma_f32_16x16x32_bf16 v[0:3], v[172:175], v[214:217], v[0:3]
	v_mfma_f32_16x16x32_bf16 v[4:7], v[144:147], v[214:217], v[4:7]
	v_mfma_f32_16x16x32_bf16 v[4:7], v[148:151], v[218:221], v[4:7]
	v_mfma_f32_16x16x32_bf16 v[20:23], v[148:151], v[210:213], v[20:23]
	v_mfma_f32_16x16x32_bf16 v[20:23], v[144:147], v[206:209], v[20:23]
	v_mfma_f32_16x16x32_bf16 v[36:39], v[144:147], v[198:201], v[36:39]
	v_mfma_f32_16x16x32_bf16 v[36:39], v[148:151], v[202:205], v[36:39]
	v_mfma_f32_16x16x32_bf16 v[52:55], v[148:151], v[194:197], v[52:55]
	v_mfma_f32_16x16x32_bf16 v[52:55], v[144:147], v[180:183], v[52:55]
	s_barrier
	s_setprio 0
	s_add_i32 s83, s83, 2
	s_add_u32 s81, s81, 0x100
	s_addc_u32 s82, s82, 0
	s_cmp_gt_u32 s83, 41
	s_mov_b64 s[54:55], s[56:57]
.LBB0_159:
	ds_read_b128 v[128:131], v189
	v_xor_b32_e32 v253, 64, v189
	ds_read_b128 v[132:135], v253
	ds_read_b128 v[136:139], v189 offset:2048
	ds_read_b128 v[140:143], v253 offset:2048
	ds_read_b128 v[144:147], v190
	v_xor_b32_e32 v253, 64, v190
	ds_read_b128 v[148:151], v253
	ds_read_b128 v[172:175], v190 offset:2048
	ds_read_b128 v[176:179], v253 offset:2048
	s_add_u32 s56, s54, 0x100
	s_addc_u32 s57, s55, 0
	s_cmp_eq_u32 s83, 40
	s_cselect_b32 s61, s15, s57
	s_cselect_b32 s60, s14, s56
	s_cselect_b32 s59, s53, s82
	s_cselect_b32 s58, s52, s81
	v_lshl_add_u64 v[222:223], s[54:55], 0, v[166:167]
	s_add_i32 m0, s66, 0xc000
	ds_read_b128 v[180:183], v191
	v_xor_b32_e32 v253, 64, v191
	ds_read_b128 v[194:197], v253
	ds_read_b128 v[198:201], v191 offset:2048
	ds_read_b128 v[202:205], v253 offset:2048
	ds_read_b128 v[206:209], v191 offset:4096
	ds_read_b128 v[210:213], v253 offset:4096
	ds_read_b128 v[214:217], v191 offset:6144
	ds_read_b128 v[218:221], v253 offset:6144
	global_load_lds_dwordx4 v[222:223], off
	v_lshl_add_u64 v[222:223], s[54:55], 0, v[164:165]
	s_add_i32 m0, s66, 0xe000
	s_nop 0
	global_load_lds_dwordx4 v[222:223], off
	s_waitcnt vmcnt(8)
	s_waitcnt lgkmcnt(0)
	s_setprio 1
	s_barrier
	v_mfma_f32_16x16x32_bf16 v[124:127], v[128:131], v[180:183], v[124:127]
	v_mfma_f32_16x16x32_bf16 v[124:127], v[132:135], v[194:197], v[124:127]
	v_mfma_f32_16x16x32_bf16 v[108:111], v[132:135], v[202:205], v[108:111]
	v_mfma_f32_16x16x32_bf16 v[108:111], v[128:131], v[198:201], v[108:111]
	v_mfma_f32_16x16x32_bf16 v[92:95], v[128:131], v[206:209], v[92:95]
	v_mfma_f32_16x16x32_bf16 v[92:95], v[132:135], v[210:213], v[92:95]
	v_mfma_f32_16x16x32_bf16 v[76:79], v[132:135], v[218:221], v[76:79]
	v_mfma_f32_16x16x32_bf16 v[76:79], v[128:131], v[214:217], v[76:79]
	v_mfma_f32_16x16x32_bf16 v[72:75], v[136:139], v[214:217], v[72:75]
	v_mfma_f32_16x16x32_bf16 v[72:75], v[140:143], v[218:221], v[72:75]
	v_mfma_f32_16x16x32_bf16 v[88:91], v[140:143], v[210:213], v[88:91]
	v_mfma_f32_16x16x32_bf16 v[88:91], v[136:139], v[206:209], v[88:91]
	v_mfma_f32_16x16x32_bf16 v[104:107], v[136:139], v[198:201], v[104:107]
	v_mfma_f32_16x16x32_bf16 v[104:107], v[140:143], v[202:205], v[104:107]
	v_mfma_f32_16x16x32_bf16 v[120:123], v[140:143], v[194:197], v[120:123]
	v_mfma_f32_16x16x32_bf16 v[120:123], v[136:139], v[180:183], v[120:123]
	s_setprio 0
	s_setprio 1
	v_mfma_f32_16x16x32_bf16 v[112:115], v[172:175], v[180:183], v[112:115]
	v_mfma_f32_16x16x32_bf16 v[112:115], v[176:179], v[194:197], v[112:115]
	v_mfma_f32_16x16x32_bf16 v[96:99], v[176:179], v[202:205], v[96:99]
	v_mfma_f32_16x16x32_bf16 v[96:99], v[172:175], v[198:201], v[96:99]
	v_mfma_f32_16x16x32_bf16 v[80:83], v[172:175], v[206:209], v[80:83]
	v_mfma_f32_16x16x32_bf16 v[80:83], v[176:179], v[210:213], v[80:83]
	v_mfma_f32_16x16x32_bf16 v[64:67], v[176:179], v[218:221], v[64:67]
	v_mfma_f32_16x16x32_bf16 v[64:67], v[172:175], v[214:217], v[64:67]
	v_mfma_f32_16x16x32_bf16 v[68:71], v[144:147], v[214:217], v[68:71]
	v_mfma_f32_16x16x32_bf16 v[68:71], v[148:151], v[218:221], v[68:71]
	v_mfma_f32_16x16x32_bf16 v[84:87], v[148:151], v[210:213], v[84:87]
	v_mfma_f32_16x16x32_bf16 v[84:87], v[144:147], v[206:209], v[84:87]
	v_mfma_f32_16x16x32_bf16 v[100:103], v[144:147], v[198:201], v[100:103]
	v_mfma_f32_16x16x32_bf16 v[100:103], v[148:151], v[202:205], v[100:103]
	v_mfma_f32_16x16x32_bf16 v[116:119], v[148:151], v[194:197], v[116:119]
	v_mfma_f32_16x16x32_bf16 v[116:119], v[144:147], v[180:183], v[116:119]
	s_barrier
	s_setprio 0
	s_add_i32 s54, s77, s65
	v_lshl_add_u64 v[222:223], s[58:59], 0, v[154:155]
	s_mov_b32 m0, s54
	ds_read_b128 v[180:183], v191 offset:16384
	v_xor_b32_e32 v253, 64, v191
	ds_read_b128 v[194:197], v253 offset:16384
	ds_read_b128 v[198:201], v191 offset:18432
	ds_read_b128 v[202:205], v253 offset:18432
	ds_read_b128 v[206:209], v191 offset:20480
	ds_read_b128 v[210:213], v253 offset:20480
	ds_read_b128 v[214:217], v191 offset:22528
	ds_read_b128 v[218:221], v253 offset:22528
	global_load_lds_dwordx4 v[222:223], off
	s_add_i32 m0, s54, 0x2000
	s_add_u32 s54, s58, 0xb0000
	v_lshl_add_u64 v[224:225], s[58:59], 0, v[162:163]
	s_addc_u32 s55, s59, 0
	s_add_i32 s84, s78, s65
	global_load_lds_dwordx4 v[224:225], off
	v_lshl_add_u64 v[226:227], s[54:55], 0, v[154:155]
	s_mov_b32 m0, s84
	v_lshl_add_u64 v[228:229], s[60:61], 0, v[160:161]
	global_load_lds_dwordx4 v[226:227], off
	v_lshl_add_u64 v[226:227], s[54:55], 0, v[162:163]
	s_add_i32 m0, s84, 0x2000
	s_nop 0
	global_load_lds_dwordx4 v[226:227], off
	v_lshl_add_u64 v[226:227], s[60:61], 0, v[152:153]
	s_mov_b32 m0, s66
	s_nop 0
	global_load_lds_dwordx4 v[226:227], off
	s_mov_b32 m0, s67
	s_nop 0
	global_load_lds_dwordx4 v[228:229], off
	s_waitcnt vmcnt(8)
	s_waitcnt lgkmcnt(0)
	s_setprio 1
	s_barrier
	v_mfma_f32_16x16x32_bf16 v[60:63], v[128:131], v[180:183], v[60:63]
	v_mfma_f32_16x16x32_bf16 v[60:63], v[132:135], v[194:197], v[60:63]
	v_mfma_f32_16x16x32_bf16 v[44:47], v[132:135], v[202:205], v[44:47]
	v_mfma_f32_16x16x32_bf16 v[44:47], v[128:131], v[198:201], v[44:47]
	v_mfma_f32_16x16x32_bf16 v[28:31], v[128:131], v[206:209], v[28:31]
	v_mfma_f32_16x16x32_bf16 v[28:31], v[132:135], v[210:213], v[28:31]
	v_mfma_f32_16x16x32_bf16 v[12:15], v[132:135], v[218:221], v[12:15]
	v_mfma_f32_16x16x32_bf16 v[12:15], v[128:131], v[214:217], v[12:15]
	v_mfma_f32_16x16x32_bf16 v[8:11], v[136:139], v[214:217], v[8:11]
	v_mfma_f32_16x16x32_bf16 v[8:11], v[140:143], v[218:221], v[8:11]
	v_mfma_f32_16x16x32_bf16 v[24:27], v[140:143], v[210:213], v[24:27]
	v_mfma_f32_16x16x32_bf16 v[24:27], v[136:139], v[206:209], v[24:27]
	v_mfma_f32_16x16x32_bf16 v[40:43], v[136:139], v[198:201], v[40:43]
	v_mfma_f32_16x16x32_bf16 v[40:43], v[140:143], v[202:205], v[40:43]
	v_mfma_f32_16x16x32_bf16 v[56:59], v[140:143], v[194:197], v[56:59]
	v_mfma_f32_16x16x32_bf16 v[56:59], v[136:139], v[180:183], v[56:59]
	s_setprio 0
	s_setprio 1
	v_mfma_f32_16x16x32_bf16 v[48:51], v[172:175], v[180:183], v[48:51]
	v_mfma_f32_16x16x32_bf16 v[48:51], v[176:179], v[194:197], v[48:51]
	v_mfma_f32_16x16x32_bf16 v[32:35], v[176:179], v[202:205], v[32:35]
	v_mfma_f32_16x16x32_bf16 v[32:35], v[172:175], v[198:201], v[32:35]
	v_mfma_f32_16x16x32_bf16 v[16:19], v[172:175], v[206:209], v[16:19]
	v_mfma_f32_16x16x32_bf16 v[16:19], v[176:179], v[210:213], v[16:19]
	v_mfma_f32_16x16x32_bf16 v[0:3], v[176:179], v[218:221], v[0:3]
	v_mfma_f32_16x16x32_bf16 v[0:3], v[172:175], v[214:217], v[0:3]
	v_mfma_f32_16x16x32_bf16 v[4:7], v[144:147], v[214:217], v[4:7]
	v_mfma_f32_16x16x32_bf16 v[4:7], v[148:151], v[218:221], v[4:7]
	v_mfma_f32_16x16x32_bf16 v[20:23], v[148:151], v[210:213], v[20:23]
	v_mfma_f32_16x16x32_bf16 v[20:23], v[144:147], v[206:209], v[20:23]
	v_mfma_f32_16x16x32_bf16 v[36:39], v[144:147], v[198:201], v[36:39]
	v_mfma_f32_16x16x32_bf16 v[36:39], v[148:151], v[202:205], v[36:39]
	v_mfma_f32_16x16x32_bf16 v[52:55], v[148:151], v[194:197], v[52:55]
	v_mfma_f32_16x16x32_bf16 v[52:55], v[144:147], v[180:183], v[52:55]
	s_barrier
	s_setprio 0
	s_add_i32 s84, 0, 0x18000
	s_add_i32 s85, 0, 0x1c000
	v_add_u32_e32 v140, s84, v186
	v_add_u32_e32 v176, s85, v186
	ds_read_b128 v[128:131], v140
	v_xor_b32_e32 v253, 64, v140
	ds_read_b128 v[132:135], v253
	ds_read_b128 v[136:139], v140 offset:2048
	ds_read_b128 v[140:143], v253 offset:2048
	ds_read_b128 v[144:147], v176
	v_xor_b32_e32 v253, 64, v176
	ds_read_b128 v[148:151], v253
	ds_read_b128 v[172:175], v176 offset:2048
	ds_read_b128 v[176:179], v253 offset:2048
	s_add_u32 s54, s60, 0xb0000
	s_addc_u32 s55, s61, 0
	s_mov_b32 m0, s68
	v_lshl_add_u64 v[230:231], s[54:55], 0, v[152:153]
	ds_read_b128 v[180:183], v191 offset:32768
	v_xor_b32_e32 v253, 64, v191
	ds_read_b128 v[194:197], v253 offset:32768
	ds_read_b128 v[198:201], v191 offset:34816
	ds_read_b128 v[202:205], v253 offset:34816
	ds_read_b128 v[206:209], v191 offset:36864
	ds_read_b128 v[210:213], v253 offset:36864
	ds_read_b128 v[214:217], v191 offset:38912
	ds_read_b128 v[218:221], v253 offset:38912
	global_load_lds_dwordx4 v[230:231], off
	v_lshl_add_u64 v[230:231], s[54:55], 0, v[160:161]
	s_mov_b32 m0, s69
	s_nop 0
	global_load_lds_dwordx4 v[230:231], off
	s_waitcnt vmcnt(8)
	s_waitcnt lgkmcnt(0)
	s_setprio 1
	s_barrier
	v_mfma_f32_16x16x32_bf16 v[124:127], v[128:131], v[180:183], v[124:127]
	v_mfma_f32_16x16x32_bf16 v[124:127], v[132:135], v[194:197], v[124:127]
	v_mfma_f32_16x16x32_bf16 v[108:111], v[132:135], v[202:205], v[108:111]
	v_mfma_f32_16x16x32_bf16 v[108:111], v[128:131], v[198:201], v[108:111]
	v_mfma_f32_16x16x32_bf16 v[92:95], v[128:131], v[206:209], v[92:95]
	v_mfma_f32_16x16x32_bf16 v[92:95], v[132:135], v[210:213], v[92:95]
	v_mfma_f32_16x16x32_bf16 v[76:79], v[132:135], v[218:221], v[76:79]
	v_mfma_f32_16x16x32_bf16 v[76:79], v[128:131], v[214:217], v[76:79]
	v_mfma_f32_16x16x32_bf16 v[72:75], v[136:139], v[214:217], v[72:75]
	v_mfma_f32_16x16x32_bf16 v[72:75], v[140:143], v[218:221], v[72:75]
	v_mfma_f32_16x16x32_bf16 v[88:91], v[140:143], v[210:213], v[88:91]
	v_mfma_f32_16x16x32_bf16 v[88:91], v[136:139], v[206:209], v[88:91]
	v_mfma_f32_16x16x32_bf16 v[104:107], v[136:139], v[198:201], v[104:107]
	v_mfma_f32_16x16x32_bf16 v[104:107], v[140:143], v[202:205], v[104:107]
	v_mfma_f32_16x16x32_bf16 v[120:123], v[140:143], v[194:197], v[120:123]
	v_mfma_f32_16x16x32_bf16 v[120:123], v[136:139], v[180:183], v[120:123]
	s_setprio 0
	s_setprio 1
	v_mfma_f32_16x16x32_bf16 v[112:115], v[172:175], v[180:183], v[112:115]
	v_mfma_f32_16x16x32_bf16 v[112:115], v[176:179], v[194:197], v[112:115]
	v_mfma_f32_16x16x32_bf16 v[96:99], v[176:179], v[202:205], v[96:99]
	v_mfma_f32_16x16x32_bf16 v[96:99], v[172:175], v[198:201], v[96:99]
	v_mfma_f32_16x16x32_bf16 v[80:83], v[172:175], v[206:209], v[80:83]
	v_mfma_f32_16x16x32_bf16 v[80:83], v[176:179], v[210:213], v[80:83]
	v_mfma_f32_16x16x32_bf16 v[64:67], v[176:179], v[218:221], v[64:67]
	v_mfma_f32_16x16x32_bf16 v[64:67], v[172:175], v[214:217], v[64:67]
	v_mfma_f32_16x16x32_bf16 v[68:71], v[144:147], v[214:217], v[68:71]
	v_mfma_f32_16x16x32_bf16 v[68:71], v[148:151], v[218:221], v[68:71]
	v_mfma_f32_16x16x32_bf16 v[84:87], v[148:151], v[210:213], v[84:87]
	v_mfma_f32_16x16x32_bf16 v[84:87], v[144:147], v[206:209], v[84:87]
	v_mfma_f32_16x16x32_bf16 v[100:103], v[144:147], v[198:201], v[100:103]
	v_mfma_f32_16x16x32_bf16 v[100:103], v[148:151], v[202:205], v[100:103]
	v_mfma_f32_16x16x32_bf16 v[116:119], v[148:151], v[194:197], v[116:119]
	v_mfma_f32_16x16x32_bf16 v[116:119], v[144:147], v[180:183], v[116:119]
	s_barrier
	s_setprio 0
	s_add_i32 s54, s84, s65
	v_lshl_add_u64 v[222:223], v[222:223], 0, s[28:29]
	s_mov_b32 m0, s54
	ds_read_b128 v[180:183], v191 offset:49152
	v_xor_b32_e32 v253, 64, v191
	ds_read_b128 v[194:197], v253 offset:49152
	ds_read_b128 v[198:201], v191 offset:51200
	ds_read_b128 v[202:205], v253 offset:51200
	ds_read_b128 v[206:209], v191 offset:53248
	ds_read_b128 v[210:213], v253 offset:53248
	ds_read_b128 v[214:217], v191 offset:55296
	ds_read_b128 v[218:221], v253 offset:55296
	global_load_lds_dwordx4 v[222:223], off
	s_add_i32 m0, s54, 0x2000
	s_add_u32 s54, s58, 0xb0080
	v_lshl_add_u64 v[222:223], v[224:225], 0, s[28:29]
	s_addc_u32 s55, s59, 0
	s_add_i32 s58, s85, s65
	global_load_lds_dwordx4 v[222:223], off
	v_lshl_add_u64 v[222:223], s[54:55], 0, v[154:155]
	s_mov_b32 m0, s58
	s_nop 0
	global_load_lds_dwordx4 v[222:223], off
	v_lshl_add_u64 v[222:223], s[54:55], 0, v[162:163]
	s_add_i32 m0, s58, 0x2000
	s_nop 0
	global_load_lds_dwordx4 v[222:223], off
	v_lshl_add_u64 v[222:223], v[226:227], 0, s[28:29]
	s_mov_b32 m0, s3
	s_nop 0
	global_load_lds_dwordx4 v[222:223], off
	v_lshl_add_u64 v[222:223], v[228:229], 0, s[28:29]
	s_mov_b32 m0, s71
	s_nop 0
	global_load_lds_dwordx4 v[222:223], off
	s_waitcnt vmcnt(8)
	s_waitcnt lgkmcnt(0)
	s_setprio 1
	s_barrier
	v_mfma_f32_16x16x32_bf16 v[60:63], v[128:131], v[180:183], v[60:63]
	v_mfma_f32_16x16x32_bf16 v[60:63], v[132:135], v[194:197], v[60:63]
	v_mfma_f32_16x16x32_bf16 v[44:47], v[132:135], v[202:205], v[44:47]
	v_mfma_f32_16x16x32_bf16 v[44:47], v[128:131], v[198:201], v[44:47]
	v_mfma_f32_16x16x32_bf16 v[28:31], v[128:131], v[206:209], v[28:31]
	v_mfma_f32_16x16x32_bf16 v[28:31], v[132:135], v[210:213], v[28:31]
	v_mfma_f32_16x16x32_bf16 v[12:15], v[132:135], v[218:221], v[12:15]
	v_mfma_f32_16x16x32_bf16 v[12:15], v[128:131], v[214:217], v[12:15]
	v_mfma_f32_16x16x32_bf16 v[8:11], v[136:139], v[214:217], v[8:11]
	v_mfma_f32_16x16x32_bf16 v[8:11], v[140:143], v[218:221], v[8:11]
	v_mfma_f32_16x16x32_bf16 v[24:27], v[140:143], v[210:213], v[24:27]
	v_mfma_f32_16x16x32_bf16 v[24:27], v[136:139], v[206:209], v[24:27]
	v_mfma_f32_16x16x32_bf16 v[40:43], v[136:139], v[198:201], v[40:43]
	v_mfma_f32_16x16x32_bf16 v[40:43], v[140:143], v[202:205], v[40:43]
	v_mfma_f32_16x16x32_bf16 v[56:59], v[140:143], v[194:197], v[56:59]
	v_mfma_f32_16x16x32_bf16 v[56:59], v[136:139], v[180:183], v[56:59]
	s_setprio 0
	s_setprio 1
	v_mfma_f32_16x16x32_bf16 v[48:51], v[172:175], v[180:183], v[48:51]
	v_mfma_f32_16x16x32_bf16 v[48:51], v[176:179], v[194:197], v[48:51]
	v_mfma_f32_16x16x32_bf16 v[32:35], v[176:179], v[202:205], v[32:35]
	v_mfma_f32_16x16x32_bf16 v[32:35], v[172:175], v[198:201], v[32:35]
	v_mfma_f32_16x16x32_bf16 v[16:19], v[172:175], v[206:209], v[16:19]
	v_mfma_f32_16x16x32_bf16 v[16:19], v[176:179], v[210:213], v[16:19]
	v_mfma_f32_16x16x32_bf16 v[0:3], v[176:179], v[218:221], v[0:3]
	v_mfma_f32_16x16x32_bf16 v[0:3], v[172:175], v[214:217], v[0:3]
	v_mfma_f32_16x16x32_bf16 v[4:7], v[144:147], v[214:217], v[4:7]
	v_mfma_f32_16x16x32_bf16 v[4:7], v[148:151], v[218:221], v[4:7]
	v_mfma_f32_16x16x32_bf16 v[20:23], v[148:151], v[210:213], v[20:23]
	v_mfma_f32_16x16x32_bf16 v[20:23], v[144:147], v[206:209], v[20:23]
	v_mfma_f32_16x16x32_bf16 v[36:39], v[144:147], v[198:201], v[36:39]
	v_mfma_f32_16x16x32_bf16 v[36:39], v[148:151], v[202:205], v[36:39]
	v_mfma_f32_16x16x32_bf16 v[52:55], v[148:151], v[194:197], v[52:55]
	v_mfma_f32_16x16x32_bf16 v[52:55], v[144:147], v[180:183], v[52:55]
	s_barrier
	s_setprio 0
	s_add_i32 s83, s83, 2
	s_add_u32 s81, s81, 0x100
	s_addc_u32 s82, s82, 0
	s_cmp_gt_u32 s83, 41
	s_mov_b64 s[54:55], s[56:57]
	s_cbranch_scc0 .LBB0_159
	s_and_b64 vcc, exec, s[30:31]
	s_cbranch_vccz .LBB0_162
	s_barrier

.LBB0_254:
	s_ashr_i32 s61, s60, 31
	s_lshl_b64 s[62:63], s[60:61], 19
	s_add_u32 s62, s35, s62
	s_addc_u32 s63, s47, s63
	s_and_b64 s[64:65], s[12:13], exec
	s_cselect_b32 s3, s63, s69
	s_cselect_b32 s61, s62, s68
	s_ashr_i32 s59, s58, 31
	s_lshl_b64 s[64:65], s[58:59], 19
	s_add_u32 s64, s49, s64
	s_addc_u32 s65, s70, s65
	s_and_b64 s[92:93], s[12:13], exec
	s_cselect_b32 s91, s65, s67
	s_cselect_b32 s92, s64, s66
	s_lshl_b32 s59, s14, 8
	v_add_u32_e32 v0, s59, v182
	s_add_u32 s93, s66, 0x100
	s_waitcnt lgkmcnt(0)
	v_ashrrev_i32_e32 v1, 31, v0
	s_addc_u32 s94, s67, 0
	v_lshl_add_u64 v[72:73], v[0:1], 4, s[26:27]
	s_add_u32 s14, s68, 0x40080
	s_addc_u32 s15, s69, 0
	s_mov_b32 s95, -2
	s_mov_b64 s[66:67], 0
	s_cmp_eq_u32 s90, 1
	s_cbranch_scc1 .Lfa_2
	v_add_u32_e32 v74, s83, v181
	ds_read_b128 v[88:91], v74
	v_xor_b32_e32 v253, 64, v74
	ds_read_b128 v[108:111], v253
	ds_read_b128 v[128:131], v74 offset:2048
	ds_read_b128 v[144:147], v253 offset:2048
	v_add_u32_e32 v74, s84, v181
	ds_read_b128 v[148:151], v74
	v_xor_b32_e32 v253, 64, v74
	ds_read_b128 v[152:155], v253
	ds_read_b128 v[176:179], v74 offset:2048
	ds_read_b128 v[190:193], v253 offset:2048
	s_add_u32 s68, s14, 0xfffc0080
	s_addc_u32 s69, s15, -1
	s_and_b64 s[66:67], s[66:67], exec
	s_cselect_b32 s69, s3, s69
	s_cselect_b32 s68, s61, s68
	s_cselect_b32 s67, s91, s94
	s_cselect_b32 s66, s92, s93
	v_lshl_add_u64 v[74:75], s[14:15], 0, v[170:171]
	s_add_i32 m0, s74, 0xc000
	ds_read_b128 v[194:197], v187
	v_xor_b32_e32 v253, 64, v187
	ds_read_b128 v[198:201], v253
	ds_read_b128 v[202:205], v187 offset:2048
	ds_read_b128 v[206:209], v253 offset:2048
	ds_read_b128 v[210:213], v187 offset:4096
	ds_read_b128 v[214:217], v253 offset:4096
	ds_read_b128 v[218:221], v187 offset:6144
	ds_read_b128 v[222:225], v253 offset:6144
	global_load_lds_dwordx4 v[74:75], off
	v_lshl_add_u64 v[74:75], s[14:15], 0, v[168:169]
	s_add_i32 m0, s74, 0xe000
	s_nop 0
	global_load_lds_dwordx4 v[74:75], off
	s_waitcnt vmcnt(24)
	s_waitcnt lgkmcnt(0)
	s_setprio 1
	s_barrier
	v_mfma_f32_16x16x32_bf16 v[140:143], v[88:91], v[194:197], 0
	v_mfma_f32_16x16x32_bf16 v[136:139], v[128:131], v[194:197], 0
	v_mfma_f32_16x16x32_bf16 v[120:123], v[88:91], v[202:205], 0
	v_mfma_f32_16x16x32_bf16 v[116:119], v[128:131], v[202:205], 0
	v_mfma_f32_16x16x32_bf16 v[100:103], v[88:91], v[210:213], 0
	v_mfma_f32_16x16x32_bf16 v[96:99], v[128:131], v[210:213], 0
	v_mfma_f32_16x16x32_bf16 v[80:83], v[88:91], v[218:221], 0
	v_mfma_f32_16x16x32_bf16 v[74:77], v[128:131], v[218:221], 0
	v_mfma_f32_16x16x32_bf16 v[140:143], v[108:111], v[198:201], v[140:143]
	v_mfma_f32_16x16x32_bf16 v[136:139], v[144:147], v[198:201], v[136:139]
	v_mfma_f32_16x16x32_bf16 v[120:123], v[108:111], v[206:209], v[120:123]
	v_mfma_f32_16x16x32_bf16 v[116:119], v[144:147], v[206:209], v[116:119]
	v_mfma_f32_16x16x32_bf16 v[100:103], v[108:111], v[214:217], v[100:103]
	v_mfma_f32_16x16x32_bf16 v[96:99], v[144:147], v[214:217], v[96:99]
	v_mfma_f32_16x16x32_bf16 v[80:83], v[108:111], v[222:225], v[80:83]
	v_mfma_f32_16x16x32_bf16 v[74:77], v[144:147], v[222:225], v[74:77]
	s_setprio 0
	s_setprio 1
	v_mfma_f32_16x16x32_bf16 v[132:135], v[148:151], v[194:197], 0
	v_mfma_f32_16x16x32_bf16 v[124:127], v[176:179], v[194:197], 0
	v_mfma_f32_16x16x32_bf16 v[112:115], v[148:151], v[202:205], 0
	v_mfma_f32_16x16x32_bf16 v[104:107], v[176:179], v[202:205], 0
	v_mfma_f32_16x16x32_bf16 v[92:95], v[148:151], v[210:213], 0
	v_mfma_f32_16x16x32_bf16 v[84:87], v[176:179], v[210:213], 0
	v_mfma_f32_16x16x32_bf16 v[68:71], v[148:151], v[218:221], 0
	v_mfma_f32_16x16x32_bf16 v[64:67], v[176:179], v[218:221], 0
	v_mfma_f32_16x16x32_bf16 v[132:135], v[152:155], v[198:201], v[132:135]
	v_mfma_f32_16x16x32_bf16 v[124:127], v[190:193], v[198:201], v[124:127]
	v_mfma_f32_16x16x32_bf16 v[112:115], v[152:155], v[206:209], v[112:115]
	v_mfma_f32_16x16x32_bf16 v[104:107], v[190:193], v[206:209], v[104:107]
	v_mfma_f32_16x16x32_bf16 v[92:95], v[152:155], v[214:217], v[92:95]
	v_mfma_f32_16x16x32_bf16 v[84:87], v[190:193], v[214:217], v[84:87]
	v_mfma_f32_16x16x32_bf16 v[68:71], v[152:155], v[222:225], v[68:71]
	v_mfma_f32_16x16x32_bf16 v[64:67], v[190:193], v[222:225], v[64:67]
	s_barrier
	s_setprio 0
	s_add_i32 s96, s83, s71
	v_lshl_add_u64 v[226:227], s[66:67], 0, v[162:163]
	s_mov_b32 m0, s96
	ds_read_b128 v[194:197], v187 offset:16384
	v_xor_b32_e32 v253, 64, v187
	ds_read_b128 v[198:201], v253 offset:16384
	ds_read_b128 v[202:205], v187 offset:18432
	ds_read_b128 v[206:209], v253 offset:18432
	ds_read_b128 v[210:213], v187 offset:20480
	ds_read_b128 v[214:217], v253 offset:20480
	ds_read_b128 v[218:221], v187 offset:22528
	ds_read_b128 v[222:225], v253 offset:22528
	global_load_lds_dwordx4 v[226:227], off
	s_add_i32 m0, s96, 0x2000
	s_add_u32 s96, s66, 0x40000
	v_lshl_add_u64 v[228:229], s[66:67], 0, v[166:167]
	s_addc_u32 s97, s67, 0
	s_add_i32 vcc_lo, s84, s71
	global_load_lds_dwordx4 v[228:229], off
	v_lshl_add_u64 v[78:79], s[96:97], 0, v[162:163]
	s_mov_b32 m0, vcc_lo
	v_lshl_add_u64 v[230:231], s[68:69], 0, v[160:161]
	global_load_lds_dwordx4 v[78:79], off
	v_lshl_add_u64 v[78:79], s[96:97], 0, v[166:167]
	s_add_i32 m0, vcc_lo, 0x2000
	v_lshl_add_u64 v[232:233], s[68:69], 0, v[164:165]
	global_load_lds_dwordx4 v[78:79], off
	s_mov_b32 m0, s74
	s_nop 0
	global_load_lds_dwordx4 v[230:231], off
	s_mov_b32 m0, s75
	s_nop 0
	global_load_lds_dwordx4 v[232:233], off
	s_waitcnt vmcnt(24)
	s_waitcnt lgkmcnt(0)
	s_setprio 1
	s_barrier
	v_mfma_f32_16x16x32_bf16 v[60:63], v[88:91], v[194:197], 0
	v_mfma_f32_16x16x32_bf16 v[56:59], v[128:131], v[194:197], 0
	v_mfma_f32_16x16x32_bf16 v[44:47], v[88:91], v[202:205], 0
	v_mfma_f32_16x16x32_bf16 v[40:43], v[128:131], v[202:205], 0
	v_mfma_f32_16x16x32_bf16 v[28:31], v[88:91], v[210:213], 0
	v_mfma_f32_16x16x32_bf16 v[24:27], v[128:131], v[210:213], 0
	v_mfma_f32_16x16x32_bf16 v[12:15], v[88:91], v[218:221], 0
	v_mfma_f32_16x16x32_bf16 v[8:11], v[128:131], v[218:221], 0
	v_mfma_f32_16x16x32_bf16 v[60:63], v[108:111], v[198:201], v[60:63]
	v_mfma_f32_16x16x32_bf16 v[56:59], v[144:147], v[198:201], v[56:59]
	v_mfma_f32_16x16x32_bf16 v[44:47], v[108:111], v[206:209], v[44:47]
	v_mfma_f32_16x16x32_bf16 v[40:43], v[144:147], v[206:209], v[40:43]
	v_mfma_f32_16x16x32_bf16 v[28:31], v[108:111], v[214:217], v[28:31]
	v_mfma_f32_16x16x32_bf16 v[24:27], v[144:147], v[214:217], v[24:27]
	v_mfma_f32_16x16x32_bf16 v[12:15], v[108:111], v[222:225], v[12:15]
	v_mfma_f32_16x16x32_bf16 v[8:11], v[144:147], v[222:225], v[8:11]
	s_setprio 0
	s_setprio 1
	v_mfma_f32_16x16x32_bf16 v[52:55], v[148:151], v[194:197], 0
	v_mfma_f32_16x16x32_bf16 v[48:51], v[176:179], v[194:197], 0
	v_mfma_f32_16x16x32_bf16 v[36:39], v[148:151], v[202:205], 0
	v_mfma_f32_16x16x32_bf16 v[32:35], v[176:179], v[202:205], 0
	v_mfma_f32_16x16x32_bf16 v[20:23], v[148:151], v[210:213], 0
	v_mfma_f32_16x16x32_bf16 v[16:19], v[176:179], v[210:213], 0
	v_mfma_f32_16x16x32_bf16 v[4:7], v[148:151], v[218:221], 0
	v_mfma_f32_16x16x32_bf16 v[0:3], v[176:179], v[218:221], 0
	v_mfma_f32_16x16x32_bf16 v[52:55], v[152:155], v[198:201], v[52:55]
	v_mfma_f32_16x16x32_bf16 v[48:51], v[190:193], v[198:201], v[48:51]
	v_mfma_f32_16x16x32_bf16 v[36:39], v[152:155], v[206:209], v[36:39]
	v_mfma_f32_16x16x32_bf16 v[32:35], v[190:193], v[206:209], v[32:35]
	v_mfma_f32_16x16x32_bf16 v[20:23], v[152:155], v[214:217], v[20:23]
	v_mfma_f32_16x16x32_bf16 v[16:19], v[190:193], v[214:217], v[16:19]
	v_mfma_f32_16x16x32_bf16 v[4:7], v[152:155], v[222:225], v[4:7]
	v_mfma_f32_16x16x32_bf16 v[0:3], v[190:193], v[222:225], v[0:3]
	s_barrier
	s_setprio 0
	s_add_i32 s96, 0, 0x18000
	v_add_u32_e32 v78, s96, v181
	s_add_i32 s97, 0, 0x1c000
	ds_read_b128 v[88:91], v78
	v_xor_b32_e32 v253, 64, v78
	ds_read_b128 v[108:111], v253
	ds_read_b128 v[128:131], v78 offset:2048
	ds_read_b128 v[144:147], v253 offset:2048
	v_add_u32_e32 v78, s97, v181
	ds_read_b128 v[148:151], v78
	v_xor_b32_e32 v253, 64, v78
	ds_read_b128 v[152:155], v253
	ds_read_b128 v[176:179], v78 offset:2048
	ds_read_b128 v[190:193], v253 offset:2048
	s_add_u32 s68, s68, 0x40000
	s_addc_u32 s69, s69, 0
	s_mov_b32 m0, s76
	v_lshl_add_u64 v[78:79], s[68:69], 0, v[160:161]
	ds_read_b128 v[194:197], v187 offset:32768
	v_xor_b32_e32 v253, 64, v187
	ds_read_b128 v[198:201], v253 offset:32768
	ds_read_b128 v[202:205], v187 offset:34816
	ds_read_b128 v[206:209], v253 offset:34816
	ds_read_b128 v[210:213], v187 offset:36864
	ds_read_b128 v[214:217], v253 offset:36864
	ds_read_b128 v[218:221], v187 offset:38912
	ds_read_b128 v[222:225], v253 offset:38912
	global_load_lds_dwordx4 v[78:79], off
	v_lshl_add_u64 v[78:79], s[68:69], 0, v[164:165]
	s_mov_b32 m0, s77
	s_nop 0
	global_load_lds_dwordx4 v[78:79], off
	s_waitcnt vmcnt(8)
	s_waitcnt lgkmcnt(0)
	s_setprio 1
	s_barrier
	v_mfma_f32_16x16x32_bf16 v[140:143], v[88:91], v[194:197], v[140:143]
	v_mfma_f32_16x16x32_bf16 v[136:139], v[128:131], v[194:197], v[136:139]
	v_mfma_f32_16x16x32_bf16 v[120:123], v[88:91], v[202:205], v[120:123]
	v_mfma_f32_16x16x32_bf16 v[116:119], v[128:131], v[202:205], v[116:119]
	v_mfma_f32_16x16x32_bf16 v[100:103], v[88:91], v[210:213], v[100:103]
	v_mfma_f32_16x16x32_bf16 v[96:99], v[128:131], v[210:213], v[96:99]
	v_mfma_f32_16x16x32_bf16 v[78:81], v[88:91], v[218:221], v[80:83]
	v_mfma_f32_16x16x32_bf16 v[74:77], v[128:131], v[218:221], v[74:77]
	v_mfma_f32_16x16x32_bf16 v[140:143], v[108:111], v[198:201], v[140:143]
	v_mfma_f32_16x16x32_bf16 v[136:139], v[144:147], v[198:201], v[136:139]
	v_mfma_f32_16x16x32_bf16 v[120:123], v[108:111], v[206:209], v[120:123]
	v_mfma_f32_16x16x32_bf16 v[116:119], v[144:147], v[206:209], v[116:119]
	v_mfma_f32_16x16x32_bf16 v[100:103], v[108:111], v[214:217], v[100:103]
	v_mfma_f32_16x16x32_bf16 v[96:99], v[144:147], v[214:217], v[96:99]
	v_mfma_f32_16x16x32_bf16 v[80:83], v[108:111], v[222:225], v[78:81]
	v_mfma_f32_16x16x32_bf16 v[76:79], v[144:147], v[222:225], v[74:77]
	s_setprio 0
	s_setprio 1
	v_mfma_f32_16x16x32_bf16 v[132:135], v[148:151], v[194:197], v[132:135]
	v_mfma_f32_16x16x32_bf16 v[124:127], v[176:179], v[194:197], v[124:127]
	v_mfma_f32_16x16x32_bf16 v[112:115], v[148:151], v[202:205], v[112:115]
	v_mfma_f32_16x16x32_bf16 v[104:107], v[176:179], v[202:205], v[104:107]
	v_mfma_f32_16x16x32_bf16 v[92:95], v[148:151], v[210:213], v[92:95]
	v_mfma_f32_16x16x32_bf16 v[84:87], v[176:179], v[210:213], v[84:87]
	v_mfma_f32_16x16x32_bf16 v[68:71], v[148:151], v[218:221], v[68:71]
	v_mfma_f32_16x16x32_bf16 v[64:67], v[176:179], v[218:221], v[64:67]
	v_mfma_f32_16x16x32_bf16 v[132:135], v[152:155], v[198:201], v[132:135]
	v_mfma_f32_16x16x32_bf16 v[124:127], v[190:193], v[198:201], v[124:127]
	v_mfma_f32_16x16x32_bf16 v[112:115], v[152:155], v[206:209], v[112:115]
	v_mfma_f32_16x16x32_bf16 v[104:107], v[190:193], v[206:209], v[104:107]
	v_mfma_f32_16x16x32_bf16 v[92:95], v[152:155], v[214:217], v[92:95]
	v_mfma_f32_16x16x32_bf16 v[84:87], v[190:193], v[214:217], v[84:87]
	v_mfma_f32_16x16x32_bf16 v[68:71], v[152:155], v[222:225], v[68:71]
	v_mfma_f32_16x16x32_bf16 v[64:67], v[190:193], v[222:225], v[64:67]
	s_barrier
	s_setprio 0
	s_add_i32 s68, s96, s71
	v_lshl_add_u64 v[74:75], v[226:227], 0, s[28:29]
	s_mov_b32 m0, s68
	ds_read_b128 v[194:197], v187 offset:49152
	v_xor_b32_e32 v253, 64, v187
	ds_read_b128 v[198:201], v253 offset:49152
	ds_read_b128 v[202:205], v187 offset:51200
	ds_read_b128 v[206:209], v253 offset:51200
	ds_read_b128 v[210:213], v187 offset:53248
	ds_read_b128 v[214:217], v253 offset:53248
	ds_read_b128 v[218:221], v187 offset:55296
	ds_read_b128 v[222:225], v253 offset:55296
	global_load_lds_dwordx4 v[74:75], off
	s_add_i32 m0, s68, 0x2000
	s_add_u32 s66, s66, 0x40080
	v_lshl_add_u64 v[74:75], v[228:229], 0, s[28:29]
	s_addc_u32 s67, s67, 0
	s_add_i32 s68, s97, s71
	global_load_lds_dwordx4 v[74:75], off
	v_lshl_add_u64 v[74:75], s[66:67], 0, v[162:163]
	s_mov_b32 m0, s68
	s_nop 0
	global_load_lds_dwordx4 v[74:75], off
	v_lshl_add_u64 v[74:75], s[66:67], 0, v[166:167]
	s_add_i32 m0, s68, 0x2000
	s_nop 0
	global_load_lds_dwordx4 v[74:75], off
	v_lshl_add_u64 v[74:75], v[230:231], 0, s[28:29]
	s_mov_b32 m0, s78
	s_nop 0
	global_load_lds_dwordx4 v[74:75], off
	v_lshl_add_u64 v[74:75], v[232:233], 0, s[28:29]
	s_mov_b32 m0, s79
	s_nop 0
	global_load_lds_dwordx4 v[74:75], off
	s_waitcnt vmcnt(8)
	s_waitcnt lgkmcnt(0)
	s_setprio 1
	s_barrier
	v_mfma_f32_16x16x32_bf16 v[60:63], v[88:91], v[194:197], v[60:63]
	v_mfma_f32_16x16x32_bf16 v[60:63], v[108:111], v[198:201], v[60:63]
	v_mfma_f32_16x16x32_bf16 v[44:47], v[108:111], v[206:209], v[44:47]
	v_mfma_f32_16x16x32_bf16 v[44:47], v[88:91], v[202:205], v[44:47]
	v_mfma_f32_16x16x32_bf16 v[28:31], v[88:91], v[210:213], v[28:31]
	v_mfma_f32_16x16x32_bf16 v[28:31], v[108:111], v[214:217], v[28:31]
	v_mfma_f32_16x16x32_bf16 v[12:15], v[108:111], v[222:225], v[12:15]
	v_mfma_f32_16x16x32_bf16 v[12:15], v[88:91], v[218:221], v[12:15]
	v_mfma_f32_16x16x32_bf16 v[8:11], v[128:131], v[218:221], v[8:11]
	v_mfma_f32_16x16x32_bf16 v[8:11], v[144:147], v[222:225], v[8:11]
	v_mfma_f32_16x16x32_bf16 v[24:27], v[144:147], v[214:217], v[24:27]
	v_mfma_f32_16x16x32_bf16 v[24:27], v[128:131], v[210:213], v[24:27]
	v_mfma_f32_16x16x32_bf16 v[40:43], v[128:131], v[202:205], v[40:43]
	v_mfma_f32_16x16x32_bf16 v[40:43], v[144:147], v[206:209], v[40:43]
	v_mfma_f32_16x16x32_bf16 v[56:59], v[144:147], v[198:201], v[56:59]
	v_mfma_f32_16x16x32_bf16 v[56:59], v[128:131], v[194:197], v[56:59]
	s_setprio 0
	s_setprio 1
	v_mfma_f32_16x16x32_bf16 v[48:51], v[176:179], v[194:197], v[48:51]
	v_mfma_f32_16x16x32_bf16 v[48:51], v[190:193], v[198:201], v[48:51]
	v_mfma_f32_16x16x32_bf16 v[32:35], v[190:193], v[206:209], v[32:35]
	v_mfma_f32_16x16x32_bf16 v[32:35], v[176:179], v[202:205], v[32:35]
	v_mfma_f32_16x16x32_bf16 v[16:19], v[176:179], v[210:213], v[16:19]
	v_mfma_f32_16x16x32_bf16 v[16:19], v[190:193], v[214:217], v[16:19]
	v_mfma_f32_16x16x32_bf16 v[0:3], v[190:193], v[222:225], v[0:3]
	v_mfma_f32_16x16x32_bf16 v[0:3], v[176:179], v[218:221], v[0:3]
	v_mfma_f32_16x16x32_bf16 v[4:7], v[148:151], v[218:221], v[4:7]
	v_mfma_f32_16x16x32_bf16 v[4:7], v[152:155], v[222:225], v[4:7]
	v_mfma_f32_16x16x32_bf16 v[20:23], v[152:155], v[214:217], v[20:23]
	v_mfma_f32_16x16x32_bf16 v[20:23], v[148:151], v[210:213], v[20:23]
	v_mfma_f32_16x16x32_bf16 v[36:39], v[148:151], v[202:205], v[36:39]
	v_mfma_f32_16x16x32_bf16 v[36:39], v[152:155], v[206:209], v[36:39]
	v_mfma_f32_16x16x32_bf16 v[52:55], v[152:155], v[198:201], v[52:55]
	v_mfma_f32_16x16x32_bf16 v[52:55], v[148:151], v[194:197], v[52:55]
	s_barrier
	s_setprio 0
	s_add_i32 s95, s95, 2
	s_add_u32 s93, s93, 0x100
	s_addc_u32 s94, s94, 0
	s_add_u32 s14, s14, 0x100
	s_addc_u32 s15, s15, 0
	s_branch .LBB0_256
.Lfa_2:
	v_add_u32_e32 v74, s83, v181
	ds_read_b128 v[88:91], v74
	v_xor_b32_e32 v253, 64, v74
	ds_read_b128 v[108:111], v253
	ds_read_b128 v[128:131], v74 offset:2048
	ds_read_b128 v[144:147], v253 offset:2048
	v_add_u32_e32 v74, s84, v181
	ds_read_b128 v[148:151], v74
	v_xor_b32_e32 v253, 64, v74
	ds_read_b128 v[152:155], v253
	ds_read_b128 v[176:179], v74 offset:2048
	ds_read_b128 v[190:193], v253 offset:2048
	s_add_u32 s68, s14, 0xfffc0080
	s_addc_u32 s69, s15, -1
	s_and_b64 s[66:67], s[66:67], exec
	s_cselect_b32 s69, s3, s69
	s_cselect_b32 s68, s61, s68
	s_cselect_b32 s67, s91, s94
	s_cselect_b32 s66, s92, s93
	v_lshl_add_u64 v[74:75], s[14:15], 0, v[170:171]
	s_add_i32 m0, s74, 0xc000
	ds_read_b128 v[194:197], v187
	v_xor_b32_e32 v253, 64, v187
	ds_read_b128 v[198:201], v253
	ds_read_b128 v[202:205], v187 offset:2048
	ds_read_b128 v[206:209], v253 offset:2048
	ds_read_b128 v[210:213], v187 offset:4096
	ds_read_b128 v[214:217], v253 offset:4096
	ds_read_b128 v[218:221], v187 offset:6144
	ds_read_b128 v[222:225], v253 offset:6144
	global_load_lds_dwordx4 v[74:75], off
	v_lshl_add_u64 v[74:75], s[14:15], 0, v[168:169]
	s_add_i32 m0, s74, 0xe000
	s_nop 0
	global_load_lds_dwordx4 v[74:75], off
	s_waitcnt vmcnt(8)
	s_waitcnt lgkmcnt(0)
	s_setprio 1
	s_barrier
	v_mfma_f32_16x16x32_bf16 v[140:143], v[88:91], v[194:197], 0
	v_mfma_f32_16x16x32_bf16 v[136:139], v[128:131], v[194:197], 0
	v_mfma_f32_16x16x32_bf16 v[120:123], v[88:91], v[202:205], 0
	v_mfma_f32_16x16x32_bf16 v[116:119], v[128:131], v[202:205], 0
	v_mfma_f32_16x16x32_bf16 v[100:103], v[88:91], v[210:213], 0
	v_mfma_f32_16x16x32_bf16 v[96:99], v[128:131], v[210:213], 0
	v_mfma_f32_16x16x32_bf16 v[80:83], v[88:91], v[218:221], 0
	v_mfma_f32_16x16x32_bf16 v[74:77], v[128:131], v[218:221], 0
	v_mfma_f32_16x16x32_bf16 v[140:143], v[108:111], v[198:201], v[140:143]
	v_mfma_f32_16x16x32_bf16 v[136:139], v[144:147], v[198:201], v[136:139]
	v_mfma_f32_16x16x32_bf16 v[120:123], v[108:111], v[206:209], v[120:123]
	v_mfma_f32_16x16x32_bf16 v[116:119], v[144:147], v[206:209], v[116:119]
	v_mfma_f32_16x16x32_bf16 v[100:103], v[108:111], v[214:217], v[100:103]
	v_mfma_f32_16x16x32_bf16 v[96:99], v[144:147], v[214:217], v[96:99]
	v_mfma_f32_16x16x32_bf16 v[80:83], v[108:111], v[222:225], v[80:83]
	v_mfma_f32_16x16x32_bf16 v[74:77], v[144:147], v[222:225], v[74:77]
	s_setprio 0
	s_setprio 1
	v_mfma_f32_16x16x32_bf16 v[132:135], v[148:151], v[194:197], 0
	v_mfma_f32_16x16x32_bf16 v[124:127], v[176:179], v[194:197], 0
	v_mfma_f32_16x16x32_bf16 v[112:115], v[148:151], v[202:205], 0
	v_mfma_f32_16x16x32_bf16 v[104:107], v[176:179], v[202:205], 0
	v_mfma_f32_16x16x32_bf16 v[92:95], v[148:151], v[210:213], 0
	v_mfma_f32_16x16x32_bf16 v[84:87], v[176:179], v[210:213], 0
	v_mfma_f32_16x16x32_bf16 v[68:71], v[148:151], v[218:221], 0
	v_mfma_f32_16x16x32_bf16 v[64:67], v[176:179], v[218:221], 0
	v_mfma_f32_16x16x32_bf16 v[132:135], v[152:155], v[198:201], v[132:135]
	v_mfma_f32_16x16x32_bf16 v[124:127], v[190:193], v[198:201], v[124:127]
	v_mfma_f32_16x16x32_bf16 v[112:115], v[152:155], v[206:209], v[112:115]
	v_mfma_f32_16x16x32_bf16 v[104:107], v[190:193], v[206:209], v[104:107]
	v_mfma_f32_16x16x32_bf16 v[92:95], v[152:155], v[214:217], v[92:95]
	v_mfma_f32_16x16x32_bf16 v[84:87], v[190:193], v[214:217], v[84:87]
	v_mfma_f32_16x16x32_bf16 v[68:71], v[152:155], v[222:225], v[68:71]
	v_mfma_f32_16x16x32_bf16 v[64:67], v[190:193], v[222:225], v[64:67]
	s_barrier
	s_setprio 0
	s_add_i32 s96, s83, s71
	v_lshl_add_u64 v[226:227], s[66:67], 0, v[162:163]
	s_mov_b32 m0, s96
	ds_read_b128 v[194:197], v187 offset:16384
	v_xor_b32_e32 v253, 64, v187
	ds_read_b128 v[198:201], v253 offset:16384
	ds_read_b128 v[202:205], v187 offset:18432
	ds_read_b128 v[206:209], v253 offset:18432
	ds_read_b128 v[210:213], v187 offset:20480
	ds_read_b128 v[214:217], v253 offset:20480
	ds_read_b128 v[218:221], v187 offset:22528
	ds_read_b128 v[222:225], v253 offset:22528
	global_load_lds_dwordx4 v[226:227], off
	s_add_i32 m0, s96, 0x2000
	s_add_u32 s96, s66, 0x40000
	v_lshl_add_u64 v[228:229], s[66:67], 0, v[166:167]
	s_addc_u32 s97, s67, 0
	s_add_i32 vcc_lo, s84, s71
	global_load_lds_dwordx4 v[228:229], off
	v_lshl_add_u64 v[78:79], s[96:97], 0, v[162:163]
	s_mov_b32 m0, vcc_lo
	v_lshl_add_u64 v[230:231], s[68:69], 0, v[160:161]
	global_load_lds_dwordx4 v[78:79], off
	v_lshl_add_u64 v[78:79], s[96:97], 0, v[166:167]
	s_add_i32 m0, vcc_lo, 0x2000
	v_lshl_add_u64 v[232:233], s[68:69], 0, v[164:165]
	global_load_lds_dwordx4 v[78:79], off
	s_mov_b32 m0, s74
	s_nop 0
	global_load_lds_dwordx4 v[230:231], off
	s_mov_b32 m0, s75
	s_nop 0
	global_load_lds_dwordx4 v[232:233], off
	s_waitcnt vmcnt(8)
	s_waitcnt lgkmcnt(0)
	s_setprio 1
	s_barrier
	v_mfma_f32_16x16x32_bf16 v[60:63], v[88:91], v[194:197], 0
	v_mfma_f32_16x16x32_bf16 v[56:59], v[128:131], v[194:197], 0
	v_mfma_f32_16x16x32_bf16 v[44:47], v[88:91], v[202:205], 0
	v_mfma_f32_16x16x32_bf16 v[40:43], v[128:131], v[202:205], 0
	v_mfma_f32_16x16x32_bf16 v[28:31], v[88:91], v[210:213], 0
	v_mfma_f32_16x16x32_bf16 v[24:27], v[128:131], v[210:213], 0
	v_mfma_f32_16x16x32_bf16 v[12:15], v[88:91], v[218:221], 0
	v_mfma_f32_16x16x32_bf16 v[8:11], v[128:131], v[218:221], 0
	v_mfma_f32_16x16x32_bf16 v[60:63], v[108:111], v[198:201], v[60:63]
	v_mfma_f32_16x16x32_bf16 v[56:59], v[144:147], v[198:201], v[56:59]
	v_mfma_f32_16x16x32_bf16 v[44:47], v[108:111], v[206:209], v[44:47]
	v_mfma_f32_16x16x32_bf16 v[40:43], v[144:147], v[206:209], v[40:43]
	v_mfma_f32_16x16x32_bf16 v[28:31], v[108:111], v[214:217], v[28:31]
	v_mfma_f32_16x16x32_bf16 v[24:27], v[144:147], v[214:217], v[24:27]
	v_mfma_f32_16x16x32_bf16 v[12:15], v[108:111], v[222:225], v[12:15]
	v_mfma_f32_16x16x32_bf16 v[8:11], v[144:147], v[222:225], v[8:11]
	s_setprio 0
	s_setprio 1
	v_mfma_f32_16x16x32_bf16 v[52:55], v[148:151], v[194:197], 0
	v_mfma_f32_16x16x32_bf16 v[48:51], v[176:179], v[194:197], 0
	v_mfma_f32_16x16x32_bf16 v[36:39], v[148:151], v[202:205], 0
	v_mfma_f32_16x16x32_bf16 v[32:35], v[176:179], v[202:205], 0
	v_mfma_f32_16x16x32_bf16 v[20:23], v[148:151], v[210:213], 0
	v_mfma_f32_16x16x32_bf16 v[16:19], v[176:179], v[210:213], 0
	v_mfma_f32_16x16x32_bf16 v[4:7], v[148:151], v[218:221], 0
	v_mfma_f32_16x16x32_bf16 v[0:3], v[176:179], v[218:221], 0
	v_mfma_f32_16x16x32_bf16 v[52:55], v[152:155], v[198:201], v[52:55]
	v_mfma_f32_16x16x32_bf16 v[48:51], v[190:193], v[198:201], v[48:51]
	v_mfma_f32_16x16x32_bf16 v[36:39], v[152:155], v[206:209], v[36:39]
	v_mfma_f32_16x16x32_bf16 v[32:35], v[190:193], v[206:209], v[32:35]
	v_mfma_f32_16x16x32_bf16 v[20:23], v[152:155], v[214:217], v[20:23]
	v_mfma_f32_16x16x32_bf16 v[16:19], v[190:193], v[214:217], v[16:19]
	v_mfma_f32_16x16x32_bf16 v[4:7], v[152:155], v[222:225], v[4:7]
	v_mfma_f32_16x16x32_bf16 v[0:3], v[190:193], v[222:225], v[0:3]
	s_barrier
	s_setprio 0
	s_add_i32 s96, 0, 0x18000
	v_add_u32_e32 v78, s96, v181
	s_add_i32 s97, 0, 0x1c000
	ds_read_b128 v[88:91], v78
	v_xor_b32_e32 v253, 64, v78
	ds_read_b128 v[108:111], v253
	ds_read_b128 v[128:131], v78 offset:2048
	ds_read_b128 v[144:147], v253 offset:2048
	v_add_u32_e32 v78, s97, v181
	ds_read_b128 v[148:151], v78
	v_xor_b32_e32 v253, 64, v78
	ds_read_b128 v[152:155], v253
	ds_read_b128 v[176:179], v78 offset:2048
	ds_read_b128 v[190:193], v253 offset:2048
	s_add_u32 s68, s68, 0x40000
	s_addc_u32 s69, s69, 0
	s_mov_b32 m0, s76
	v_lshl_add_u64 v[78:79], s[68:69], 0, v[160:161]
	ds_read_b128 v[194:197], v187 offset:32768
	v_xor_b32_e32 v253, 64, v187
	ds_read_b128 v[198:201], v253 offset:32768
	ds_read_b128 v[202:205], v187 offset:34816
	ds_read_b128 v[206:209], v253 offset:34816
	ds_read_b128 v[210:213], v187 offset:36864
	ds_read_b128 v[214:217], v253 offset:36864
	ds_read_b128 v[218:221], v187 offset:38912
	ds_read_b128 v[222:225], v253 offset:38912
	global_load_lds_dwordx4 v[78:79], off
	v_lshl_add_u64 v[78:79], s[68:69], 0, v[164:165]
	s_mov_b32 m0, s77
	s_nop 0
	global_load_lds_dwordx4 v[78:79], off
	s_waitcnt vmcnt(8)
	s_waitcnt lgkmcnt(0)
	s_setprio 1
	s_barrier
	v_mfma_f32_16x16x32_bf16 v[140:143], v[88:91], v[194:197], v[140:143]
	v_mfma_f32_16x16x32_bf16 v[136:139], v[128:131], v[194:197], v[136:139]
	v_mfma_f32_16x16x32_bf16 v[120:123], v[88:91], v[202:205], v[120:123]
	v_mfma_f32_16x16x32_bf16 v[116:119], v[128:131], v[202:205], v[116:119]
	v_mfma_f32_16x16x32_bf16 v[100:103], v[88:91], v[210:213], v[100:103]
	v_mfma_f32_16x16x32_bf16 v[96:99], v[128:131], v[210:213], v[96:99]
	v_mfma_f32_16x16x32_bf16 v[78:81], v[88:91], v[218:221], v[80:83]
	v_mfma_f32_16x16x32_bf16 v[74:77], v[128:131], v[218:221], v[74:77]
	v_mfma_f32_16x16x32_bf16 v[140:143], v[108:111], v[198:201], v[140:143]
	v_mfma_f32_16x16x32_bf16 v[136:139], v[144:147], v[198:201], v[136:139]
	v_mfma_f32_16x16x32_bf16 v[120:123], v[108:111], v[206:209], v[120:123]
	v_mfma_f32_16x16x32_bf16 v[116:119], v[144:147], v[206:209], v[116:119]
	v_mfma_f32_16x16x32_bf16 v[100:103], v[108:111], v[214:217], v[100:103]
	v_mfma_f32_16x16x32_bf16 v[96:99], v[144:147], v[214:217], v[96:99]
	v_mfma_f32_16x16x32_bf16 v[80:83], v[108:111], v[222:225], v[78:81]
	v_mfma_f32_16x16x32_bf16 v[76:79], v[144:147], v[222:225], v[74:77]
	s_setprio 0
	s_setprio 1
	v_mfma_f32_16x16x32_bf16 v[132:135], v[148:151], v[194:197], v[132:135]
	v_mfma_f32_16x16x32_bf16 v[124:127], v[176:179], v[194:197], v[124:127]
	v_mfma_f32_16x16x32_bf16 v[112:115], v[148:151], v[202:205], v[112:115]
	v_mfma_f32_16x16x32_bf16 v[104:107], v[176:179], v[202:205], v[104:107]
	v_mfma_f32_16x16x32_bf16 v[92:95], v[148:151], v[210:213], v[92:95]
	v_mfma_f32_16x16x32_bf16 v[84:87], v[176:179], v[210:213], v[84:87]
	v_mfma_f32_16x16x32_bf16 v[68:71], v[148:151], v[218:221], v[68:71]
	v_mfma_f32_16x16x32_bf16 v[64:67], v[176:179], v[218:221], v[64:67]
	v_mfma_f32_16x16x32_bf16 v[132:135], v[152:155], v[198:201], v[132:135]
	v_mfma_f32_16x16x32_bf16 v[124:127], v[190:193], v[198:201], v[124:127]
	v_mfma_f32_16x16x32_bf16 v[112:115], v[152:155], v[206:209], v[112:115]
	v_mfma_f32_16x16x32_bf16 v[104:107], v[190:193], v[206:209], v[104:107]
	v_mfma_f32_16x16x32_bf16 v[92:95], v[152:155], v[214:217], v[92:95]
	v_mfma_f32_16x16x32_bf16 v[84:87], v[190:193], v[214:217], v[84:87]
	v_mfma_f32_16x16x32_bf16 v[68:71], v[152:155], v[222:225], v[68:71]
	v_mfma_f32_16x16x32_bf16 v[64:67], v[190:193], v[222:225], v[64:67]
	s_barrier
	s_setprio 0
	s_add_i32 s68, s96, s71
	v_lshl_add_u64 v[74:75], v[226:227], 0, s[28:29]
	s_mov_b32 m0, s68
	ds_read_b128 v[194:197], v187 offset:49152
	v_xor_b32_e32 v253, 64, v187
	ds_read_b128 v[198:201], v253 offset:49152
	ds_read_b128 v[202:205], v187 offset:51200
	ds_read_b128 v[206:209], v253 offset:51200
	ds_read_b128 v[210:213], v187 offset:53248
	ds_read_b128 v[214:217], v253 offset:53248
	ds_read_b128 v[218:221], v187 offset:55296
	ds_read_b128 v[222:225], v253 offset:55296
	global_load_lds_dwordx4 v[74:75], off
	s_add_i32 m0, s68, 0x2000
	s_add_u32 s66, s66, 0x40080
	v_lshl_add_u64 v[74:75], v[228:229], 0, s[28:29]
	s_addc_u32 s67, s67, 0
	s_add_i32 s68, s97, s71
	global_load_lds_dwordx4 v[74:75], off
	v_lshl_add_u64 v[74:75], s[66:67], 0, v[162:163]
	s_mov_b32 m0, s68
	s_nop 0
	global_load_lds_dwordx4 v[74:75], off
	v_lshl_add_u64 v[74:75], s[66:67], 0, v[166:167]
	s_add_i32 m0, s68, 0x2000
	s_nop 0
	global_load_lds_dwordx4 v[74:75], off
	v_lshl_add_u64 v[74:75], v[230:231], 0, s[28:29]
	s_mov_b32 m0, s78
	s_nop 0
	global_load_lds_dwordx4 v[74:75], off
	v_lshl_add_u64 v[74:75], v[232:233], 0, s[28:29]
	s_mov_b32 m0, s79
	s_nop 0
	global_load_lds_dwordx4 v[74:75], off
	s_waitcnt vmcnt(8)
	s_waitcnt lgkmcnt(0)
	s_setprio 1
	s_barrier
	v_mfma_f32_16x16x32_bf16 v[60:63], v[88:91], v[194:197], v[60:63]
	v_mfma_f32_16x16x32_bf16 v[60:63], v[108:111], v[198:201], v[60:63]
	v_mfma_f32_16x16x32_bf16 v[44:47], v[108:111], v[206:209], v[44:47]
	v_mfma_f32_16x16x32_bf16 v[44:47], v[88:91], v[202:205], v[44:47]
	v_mfma_f32_16x16x32_bf16 v[28:31], v[88:91], v[210:213], v[28:31]
	v_mfma_f32_16x16x32_bf16 v[28:31], v[108:111], v[214:217], v[28:31]
	v_mfma_f32_16x16x32_bf16 v[12:15], v[108:111], v[222:225], v[12:15]
	v_mfma_f32_16x16x32_bf16 v[12:15], v[88:91], v[218:221], v[12:15]
	v_mfma_f32_16x16x32_bf16 v[8:11], v[128:131], v[218:221], v[8:11]
	v_mfma_f32_16x16x32_bf16 v[8:11], v[144:147], v[222:225], v[8:11]
	v_mfma_f32_16x16x32_bf16 v[24:27], v[144:147], v[214:217], v[24:27]
	v_mfma_f32_16x16x32_bf16 v[24:27], v[128:131], v[210:213], v[24:27]
	v_mfma_f32_16x16x32_bf16 v[40:43], v[128:131], v[202:205], v[40:43]
	v_mfma_f32_16x16x32_bf16 v[40:43], v[144:147], v[206:209], v[40:43]
	v_mfma_f32_16x16x32_bf16 v[56:59], v[144:147], v[198:201], v[56:59]
	v_mfma_f32_16x16x32_bf16 v[56:59], v[128:131], v[194:197], v[56:59]
	s_setprio 0
	s_setprio 1
	v_mfma_f32_16x16x32_bf16 v[48:51], v[176:179], v[194:197], v[48:51]
	v_mfma_f32_16x16x32_bf16 v[48:51], v[190:193], v[198:201], v[48:51]
	v_mfma_f32_16x16x32_bf16 v[32:35], v[190:193], v[206:209], v[32:35]
	v_mfma_f32_16x16x32_bf16 v[32:35], v[176:179], v[202:205], v[32:35]
	v_mfma_f32_16x16x32_bf16 v[16:19], v[176:179], v[210:213], v[16:19]
	v_mfma_f32_16x16x32_bf16 v[16:19], v[190:193], v[214:217], v[16:19]
	v_mfma_f32_16x16x32_bf16 v[0:3], v[190:193], v[222:225], v[0:3]
	v_mfma_f32_16x16x32_bf16 v[0:3], v[176:179], v[218:221], v[0:3]
	v_mfma_f32_16x16x32_bf16 v[4:7], v[148:151], v[218:221], v[4:7]
	v_mfma_f32_16x16x32_bf16 v[4:7], v[152:155], v[222:225], v[4:7]
	v_mfma_f32_16x16x32_bf16 v[20:23], v[152:155], v[214:217], v[20:23]
	v_mfma_f32_16x16x32_bf16 v[20:23], v[148:151], v[210:213], v[20:23]
	v_mfma_f32_16x16x32_bf16 v[36:39], v[148:151], v[202:205], v[36:39]
	v_mfma_f32_16x16x32_bf16 v[36:39], v[152:155], v[206:209], v[36:39]
	v_mfma_f32_16x16x32_bf16 v[52:55], v[152:155], v[198:201], v[52:55]
	v_mfma_f32_16x16x32_bf16 v[52:55], v[148:151], v[194:197], v[52:55]
	s_barrier
	s_setprio 0
	s_add_i32 s95, s95, 2
	s_add_u32 s93, s93, 0x100
	s_addc_u32 s94, s94, 0
	s_add_u32 s14, s14, 0x100
	s_addc_u32 s15, s15, 0
	s_branch .LBB0_256
.LBB0_255:
	v_add_u32_e32 v74, s83, v181
	ds_read_b128 v[88:91], v74
	v_xor_b32_e32 v253, 64, v74
	ds_read_b128 v[108:111], v253
	ds_read_b128 v[128:131], v74 offset:2048
	ds_read_b128 v[144:147], v253 offset:2048
	v_add_u32_e32 v74, s84, v181
	ds_read_b128 v[148:151], v74
	v_xor_b32_e32 v253, 64, v74
	ds_read_b128 v[152:155], v253
	ds_read_b128 v[176:179], v74 offset:2048
	ds_read_b128 v[190:193], v253 offset:2048
	s_add_u32 s68, s14, 0xfffc0080
	s_addc_u32 s69, s15, -1
	s_and_b64 s[66:67], s[66:67], exec
	s_cselect_b32 s69, s3, s69
	s_cselect_b32 s68, s61, s68
	s_cselect_b32 s67, s91, s94
	s_cselect_b32 s66, s92, s93
	v_lshl_add_u64 v[74:75], s[14:15], 0, v[170:171]
	s_add_i32 m0, s74, 0xc000
	ds_read_b128 v[194:197], v187
	v_xor_b32_e32 v253, 64, v187
	ds_read_b128 v[198:201], v253
	ds_read_b128 v[202:205], v187 offset:2048
	ds_read_b128 v[206:209], v253 offset:2048
	ds_read_b128 v[210:213], v187 offset:4096
	ds_read_b128 v[214:217], v253 offset:4096
	ds_read_b128 v[218:221], v187 offset:6144
	ds_read_b128 v[222:225], v253 offset:6144
	global_load_lds_dwordx4 v[74:75], off
	v_lshl_add_u64 v[74:75], s[14:15], 0, v[168:169]
	s_add_i32 m0, s74, 0xe000
	s_nop 0
	global_load_lds_dwordx4 v[74:75], off
	s_waitcnt vmcnt(8)
	s_waitcnt lgkmcnt(0)
	s_setprio 1
	s_barrier
	v_mfma_f32_16x16x32_bf16 v[140:143], v[88:91], v[194:197], v[140:143]
	v_mfma_f32_16x16x32_bf16 v[136:139], v[128:131], v[194:197], v[136:139]
	v_mfma_f32_16x16x32_bf16 v[120:123], v[88:91], v[202:205], v[120:123]
	v_mfma_f32_16x16x32_bf16 v[116:119], v[128:131], v[202:205], v[116:119]
	v_mfma_f32_16x16x32_bf16 v[100:103], v[88:91], v[210:213], v[100:103]
	v_mfma_f32_16x16x32_bf16 v[96:99], v[128:131], v[210:213], v[96:99]
	v_mfma_f32_16x16x32_bf16 v[80:83], v[88:91], v[218:221], v[80:83]
	v_mfma_f32_16x16x32_bf16 v[74:77], v[128:131], v[218:221], v[76:79]
	v_mfma_f32_16x16x32_bf16 v[140:143], v[108:111], v[198:201], v[140:143]
	v_mfma_f32_16x16x32_bf16 v[136:139], v[144:147], v[198:201], v[136:139]
	v_mfma_f32_16x16x32_bf16 v[120:123], v[108:111], v[206:209], v[120:123]
	v_mfma_f32_16x16x32_bf16 v[116:119], v[144:147], v[206:209], v[116:119]
	v_mfma_f32_16x16x32_bf16 v[100:103], v[108:111], v[214:217], v[100:103]
	v_mfma_f32_16x16x32_bf16 v[96:99], v[144:147], v[214:217], v[96:99]
	v_mfma_f32_16x16x32_bf16 v[80:83], v[108:111], v[222:225], v[80:83]
	v_mfma_f32_16x16x32_bf16 v[74:77], v[144:147], v[222:225], v[74:77]
	s_setprio 0
	s_setprio 1
	v_mfma_f32_16x16x32_bf16 v[132:135], v[148:151], v[194:197], v[132:135]
	v_mfma_f32_16x16x32_bf16 v[124:127], v[176:179], v[194:197], v[124:127]
	v_mfma_f32_16x16x32_bf16 v[112:115], v[148:151], v[202:205], v[112:115]
	v_mfma_f32_16x16x32_bf16 v[104:107], v[176:179], v[202:205], v[104:107]
	v_mfma_f32_16x16x32_bf16 v[92:95], v[148:151], v[210:213], v[92:95]
	v_mfma_f32_16x16x32_bf16 v[84:87], v[176:179], v[210:213], v[84:87]
	v_mfma_f32_16x16x32_bf16 v[68:71], v[148:151], v[218:221], v[68:71]
	v_mfma_f32_16x16x32_bf16 v[64:67], v[176:179], v[218:221], v[64:67]
	v_mfma_f32_16x16x32_bf16 v[132:135], v[152:155], v[198:201], v[132:135]
	v_mfma_f32_16x16x32_bf16 v[124:127], v[190:193], v[198:201], v[124:127]
	v_mfma_f32_16x16x32_bf16 v[112:115], v[152:155], v[206:209], v[112:115]
	v_mfma_f32_16x16x32_bf16 v[104:107], v[190:193], v[206:209], v[104:107]
	v_mfma_f32_16x16x32_bf16 v[92:95], v[152:155], v[214:217], v[92:95]
	v_mfma_f32_16x16x32_bf16 v[84:87], v[190:193], v[214:217], v[84:87]
	v_mfma_f32_16x16x32_bf16 v[68:71], v[152:155], v[222:225], v[68:71]
	v_mfma_f32_16x16x32_bf16 v[64:67], v[190:193], v[222:225], v[64:67]
	s_barrier
	s_setprio 0
	s_add_i32 s96, s83, s71
	v_lshl_add_u64 v[226:227], s[66:67], 0, v[162:163]
	s_mov_b32 m0, s96
	ds_read_b128 v[194:197], v187 offset:16384
	v_xor_b32_e32 v253, 64, v187
	ds_read_b128 v[198:201], v253 offset:16384
	ds_read_b128 v[202:205], v187 offset:18432
	ds_read_b128 v[206:209], v253 offset:18432
	ds_read_b128 v[210:213], v187 offset:20480
	ds_read_b128 v[214:217], v253 offset:20480
	ds_read_b128 v[218:221], v187 offset:22528
	ds_read_b128 v[222:225], v253 offset:22528
	global_load_lds_dwordx4 v[226:227], off
	s_add_i32 m0, s96, 0x2000
	s_add_u32 s96, s66, 0x40000
	v_lshl_add_u64 v[228:229], s[66:67], 0, v[166:167]
	s_addc_u32 s97, s67, 0
	s_add_i32 vcc_lo, s84, s71
	global_load_lds_dwordx4 v[228:229], off
	v_lshl_add_u64 v[78:79], s[96:97], 0, v[162:163]
	s_mov_b32 m0, vcc_lo
	v_lshl_add_u64 v[230:231], s[68:69], 0, v[160:161]
	global_load_lds_dwordx4 v[78:79], off
	v_lshl_add_u64 v[78:79], s[96:97], 0, v[166:167]
	s_add_i32 m0, vcc_lo, 0x2000
	v_lshl_add_u64 v[232:233], s[68:69], 0, v[164:165]
	global_load_lds_dwordx4 v[78:79], off
	s_mov_b32 m0, s74
	s_nop 0
	global_load_lds_dwordx4 v[230:231], off
	s_mov_b32 m0, s75
	s_nop 0
	global_load_lds_dwordx4 v[232:233], off
	s_waitcnt vmcnt(8)
	s_waitcnt lgkmcnt(0)
	s_setprio 1
	s_barrier
	v_mfma_f32_16x16x32_bf16 v[60:63], v[88:91], v[194:197], v[60:63]
	v_mfma_f32_16x16x32_bf16 v[60:63], v[108:111], v[198:201], v[60:63]
	v_mfma_f32_16x16x32_bf16 v[44:47], v[108:111], v[206:209], v[44:47]
	v_mfma_f32_16x16x32_bf16 v[44:47], v[88:91], v[202:205], v[44:47]
	v_mfma_f32_16x16x32_bf16 v[28:31], v[88:91], v[210:213], v[28:31]
	v_mfma_f32_16x16x32_bf16 v[28:31], v[108:111], v[214:217], v[28:31]
	v_mfma_f32_16x16x32_bf16 v[12:15], v[108:111], v[222:225], v[12:15]
	v_mfma_f32_16x16x32_bf16 v[12:15], v[88:91], v[218:221], v[12:15]
	v_mfma_f32_16x16x32_bf16 v[8:11], v[128:131], v[218:221], v[8:11]
	v_mfma_f32_16x16x32_bf16 v[8:11], v[144:147], v[222:225], v[8:11]
	v_mfma_f32_16x16x32_bf16 v[24:27], v[144:147], v[214:217], v[24:27]
	v_mfma_f32_16x16x32_bf16 v[24:27], v[128:131], v[210:213], v[24:27]
	v_mfma_f32_16x16x32_bf16 v[40:43], v[128:131], v[202:205], v[40:43]
	v_mfma_f32_16x16x32_bf16 v[40:43], v[144:147], v[206:209], v[40:43]
	v_mfma_f32_16x16x32_bf16 v[56:59], v[144:147], v[198:201], v[56:59]
	v_mfma_f32_16x16x32_bf16 v[56:59], v[128:131], v[194:197], v[56:59]
	s_setprio 0
	s_setprio 1
	v_mfma_f32_16x16x32_bf16 v[48:51], v[176:179], v[194:197], v[48:51]
	v_mfma_f32_16x16x32_bf16 v[48:51], v[190:193], v[198:201], v[48:51]
	v_mfma_f32_16x16x32_bf16 v[32:35], v[190:193], v[206:209], v[32:35]
	v_mfma_f32_16x16x32_bf16 v[32:35], v[176:179], v[202:205], v[32:35]
	v_mfma_f32_16x16x32_bf16 v[16:19], v[176:179], v[210:213], v[16:19]
	v_mfma_f32_16x16x32_bf16 v[16:19], v[190:193], v[214:217], v[16:19]
	v_mfma_f32_16x16x32_bf16 v[0:3], v[190:193], v[222:225], v[0:3]
	v_mfma_f32_16x16x32_bf16 v[0:3], v[176:179], v[218:221], v[0:3]
	v_mfma_f32_16x16x32_bf16 v[4:7], v[148:151], v[218:221], v[4:7]
	v_mfma_f32_16x16x32_bf16 v[4:7], v[152:155], v[222:225], v[4:7]
	v_mfma_f32_16x16x32_bf16 v[20:23], v[152:155], v[214:217], v[20:23]
	v_mfma_f32_16x16x32_bf16 v[20:23], v[148:151], v[210:213], v[20:23]
	v_mfma_f32_16x16x32_bf16 v[36:39], v[148:151], v[202:205], v[36:39]
	v_mfma_f32_16x16x32_bf16 v[36:39], v[152:155], v[206:209], v[36:39]
	v_mfma_f32_16x16x32_bf16 v[52:55], v[152:155], v[198:201], v[52:55]
	v_mfma_f32_16x16x32_bf16 v[52:55], v[148:151], v[194:197], v[52:55]
	s_barrier
	s_setprio 0
	s_add_i32 s96, 0, 0x18000
	v_add_u32_e32 v78, s96, v181
	s_add_i32 s97, 0, 0x1c000
	ds_read_b128 v[88:91], v78
	v_xor_b32_e32 v253, 64, v78
	ds_read_b128 v[108:111], v253
	ds_read_b128 v[128:131], v78 offset:2048
	ds_read_b128 v[144:147], v253 offset:2048
	v_add_u32_e32 v78, s97, v181
	ds_read_b128 v[148:151], v78
	v_xor_b32_e32 v253, 64, v78
	ds_read_b128 v[152:155], v253
	ds_read_b128 v[176:179], v78 offset:2048
	ds_read_b128 v[190:193], v253 offset:2048
	s_add_u32 s68, s68, 0x40000
	s_addc_u32 s69, s69, 0
	s_mov_b32 m0, s76
	v_lshl_add_u64 v[78:79], s[68:69], 0, v[160:161]
	ds_read_b128 v[194:197], v187 offset:32768
	v_xor_b32_e32 v253, 64, v187
	ds_read_b128 v[198:201], v253 offset:32768
	ds_read_b128 v[202:205], v187 offset:34816
	ds_read_b128 v[206:209], v253 offset:34816
	ds_read_b128 v[210:213], v187 offset:36864
	ds_read_b128 v[214:217], v253 offset:36864
	ds_read_b128 v[218:221], v187 offset:38912
	ds_read_b128 v[222:225], v253 offset:38912
	global_load_lds_dwordx4 v[78:79], off
	v_lshl_add_u64 v[78:79], s[68:69], 0, v[164:165]
	s_mov_b32 m0, s77
	s_nop 0
	global_load_lds_dwordx4 v[78:79], off
	s_waitcnt vmcnt(8)
	s_waitcnt lgkmcnt(0)
	s_setprio 1
	s_barrier
	v_mfma_f32_16x16x32_bf16 v[140:143], v[88:91], v[194:197], v[140:143]
	v_mfma_f32_16x16x32_bf16 v[136:139], v[128:131], v[194:197], v[136:139]
	v_mfma_f32_16x16x32_bf16 v[120:123], v[88:91], v[202:205], v[120:123]
	v_mfma_f32_16x16x32_bf16 v[116:119], v[128:131], v[202:205], v[116:119]
	v_mfma_f32_16x16x32_bf16 v[100:103], v[88:91], v[210:213], v[100:103]
	v_mfma_f32_16x16x32_bf16 v[96:99], v[128:131], v[210:213], v[96:99]
	v_mfma_f32_16x16x32_bf16 v[78:81], v[88:91], v[218:221], v[80:83]
	v_mfma_f32_16x16x32_bf16 v[74:77], v[128:131], v[218:221], v[74:77]
	v_mfma_f32_16x16x32_bf16 v[140:143], v[108:111], v[198:201], v[140:143]
	v_mfma_f32_16x16x32_bf16 v[136:139], v[144:147], v[198:201], v[136:139]
	v_mfma_f32_16x16x32_bf16 v[120:123], v[108:111], v[206:209], v[120:123]
	v_mfma_f32_16x16x32_bf16 v[116:119], v[144:147], v[206:209], v[116:119]
	v_mfma_f32_16x16x32_bf16 v[100:103], v[108:111], v[214:217], v[100:103]
	v_mfma_f32_16x16x32_bf16 v[96:99], v[144:147], v[214:217], v[96:99]
	v_mfma_f32_16x16x32_bf16 v[80:83], v[108:111], v[222:225], v[78:81]
	v_mfma_f32_16x16x32_bf16 v[76:79], v[144:147], v[222:225], v[74:77]
	s_setprio 0
	s_setprio 1
	v_mfma_f32_16x16x32_bf16 v[132:135], v[148:151], v[194:197], v[132:135]
	v_mfma_f32_16x16x32_bf16 v[124:127], v[176:179], v[194:197], v[124:127]
	v_mfma_f32_16x16x32_bf16 v[112:115], v[148:151], v[202:205], v[112:115]
	v_mfma_f32_16x16x32_bf16 v[104:107], v[176:179], v[202:205], v[104:107]
	v_mfma_f32_16x16x32_bf16 v[92:95], v[148:151], v[210:213], v[92:95]
	v_mfma_f32_16x16x32_bf16 v[84:87], v[176:179], v[210:213], v[84:87]
	v_mfma_f32_16x16x32_bf16 v[68:71], v[148:151], v[218:221], v[68:71]
	v_mfma_f32_16x16x32_bf16 v[64:67], v[176:179], v[218:221], v[64:67]
	v_mfma_f32_16x16x32_bf16 v[132:135], v[152:155], v[198:201], v[132:135]
	v_mfma_f32_16x16x32_bf16 v[124:127], v[190:193], v[198:201], v[124:127]
	v_mfma_f32_16x16x32_bf16 v[112:115], v[152:155], v[206:209], v[112:115]
	v_mfma_f32_16x16x32_bf16 v[104:107], v[190:193], v[206:209], v[104:107]
	v_mfma_f32_16x16x32_bf16 v[92:95], v[152:155], v[214:217], v[92:95]
	v_mfma_f32_16x16x32_bf16 v[84:87], v[190:193], v[214:217], v[84:87]
	v_mfma_f32_16x16x32_bf16 v[68:71], v[152:155], v[222:225], v[68:71]
	v_mfma_f32_16x16x32_bf16 v[64:67], v[190:193], v[222:225], v[64:67]
	s_barrier
	s_setprio 0
	s_add_i32 s68, s96, s71
	v_lshl_add_u64 v[74:75], v[226:227], 0, s[28:29]
	s_mov_b32 m0, s68
	ds_read_b128 v[194:197], v187 offset:49152
	v_xor_b32_e32 v253, 64, v187
	ds_read_b128 v[198:201], v253 offset:49152
	ds_read_b128 v[202:205], v187 offset:51200
	ds_read_b128 v[206:209], v253 offset:51200
	ds_read_b128 v[210:213], v187 offset:53248
	ds_read_b128 v[214:217], v253 offset:53248
	ds_read_b128 v[218:221], v187 offset:55296
	ds_read_b128 v[222:225], v253 offset:55296
	global_load_lds_dwordx4 v[74:75], off
	s_add_i32 m0, s68, 0x2000
	s_add_u32 s66, s66, 0x40080
	v_lshl_add_u64 v[74:75], v[228:229], 0, s[28:29]
	s_addc_u32 s67, s67, 0
	s_add_i32 s68, s97, s71
	global_load_lds_dwordx4 v[74:75], off
	v_lshl_add_u64 v[74:75], s[66:67], 0, v[162:163]
	s_mov_b32 m0, s68
	s_nop 0
	global_load_lds_dwordx4 v[74:75], off
	v_lshl_add_u64 v[74:75], s[66:67], 0, v[166:167]
	s_add_i32 m0, s68, 0x2000
	s_nop 0
	global_load_lds_dwordx4 v[74:75], off
	v_lshl_add_u64 v[74:75], v[230:231], 0, s[28:29]
	s_mov_b32 m0, s78
	s_nop 0
	global_load_lds_dwordx4 v[74:75], off
	v_lshl_add_u64 v[74:75], v[232:233], 0, s[28:29]
	s_mov_b32 m0, s79
	s_nop 0
	global_load_lds_dwordx4 v[74:75], off
	s_waitcnt vmcnt(8)
	s_waitcnt lgkmcnt(0)
	s_setprio 1
	s_barrier
	v_mfma_f32_16x16x32_bf16 v[60:63], v[88:91], v[194:197], v[60:63]
	v_mfma_f32_16x16x32_bf16 v[60:63], v[108:111], v[198:201], v[60:63]
	v_mfma_f32_16x16x32_bf16 v[44:47], v[108:111], v[206:209], v[44:47]
	v_mfma_f32_16x16x32_bf16 v[44:47], v[88:91], v[202:205], v[44:47]
	v_mfma_f32_16x16x32_bf16 v[28:31], v[88:91], v[210:213], v[28:31]
	v_mfma_f32_16x16x32_bf16 v[28:31], v[108:111], v[214:217], v[28:31]
	v_mfma_f32_16x16x32_bf16 v[12:15], v[108:111], v[222:225], v[12:15]
	v_mfma_f32_16x16x32_bf16 v[12:15], v[88:91], v[218:221], v[12:15]
	v_mfma_f32_16x16x32_bf16 v[8:11], v[128:131], v[218:221], v[8:11]
	v_mfma_f32_16x16x32_bf16 v[8:11], v[144:147], v[222:225], v[8:11]
	v_mfma_f32_16x16x32_bf16 v[24:27], v[144:147], v[214:217], v[24:27]
	v_mfma_f32_16x16x32_bf16 v[24:27], v[128:131], v[210:213], v[24:27]
	v_mfma_f32_16x16x32_bf16 v[40:43], v[128:131], v[202:205], v[40:43]
	v_mfma_f32_16x16x32_bf16 v[40:43], v[144:147], v[206:209], v[40:43]
	v_mfma_f32_16x16x32_bf16 v[56:59], v[144:147], v[198:201], v[56:59]
	v_mfma_f32_16x16x32_bf16 v[56:59], v[128:131], v[194:197], v[56:59]
	s_setprio 0
	s_setprio 1
	v_mfma_f32_16x16x32_bf16 v[48:51], v[176:179], v[194:197], v[48:51]
	v_mfma_f32_16x16x32_bf16 v[48:51], v[190:193], v[198:201], v[48:51]
	v_mfma_f32_16x16x32_bf16 v[32:35], v[190:193], v[206:209], v[32:35]
	v_mfma_f32_16x16x32_bf16 v[32:35], v[176:179], v[202:205], v[32:35]
	v_mfma_f32_16x16x32_bf16 v[16:19], v[176:179], v[210:213], v[16:19]
	v_mfma_f32_16x16x32_bf16 v[16:19], v[190:193], v[214:217], v[16:19]
	v_mfma_f32_16x16x32_bf16 v[0:3], v[190:193], v[222:225], v[0:3]
	v_mfma_f32_16x16x32_bf16 v[0:3], v[176:179], v[218:221], v[0:3]
	v_mfma_f32_16x16x32_bf16 v[4:7], v[148:151], v[218:221], v[4:7]
	v_mfma_f32_16x16x32_bf16 v[4:7], v[152:155], v[222:225], v[4:7]
	v_mfma_f32_16x16x32_bf16 v[20:23], v[152:155], v[214:217], v[20:23]
	v_mfma_f32_16x16x32_bf16 v[20:23], v[148:151], v[210:213], v[20:23]
	v_mfma_f32_16x16x32_bf16 v[36:39], v[148:151], v[202:205], v[36:39]
	v_mfma_f32_16x16x32_bf16 v[36:39], v[152:155], v[206:209], v[36:39]
	v_mfma_f32_16x16x32_bf16 v[52:55], v[152:155], v[198:201], v[52:55]
	v_mfma_f32_16x16x32_bf16 v[52:55], v[148:151], v[194:197], v[52:55]
	s_barrier
	s_setprio 0
	s_add_i32 s95, s95, 2
	s_add_u32 s93, s93, 0x100
	s_addc_u32 s94, s94, 0
	s_add_u32 s14, s14, 0x100
	s_addc_u32 s15, s15, 0
	s_cmp_gt_u32 s95, 13
	s_cbranch_scc1 .LBB0_258

.LBB0_439:
	s_ashr_i32 s53, s52, 31
	s_lshl_b64 s[54:55], s[52:53], 20
	s_add_u32 s54, s35, s54
	s_addc_u32 s55, s66, s55
	s_and_b64 s[56:57], s[12:13], exec
	s_cselect_b32 s15, s55, s63
	s_cselect_b32 s53, s54, s62
	s_ashr_i32 s51, s50, 31
	s_lshl_b64 s[56:57], s[50:51], 20
	s_add_u32 s56, s67, s56
	s_addc_u32 s57, s68, s57
	s_and_b64 s[64:65], s[12:13], exec
	s_cselect_b32 s51, s57, s61
	s_cselect_b32 s59, s56, s60
	s_add_u32 s81, s60, 0x100
	s_addc_u32 s82, s61, 0
	s_add_u32 s60, s62, 0x80080
	s_addc_u32 s61, s63, 0
	s_mov_b32 s83, -2
	s_waitcnt lgkmcnt(0)
	s_cmp_eq_u32 s74, 1
	s_cbranch_scc1 .Lfa_3
	ds_read_b128 v[128:131], v189
	v_xor_b32_e32 v253, 64, v189
	ds_read_b128 v[132:135], v253
	ds_read_b128 v[136:139], v189 offset:2048
	ds_read_b128 v[140:143], v253 offset:2048
	ds_read_b128 v[144:147], v190
	v_xor_b32_e32 v253, 64, v190
	ds_read_b128 v[148:151], v253
	ds_read_b128 v[172:175], v190 offset:2048
	ds_read_b128 v[176:179], v253 offset:2048
	s_add_u32 s62, s60, 0xfff80080
	s_addc_u32 s63, s61, -1
	s_cmp_eq_u32 s83, 28
	s_cselect_b32 s65, s15, s63
	s_cselect_b32 s64, s53, s62
	s_cselect_b32 s63, s51, s82
	s_cselect_b32 s62, s59, s81
	v_lshl_add_u64 v[222:223], s[60:61], 0, v[166:167]
	s_add_i32 m0, s70, 0xc000
	ds_read_b128 v[180:183], v191
	v_xor_b32_e32 v253, 64, v191
	ds_read_b128 v[194:197], v253
	ds_read_b128 v[198:201], v191 offset:2048
	ds_read_b128 v[202:205], v253 offset:2048
	ds_read_b128 v[206:209], v191 offset:4096
	ds_read_b128 v[210:213], v253 offset:4096
	ds_read_b128 v[214:217], v191 offset:6144
	ds_read_b128 v[218:221], v253 offset:6144
	global_load_lds_dwordx4 v[222:223], off
	v_lshl_add_u64 v[222:223], s[60:61], 0, v[164:165]
	s_add_i32 m0, s70, 0xe000
	s_nop 0
	global_load_lds_dwordx4 v[222:223], off
	s_waitcnt vmcnt(24)
	s_waitcnt lgkmcnt(0)
	s_setprio 1
	s_barrier
	v_mfma_f32_16x16x32_bf16 v[124:127], v[128:131], v[180:183], 0
	v_mfma_f32_16x16x32_bf16 v[120:123], v[136:139], v[180:183], 0
	v_mfma_f32_16x16x32_bf16 v[108:111], v[128:131], v[198:201], 0
	v_mfma_f32_16x16x32_bf16 v[104:107], v[136:139], v[198:201], 0
	v_mfma_f32_16x16x32_bf16 v[92:95], v[128:131], v[206:209], 0
	v_mfma_f32_16x16x32_bf16 v[88:91], v[136:139], v[206:209], 0
	v_mfma_f32_16x16x32_bf16 v[76:79], v[128:131], v[214:217], 0
	v_mfma_f32_16x16x32_bf16 v[72:75], v[136:139], v[214:217], 0
	v_mfma_f32_16x16x32_bf16 v[124:127], v[132:135], v[194:197], v[124:127]
	v_mfma_f32_16x16x32_bf16 v[120:123], v[140:143], v[194:197], v[120:123]
	v_mfma_f32_16x16x32_bf16 v[108:111], v[132:135], v[202:205], v[108:111]
	v_mfma_f32_16x16x32_bf16 v[104:107], v[140:143], v[202:205], v[104:107]
	v_mfma_f32_16x16x32_bf16 v[92:95], v[132:135], v[210:213], v[92:95]
	v_mfma_f32_16x16x32_bf16 v[88:91], v[140:143], v[210:213], v[88:91]
	v_mfma_f32_16x16x32_bf16 v[76:79], v[132:135], v[218:221], v[76:79]
	v_mfma_f32_16x16x32_bf16 v[72:75], v[140:143], v[218:221], v[72:75]
	s_setprio 0
	s_setprio 1
	v_mfma_f32_16x16x32_bf16 v[116:119], v[144:147], v[180:183], 0
	v_mfma_f32_16x16x32_bf16 v[112:115], v[172:175], v[180:183], 0
	v_mfma_f32_16x16x32_bf16 v[100:103], v[144:147], v[198:201], 0
	v_mfma_f32_16x16x32_bf16 v[96:99], v[172:175], v[198:201], 0
	v_mfma_f32_16x16x32_bf16 v[84:87], v[144:147], v[206:209], 0
	v_mfma_f32_16x16x32_bf16 v[80:83], v[172:175], v[206:209], 0
	v_mfma_f32_16x16x32_bf16 v[68:71], v[144:147], v[214:217], 0
	v_mfma_f32_16x16x32_bf16 v[64:67], v[172:175], v[214:217], 0
	v_mfma_f32_16x16x32_bf16 v[116:119], v[148:151], v[194:197], v[116:119]
	v_mfma_f32_16x16x32_bf16 v[112:115], v[176:179], v[194:197], v[112:115]
	v_mfma_f32_16x16x32_bf16 v[100:103], v[148:151], v[202:205], v[100:103]
	v_mfma_f32_16x16x32_bf16 v[96:99], v[176:179], v[202:205], v[96:99]
	v_mfma_f32_16x16x32_bf16 v[84:87], v[148:151], v[210:213], v[84:87]
	v_mfma_f32_16x16x32_bf16 v[80:83], v[176:179], v[210:213], v[80:83]
	v_mfma_f32_16x16x32_bf16 v[68:71], v[148:151], v[218:221], v[68:71]
	v_mfma_f32_16x16x32_bf16 v[64:67], v[176:179], v[218:221], v[64:67]
	s_barrier
	s_setprio 0
	s_add_i32 s84, s79, s69
	v_lshl_add_u64 v[222:223], s[62:63], 0, v[154:155]
	s_mov_b32 m0, s84
	ds_read_b128 v[180:183], v191 offset:16384
	v_xor_b32_e32 v253, 64, v191
	ds_read_b128 v[194:197], v253 offset:16384
	ds_read_b128 v[198:201], v191 offset:18432
	ds_read_b128 v[202:205], v253 offset:18432
	ds_read_b128 v[206:209], v191 offset:20480
	ds_read_b128 v[210:213], v253 offset:20480
	ds_read_b128 v[214:217], v191 offset:22528
	ds_read_b128 v[218:221], v253 offset:22528
	global_load_lds_dwordx4 v[222:223], off
	s_add_i32 m0, s84, 0x2000
	s_add_u32 s84, s62, 0x80000
	v_lshl_add_u64 v[224:225], s[62:63], 0, v[162:163]
	s_addc_u32 s85, s63, 0
	s_add_i32 s86, s80, s69
	global_load_lds_dwordx4 v[224:225], off
	v_lshl_add_u64 v[226:227], s[84:85], 0, v[154:155]
	s_mov_b32 m0, s86
	v_lshl_add_u64 v[228:229], s[64:65], 0, v[160:161]
	global_load_lds_dwordx4 v[226:227], off
	v_lshl_add_u64 v[226:227], s[84:85], 0, v[162:163]
	s_add_i32 m0, s86, 0x2000
	s_nop 0
	global_load_lds_dwordx4 v[226:227], off
	v_lshl_add_u64 v[226:227], s[64:65], 0, v[152:153]
	s_mov_b32 m0, s70
	s_nop 0
	global_load_lds_dwordx4 v[226:227], off
	s_mov_b32 m0, s71
	s_nop 0
	global_load_lds_dwordx4 v[228:229], off
	s_waitcnt vmcnt(24)
	s_waitcnt lgkmcnt(0)
	s_setprio 1
	s_barrier
	v_mfma_f32_16x16x32_bf16 v[60:63], v[128:131], v[180:183], 0
	v_mfma_f32_16x16x32_bf16 v[56:59], v[136:139], v[180:183], 0
	v_mfma_f32_16x16x32_bf16 v[44:47], v[128:131], v[198:201], 0
	v_mfma_f32_16x16x32_bf16 v[40:43], v[136:139], v[198:201], 0
	v_mfma_f32_16x16x32_bf16 v[28:31], v[128:131], v[206:209], 0
	v_mfma_f32_16x16x32_bf16 v[24:27], v[136:139], v[206:209], 0
	v_mfma_f32_16x16x32_bf16 v[12:15], v[128:131], v[214:217], 0
	v_mfma_f32_16x16x32_bf16 v[8:11], v[136:139], v[214:217], 0
	v_mfma_f32_16x16x32_bf16 v[60:63], v[132:135], v[194:197], v[60:63]
	v_mfma_f32_16x16x32_bf16 v[56:59], v[140:143], v[194:197], v[56:59]
	v_mfma_f32_16x16x32_bf16 v[44:47], v[132:135], v[202:205], v[44:47]
	v_mfma_f32_16x16x32_bf16 v[40:43], v[140:143], v[202:205], v[40:43]
	v_mfma_f32_16x16x32_bf16 v[28:31], v[132:135], v[210:213], v[28:31]
	v_mfma_f32_16x16x32_bf16 v[24:27], v[140:143], v[210:213], v[24:27]
	v_mfma_f32_16x16x32_bf16 v[12:15], v[132:135], v[218:221], v[12:15]
	v_mfma_f32_16x16x32_bf16 v[8:11], v[140:143], v[218:221], v[8:11]
	s_setprio 0
	s_setprio 1
	v_mfma_f32_16x16x32_bf16 v[52:55], v[144:147], v[180:183], 0
	v_mfma_f32_16x16x32_bf16 v[48:51], v[172:175], v[180:183], 0
	v_mfma_f32_16x16x32_bf16 v[36:39], v[144:147], v[198:201], 0
	v_mfma_f32_16x16x32_bf16 v[32:35], v[172:175], v[198:201], 0
	v_mfma_f32_16x16x32_bf16 v[20:23], v[144:147], v[206:209], 0
	v_mfma_f32_16x16x32_bf16 v[16:19], v[172:175], v[206:209], 0
	v_mfma_f32_16x16x32_bf16 v[4:7], v[144:147], v[214:217], 0
	v_mfma_f32_16x16x32_bf16 v[0:3], v[172:175], v[214:217], 0
	v_mfma_f32_16x16x32_bf16 v[52:55], v[148:151], v[194:197], v[52:55]
	v_mfma_f32_16x16x32_bf16 v[48:51], v[176:179], v[194:197], v[48:51]
	v_mfma_f32_16x16x32_bf16 v[36:39], v[148:151], v[202:205], v[36:39]
	v_mfma_f32_16x16x32_bf16 v[32:35], v[176:179], v[202:205], v[32:35]
	v_mfma_f32_16x16x32_bf16 v[20:23], v[148:151], v[210:213], v[20:23]
	v_mfma_f32_16x16x32_bf16 v[16:19], v[176:179], v[210:213], v[16:19]
	v_mfma_f32_16x16x32_bf16 v[4:7], v[148:151], v[218:221], v[4:7]
	v_mfma_f32_16x16x32_bf16 v[0:3], v[176:179], v[218:221], v[0:3]
	s_barrier
	s_setprio 0
	s_add_i32 s84, 0, 0x18000
	s_add_i32 s85, 0, 0x1c000
	v_add_u32_e32 v140, s84, v186
	v_add_u32_e32 v176, s85, v186
	ds_read_b128 v[128:131], v140
	v_xor_b32_e32 v253, 64, v140
	ds_read_b128 v[132:135], v253
	ds_read_b128 v[136:139], v140 offset:2048
	ds_read_b128 v[140:143], v253 offset:2048
	ds_read_b128 v[144:147], v176
	v_xor_b32_e32 v253, 64, v176
	ds_read_b128 v[148:151], v253
	ds_read_b128 v[172:175], v176 offset:2048
	ds_read_b128 v[176:179], v253 offset:2048
	s_add_u32 s64, s64, 0x80000
	s_addc_u32 s65, s65, 0
	s_mov_b32 m0, s72
	v_lshl_add_u64 v[230:231], s[64:65], 0, v[152:153]
	ds_read_b128 v[180:183], v191 offset:32768
	v_xor_b32_e32 v253, 64, v191
	ds_read_b128 v[194:197], v253 offset:32768
	ds_read_b128 v[198:201], v191 offset:34816
	ds_read_b128 v[202:205], v253 offset:34816
	ds_read_b128 v[206:209], v191 offset:36864
	ds_read_b128 v[210:213], v253 offset:36864
	ds_read_b128 v[214:217], v191 offset:38912
	ds_read_b128 v[218:221], v253 offset:38912
	global_load_lds_dwordx4 v[230:231], off
	v_lshl_add_u64 v[230:231], s[64:65], 0, v[160:161]
	s_mov_b32 m0, s73
	s_nop 0
	global_load_lds_dwordx4 v[230:231], off
	s_waitcnt vmcnt(8)
	s_waitcnt lgkmcnt(0)
	s_setprio 1
	s_barrier
	v_mfma_f32_16x16x32_bf16 v[124:127], v[128:131], v[180:183], v[124:127]
	v_mfma_f32_16x16x32_bf16 v[124:127], v[132:135], v[194:197], v[124:127]
	v_mfma_f32_16x16x32_bf16 v[108:111], v[132:135], v[202:205], v[108:111]
	v_mfma_f32_16x16x32_bf16 v[108:111], v[128:131], v[198:201], v[108:111]
	v_mfma_f32_16x16x32_bf16 v[92:95], v[128:131], v[206:209], v[92:95]
	v_mfma_f32_16x16x32_bf16 v[92:95], v[132:135], v[210:213], v[92:95]
	v_mfma_f32_16x16x32_bf16 v[76:79], v[132:135], v[218:221], v[76:79]
	v_mfma_f32_16x16x32_bf16 v[76:79], v[128:131], v[214:217], v[76:79]
	v_mfma_f32_16x16x32_bf16 v[72:75], v[136:139], v[214:217], v[72:75]
	v_mfma_f32_16x16x32_bf16 v[72:75], v[140:143], v[218:221], v[72:75]
	v_mfma_f32_16x16x32_bf16 v[88:91], v[140:143], v[210:213], v[88:91]
	v_mfma_f32_16x16x32_bf16 v[88:91], v[136:139], v[206:209], v[88:91]
	v_mfma_f32_16x16x32_bf16 v[104:107], v[136:139], v[198:201], v[104:107]
	v_mfma_f32_16x16x32_bf16 v[104:107], v[140:143], v[202:205], v[104:107]
	v_mfma_f32_16x16x32_bf16 v[120:123], v[140:143], v[194:197], v[120:123]
	v_mfma_f32_16x16x32_bf16 v[120:123], v[136:139], v[180:183], v[120:123]
	s_setprio 0
	s_setprio 1
	v_mfma_f32_16x16x32_bf16 v[112:115], v[172:175], v[180:183], v[112:115]
	v_mfma_f32_16x16x32_bf16 v[112:115], v[176:179], v[194:197], v[112:115]
	v_mfma_f32_16x16x32_bf16 v[96:99], v[176:179], v[202:205], v[96:99]
	v_mfma_f32_16x16x32_bf16 v[96:99], v[172:175], v[198:201], v[96:99]
	v_mfma_f32_16x16x32_bf16 v[80:83], v[172:175], v[206:209], v[80:83]
	v_mfma_f32_16x16x32_bf16 v[80:83], v[176:179], v[210:213], v[80:83]
	v_mfma_f32_16x16x32_bf16 v[64:67], v[176:179], v[218:221], v[64:67]
	v_mfma_f32_16x16x32_bf16 v[64:67], v[172:175], v[214:217], v[64:67]
	v_mfma_f32_16x16x32_bf16 v[68:71], v[144:147], v[214:217], v[68:71]
	v_mfma_f32_16x16x32_bf16 v[68:71], v[148:151], v[218:221], v[68:71]
	v_mfma_f32_16x16x32_bf16 v[84:87], v[148:151], v[210:213], v[84:87]
	v_mfma_f32_16x16x32_bf16 v[84:87], v[144:147], v[206:209], v[84:87]
	v_mfma_f32_16x16x32_bf16 v[100:103], v[144:147], v[198:201], v[100:103]
	v_mfma_f32_16x16x32_bf16 v[100:103], v[148:151], v[202:205], v[100:103]
	v_mfma_f32_16x16x32_bf16 v[116:119], v[148:151], v[194:197], v[116:119]
	v_mfma_f32_16x16x32_bf16 v[116:119], v[144:147], v[180:183], v[116:119]
	s_barrier
	s_setprio 0
	s_add_i32 s64, s84, s69
	v_lshl_add_u64 v[222:223], v[222:223], 0, s[26:27]
	s_mov_b32 m0, s64
	ds_read_b128 v[180:183], v191 offset:49152
	v_xor_b32_e32 v253, 64, v191
	ds_read_b128 v[194:197], v253 offset:49152
	ds_read_b128 v[198:201], v191 offset:51200
	ds_read_b128 v[202:205], v253 offset:51200
	ds_read_b128 v[206:209], v191 offset:53248
	ds_read_b128 v[210:213], v253 offset:53248
	ds_read_b128 v[214:217], v191 offset:55296
	ds_read_b128 v[218:221], v253 offset:55296
	global_load_lds_dwordx4 v[222:223], off
	s_add_i32 m0, s64, 0x2000
	s_add_u32 s62, s62, 0x80080
	v_lshl_add_u64 v[222:223], v[224:225], 0, s[26:27]
	s_addc_u32 s63, s63, 0
	s_add_i32 s64, s85, s69
	global_load_lds_dwordx4 v[222:223], off
	v_lshl_add_u64 v[222:223], s[62:63], 0, v[154:155]
	s_mov_b32 m0, s64
	s_nop 0
	global_load_lds_dwordx4 v[222:223], off
	v_lshl_add_u64 v[222:223], s[62:63], 0, v[162:163]
	s_add_i32 m0, s64, 0x2000
	s_nop 0
	global_load_lds_dwordx4 v[222:223], off
	v_lshl_add_u64 v[222:223], v[226:227], 0, s[26:27]
	s_mov_b32 m0, s3
	s_nop 0
	global_load_lds_dwordx4 v[222:223], off
	v_lshl_add_u64 v[222:223], v[228:229], 0, s[26:27]
	s_mov_b32 m0, s75
	s_nop 0
	global_load_lds_dwordx4 v[222:223], off
	s_waitcnt vmcnt(8)
	s_waitcnt lgkmcnt(0)
	s_setprio 1
	s_barrier
	v_mfma_f32_16x16x32_bf16 v[60:63], v[128:131], v[180:183], v[60:63]
	v_mfma_f32_16x16x32_bf16 v[60:63], v[132:135], v[194:197], v[60:63]
	v_mfma_f32_16x16x32_bf16 v[44:47], v[132:135], v[202:205], v[44:47]
	v_mfma_f32_16x16x32_bf16 v[44:47], v[128:131], v[198:201], v[44:47]
	v_mfma_f32_16x16x32_bf16 v[28:31], v[128:131], v[206:209], v[28:31]
	v_mfma_f32_16x16x32_bf16 v[28:31], v[132:135], v[210:213], v[28:31]
	v_mfma_f32_16x16x32_bf16 v[12:15], v[132:135], v[218:221], v[12:15]
	v_mfma_f32_16x16x32_bf16 v[12:15], v[128:131], v[214:217], v[12:15]
	v_mfma_f32_16x16x32_bf16 v[8:11], v[136:139], v[214:217], v[8:11]
	v_mfma_f32_16x16x32_bf16 v[8:11], v[140:143], v[218:221], v[8:11]
	v_mfma_f32_16x16x32_bf16 v[24:27], v[140:143], v[210:213], v[24:27]
	v_mfma_f32_16x16x32_bf16 v[24:27], v[136:139], v[206:209], v[24:27]
	v_mfma_f32_16x16x32_bf16 v[40:43], v[136:139], v[198:201], v[40:43]
	v_mfma_f32_16x16x32_bf16 v[40:43], v[140:143], v[202:205], v[40:43]
	v_mfma_f32_16x16x32_bf16 v[56:59], v[140:143], v[194:197], v[56:59]
	v_mfma_f32_16x16x32_bf16 v[56:59], v[136:139], v[180:183], v[56:59]
	s_setprio 0
	s_setprio 1
	v_mfma_f32_16x16x32_bf16 v[48:51], v[172:175], v[180:183], v[48:51]
	v_mfma_f32_16x16x32_bf16 v[48:51], v[176:179], v[194:197], v[48:51]
	v_mfma_f32_16x16x32_bf16 v[32:35], v[176:179], v[202:205], v[32:35]
	v_mfma_f32_16x16x32_bf16 v[32:35], v[172:175], v[198:201], v[32:35]
	v_mfma_f32_16x16x32_bf16 v[16:19], v[172:175], v[206:209], v[16:19]
	v_mfma_f32_16x16x32_bf16 v[16:19], v[176:179], v[210:213], v[16:19]
	v_mfma_f32_16x16x32_bf16 v[0:3], v[176:179], v[218:221], v[0:3]
	v_mfma_f32_16x16x32_bf16 v[0:3], v[172:175], v[214:217], v[0:3]
	v_mfma_f32_16x16x32_bf16 v[4:7], v[144:147], v[214:217], v[4:7]
	v_mfma_f32_16x16x32_bf16 v[4:7], v[148:151], v[218:221], v[4:7]
	v_mfma_f32_16x16x32_bf16 v[20:23], v[148:151], v[210:213], v[20:23]
	v_mfma_f32_16x16x32_bf16 v[20:23], v[144:147], v[206:209], v[20:23]
	v_mfma_f32_16x16x32_bf16 v[36:39], v[144:147], v[198:201], v[36:39]
	v_mfma_f32_16x16x32_bf16 v[36:39], v[148:151], v[202:205], v[36:39]
	v_mfma_f32_16x16x32_bf16 v[52:55], v[148:151], v[194:197], v[52:55]
	v_mfma_f32_16x16x32_bf16 v[52:55], v[144:147], v[180:183], v[52:55]
	s_barrier
	s_setprio 0
	s_add_i32 s83, s83, 2
	s_add_u32 s81, s81, 0x100
	s_addc_u32 s82, s82, 0
	s_add_u32 s60, s60, 0x100
	s_addc_u32 s61, s61, 0
	s_cmp_gt_u32 s83, 29
	s_branch .LBB0_440
.Lfa_3:
	ds_read_b128 v[128:131], v189
	v_xor_b32_e32 v253, 64, v189
	ds_read_b128 v[132:135], v253
	ds_read_b128 v[136:139], v189 offset:2048
	ds_read_b128 v[140:143], v253 offset:2048
	ds_read_b128 v[144:147], v190
	v_xor_b32_e32 v253, 64, v190
	ds_read_b128 v[148:151], v253
	ds_read_b128 v[172:175], v190 offset:2048
	ds_read_b128 v[176:179], v253 offset:2048
	s_add_u32 s62, s60, 0xfff80080
	s_addc_u32 s63, s61, -1
	s_cmp_eq_u32 s83, 28
	s_cselect_b32 s65, s15, s63
	s_cselect_b32 s64, s53, s62
	s_cselect_b32 s63, s51, s82
	s_cselect_b32 s62, s59, s81
	v_lshl_add_u64 v[222:223], s[60:61], 0, v[166:167]
	s_add_i32 m0, s70, 0xc000
	ds_read_b128 v[180:183], v191
	v_xor_b32_e32 v253, 64, v191
	ds_read_b128 v[194:197], v253
	ds_read_b128 v[198:201], v191 offset:2048
	ds_read_b128 v[202:205], v253 offset:2048
	ds_read_b128 v[206:209], v191 offset:4096
	ds_read_b128 v[210:213], v253 offset:4096
	ds_read_b128 v[214:217], v191 offset:6144
	ds_read_b128 v[218:221], v253 offset:6144
	global_load_lds_dwordx4 v[222:223], off
	v_lshl_add_u64 v[222:223], s[60:61], 0, v[164:165]
	s_add_i32 m0, s70, 0xe000
	s_nop 0
	global_load_lds_dwordx4 v[222:223], off
	s_waitcnt vmcnt(8)
	s_waitcnt lgkmcnt(0)
	s_setprio 1
	s_barrier
	v_mfma_f32_16x16x32_bf16 v[124:127], v[128:131], v[180:183], 0
	v_mfma_f32_16x16x32_bf16 v[120:123], v[136:139], v[180:183], 0
	v_mfma_f32_16x16x32_bf16 v[108:111], v[128:131], v[198:201], 0
	v_mfma_f32_16x16x32_bf16 v[104:107], v[136:139], v[198:201], 0
	v_mfma_f32_16x16x32_bf16 v[92:95], v[128:131], v[206:209], 0
	v_mfma_f32_16x16x32_bf16 v[88:91], v[136:139], v[206:209], 0
	v_mfma_f32_16x16x32_bf16 v[76:79], v[128:131], v[214:217], 0
	v_mfma_f32_16x16x32_bf16 v[72:75], v[136:139], v[214:217], 0
	v_mfma_f32_16x16x32_bf16 v[124:127], v[132:135], v[194:197], v[124:127]
	v_mfma_f32_16x16x32_bf16 v[120:123], v[140:143], v[194:197], v[120:123]
	v_mfma_f32_16x16x32_bf16 v[108:111], v[132:135], v[202:205], v[108:111]
	v_mfma_f32_16x16x32_bf16 v[104:107], v[140:143], v[202:205], v[104:107]
	v_mfma_f32_16x16x32_bf16 v[92:95], v[132:135], v[210:213], v[92:95]
	v_mfma_f32_16x16x32_bf16 v[88:91], v[140:143], v[210:213], v[88:91]
	v_mfma_f32_16x16x32_bf16 v[76:79], v[132:135], v[218:221], v[76:79]
	v_mfma_f32_16x16x32_bf16 v[72:75], v[140:143], v[218:221], v[72:75]
	s_setprio 0
	s_setprio 1
	v_mfma_f32_16x16x32_bf16 v[116:119], v[144:147], v[180:183], 0
	v_mfma_f32_16x16x32_bf16 v[112:115], v[172:175], v[180:183], 0
	v_mfma_f32_16x16x32_bf16 v[100:103], v[144:147], v[198:201], 0
	v_mfma_f32_16x16x32_bf16 v[96:99], v[172:175], v[198:201], 0
	v_mfma_f32_16x16x32_bf16 v[84:87], v[144:147], v[206:209], 0
	v_mfma_f32_16x16x32_bf16 v[80:83], v[172:175], v[206:209], 0
	v_mfma_f32_16x16x32_bf16 v[68:71], v[144:147], v[214:217], 0
	v_mfma_f32_16x16x32_bf16 v[64:67], v[172:175], v[214:217], 0
	v_mfma_f32_16x16x32_bf16 v[116:119], v[148:151], v[194:197], v[116:119]
	v_mfma_f32_16x16x32_bf16 v[112:115], v[176:179], v[194:197], v[112:115]
	v_mfma_f32_16x16x32_bf16 v[100:103], v[148:151], v[202:205], v[100:103]
	v_mfma_f32_16x16x32_bf16 v[96:99], v[176:179], v[202:205], v[96:99]
	v_mfma_f32_16x16x32_bf16 v[84:87], v[148:151], v[210:213], v[84:87]
	v_mfma_f32_16x16x32_bf16 v[80:83], v[176:179], v[210:213], v[80:83]
	v_mfma_f32_16x16x32_bf16 v[68:71], v[148:151], v[218:221], v[68:71]
	v_mfma_f32_16x16x32_bf16 v[64:67], v[176:179], v[218:221], v[64:67]
	s_barrier
	s_setprio 0
	s_add_i32 s84, s79, s69
	v_lshl_add_u64 v[222:223], s[62:63], 0, v[154:155]
	s_mov_b32 m0, s84
	ds_read_b128 v[180:183], v191 offset:16384
	v_xor_b32_e32 v253, 64, v191
	ds_read_b128 v[194:197], v253 offset:16384
	ds_read_b128 v[198:201], v191 offset:18432
	ds_read_b128 v[202:205], v253 offset:18432
	ds_read_b128 v[206:209], v191 offset:20480
	ds_read_b128 v[210:213], v253 offset:20480
	ds_read_b128 v[214:217], v191 offset:22528
	ds_read_b128 v[218:221], v253 offset:22528
	global_load_lds_dwordx4 v[222:223], off
	s_add_i32 m0, s84, 0x2000
	s_add_u32 s84, s62, 0x80000
	v_lshl_add_u64 v[224:225], s[62:63], 0, v[162:163]
	s_addc_u32 s85, s63, 0
	s_add_i32 s86, s80, s69
	global_load_lds_dwordx4 v[224:225], off
	v_lshl_add_u64 v[226:227], s[84:85], 0, v[154:155]
	s_mov_b32 m0, s86
	v_lshl_add_u64 v[228:229], s[64:65], 0, v[160:161]
	global_load_lds_dwordx4 v[226:227], off
	v_lshl_add_u64 v[226:227], s[84:85], 0, v[162:163]
	s_add_i32 m0, s86, 0x2000
	s_nop 0
	global_load_lds_dwordx4 v[226:227], off
	v_lshl_add_u64 v[226:227], s[64:65], 0, v[152:153]
	s_mov_b32 m0, s70
	s_nop 0
	global_load_lds_dwordx4 v[226:227], off
	s_mov_b32 m0, s71
	s_nop 0
	global_load_lds_dwordx4 v[228:229], off
	s_waitcnt vmcnt(8)
	s_waitcnt lgkmcnt(0)
	s_setprio 1
	s_barrier
	v_mfma_f32_16x16x32_bf16 v[60:63], v[128:131], v[180:183], 0
	v_mfma_f32_16x16x32_bf16 v[56:59], v[136:139], v[180:183], 0
	v_mfma_f32_16x16x32_bf16 v[44:47], v[128:131], v[198:201], 0
	v_mfma_f32_16x16x32_bf16 v[40:43], v[136:139], v[198:201], 0
	v_mfma_f32_16x16x32_bf16 v[28:31], v[128:131], v[206:209], 0
	v_mfma_f32_16x16x32_bf16 v[24:27], v[136:139], v[206:209], 0
	v_mfma_f32_16x16x32_bf16 v[12:15], v[128:131], v[214:217], 0
	v_mfma_f32_16x16x32_bf16 v[8:11], v[136:139], v[214:217], 0
	v_mfma_f32_16x16x32_bf16 v[60:63], v[132:135], v[194:197], v[60:63]
	v_mfma_f32_16x16x32_bf16 v[56:59], v[140:143], v[194:197], v[56:59]
	v_mfma_f32_16x16x32_bf16 v[44:47], v[132:135], v[202:205], v[44:47]
	v_mfma_f32_16x16x32_bf16 v[40:43], v[140:143], v[202:205], v[40:43]
	v_mfma_f32_16x16x32_bf16 v[28:31], v[132:135], v[210:213], v[28:31]
	v_mfma_f32_16x16x32_bf16 v[24:27], v[140:143], v[210:213], v[24:27]
	v_mfma_f32_16x16x32_bf16 v[12:15], v[132:135], v[218:221], v[12:15]
	v_mfma_f32_16x16x32_bf16 v[8:11], v[140:143], v[218:221], v[8:11]
	s_setprio 0
	s_setprio 1
	v_mfma_f32_16x16x32_bf16 v[52:55], v[144:147], v[180:183], 0
	v_mfma_f32_16x16x32_bf16 v[48:51], v[172:175], v[180:183], 0
	v_mfma_f32_16x16x32_bf16 v[36:39], v[144:147], v[198:201], 0
	v_mfma_f32_16x16x32_bf16 v[32:35], v[172:175], v[198:201], 0
	v_mfma_f32_16x16x32_bf16 v[20:23], v[144:147], v[206:209], 0
	v_mfma_f32_16x16x32_bf16 v[16:19], v[172:175], v[206:209], 0
	v_mfma_f32_16x16x32_bf16 v[4:7], v[144:147], v[214:217], 0
	v_mfma_f32_16x16x32_bf16 v[0:3], v[172:175], v[214:217], 0
	v_mfma_f32_16x16x32_bf16 v[52:55], v[148:151], v[194:197], v[52:55]
	v_mfma_f32_16x16x32_bf16 v[48:51], v[176:179], v[194:197], v[48:51]
	v_mfma_f32_16x16x32_bf16 v[36:39], v[148:151], v[202:205], v[36:39]
	v_mfma_f32_16x16x32_bf16 v[32:35], v[176:179], v[202:205], v[32:35]
	v_mfma_f32_16x16x32_bf16 v[20:23], v[148:151], v[210:213], v[20:23]
	v_mfma_f32_16x16x32_bf16 v[16:19], v[176:179], v[210:213], v[16:19]
	v_mfma_f32_16x16x32_bf16 v[4:7], v[148:151], v[218:221], v[4:7]
	v_mfma_f32_16x16x32_bf16 v[0:3], v[176:179], v[218:221], v[0:3]
	s_barrier
	s_setprio 0
	s_add_i32 s84, 0, 0x18000
	s_add_i32 s85, 0, 0x1c000
	v_add_u32_e32 v140, s84, v186
	v_add_u32_e32 v176, s85, v186
	ds_read_b128 v[128:131], v140
	v_xor_b32_e32 v253, 64, v140
	ds_read_b128 v[132:135], v253
	ds_read_b128 v[136:139], v140 offset:2048
	ds_read_b128 v[140:143], v253 offset:2048
	ds_read_b128 v[144:147], v176
	v_xor_b32_e32 v253, 64, v176
	ds_read_b128 v[148:151], v253
	ds_read_b128 v[172:175], v176 offset:2048
	ds_read_b128 v[176:179], v253 offset:2048
	s_add_u32 s64, s64, 0x80000
	s_addc_u32 s65, s65, 0
	s_mov_b32 m0, s72
	v_lshl_add_u64 v[230:231], s[64:65], 0, v[152:153]
	ds_read_b128 v[180:183], v191 offset:32768
	v_xor_b32_e32 v253, 64, v191
	ds_read_b128 v[194:197], v253 offset:32768
	ds_read_b128 v[198:201], v191 offset:34816
	ds_read_b128 v[202:205], v253 offset:34816
	ds_read_b128 v[206:209], v191 offset:36864
	ds_read_b128 v[210:213], v253 offset:36864
	ds_read_b128 v[214:217], v191 offset:38912
	ds_read_b128 v[218:221], v253 offset:38912
	global_load_lds_dwordx4 v[230:231], off
	v_lshl_add_u64 v[230:231], s[64:65], 0, v[160:161]
	s_mov_b32 m0, s73
	s_nop 0
	global_load_lds_dwordx4 v[230:231], off
	s_waitcnt vmcnt(8)
	s_waitcnt lgkmcnt(0)
	s_setprio 1
	s_barrier
	v_mfma_f32_16x16x32_bf16 v[124:127], v[128:131], v[180:183], v[124:127]
	v_mfma_f32_16x16x32_bf16 v[124:127], v[132:135], v[194:197], v[124:127]
	v_mfma_f32_16x16x32_bf16 v[108:111], v[132:135], v[202:205], v[108:111]
	v_mfma_f32_16x16x32_bf16 v[108:111], v[128:131], v[198:201], v[108:111]
	v_mfma_f32_16x16x32_bf16 v[92:95], v[128:131], v[206:209], v[92:95]
	v_mfma_f32_16x16x32_bf16 v[92:95], v[132:135], v[210:213], v[92:95]
	v_mfma_f32_16x16x32_bf16 v[76:79], v[132:135], v[218:221], v[76:79]
	v_mfma_f32_16x16x32_bf16 v[76:79], v[128:131], v[214:217], v[76:79]
	v_mfma_f32_16x16x32_bf16 v[72:75], v[136:139], v[214:217], v[72:75]
	v_mfma_f32_16x16x32_bf16 v[72:75], v[140:143], v[218:221], v[72:75]
	v_mfma_f32_16x16x32_bf16 v[88:91], v[140:143], v[210:213], v[88:91]
	v_mfma_f32_16x16x32_bf16 v[88:91], v[136:139], v[206:209], v[88:91]
	v_mfma_f32_16x16x32_bf16 v[104:107], v[136:139], v[198:201], v[104:107]
	v_mfma_f32_16x16x32_bf16 v[104:107], v[140:143], v[202:205], v[104:107]
	v_mfma_f32_16x16x32_bf16 v[120:123], v[140:143], v[194:197], v[120:123]
	v_mfma_f32_16x16x32_bf16 v[120:123], v[136:139], v[180:183], v[120:123]
	s_setprio 0
	s_setprio 1
	v_mfma_f32_16x16x32_bf16 v[112:115], v[172:175], v[180:183], v[112:115]
	v_mfma_f32_16x16x32_bf16 v[112:115], v[176:179], v[194:197], v[112:115]
	v_mfma_f32_16x16x32_bf16 v[96:99], v[176:179], v[202:205], v[96:99]
	v_mfma_f32_16x16x32_bf16 v[96:99], v[172:175], v[198:201], v[96:99]
	v_mfma_f32_16x16x32_bf16 v[80:83], v[172:175], v[206:209], v[80:83]
	v_mfma_f32_16x16x32_bf16 v[80:83], v[176:179], v[210:213], v[80:83]
	v_mfma_f32_16x16x32_bf16 v[64:67], v[176:179], v[218:221], v[64:67]
	v_mfma_f32_16x16x32_bf16 v[64:67], v[172:175], v[214:217], v[64:67]
	v_mfma_f32_16x16x32_bf16 v[68:71], v[144:147], v[214:217], v[68:71]
	v_mfma_f32_16x16x32_bf16 v[68:71], v[148:151], v[218:221], v[68:71]
	v_mfma_f32_16x16x32_bf16 v[84:87], v[148:151], v[210:213], v[84:87]
	v_mfma_f32_16x16x32_bf16 v[84:87], v[144:147], v[206:209], v[84:87]
	v_mfma_f32_16x16x32_bf16 v[100:103], v[144:147], v[198:201], v[100:103]
	v_mfma_f32_16x16x32_bf16 v[100:103], v[148:151], v[202:205], v[100:103]
	v_mfma_f32_16x16x32_bf16 v[116:119], v[148:151], v[194:197], v[116:119]
	v_mfma_f32_16x16x32_bf16 v[116:119], v[144:147], v[180:183], v[116:119]
	s_barrier
	s_setprio 0
	s_add_i32 s64, s84, s69
	v_lshl_add_u64 v[222:223], v[222:223], 0, s[26:27]
	s_mov_b32 m0, s64
	ds_read_b128 v[180:183], v191 offset:49152
	v_xor_b32_e32 v253, 64, v191
	ds_read_b128 v[194:197], v253 offset:49152
	ds_read_b128 v[198:201], v191 offset:51200
	ds_read_b128 v[202:205], v253 offset:51200
	ds_read_b128 v[206:209], v191 offset:53248
	ds_read_b128 v[210:213], v253 offset:53248
	ds_read_b128 v[214:217], v191 offset:55296
	ds_read_b128 v[218:221], v253 offset:55296
	global_load_lds_dwordx4 v[222:223], off
	s_add_i32 m0, s64, 0x2000
	s_add_u32 s62, s62, 0x80080
	v_lshl_add_u64 v[222:223], v[224:225], 0, s[26:27]
	s_addc_u32 s63, s63, 0
	s_add_i32 s64, s85, s69
	global_load_lds_dwordx4 v[222:223], off
	v_lshl_add_u64 v[222:223], s[62:63], 0, v[154:155]
	s_mov_b32 m0, s64
	s_nop 0
	global_load_lds_dwordx4 v[222:223], off
	v_lshl_add_u64 v[222:223], s[62:63], 0, v[162:163]
	s_add_i32 m0, s64, 0x2000
	s_nop 0
	global_load_lds_dwordx4 v[222:223], off
	v_lshl_add_u64 v[222:223], v[226:227], 0, s[26:27]
	s_mov_b32 m0, s3
	s_nop 0
	global_load_lds_dwordx4 v[222:223], off
	v_lshl_add_u64 v[222:223], v[228:229], 0, s[26:27]
	s_mov_b32 m0, s75
	s_nop 0
	global_load_lds_dwordx4 v[222:223], off
	s_waitcnt vmcnt(8)
	s_waitcnt lgkmcnt(0)
	s_setprio 1
	s_barrier
	v_mfma_f32_16x16x32_bf16 v[60:63], v[128:131], v[180:183], v[60:63]
	v_mfma_f32_16x16x32_bf16 v[60:63], v[132:135], v[194:197], v[60:63]
	v_mfma_f32_16x16x32_bf16 v[44:47], v[132:135], v[202:205], v[44:47]
	v_mfma_f32_16x16x32_bf16 v[44:47], v[128:131], v[198:201], v[44:47]
	v_mfma_f32_16x16x32_bf16 v[28:31], v[128:131], v[206:209], v[28:31]
	v_mfma_f32_16x16x32_bf16 v[28:31], v[132:135], v[210:213], v[28:31]
	v_mfma_f32_16x16x32_bf16 v[12:15], v[132:135], v[218:221], v[12:15]
	v_mfma_f32_16x16x32_bf16 v[12:15], v[128:131], v[214:217], v[12:15]
	v_mfma_f32_16x16x32_bf16 v[8:11], v[136:139], v[214:217], v[8:11]
	v_mfma_f32_16x16x32_bf16 v[8:11], v[140:143], v[218:221], v[8:11]
	v_mfma_f32_16x16x32_bf16 v[24:27], v[140:143], v[210:213], v[24:27]
	v_mfma_f32_16x16x32_bf16 v[24:27], v[136:139], v[206:209], v[24:27]
	v_mfma_f32_16x16x32_bf16 v[40:43], v[136:139], v[198:201], v[40:43]
	v_mfma_f32_16x16x32_bf16 v[40:43], v[140:143], v[202:205], v[40:43]
	v_mfma_f32_16x16x32_bf16 v[56:59], v[140:143], v[194:197], v[56:59]
	v_mfma_f32_16x16x32_bf16 v[56:59], v[136:139], v[180:183], v[56:59]
	s_setprio 0
	s_setprio 1
	v_mfma_f32_16x16x32_bf16 v[48:51], v[172:175], v[180:183], v[48:51]
	v_mfma_f32_16x16x32_bf16 v[48:51], v[176:179], v[194:197], v[48:51]
	v_mfma_f32_16x16x32_bf16 v[32:35], v[176:179], v[202:205], v[32:35]
	v_mfma_f32_16x16x32_bf16 v[32:35], v[172:175], v[198:201], v[32:35]
	v_mfma_f32_16x16x32_bf16 v[16:19], v[172:175], v[206:209], v[16:19]
	v_mfma_f32_16x16x32_bf16 v[16:19], v[176:179], v[210:213], v[16:19]
	v_mfma_f32_16x16x32_bf16 v[0:3], v[176:179], v[218:221], v[0:3]
	v_mfma_f32_16x16x32_bf16 v[0:3], v[172:175], v[214:217], v[0:3]
	v_mfma_f32_16x16x32_bf16 v[4:7], v[144:147], v[214:217], v[4:7]
	v_mfma_f32_16x16x32_bf16 v[4:7], v[148:151], v[218:221], v[4:7]
	v_mfma_f32_16x16x32_bf16 v[20:23], v[148:151], v[210:213], v[20:23]
	v_mfma_f32_16x16x32_bf16 v[20:23], v[144:147], v[206:209], v[20:23]
	v_mfma_f32_16x16x32_bf16 v[36:39], v[144:147], v[198:201], v[36:39]
	v_mfma_f32_16x16x32_bf16 v[36:39], v[148:151], v[202:205], v[36:39]
	v_mfma_f32_16x16x32_bf16 v[52:55], v[148:151], v[194:197], v[52:55]
	v_mfma_f32_16x16x32_bf16 v[52:55], v[144:147], v[180:183], v[52:55]
	s_barrier
	s_setprio 0
	s_add_i32 s83, s83, 2
	s_add_u32 s81, s81, 0x100
	s_addc_u32 s82, s82, 0
	s_add_u32 s60, s60, 0x100
	s_addc_u32 s61, s61, 0
	s_cmp_gt_u32 s83, 29
.LBB0_440:
	ds_read_b128 v[128:131], v189
	v_xor_b32_e32 v253, 64, v189
	ds_read_b128 v[132:135], v253
	ds_read_b128 v[136:139], v189 offset:2048
	ds_read_b128 v[140:143], v253 offset:2048
	ds_read_b128 v[144:147], v190
	v_xor_b32_e32 v253, 64, v190
	ds_read_b128 v[148:151], v253
	ds_read_b128 v[172:175], v190 offset:2048
	ds_read_b128 v[176:179], v253 offset:2048
	s_add_u32 s62, s60, 0xfff80080
	s_addc_u32 s63, s61, -1
	s_cmp_eq_u32 s83, 28
	s_cselect_b32 s65, s15, s63
	s_cselect_b32 s64, s53, s62
	s_cselect_b32 s63, s51, s82
	s_cselect_b32 s62, s59, s81
	v_lshl_add_u64 v[222:223], s[60:61], 0, v[166:167]
	s_add_i32 m0, s70, 0xc000
	ds_read_b128 v[180:183], v191
	v_xor_b32_e32 v253, 64, v191
	ds_read_b128 v[194:197], v253
	ds_read_b128 v[198:201], v191 offset:2048
	ds_read_b128 v[202:205], v253 offset:2048
	ds_read_b128 v[206:209], v191 offset:4096
	ds_read_b128 v[210:213], v253 offset:4096
	ds_read_b128 v[214:217], v191 offset:6144
	ds_read_b128 v[218:221], v253 offset:6144
	global_load_lds_dwordx4 v[222:223], off
	v_lshl_add_u64 v[222:223], s[60:61], 0, v[164:165]
	s_add_i32 m0, s70, 0xe000
	s_nop 0
	global_load_lds_dwordx4 v[222:223], off
	s_waitcnt vmcnt(8)
	s_waitcnt lgkmcnt(0)
	s_setprio 1
	s_barrier
	v_mfma_f32_16x16x32_bf16 v[124:127], v[128:131], v[180:183], v[124:127]
	v_mfma_f32_16x16x32_bf16 v[124:127], v[132:135], v[194:197], v[124:127]
	v_mfma_f32_16x16x32_bf16 v[108:111], v[132:135], v[202:205], v[108:111]
	v_mfma_f32_16x16x32_bf16 v[108:111], v[128:131], v[198:201], v[108:111]
	v_mfma_f32_16x16x32_bf16 v[92:95], v[128:131], v[206:209], v[92:95]
	v_mfma_f32_16x16x32_bf16 v[92:95], v[132:135], v[210:213], v[92:95]
	v_mfma_f32_16x16x32_bf16 v[76:79], v[132:135], v[218:221], v[76:79]
	v_mfma_f32_16x16x32_bf16 v[76:79], v[128:131], v[214:217], v[76:79]
	v_mfma_f32_16x16x32_bf16 v[72:75], v[136:139], v[214:217], v[72:75]
	v_mfma_f32_16x16x32_bf16 v[72:75], v[140:143], v[218:221], v[72:75]
	v_mfma_f32_16x16x32_bf16 v[88:91], v[140:143], v[210:213], v[88:91]
	v_mfma_f32_16x16x32_bf16 v[88:91], v[136:139], v[206:209], v[88:91]
	v_mfma_f32_16x16x32_bf16 v[104:107], v[136:139], v[198:201], v[104:107]
	v_mfma_f32_16x16x32_bf16 v[104:107], v[140:143], v[202:205], v[104:107]
	v_mfma_f32_16x16x32_bf16 v[120:123], v[140:143], v[194:197], v[120:123]
	v_mfma_f32_16x16x32_bf16 v[120:123], v[136:139], v[180:183], v[120:123]
	s_setprio 0
	s_setprio 1
	v_mfma_f32_16x16x32_bf16 v[112:115], v[172:175], v[180:183], v[112:115]
	v_mfma_f32_16x16x32_bf16 v[112:115], v[176:179], v[194:197], v[112:115]
	v_mfma_f32_16x16x32_bf16 v[96:99], v[176:179], v[202:205], v[96:99]
	v_mfma_f32_16x16x32_bf16 v[96:99], v[172:175], v[198:201], v[96:99]
	v_mfma_f32_16x16x32_bf16 v[80:83], v[172:175], v[206:209], v[80:83]
	v_mfma_f32_16x16x32_bf16 v[80:83], v[176:179], v[210:213], v[80:83]
	v_mfma_f32_16x16x32_bf16 v[64:67], v[176:179], v[218:221], v[64:67]
	v_mfma_f32_16x16x32_bf16 v[64:67], v[172:175], v[214:217], v[64:67]
	v_mfma_f32_16x16x32_bf16 v[68:71], v[144:147], v[214:217], v[68:71]
	v_mfma_f32_16x16x32_bf16 v[68:71], v[148:151], v[218:221], v[68:71]
	v_mfma_f32_16x16x32_bf16 v[84:87], v[148:151], v[210:213], v[84:87]
	v_mfma_f32_16x16x32_bf16 v[84:87], v[144:147], v[206:209], v[84:87]
	v_mfma_f32_16x16x32_bf16 v[100:103], v[144:147], v[198:201], v[100:103]
	v_mfma_f32_16x16x32_bf16 v[100:103], v[148:151], v[202:205], v[100:103]
	v_mfma_f32_16x16x32_bf16 v[116:119], v[148:151], v[194:197], v[116:119]
	v_mfma_f32_16x16x32_bf16 v[116:119], v[144:147], v[180:183], v[116:119]
	s_barrier
	s_setprio 0
	s_add_i32 s84, s79, s69
	v_lshl_add_u64 v[222:223], s[62:63], 0, v[154:155]
	s_mov_b32 m0, s84
	ds_read_b128 v[180:183], v191 offset:16384
	v_xor_b32_e32 v253, 64, v191
	ds_read_b128 v[194:197], v253 offset:16384
	ds_read_b128 v[198:201], v191 offset:18432
	ds_read_b128 v[202:205], v253 offset:18432
	ds_read_b128 v[206:209], v191 offset:20480
	ds_read_b128 v[210:213], v253 offset:20480
	ds_read_b128 v[214:217], v191 offset:22528
	ds_read_b128 v[218:221], v253 offset:22528
	global_load_lds_dwordx4 v[222:223], off
	s_add_i32 m0, s84, 0x2000
	s_add_u32 s84, s62, 0x80000
	v_lshl_add_u64 v[224:225], s[62:63], 0, v[162:163]
	s_addc_u32 s85, s63, 0
	s_add_i32 s86, s80, s69
	global_load_lds_dwordx4 v[224:225], off
	v_lshl_add_u64 v[226:227], s[84:85], 0, v[154:155]
	s_mov_b32 m0, s86
	v_lshl_add_u64 v[228:229], s[64:65], 0, v[160:161]
	global_load_lds_dwordx4 v[226:227], off
	v_lshl_add_u64 v[226:227], s[84:85], 0, v[162:163]
	s_add_i32 m0, s86, 0x2000
	s_nop 0
	global_load_lds_dwordx4 v[226:227], off
	v_lshl_add_u64 v[226:227], s[64:65], 0, v[152:153]
	s_mov_b32 m0, s70
	s_nop 0
	global_load_lds_dwordx4 v[226:227], off
	s_mov_b32 m0, s71
	s_nop 0
	global_load_lds_dwordx4 v[228:229], off
	s_waitcnt vmcnt(8)
	s_waitcnt lgkmcnt(0)
	s_setprio 1
	s_barrier
	v_mfma_f32_16x16x32_bf16 v[60:63], v[128:131], v[180:183], v[60:63]
	v_mfma_f32_16x16x32_bf16 v[60:63], v[132:135], v[194:197], v[60:63]
	v_mfma_f32_16x16x32_bf16 v[44:47], v[132:135], v[202:205], v[44:47]
	v_mfma_f32_16x16x32_bf16 v[44:47], v[128:131], v[198:201], v[44:47]
	v_mfma_f32_16x16x32_bf16 v[28:31], v[128:131], v[206:209], v[28:31]
	v_mfma_f32_16x16x32_bf16 v[28:31], v[132:135], v[210:213], v[28:31]
	v_mfma_f32_16x16x32_bf16 v[12:15], v[132:135], v[218:221], v[12:15]
	v_mfma_f32_16x16x32_bf16 v[12:15], v[128:131], v[214:217], v[12:15]
	v_mfma_f32_16x16x32_bf16 v[8:11], v[136:139], v[214:217], v[8:11]
	v_mfma_f32_16x16x32_bf16 v[8:11], v[140:143], v[218:221], v[8:11]
	v_mfma_f32_16x16x32_bf16 v[24:27], v[140:143], v[210:213], v[24:27]
	v_mfma_f32_16x16x32_bf16 v[24:27], v[136:139], v[206:209], v[24:27]
	v_mfma_f32_16x16x32_bf16 v[40:43], v[136:139], v[198:201], v[40:43]
	v_mfma_f32_16x16x32_bf16 v[40:43], v[140:143], v[202:205], v[40:43]
	v_mfma_f32_16x16x32_bf16 v[56:59], v[140:143], v[194:197], v[56:59]
	v_mfma_f32_16x16x32_bf16 v[56:59], v[136:139], v[180:183], v[56:59]
	s_setprio 0
	s_setprio 1
	v_mfma_f32_16x16x32_bf16 v[48:51], v[172:175], v[180:183], v[48:51]
	v_mfma_f32_16x16x32_bf16 v[48:51], v[176:179], v[194:197], v[48:51]
	v_mfma_f32_16x16x32_bf16 v[32:35], v[176:179], v[202:205], v[32:35]
	v_mfma_f32_16x16x32_bf16 v[32:35], v[172:175], v[198:201], v[32:35]
	v_mfma_f32_16x16x32_bf16 v[16:19], v[172:175], v[206:209], v[16:19]
	v_mfma_f32_16x16x32_bf16 v[16:19], v[176:179], v[210:213], v[16:19]
	v_mfma_f32_16x16x32_bf16 v[0:3], v[176:179], v[218:221], v[0:3]
	v_mfma_f32_16x16x32_bf16 v[0:3], v[172:175], v[214:217], v[0:3]
	v_mfma_f32_16x16x32_bf16 v[4:7], v[144:147], v[214:217], v[4:7]
	v_mfma_f32_16x16x32_bf16 v[4:7], v[148:151], v[218:221], v[4:7]
	v_mfma_f32_16x16x32_bf16 v[20:23], v[148:151], v[210:213], v[20:23]
	v_mfma_f32_16x16x32_bf16 v[20:23], v[144:147], v[206:209], v[20:23]
	v_mfma_f32_16x16x32_bf16 v[36:39], v[144:147], v[198:201], v[36:39]
	v_mfma_f32_16x16x32_bf16 v[36:39], v[148:151], v[202:205], v[36:39]
	v_mfma_f32_16x16x32_bf16 v[52:55], v[148:151], v[194:197], v[52:55]
	v_mfma_f32_16x16x32_bf16 v[52:55], v[144:147], v[180:183], v[52:55]
	s_barrier
	s_setprio 0
	s_add_i32 s84, 0, 0x18000
	s_add_i32 s85, 0, 0x1c000
	v_add_u32_e32 v140, s84, v186
	v_add_u32_e32 v176, s85, v186
	ds_read_b128 v[128:131], v140
	v_xor_b32_e32 v253, 64, v140
	ds_read_b128 v[132:135], v253
	ds_read_b128 v[136:139], v140 offset:2048
	ds_read_b128 v[140:143], v253 offset:2048
	ds_read_b128 v[144:147], v176
	v_xor_b32_e32 v253, 64, v176
	ds_read_b128 v[148:151], v253
	ds_read_b128 v[172:175], v176 offset:2048
	ds_read_b128 v[176:179], v253 offset:2048
	s_add_u32 s64, s64, 0x80000
	s_addc_u32 s65, s65, 0
	s_mov_b32 m0, s72
	v_lshl_add_u64 v[230:231], s[64:65], 0, v[152:153]
	ds_read_b128 v[180:183], v191 offset:32768
	v_xor_b32_e32 v253, 64, v191
	ds_read_b128 v[194:197], v253 offset:32768
	ds_read_b128 v[198:201], v191 offset:34816
	ds_read_b128 v[202:205], v253 offset:34816
	ds_read_b128 v[206:209], v191 offset:36864
	ds_read_b128 v[210:213], v253 offset:36864
	ds_read_b128 v[214:217], v191 offset:38912
	ds_read_b128 v[218:221], v253 offset:38912
	global_load_lds_dwordx4 v[230:231], off
	v_lshl_add_u64 v[230:231], s[64:65], 0, v[160:161]
	s_mov_b32 m0, s73
	s_nop 0
	global_load_lds_dwordx4 v[230:231], off
	s_waitcnt vmcnt(8)
	s_waitcnt lgkmcnt(0)
	s_setprio 1
	s_barrier
	v_mfma_f32_16x16x32_bf16 v[124:127], v[128:131], v[180:183], v[124:127]
	v_mfma_f32_16x16x32_bf16 v[124:127], v[132:135], v[194:197], v[124:127]
	v_mfma_f32_16x16x32_bf16 v[108:111], v[132:135], v[202:205], v[108:111]
	v_mfma_f32_16x16x32_bf16 v[108:111], v[128:131], v[198:201], v[108:111]
	v_mfma_f32_16x16x32_bf16 v[92:95], v[128:131], v[206:209], v[92:95]
	v_mfma_f32_16x16x32_bf16 v[92:95], v[132:135], v[210:213], v[92:95]
	v_mfma_f32_16x16x32_bf16 v[76:79], v[132:135], v[218:221], v[76:79]
	v_mfma_f32_16x16x32_bf16 v[76:79], v[128:131], v[214:217], v[76:79]
	v_mfma_f32_16x16x32_bf16 v[72:75], v[136:139], v[214:217], v[72:75]
	v_mfma_f32_16x16x32_bf16 v[72:75], v[140:143], v[218:221], v[72:75]
	v_mfma_f32_16x16x32_bf16 v[88:91], v[140:143], v[210:213], v[88:91]
	v_mfma_f32_16x16x32_bf16 v[88:91], v[136:139], v[206:209], v[88:91]
	v_mfma_f32_16x16x32_bf16 v[104:107], v[136:139], v[198:201], v[104:107]
	v_mfma_f32_16x16x32_bf16 v[104:107], v[140:143], v[202:205], v[104:107]
	v_mfma_f32_16x16x32_bf16 v[120:123], v[140:143], v[194:197], v[120:123]
	v_mfma_f32_16x16x32_bf16 v[120:123], v[136:139], v[180:183], v[120:123]
	s_setprio 0
	s_setprio 1
	v_mfma_f32_16x16x32_bf16 v[112:115], v[172:175], v[180:183], v[112:115]
	v_mfma_f32_16x16x32_bf16 v[112:115], v[176:179], v[194:197], v[112:115]
	v_mfma_f32_16x16x32_bf16 v[96:99], v[176:179], v[202:205], v[96:99]
	v_mfma_f32_16x16x32_bf16 v[96:99], v[172:175], v[198:201], v[96:99]
	v_mfma_f32_16x16x32_bf16 v[80:83], v[172:175], v[206:209], v[80:83]
	v_mfma_f32_16x16x32_bf16 v[80:83], v[176:179], v[210:213], v[80:83]
	v_mfma_f32_16x16x32_bf16 v[64:67], v[176:179], v[218:221], v[64:67]
	v_mfma_f32_16x16x32_bf16 v[64:67], v[172:175], v[214:217], v[64:67]
	v_mfma_f32_16x16x32_bf16 v[68:71], v[144:147], v[214:217], v[68:71]
	v_mfma_f32_16x16x32_bf16 v[68:71], v[148:151], v[218:221], v[68:71]
	v_mfma_f32_16x16x32_bf16 v[84:87], v[148:151], v[210:213], v[84:87]
	v_mfma_f32_16x16x32_bf16 v[84:87], v[144:147], v[206:209], v[84:87]
	v_mfma_f32_16x16x32_bf16 v[100:103], v[144:147], v[198:201], v[100:103]
	v_mfma_f32_16x16x32_bf16 v[100:103], v[148:151], v[202:205], v[100:103]
	v_mfma_f32_16x16x32_bf16 v[116:119], v[148:151], v[194:197], v[116:119]
	v_mfma_f32_16x16x32_bf16 v[116:119], v[144:147], v[180:183], v[116:119]
	s_barrier
	s_setprio 0
	s_add_i32 s64, s84, s69
	v_lshl_add_u64 v[222:223], v[222:223], 0, s[26:27]
	s_mov_b32 m0, s64
	ds_read_b128 v[180:183], v191 offset:49152
	v_xor_b32_e32 v253, 64, v191
	ds_read_b128 v[194:197], v253 offset:49152
	ds_read_b128 v[198:201], v191 offset:51200
	ds_read_b128 v[202:205], v253 offset:51200
	ds_read_b128 v[206:209], v191 offset:53248
	ds_read_b128 v[210:213], v253 offset:53248
	ds_read_b128 v[214:217], v191 offset:55296
	ds_read_b128 v[218:221], v253 offset:55296
	global_load_lds_dwordx4 v[222:223], off
	s_add_i32 m0, s64, 0x2000
	s_add_u32 s62, s62, 0x80080
	v_lshl_add_u64 v[222:223], v[224:225], 0, s[26:27]
	s_addc_u32 s63, s63, 0
	s_add_i32 s64, s85, s69
	global_load_lds_dwordx4 v[222:223], off
	v_lshl_add_u64 v[222:223], s[62:63], 0, v[154:155]
	s_mov_b32 m0, s64
	s_nop 0
	global_load_lds_dwordx4 v[222:223], off
	v_lshl_add_u64 v[222:223], s[62:63], 0, v[162:163]
	s_add_i32 m0, s64, 0x2000
	s_nop 0
	global_load_lds_dwordx4 v[222:223], off
	v_lshl_add_u64 v[222:223], v[226:227], 0, s[26:27]
	s_mov_b32 m0, s3
	s_nop 0
	global_load_lds_dwordx4 v[222:223], off
	v_lshl_add_u64 v[222:223], v[228:229], 0, s[26:27]
	s_mov_b32 m0, s75
	s_nop 0
	global_load_lds_dwordx4 v[222:223], off
	s_waitcnt vmcnt(8)
	s_waitcnt lgkmcnt(0)
	s_setprio 1
	s_barrier
	v_mfma_f32_16x16x32_bf16 v[60:63], v[128:131], v[180:183], v[60:63]
	v_mfma_f32_16x16x32_bf16 v[60:63], v[132:135], v[194:197], v[60:63]
	v_mfma_f32_16x16x32_bf16 v[44:47], v[132:135], v[202:205], v[44:47]
	v_mfma_f32_16x16x32_bf16 v[44:47], v[128:131], v[198:201], v[44:47]
	v_mfma_f32_16x16x32_bf16 v[28:31], v[128:131], v[206:209], v[28:31]
	v_mfma_f32_16x16x32_bf16 v[28:31], v[132:135], v[210:213], v[28:31]
	v_mfma_f32_16x16x32_bf16 v[12:15], v[132:135], v[218:221], v[12:15]
	v_mfma_f32_16x16x32_bf16 v[12:15], v[128:131], v[214:217], v[12:15]
	v_mfma_f32_16x16x32_bf16 v[8:11], v[136:139], v[214:217], v[8:11]
	v_mfma_f32_16x16x32_bf16 v[8:11], v[140:143], v[218:221], v[8:11]
	v_mfma_f32_16x16x32_bf16 v[24:27], v[140:143], v[210:213], v[24:27]
	v_mfma_f32_16x16x32_bf16 v[24:27], v[136:139], v[206:209], v[24:27]
	v_mfma_f32_16x16x32_bf16 v[40:43], v[136:139], v[198:201], v[40:43]
	v_mfma_f32_16x16x32_bf16 v[40:43], v[140:143], v[202:205], v[40:43]
	v_mfma_f32_16x16x32_bf16 v[56:59], v[140:143], v[194:197], v[56:59]
	v_mfma_f32_16x16x32_bf16 v[56:59], v[136:139], v[180:183], v[56:59]
	s_setprio 0
	s_setprio 1
	v_mfma_f32_16x16x32_bf16 v[48:51], v[172:175], v[180:183], v[48:51]
	v_mfma_f32_16x16x32_bf16 v[48:51], v[176:179], v[194:197], v[48:51]
	v_mfma_f32_16x16x32_bf16 v[32:35], v[176:179], v[202:205], v[32:35]
	v_mfma_f32_16x16x32_bf16 v[32:35], v[172:175], v[198:201], v[32:35]
	v_mfma_f32_16x16x32_bf16 v[16:19], v[172:175], v[206:209], v[16:19]
	v_mfma_f32_16x16x32_bf16 v[16:19], v[176:179], v[210:213], v[16:19]
	v_mfma_f32_16x16x32_bf16 v[0:3], v[176:179], v[218:221], v[0:3]
	v_mfma_f32_16x16x32_bf16 v[0:3], v[172:175], v[214:217], v[0:3]
	v_mfma_f32_16x16x32_bf16 v[4:7], v[144:147], v[214:217], v[4:7]
	v_mfma_f32_16x16x32_bf16 v[4:7], v[148:151], v[218:221], v[4:7]
	v_mfma_f32_16x16x32_bf16 v[20:23], v[148:151], v[210:213], v[20:23]
	v_mfma_f32_16x16x32_bf16 v[20:23], v[144:147], v[206:209], v[20:23]
	v_mfma_f32_16x16x32_bf16 v[36:39], v[144:147], v[198:201], v[36:39]
	v_mfma_f32_16x16x32_bf16 v[36:39], v[148:151], v[202:205], v[36:39]
	v_mfma_f32_16x16x32_bf16 v[52:55], v[148:151], v[194:197], v[52:55]
	v_mfma_f32_16x16x32_bf16 v[52:55], v[144:147], v[180:183], v[52:55]
	s_barrier
	s_setprio 0
	s_add_i32 s83, s83, 2
	s_add_u32 s81, s81, 0x100
	s_addc_u32 s82, s82, 0
	s_add_u32 s60, s60, 0x100
	s_addc_u32 s61, s61, 0
	s_cmp_gt_u32 s83, 29
	s_cbranch_scc0 .LBB0_440
	s_and_b64 vcc, exec, s[28:29]
	s_cbranch_vccz .LBB0_443
	s_barrier

.LBB0_525:
	s_ashr_i32 s29, s28, 31
	s_lshl_b64 s[30:31], s[28:29], 19
	s_add_u32 s30, s3, s30
	s_addc_u32 s31, s35, s31
	s_and_b64 s[44:45], s[10:11], exec
	s_cselect_b32 s29, s31, s51
	s_cselect_b32 s70, s30, s50
	s_ashr_i32 s27, s26, 31
	s_lshl_b64 s[44:45], s[26:27], 19
	s_add_u32 s44, s52, s44
	s_addc_u32 s45, s53, s45
	s_and_b64 s[72:73], s[10:11], exec
	s_cselect_b32 s71, s45, s49
	s_cselect_b32 s72, s44, s48
	s_lshl_b32 s27, s46, 8
	v_add_u32_e32 v0, s27, v148
	s_add_u32 s73, s48, 0x100
	v_ashrrev_i32_e32 v1, 31, v0
	s_addc_u32 s74, s49, 0
	v_lshl_add_u64 v[144:145], v[0:1], 4, s[16:17]
	s_add_u32 s46, s50, 0x40080
	s_addc_u32 s47, s51, 0
	s_mov_b32 s75, -2
	s_mov_b64 s[48:49], 0
	s_cmp_eq_u32 s61, 1
	s_cbranch_scc1 .Lfa_4
	v_add_u32_e32 v153, s66, v147
	ds_read_b128 v[160:163], v153
	v_xor_b32_e32 v253, 64, v153
	ds_read_b128 v[164:167], v253
	ds_read_b128 v[168:171], v153 offset:2048
	ds_read_b128 v[172:175], v253 offset:2048
	v_add_u32_e32 v153, s67, v147
	ds_read_b128 v[176:179], v153
	v_xor_b32_e32 v253, 64, v153
	ds_read_b128 v[180:183], v253
	ds_read_b128 v[186:189], v153 offset:2048
	ds_read_b128 v[190:193], v253 offset:2048
	s_add_u32 s50, s46, 0xfffc0080
	s_addc_u32 s51, s47, -1
	s_and_b64 s[48:49], s[48:49], exec
	s_cselect_b32 s51, s29, s51
	s_cselect_b32 s50, s70, s50
	s_cselect_b32 s49, s71, s74
	s_cselect_b32 s48, s72, s73
	v_lshl_add_u64 v[154:155], s[46:47], 0, v[138:139]
	s_add_i32 m0, s57, 0xc000
	ds_read_b128 v[194:197], v150
	v_xor_b32_e32 v253, 64, v150
	ds_read_b128 v[198:201], v253
	ds_read_b128 v[202:205], v150 offset:2048
	ds_read_b128 v[206:209], v253 offset:2048
	ds_read_b128 v[210:213], v150 offset:4096
	ds_read_b128 v[214:217], v253 offset:4096
	ds_read_b128 v[218:221], v150 offset:6144
	ds_read_b128 v[222:225], v253 offset:6144
	global_load_lds_dwordx4 v[154:155], off
	v_lshl_add_u64 v[154:155], s[46:47], 0, v[136:137]
	s_add_i32 m0, s57, 0xe000
	s_nop 0
	global_load_lds_dwordx4 v[154:155], off
	s_waitcnt vmcnt(16)
	s_waitcnt lgkmcnt(0)
	s_setprio 1
	s_barrier
	v_mfma_f32_16x16x32_bf16 v[124:127], v[160:163], v[194:197], 0
	v_mfma_f32_16x16x32_bf16 v[116:119], v[168:171], v[194:197], 0
	v_mfma_f32_16x16x32_bf16 v[108:111], v[160:163], v[202:205], 0
	v_mfma_f32_16x16x32_bf16 v[100:103], v[168:171], v[202:205], 0
	v_mfma_f32_16x16x32_bf16 v[92:95], v[160:163], v[210:213], 0
	v_mfma_f32_16x16x32_bf16 v[84:87], v[168:171], v[210:213], 0
	v_mfma_f32_16x16x32_bf16 v[76:79], v[160:163], v[218:221], 0
	v_mfma_f32_16x16x32_bf16 v[68:71], v[168:171], v[218:221], 0
	v_mfma_f32_16x16x32_bf16 v[124:127], v[164:167], v[198:201], v[124:127]
	v_mfma_f32_16x16x32_bf16 v[116:119], v[172:175], v[198:201], v[116:119]
	v_mfma_f32_16x16x32_bf16 v[108:111], v[164:167], v[206:209], v[108:111]
	v_mfma_f32_16x16x32_bf16 v[100:103], v[172:175], v[206:209], v[100:103]
	v_mfma_f32_16x16x32_bf16 v[92:95], v[164:167], v[214:217], v[92:95]
	v_mfma_f32_16x16x32_bf16 v[84:87], v[172:175], v[214:217], v[84:87]
	v_mfma_f32_16x16x32_bf16 v[76:79], v[164:167], v[222:225], v[76:79]
	v_mfma_f32_16x16x32_bf16 v[68:71], v[172:175], v[222:225], v[68:71]
	s_setprio 0
	s_setprio 1
	v_mfma_f32_16x16x32_bf16 v[120:123], v[176:179], v[194:197], 0
	v_mfma_f32_16x16x32_bf16 v[112:115], v[186:189], v[194:197], 0
	v_mfma_f32_16x16x32_bf16 v[104:107], v[176:179], v[202:205], 0
	v_mfma_f32_16x16x32_bf16 v[96:99], v[186:189], v[202:205], 0
	v_mfma_f32_16x16x32_bf16 v[88:91], v[176:179], v[210:213], 0
	v_mfma_f32_16x16x32_bf16 v[80:83], v[186:189], v[210:213], 0
	v_mfma_f32_16x16x32_bf16 v[72:75], v[176:179], v[218:221], 0
	v_mfma_f32_16x16x32_bf16 v[64:67], v[186:189], v[218:221], 0
	v_mfma_f32_16x16x32_bf16 v[120:123], v[180:183], v[198:201], v[120:123]
	v_mfma_f32_16x16x32_bf16 v[112:115], v[190:193], v[198:201], v[112:115]
	v_mfma_f32_16x16x32_bf16 v[104:107], v[180:183], v[206:209], v[104:107]
	v_mfma_f32_16x16x32_bf16 v[96:99], v[190:193], v[206:209], v[96:99]
	v_mfma_f32_16x16x32_bf16 v[88:91], v[180:183], v[214:217], v[88:91]
	v_mfma_f32_16x16x32_bf16 v[80:83], v[190:193], v[214:217], v[80:83]
	v_mfma_f32_16x16x32_bf16 v[72:75], v[180:183], v[222:225], v[72:75]
	v_mfma_f32_16x16x32_bf16 v[64:67], v[190:193], v[222:225], v[64:67]
	s_barrier
	s_setprio 0
	s_add_i32 s76, s66, s54
	v_lshl_add_u64 v[154:155], s[48:49], 0, v[132:133]
	s_mov_b32 m0, s76
	ds_read_b128 v[194:197], v150 offset:16384
	v_xor_b32_e32 v253, 64, v150
	ds_read_b128 v[198:201], v253 offset:16384
	ds_read_b128 v[202:205], v150 offset:18432
	ds_read_b128 v[206:209], v253 offset:18432
	ds_read_b128 v[210:213], v150 offset:20480
	ds_read_b128 v[214:217], v253 offset:20480
	ds_read_b128 v[218:221], v150 offset:22528
	ds_read_b128 v[222:225], v253 offset:22528
	global_load_lds_dwordx4 v[154:155], off
	s_add_i32 m0, s76, 0x2000
	s_add_u32 s76, s48, 0x40000
	v_lshl_add_u64 v[226:227], s[48:49], 0, v[128:129]
	s_addc_u32 s77, s49, 0
	s_add_i32 s78, s67, s54
	global_load_lds_dwordx4 v[226:227], off
	v_lshl_add_u64 v[228:229], s[76:77], 0, v[132:133]
	s_mov_b32 m0, s78
	v_lshl_add_u64 v[230:231], s[50:51], 0, v[130:131]
	global_load_lds_dwordx4 v[228:229], off
	v_lshl_add_u64 v[228:229], s[76:77], 0, v[128:129]
	s_add_i32 m0, s78, 0x2000
	s_nop 0
	global_load_lds_dwordx4 v[228:229], off
	v_lshl_add_u64 v[228:229], s[50:51], 0, v[134:135]
	s_mov_b32 m0, s57
	s_nop 0
	global_load_lds_dwordx4 v[228:229], off
	s_mov_b32 m0, s58
	s_nop 0
	global_load_lds_dwordx4 v[230:231], off
	s_waitcnt vmcnt(16)
	s_waitcnt lgkmcnt(0)
	s_setprio 1
	s_barrier
	v_mfma_f32_16x16x32_bf16 v[60:63], v[160:163], v[194:197], 0
	v_mfma_f32_16x16x32_bf16 v[52:55], v[168:171], v[194:197], 0
	v_mfma_f32_16x16x32_bf16 v[44:47], v[160:163], v[202:205], 0
	v_mfma_f32_16x16x32_bf16 v[36:39], v[168:171], v[202:205], 0
	v_mfma_f32_16x16x32_bf16 v[28:31], v[160:163], v[210:213], 0
	v_mfma_f32_16x16x32_bf16 v[20:23], v[168:171], v[210:213], 0
	v_mfma_f32_16x16x32_bf16 v[12:15], v[160:163], v[218:221], 0
	v_mfma_f32_16x16x32_bf16 v[4:7], v[168:171], v[218:221], 0
	v_mfma_f32_16x16x32_bf16 v[60:63], v[164:167], v[198:201], v[60:63]
	v_mfma_f32_16x16x32_bf16 v[52:55], v[172:175], v[198:201], v[52:55]
	v_mfma_f32_16x16x32_bf16 v[44:47], v[164:167], v[206:209], v[44:47]
	v_mfma_f32_16x16x32_bf16 v[36:39], v[172:175], v[206:209], v[36:39]
	v_mfma_f32_16x16x32_bf16 v[28:31], v[164:167], v[214:217], v[28:31]
	v_mfma_f32_16x16x32_bf16 v[20:23], v[172:175], v[214:217], v[20:23]
	v_mfma_f32_16x16x32_bf16 v[12:15], v[164:167], v[222:225], v[12:15]
	v_mfma_f32_16x16x32_bf16 v[4:7], v[172:175], v[222:225], v[4:7]
	s_setprio 0
	s_setprio 1
	v_mfma_f32_16x16x32_bf16 v[56:59], v[176:179], v[194:197], 0
	v_mfma_f32_16x16x32_bf16 v[48:51], v[186:189], v[194:197], 0
	v_mfma_f32_16x16x32_bf16 v[40:43], v[176:179], v[202:205], 0
	v_mfma_f32_16x16x32_bf16 v[32:35], v[186:189], v[202:205], 0
	v_mfma_f32_16x16x32_bf16 v[24:27], v[176:179], v[210:213], 0
	v_mfma_f32_16x16x32_bf16 v[16:19], v[186:189], v[210:213], 0
	v_mfma_f32_16x16x32_bf16 v[8:11], v[176:179], v[218:221], 0
	v_mfma_f32_16x16x32_bf16 v[0:3], v[186:189], v[218:221], 0
	v_mfma_f32_16x16x32_bf16 v[56:59], v[180:183], v[198:201], v[56:59]
	v_mfma_f32_16x16x32_bf16 v[48:51], v[190:193], v[198:201], v[48:51]
	v_mfma_f32_16x16x32_bf16 v[40:43], v[180:183], v[206:209], v[40:43]
	v_mfma_f32_16x16x32_bf16 v[32:35], v[190:193], v[206:209], v[32:35]
	v_mfma_f32_16x16x32_bf16 v[24:27], v[180:183], v[214:217], v[24:27]
	v_mfma_f32_16x16x32_bf16 v[16:19], v[190:193], v[214:217], v[16:19]
	v_mfma_f32_16x16x32_bf16 v[8:11], v[180:183], v[222:225], v[8:11]
	v_mfma_f32_16x16x32_bf16 v[0:3], v[190:193], v[222:225], v[0:3]
	s_barrier
	s_setprio 0
	s_add_i32 s76, 0, 0x18000
	v_add_u32_e32 v153, s76, v147
	s_add_i32 s77, 0, 0x1c000
	ds_read_b128 v[160:163], v153
	v_xor_b32_e32 v253, 64, v153
	ds_read_b128 v[164:167], v253
	ds_read_b128 v[168:171], v153 offset:2048
	ds_read_b128 v[172:175], v253 offset:2048
	v_add_u32_e32 v153, s77, v147
	ds_read_b128 v[176:179], v153
	v_xor_b32_e32 v253, 64, v153
	ds_read_b128 v[180:183], v253
	ds_read_b128 v[186:189], v153 offset:2048
	ds_read_b128 v[190:193], v253 offset:2048
	s_add_u32 s50, s50, 0x40000
	s_addc_u32 s51, s51, 0
	s_mov_b32 m0, s59
	v_lshl_add_u64 v[232:233], s[50:51], 0, v[134:135]
	ds_read_b128 v[194:197], v150 offset:32768
	v_xor_b32_e32 v253, 64, v150
	ds_read_b128 v[198:201], v253 offset:32768
	ds_read_b128 v[202:205], v150 offset:34816
	ds_read_b128 v[206:209], v253 offset:34816
	ds_read_b128 v[210:213], v150 offset:36864
	ds_read_b128 v[214:217], v253 offset:36864
	ds_read_b128 v[218:221], v150 offset:38912
	ds_read_b128 v[222:225], v253 offset:38912
	global_load_lds_dwordx4 v[232:233], off
	v_lshl_add_u64 v[232:233], s[50:51], 0, v[130:131]
	s_mov_b32 m0, s60
	s_nop 0
	global_load_lds_dwordx4 v[232:233], off
	s_waitcnt vmcnt(8)
	s_waitcnt lgkmcnt(0)
	s_setprio 1
	s_barrier
	v_mfma_f32_16x16x32_bf16 v[124:127], v[160:163], v[194:197], v[124:127]
	v_mfma_f32_16x16x32_bf16 v[124:127], v[164:167], v[198:201], v[124:127]
	v_mfma_f32_16x16x32_bf16 v[108:111], v[164:167], v[206:209], v[108:111]
	v_mfma_f32_16x16x32_bf16 v[108:111], v[160:163], v[202:205], v[108:111]
	v_mfma_f32_16x16x32_bf16 v[92:95], v[160:163], v[210:213], v[92:95]
	v_mfma_f32_16x16x32_bf16 v[92:95], v[164:167], v[214:217], v[92:95]
	v_mfma_f32_16x16x32_bf16 v[76:79], v[164:167], v[222:225], v[76:79]
	v_mfma_f32_16x16x32_bf16 v[76:79], v[160:163], v[218:221], v[76:79]
	v_mfma_f32_16x16x32_bf16 v[68:71], v[168:171], v[218:221], v[68:71]
	v_mfma_f32_16x16x32_bf16 v[68:71], v[172:175], v[222:225], v[68:71]
	v_mfma_f32_16x16x32_bf16 v[84:87], v[172:175], v[214:217], v[84:87]
	v_mfma_f32_16x16x32_bf16 v[84:87], v[168:171], v[210:213], v[84:87]
	v_mfma_f32_16x16x32_bf16 v[100:103], v[168:171], v[202:205], v[100:103]
	v_mfma_f32_16x16x32_bf16 v[100:103], v[172:175], v[206:209], v[100:103]
	v_mfma_f32_16x16x32_bf16 v[116:119], v[172:175], v[198:201], v[116:119]
	v_mfma_f32_16x16x32_bf16 v[116:119], v[168:171], v[194:197], v[116:119]
	s_setprio 0
	s_setprio 1
	v_mfma_f32_16x16x32_bf16 v[112:115], v[186:189], v[194:197], v[112:115]
	v_mfma_f32_16x16x32_bf16 v[112:115], v[190:193], v[198:201], v[112:115]
	v_mfma_f32_16x16x32_bf16 v[96:99], v[190:193], v[206:209], v[96:99]
	v_mfma_f32_16x16x32_bf16 v[96:99], v[186:189], v[202:205], v[96:99]
	v_mfma_f32_16x16x32_bf16 v[80:83], v[186:189], v[210:213], v[80:83]
	v_mfma_f32_16x16x32_bf16 v[80:83], v[190:193], v[214:217], v[80:83]
	v_mfma_f32_16x16x32_bf16 v[64:67], v[190:193], v[222:225], v[64:67]
	v_mfma_f32_16x16x32_bf16 v[64:67], v[186:189], v[218:221], v[64:67]
	v_mfma_f32_16x16x32_bf16 v[72:75], v[176:179], v[218:221], v[72:75]
	v_mfma_f32_16x16x32_bf16 v[72:75], v[180:183], v[222:225], v[72:75]
	v_mfma_f32_16x16x32_bf16 v[88:91], v[180:183], v[214:217], v[88:91]
	v_mfma_f32_16x16x32_bf16 v[88:91], v[176:179], v[210:213], v[88:91]
	v_mfma_f32_16x16x32_bf16 v[104:107], v[176:179], v[202:205], v[104:107]
	v_mfma_f32_16x16x32_bf16 v[104:107], v[180:183], v[206:209], v[104:107]
	v_mfma_f32_16x16x32_bf16 v[120:123], v[180:183], v[198:201], v[120:123]
	v_mfma_f32_16x16x32_bf16 v[120:123], v[176:179], v[194:197], v[120:123]
	s_barrier
	s_setprio 0
	s_add_i32 s50, s76, s54
	v_lshl_add_u64 v[154:155], v[154:155], 0, s[20:21]
	s_mov_b32 m0, s50
	ds_read_b128 v[194:197], v150 offset:49152
	v_xor_b32_e32 v253, 64, v150
	ds_read_b128 v[198:201], v253 offset:49152
	ds_read_b128 v[202:205], v150 offset:51200
	ds_read_b128 v[206:209], v253 offset:51200
	ds_read_b128 v[210:213], v150 offset:53248
	ds_read_b128 v[214:217], v253 offset:53248
	ds_read_b128 v[218:221], v150 offset:55296
	ds_read_b128 v[222:225], v253 offset:55296
	global_load_lds_dwordx4 v[154:155], off
	s_add_i32 m0, s50, 0x2000
	s_add_u32 s48, s48, 0x40080
	v_lshl_add_u64 v[154:155], v[226:227], 0, s[20:21]
	s_addc_u32 s49, s49, 0
	s_add_i32 s50, s77, s54
	global_load_lds_dwordx4 v[154:155], off
	v_lshl_add_u64 v[154:155], s[48:49], 0, v[132:133]
	s_mov_b32 m0, s50
	s_nop 0
	global_load_lds_dwordx4 v[154:155], off
	v_lshl_add_u64 v[154:155], s[48:49], 0, v[128:129]
	s_add_i32 m0, s50, 0x2000
	s_nop 0
	global_load_lds_dwordx4 v[154:155], off
	v_lshl_add_u64 v[154:155], v[228:229], 0, s[20:21]
	s_mov_b32 m0, s62
	s_nop 0
	global_load_lds_dwordx4 v[154:155], off
	v_lshl_add_u64 v[154:155], v[230:231], 0, s[20:21]
	s_mov_b32 m0, s63
	s_nop 0
	global_load_lds_dwordx4 v[154:155], off
	s_waitcnt vmcnt(8)
	s_waitcnt lgkmcnt(0)
	s_setprio 1
	s_barrier
	v_mfma_f32_16x16x32_bf16 v[60:63], v[160:163], v[194:197], v[60:63]
	v_mfma_f32_16x16x32_bf16 v[60:63], v[164:167], v[198:201], v[60:63]
	v_mfma_f32_16x16x32_bf16 v[44:47], v[164:167], v[206:209], v[44:47]
	v_mfma_f32_16x16x32_bf16 v[44:47], v[160:163], v[202:205], v[44:47]
	v_mfma_f32_16x16x32_bf16 v[28:31], v[160:163], v[210:213], v[28:31]
	v_mfma_f32_16x16x32_bf16 v[28:31], v[164:167], v[214:217], v[28:31]
	v_mfma_f32_16x16x32_bf16 v[12:15], v[164:167], v[222:225], v[12:15]
	v_mfma_f32_16x16x32_bf16 v[12:15], v[160:163], v[218:221], v[12:15]
	v_mfma_f32_16x16x32_bf16 v[4:7], v[168:171], v[218:221], v[4:7]
	v_mfma_f32_16x16x32_bf16 v[4:7], v[172:175], v[222:225], v[4:7]
	v_mfma_f32_16x16x32_bf16 v[20:23], v[172:175], v[214:217], v[20:23]
	v_mfma_f32_16x16x32_bf16 v[20:23], v[168:171], v[210:213], v[20:23]
	v_mfma_f32_16x16x32_bf16 v[36:39], v[168:171], v[202:205], v[36:39]
	v_mfma_f32_16x16x32_bf16 v[36:39], v[172:175], v[206:209], v[36:39]
	v_mfma_f32_16x16x32_bf16 v[52:55], v[172:175], v[198:201], v[52:55]
	v_mfma_f32_16x16x32_bf16 v[52:55], v[168:171], v[194:197], v[52:55]
	s_setprio 0
	s_setprio 1
	v_mfma_f32_16x16x32_bf16 v[48:51], v[186:189], v[194:197], v[48:51]
	v_mfma_f32_16x16x32_bf16 v[48:51], v[190:193], v[198:201], v[48:51]
	v_mfma_f32_16x16x32_bf16 v[32:35], v[190:193], v[206:209], v[32:35]
	v_mfma_f32_16x16x32_bf16 v[32:35], v[186:189], v[202:205], v[32:35]
	v_mfma_f32_16x16x32_bf16 v[16:19], v[186:189], v[210:213], v[16:19]
	v_mfma_f32_16x16x32_bf16 v[16:19], v[190:193], v[214:217], v[16:19]
	v_mfma_f32_16x16x32_bf16 v[0:3], v[190:193], v[222:225], v[0:3]
	v_mfma_f32_16x16x32_bf16 v[0:3], v[186:189], v[218:221], v[0:3]
	v_mfma_f32_16x16x32_bf16 v[8:11], v[176:179], v[218:221], v[8:11]
	v_mfma_f32_16x16x32_bf16 v[8:11], v[180:183], v[222:225], v[8:11]
	v_mfma_f32_16x16x32_bf16 v[24:27], v[180:183], v[214:217], v[24:27]
	v_mfma_f32_16x16x32_bf16 v[24:27], v[176:179], v[210:213], v[24:27]
	v_mfma_f32_16x16x32_bf16 v[40:43], v[176:179], v[202:205], v[40:43]
	v_mfma_f32_16x16x32_bf16 v[40:43], v[180:183], v[206:209], v[40:43]
	v_mfma_f32_16x16x32_bf16 v[56:59], v[180:183], v[198:201], v[56:59]
	v_mfma_f32_16x16x32_bf16 v[56:59], v[176:179], v[194:197], v[56:59]
	s_barrier
	s_setprio 0
	s_add_i32 s75, s75, 2
	s_add_u32 s73, s73, 0x100
	s_addc_u32 s74, s74, 0
	s_add_u32 s46, s46, 0x100
	s_addc_u32 s47, s47, 0
	s_branch .LBB0_527
.Lfa_4:
	v_add_u32_e32 v153, s66, v147
	ds_read_b128 v[160:163], v153
	v_xor_b32_e32 v253, 64, v153
	ds_read_b128 v[164:167], v253
	ds_read_b128 v[168:171], v153 offset:2048
	ds_read_b128 v[172:175], v253 offset:2048
	v_add_u32_e32 v153, s67, v147
	ds_read_b128 v[176:179], v153
	v_xor_b32_e32 v253, 64, v153
	ds_read_b128 v[180:183], v253
	ds_read_b128 v[186:189], v153 offset:2048
	ds_read_b128 v[190:193], v253 offset:2048
	s_add_u32 s50, s46, 0xfffc0080
	s_addc_u32 s51, s47, -1
	s_and_b64 s[48:49], s[48:49], exec
	s_cselect_b32 s51, s29, s51
	s_cselect_b32 s50, s70, s50
	s_cselect_b32 s49, s71, s74
	s_cselect_b32 s48, s72, s73
	v_lshl_add_u64 v[154:155], s[46:47], 0, v[138:139]
	s_add_i32 m0, s57, 0xc000
	ds_read_b128 v[194:197], v150
	v_xor_b32_e32 v253, 64, v150
	ds_read_b128 v[198:201], v253
	ds_read_b128 v[202:205], v150 offset:2048
	ds_read_b128 v[206:209], v253 offset:2048
	ds_read_b128 v[210:213], v150 offset:4096
	ds_read_b128 v[214:217], v253 offset:4096
	ds_read_b128 v[218:221], v150 offset:6144
	ds_read_b128 v[222:225], v253 offset:6144
	global_load_lds_dwordx4 v[154:155], off
	v_lshl_add_u64 v[154:155], s[46:47], 0, v[136:137]
	s_add_i32 m0, s57, 0xe000
	s_nop 0
	global_load_lds_dwordx4 v[154:155], off
	s_waitcnt vmcnt(8)
	s_waitcnt lgkmcnt(0)
	s_setprio 1
	s_barrier
	v_mfma_f32_16x16x32_bf16 v[124:127], v[160:163], v[194:197], 0
	v_mfma_f32_16x16x32_bf16 v[116:119], v[168:171], v[194:197], 0
	v_mfma_f32_16x16x32_bf16 v[108:111], v[160:163], v[202:205], 0
	v_mfma_f32_16x16x32_bf16 v[100:103], v[168:171], v[202:205], 0
	v_mfma_f32_16x16x32_bf16 v[92:95], v[160:163], v[210:213], 0
	v_mfma_f32_16x16x32_bf16 v[84:87], v[168:171], v[210:213], 0
	v_mfma_f32_16x16x32_bf16 v[76:79], v[160:163], v[218:221], 0
	v_mfma_f32_16x16x32_bf16 v[68:71], v[168:171], v[218:221], 0
	v_mfma_f32_16x16x32_bf16 v[124:127], v[164:167], v[198:201], v[124:127]
	v_mfma_f32_16x16x32_bf16 v[116:119], v[172:175], v[198:201], v[116:119]
	v_mfma_f32_16x16x32_bf16 v[108:111], v[164:167], v[206:209], v[108:111]
	v_mfma_f32_16x16x32_bf16 v[100:103], v[172:175], v[206:209], v[100:103]
	v_mfma_f32_16x16x32_bf16 v[92:95], v[164:167], v[214:217], v[92:95]
	v_mfma_f32_16x16x32_bf16 v[84:87], v[172:175], v[214:217], v[84:87]
	v_mfma_f32_16x16x32_bf16 v[76:79], v[164:167], v[222:225], v[76:79]
	v_mfma_f32_16x16x32_bf16 v[68:71], v[172:175], v[222:225], v[68:71]
	s_setprio 0
	s_setprio 1
	v_mfma_f32_16x16x32_bf16 v[120:123], v[176:179], v[194:197], 0
	v_mfma_f32_16x16x32_bf16 v[112:115], v[186:189], v[194:197], 0
	v_mfma_f32_16x16x32_bf16 v[104:107], v[176:179], v[202:205], 0
	v_mfma_f32_16x16x32_bf16 v[96:99], v[186:189], v[202:205], 0
	v_mfma_f32_16x16x32_bf16 v[88:91], v[176:179], v[210:213], 0
	v_mfma_f32_16x16x32_bf16 v[80:83], v[186:189], v[210:213], 0
	v_mfma_f32_16x16x32_bf16 v[72:75], v[176:179], v[218:221], 0
	v_mfma_f32_16x16x32_bf16 v[64:67], v[186:189], v[218:221], 0
	v_mfma_f32_16x16x32_bf16 v[120:123], v[180:183], v[198:201], v[120:123]
	v_mfma_f32_16x16x32_bf16 v[112:115], v[190:193], v[198:201], v[112:115]
	v_mfma_f32_16x16x32_bf16 v[104:107], v[180:183], v[206:209], v[104:107]
	v_mfma_f32_16x16x32_bf16 v[96:99], v[190:193], v[206:209], v[96:99]
	v_mfma_f32_16x16x32_bf16 v[88:91], v[180:183], v[214:217], v[88:91]
	v_mfma_f32_16x16x32_bf16 v[80:83], v[190:193], v[214:217], v[80:83]
	v_mfma_f32_16x16x32_bf16 v[72:75], v[180:183], v[222:225], v[72:75]
	v_mfma_f32_16x16x32_bf16 v[64:67], v[190:193], v[222:225], v[64:67]
	s_barrier
	s_setprio 0
	s_add_i32 s76, s66, s54
	v_lshl_add_u64 v[154:155], s[48:49], 0, v[132:133]
	s_mov_b32 m0, s76
	ds_read_b128 v[194:197], v150 offset:16384
	v_xor_b32_e32 v253, 64, v150
	ds_read_b128 v[198:201], v253 offset:16384
	ds_read_b128 v[202:205], v150 offset:18432
	ds_read_b128 v[206:209], v253 offset:18432
	ds_read_b128 v[210:213], v150 offset:20480
	ds_read_b128 v[214:217], v253 offset:20480
	ds_read_b128 v[218:221], v150 offset:22528
	ds_read_b128 v[222:225], v253 offset:22528
	global_load_lds_dwordx4 v[154:155], off
	s_add_i32 m0, s76, 0x2000
	s_add_u32 s76, s48, 0x40000
	v_lshl_add_u64 v[226:227], s[48:49], 0, v[128:129]
	s_addc_u32 s77, s49, 0
	s_add_i32 s78, s67, s54
	global_load_lds_dwordx4 v[226:227], off
	v_lshl_add_u64 v[228:229], s[76:77], 0, v[132:133]
	s_mov_b32 m0, s78
	v_lshl_add_u64 v[230:231], s[50:51], 0, v[130:131]
	global_load_lds_dwordx4 v[228:229], off
	v_lshl_add_u64 v[228:229], s[76:77], 0, v[128:129]
	s_add_i32 m0, s78, 0x2000
	s_nop 0
	global_load_lds_dwordx4 v[228:229], off
	v_lshl_add_u64 v[228:229], s[50:51], 0, v[134:135]
	s_mov_b32 m0, s57
	s_nop 0
	global_load_lds_dwordx4 v[228:229], off
	s_mov_b32 m0, s58
	s_nop 0
	global_load_lds_dwordx4 v[230:231], off
	s_waitcnt vmcnt(8)
	s_waitcnt lgkmcnt(0)
	s_setprio 1
	s_barrier
	v_mfma_f32_16x16x32_bf16 v[60:63], v[160:163], v[194:197], 0
	v_mfma_f32_16x16x32_bf16 v[52:55], v[168:171], v[194:197], 0
	v_mfma_f32_16x16x32_bf16 v[44:47], v[160:163], v[202:205], 0
	v_mfma_f32_16x16x32_bf16 v[36:39], v[168:171], v[202:205], 0
	v_mfma_f32_16x16x32_bf16 v[28:31], v[160:163], v[210:213], 0
	v_mfma_f32_16x16x32_bf16 v[20:23], v[168:171], v[210:213], 0
	v_mfma_f32_16x16x32_bf16 v[12:15], v[160:163], v[218:221], 0
	v_mfma_f32_16x16x32_bf16 v[4:7], v[168:171], v[218:221], 0
	v_mfma_f32_16x16x32_bf16 v[60:63], v[164:167], v[198:201], v[60:63]
	v_mfma_f32_16x16x32_bf16 v[52:55], v[172:175], v[198:201], v[52:55]
	v_mfma_f32_16x16x32_bf16 v[44:47], v[164:167], v[206:209], v[44:47]
	v_mfma_f32_16x16x32_bf16 v[36:39], v[172:175], v[206:209], v[36:39]
	v_mfma_f32_16x16x32_bf16 v[28:31], v[164:167], v[214:217], v[28:31]
	v_mfma_f32_16x16x32_bf16 v[20:23], v[172:175], v[214:217], v[20:23]
	v_mfma_f32_16x16x32_bf16 v[12:15], v[164:167], v[222:225], v[12:15]
	v_mfma_f32_16x16x32_bf16 v[4:7], v[172:175], v[222:225], v[4:7]
	s_setprio 0
	s_setprio 1
	v_mfma_f32_16x16x32_bf16 v[56:59], v[176:179], v[194:197], 0
	v_mfma_f32_16x16x32_bf16 v[48:51], v[186:189], v[194:197], 0
	v_mfma_f32_16x16x32_bf16 v[40:43], v[176:179], v[202:205], 0
	v_mfma_f32_16x16x32_bf16 v[32:35], v[186:189], v[202:205], 0
	v_mfma_f32_16x16x32_bf16 v[24:27], v[176:179], v[210:213], 0
	v_mfma_f32_16x16x32_bf16 v[16:19], v[186:189], v[210:213], 0
	v_mfma_f32_16x16x32_bf16 v[8:11], v[176:179], v[218:221], 0
	v_mfma_f32_16x16x32_bf16 v[0:3], v[186:189], v[218:221], 0
	v_mfma_f32_16x16x32_bf16 v[56:59], v[180:183], v[198:201], v[56:59]
	v_mfma_f32_16x16x32_bf16 v[48:51], v[190:193], v[198:201], v[48:51]
	v_mfma_f32_16x16x32_bf16 v[40:43], v[180:183], v[206:209], v[40:43]
	v_mfma_f32_16x16x32_bf16 v[32:35], v[190:193], v[206:209], v[32:35]
	v_mfma_f32_16x16x32_bf16 v[24:27], v[180:183], v[214:217], v[24:27]
	v_mfma_f32_16x16x32_bf16 v[16:19], v[190:193], v[214:217], v[16:19]
	v_mfma_f32_16x16x32_bf16 v[8:11], v[180:183], v[222:225], v[8:11]
	v_mfma_f32_16x16x32_bf16 v[0:3], v[190:193], v[222:225], v[0:3]
	s_barrier
	s_setprio 0
	s_add_i32 s76, 0, 0x18000
	v_add_u32_e32 v153, s76, v147
	s_add_i32 s77, 0, 0x1c000
	ds_read_b128 v[160:163], v153
	v_xor_b32_e32 v253, 64, v153
	ds_read_b128 v[164:167], v253
	ds_read_b128 v[168:171], v153 offset:2048
	ds_read_b128 v[172:175], v253 offset:2048
	v_add_u32_e32 v153, s77, v147
	ds_read_b128 v[176:179], v153
	v_xor_b32_e32 v253, 64, v153
	ds_read_b128 v[180:183], v253
	ds_read_b128 v[186:189], v153 offset:2048
	ds_read_b128 v[190:193], v253 offset:2048
	s_add_u32 s50, s50, 0x40000
	s_addc_u32 s51, s51, 0
	s_mov_b32 m0, s59
	v_lshl_add_u64 v[232:233], s[50:51], 0, v[134:135]
	ds_read_b128 v[194:197], v150 offset:32768
	v_xor_b32_e32 v253, 64, v150
	ds_read_b128 v[198:201], v253 offset:32768
	ds_read_b128 v[202:205], v150 offset:34816
	ds_read_b128 v[206:209], v253 offset:34816
	ds_read_b128 v[210:213], v150 offset:36864
	ds_read_b128 v[214:217], v253 offset:36864
	ds_read_b128 v[218:221], v150 offset:38912
	ds_read_b128 v[222:225], v253 offset:38912
	global_load_lds_dwordx4 v[232:233], off
	v_lshl_add_u64 v[232:233], s[50:51], 0, v[130:131]
	s_mov_b32 m0, s60
	s_nop 0
	global_load_lds_dwordx4 v[232:233], off
	s_waitcnt vmcnt(8)
	s_waitcnt lgkmcnt(0)
	s_setprio 1
	s_barrier
	v_mfma_f32_16x16x32_bf16 v[124:127], v[160:163], v[194:197], v[124:127]
	v_mfma_f32_16x16x32_bf16 v[124:127], v[164:167], v[198:201], v[124:127]
	v_mfma_f32_16x16x32_bf16 v[108:111], v[164:167], v[206:209], v[108:111]
	v_mfma_f32_16x16x32_bf16 v[108:111], v[160:163], v[202:205], v[108:111]
	v_mfma_f32_16x16x32_bf16 v[92:95], v[160:163], v[210:213], v[92:95]
	v_mfma_f32_16x16x32_bf16 v[92:95], v[164:167], v[214:217], v[92:95]
	v_mfma_f32_16x16x32_bf16 v[76:79], v[164:167], v[222:225], v[76:79]
	v_mfma_f32_16x16x32_bf16 v[76:79], v[160:163], v[218:221], v[76:79]
	v_mfma_f32_16x16x32_bf16 v[68:71], v[168:171], v[218:221], v[68:71]
	v_mfma_f32_16x16x32_bf16 v[68:71], v[172:175], v[222:225], v[68:71]
	v_mfma_f32_16x16x32_bf16 v[84:87], v[172:175], v[214:217], v[84:87]
	v_mfma_f32_16x16x32_bf16 v[84:87], v[168:171], v[210:213], v[84:87]
	v_mfma_f32_16x16x32_bf16 v[100:103], v[168:171], v[202:205], v[100:103]
	v_mfma_f32_16x16x32_bf16 v[100:103], v[172:175], v[206:209], v[100:103]
	v_mfma_f32_16x16x32_bf16 v[116:119], v[172:175], v[198:201], v[116:119]
	v_mfma_f32_16x16x32_bf16 v[116:119], v[168:171], v[194:197], v[116:119]
	s_setprio 0
	s_setprio 1
	v_mfma_f32_16x16x32_bf16 v[112:115], v[186:189], v[194:197], v[112:115]
	v_mfma_f32_16x16x32_bf16 v[112:115], v[190:193], v[198:201], v[112:115]
	v_mfma_f32_16x16x32_bf16 v[96:99], v[190:193], v[206:209], v[96:99]
	v_mfma_f32_16x16x32_bf16 v[96:99], v[186:189], v[202:205], v[96:99]
	v_mfma_f32_16x16x32_bf16 v[80:83], v[186:189], v[210:213], v[80:83]
	v_mfma_f32_16x16x32_bf16 v[80:83], v[190:193], v[214:217], v[80:83]
	v_mfma_f32_16x16x32_bf16 v[64:67], v[190:193], v[222:225], v[64:67]
	v_mfma_f32_16x16x32_bf16 v[64:67], v[186:189], v[218:221], v[64:67]
	v_mfma_f32_16x16x32_bf16 v[72:75], v[176:179], v[218:221], v[72:75]
	v_mfma_f32_16x16x32_bf16 v[72:75], v[180:183], v[222:225], v[72:75]
	v_mfma_f32_16x16x32_bf16 v[88:91], v[180:183], v[214:217], v[88:91]
	v_mfma_f32_16x16x32_bf16 v[88:91], v[176:179], v[210:213], v[88:91]
	v_mfma_f32_16x16x32_bf16 v[104:107], v[176:179], v[202:205], v[104:107]
	v_mfma_f32_16x16x32_bf16 v[104:107], v[180:183], v[206:209], v[104:107]
	v_mfma_f32_16x16x32_bf16 v[120:123], v[180:183], v[198:201], v[120:123]
	v_mfma_f32_16x16x32_bf16 v[120:123], v[176:179], v[194:197], v[120:123]
	s_barrier
	s_setprio 0
	s_add_i32 s50, s76, s54
	v_lshl_add_u64 v[154:155], v[154:155], 0, s[20:21]
	s_mov_b32 m0, s50
	ds_read_b128 v[194:197], v150 offset:49152
	v_xor_b32_e32 v253, 64, v150
	ds_read_b128 v[198:201], v253 offset:49152
	ds_read_b128 v[202:205], v150 offset:51200
	ds_read_b128 v[206:209], v253 offset:51200
	ds_read_b128 v[210:213], v150 offset:53248
	ds_read_b128 v[214:217], v253 offset:53248
	ds_read_b128 v[218:221], v150 offset:55296
	ds_read_b128 v[222:225], v253 offset:55296
	global_load_lds_dwordx4 v[154:155], off
	s_add_i32 m0, s50, 0x2000
	s_add_u32 s48, s48, 0x40080
	v_lshl_add_u64 v[154:155], v[226:227], 0, s[20:21]
	s_addc_u32 s49, s49, 0
	s_add_i32 s50, s77, s54
	global_load_lds_dwordx4 v[154:155], off
	v_lshl_add_u64 v[154:155], s[48:49], 0, v[132:133]
	s_mov_b32 m0, s50
	s_nop 0
	global_load_lds_dwordx4 v[154:155], off
	v_lshl_add_u64 v[154:155], s[48:49], 0, v[128:129]
	s_add_i32 m0, s50, 0x2000
	s_nop 0
	global_load_lds_dwordx4 v[154:155], off
	v_lshl_add_u64 v[154:155], v[228:229], 0, s[20:21]
	s_mov_b32 m0, s62
	s_nop 0
	global_load_lds_dwordx4 v[154:155], off
	v_lshl_add_u64 v[154:155], v[230:231], 0, s[20:21]
	s_mov_b32 m0, s63
	s_nop 0
	global_load_lds_dwordx4 v[154:155], off
	s_waitcnt vmcnt(8)
	s_waitcnt lgkmcnt(0)
	s_setprio 1
	s_barrier
	v_mfma_f32_16x16x32_bf16 v[60:63], v[160:163], v[194:197], v[60:63]
	v_mfma_f32_16x16x32_bf16 v[60:63], v[164:167], v[198:201], v[60:63]
	v_mfma_f32_16x16x32_bf16 v[44:47], v[164:167], v[206:209], v[44:47]
	v_mfma_f32_16x16x32_bf16 v[44:47], v[160:163], v[202:205], v[44:47]
	v_mfma_f32_16x16x32_bf16 v[28:31], v[160:163], v[210:213], v[28:31]
	v_mfma_f32_16x16x32_bf16 v[28:31], v[164:167], v[214:217], v[28:31]
	v_mfma_f32_16x16x32_bf16 v[12:15], v[164:167], v[222:225], v[12:15]
	v_mfma_f32_16x16x32_bf16 v[12:15], v[160:163], v[218:221], v[12:15]
	v_mfma_f32_16x16x32_bf16 v[4:7], v[168:171], v[218:221], v[4:7]
	v_mfma_f32_16x16x32_bf16 v[4:7], v[172:175], v[222:225], v[4:7]
	v_mfma_f32_16x16x32_bf16 v[20:23], v[172:175], v[214:217], v[20:23]
	v_mfma_f32_16x16x32_bf16 v[20:23], v[168:171], v[210:213], v[20:23]
	v_mfma_f32_16x16x32_bf16 v[36:39], v[168:171], v[202:205], v[36:39]
	v_mfma_f32_16x16x32_bf16 v[36:39], v[172:175], v[206:209], v[36:39]
	v_mfma_f32_16x16x32_bf16 v[52:55], v[172:175], v[198:201], v[52:55]
	v_mfma_f32_16x16x32_bf16 v[52:55], v[168:171], v[194:197], v[52:55]
	s_setprio 0
	s_setprio 1
	v_mfma_f32_16x16x32_bf16 v[48:51], v[186:189], v[194:197], v[48:51]
	v_mfma_f32_16x16x32_bf16 v[48:51], v[190:193], v[198:201], v[48:51]
	v_mfma_f32_16x16x32_bf16 v[32:35], v[190:193], v[206:209], v[32:35]
	v_mfma_f32_16x16x32_bf16 v[32:35], v[186:189], v[202:205], v[32:35]
	v_mfma_f32_16x16x32_bf16 v[16:19], v[186:189], v[210:213], v[16:19]
	v_mfma_f32_16x16x32_bf16 v[16:19], v[190:193], v[214:217], v[16:19]
	v_mfma_f32_16x16x32_bf16 v[0:3], v[190:193], v[222:225], v[0:3]
	v_mfma_f32_16x16x32_bf16 v[0:3], v[186:189], v[218:221], v[0:3]
	v_mfma_f32_16x16x32_bf16 v[8:11], v[176:179], v[218:221], v[8:11]
	v_mfma_f32_16x16x32_bf16 v[8:11], v[180:183], v[222:225], v[8:11]
	v_mfma_f32_16x16x32_bf16 v[24:27], v[180:183], v[214:217], v[24:27]
	v_mfma_f32_16x16x32_bf16 v[24:27], v[176:179], v[210:213], v[24:27]
	v_mfma_f32_16x16x32_bf16 v[40:43], v[176:179], v[202:205], v[40:43]
	v_mfma_f32_16x16x32_bf16 v[40:43], v[180:183], v[206:209], v[40:43]
	v_mfma_f32_16x16x32_bf16 v[56:59], v[180:183], v[198:201], v[56:59]
	v_mfma_f32_16x16x32_bf16 v[56:59], v[176:179], v[194:197], v[56:59]
	s_barrier
	s_setprio 0
	s_add_i32 s75, s75, 2
	s_add_u32 s73, s73, 0x100
	s_addc_u32 s74, s74, 0
	s_add_u32 s46, s46, 0x100
	s_addc_u32 s47, s47, 0
	s_branch .LBB0_527
.LBB0_526:
	v_add_u32_e32 v153, s66, v147
	ds_read_b128 v[160:163], v153
	v_xor_b32_e32 v253, 64, v153
	ds_read_b128 v[164:167], v253
	ds_read_b128 v[168:171], v153 offset:2048
	ds_read_b128 v[172:175], v253 offset:2048
	v_add_u32_e32 v153, s67, v147
	ds_read_b128 v[176:179], v153
	v_xor_b32_e32 v253, 64, v153
	ds_read_b128 v[180:183], v253
	ds_read_b128 v[186:189], v153 offset:2048
	ds_read_b128 v[190:193], v253 offset:2048
	s_add_u32 s50, s46, 0xfffc0080
	s_addc_u32 s51, s47, -1
	s_and_b64 s[48:49], s[48:49], exec
	s_cselect_b32 s51, s29, s51
	s_cselect_b32 s50, s70, s50
	s_cselect_b32 s49, s71, s74
	s_cselect_b32 s48, s72, s73
	v_lshl_add_u64 v[154:155], s[46:47], 0, v[138:139]
	s_add_i32 m0, s57, 0xc000
	ds_read_b128 v[194:197], v150
	v_xor_b32_e32 v253, 64, v150
	ds_read_b128 v[198:201], v253
	ds_read_b128 v[202:205], v150 offset:2048
	ds_read_b128 v[206:209], v253 offset:2048
	ds_read_b128 v[210:213], v150 offset:4096
	ds_read_b128 v[214:217], v253 offset:4096
	ds_read_b128 v[218:221], v150 offset:6144
	ds_read_b128 v[222:225], v253 offset:6144
	global_load_lds_dwordx4 v[154:155], off
	v_lshl_add_u64 v[154:155], s[46:47], 0, v[136:137]
	s_add_i32 m0, s57, 0xe000
	s_nop 0
	global_load_lds_dwordx4 v[154:155], off
	s_waitcnt vmcnt(8)
	s_waitcnt lgkmcnt(0)
	s_setprio 1
	s_barrier
	v_mfma_f32_16x16x32_bf16 v[124:127], v[160:163], v[194:197], v[124:127]
	v_mfma_f32_16x16x32_bf16 v[124:127], v[164:167], v[198:201], v[124:127]
	v_mfma_f32_16x16x32_bf16 v[108:111], v[164:167], v[206:209], v[108:111]
	v_mfma_f32_16x16x32_bf16 v[108:111], v[160:163], v[202:205], v[108:111]
	v_mfma_f32_16x16x32_bf16 v[92:95], v[160:163], v[210:213], v[92:95]
	v_mfma_f32_16x16x32_bf16 v[92:95], v[164:167], v[214:217], v[92:95]
	v_mfma_f32_16x16x32_bf16 v[76:79], v[164:167], v[222:225], v[76:79]
	v_mfma_f32_16x16x32_bf16 v[76:79], v[160:163], v[218:221], v[76:79]
	v_mfma_f32_16x16x32_bf16 v[68:71], v[168:171], v[218:221], v[68:71]
	v_mfma_f32_16x16x32_bf16 v[68:71], v[172:175], v[222:225], v[68:71]
	v_mfma_f32_16x16x32_bf16 v[84:87], v[172:175], v[214:217], v[84:87]
	v_mfma_f32_16x16x32_bf16 v[84:87], v[168:171], v[210:213], v[84:87]
	v_mfma_f32_16x16x32_bf16 v[100:103], v[168:171], v[202:205], v[100:103]
	v_mfma_f32_16x16x32_bf16 v[100:103], v[172:175], v[206:209], v[100:103]
	v_mfma_f32_16x16x32_bf16 v[116:119], v[172:175], v[198:201], v[116:119]
	v_mfma_f32_16x16x32_bf16 v[116:119], v[168:171], v[194:197], v[116:119]
	s_setprio 0
	s_setprio 1
	v_mfma_f32_16x16x32_bf16 v[112:115], v[186:189], v[194:197], v[112:115]
	v_mfma_f32_16x16x32_bf16 v[112:115], v[190:193], v[198:201], v[112:115]
	v_mfma_f32_16x16x32_bf16 v[96:99], v[190:193], v[206:209], v[96:99]
	v_mfma_f32_16x16x32_bf16 v[96:99], v[186:189], v[202:205], v[96:99]
	v_mfma_f32_16x16x32_bf16 v[80:83], v[186:189], v[210:213], v[80:83]
	v_mfma_f32_16x16x32_bf16 v[80:83], v[190:193], v[214:217], v[80:83]
	v_mfma_f32_16x16x32_bf16 v[64:67], v[190:193], v[222:225], v[64:67]
	v_mfma_f32_16x16x32_bf16 v[64:67], v[186:189], v[218:221], v[64:67]
	v_mfma_f32_16x16x32_bf16 v[72:75], v[176:179], v[218:221], v[72:75]
	v_mfma_f32_16x16x32_bf16 v[72:75], v[180:183], v[222:225], v[72:75]
	v_mfma_f32_16x16x32_bf16 v[88:91], v[180:183], v[214:217], v[88:91]
	v_mfma_f32_16x16x32_bf16 v[88:91], v[176:179], v[210:213], v[88:91]
	v_mfma_f32_16x16x32_bf16 v[104:107], v[176:179], v[202:205], v[104:107]
	v_mfma_f32_16x16x32_bf16 v[104:107], v[180:183], v[206:209], v[104:107]
	v_mfma_f32_16x16x32_bf16 v[120:123], v[180:183], v[198:201], v[120:123]
	v_mfma_f32_16x16x32_bf16 v[120:123], v[176:179], v[194:197], v[120:123]
	s_barrier
	s_setprio 0
	s_add_i32 s76, s66, s54
	v_lshl_add_u64 v[154:155], s[48:49], 0, v[132:133]
	s_mov_b32 m0, s76
	ds_read_b128 v[194:197], v150 offset:16384
	v_xor_b32_e32 v253, 64, v150
	ds_read_b128 v[198:201], v253 offset:16384
	ds_read_b128 v[202:205], v150 offset:18432
	ds_read_b128 v[206:209], v253 offset:18432
	ds_read_b128 v[210:213], v150 offset:20480
	ds_read_b128 v[214:217], v253 offset:20480
	ds_read_b128 v[218:221], v150 offset:22528
	ds_read_b128 v[222:225], v253 offset:22528
	global_load_lds_dwordx4 v[154:155], off
	s_add_i32 m0, s76, 0x2000
	s_add_u32 s76, s48, 0x40000
	v_lshl_add_u64 v[226:227], s[48:49], 0, v[128:129]
	s_addc_u32 s77, s49, 0
	s_add_i32 s78, s67, s54
	global_load_lds_dwordx4 v[226:227], off
	v_lshl_add_u64 v[228:229], s[76:77], 0, v[132:133]
	s_mov_b32 m0, s78
	v_lshl_add_u64 v[230:231], s[50:51], 0, v[130:131]
	global_load_lds_dwordx4 v[228:229], off
	v_lshl_add_u64 v[228:229], s[76:77], 0, v[128:129]
	s_add_i32 m0, s78, 0x2000
	s_nop 0
	global_load_lds_dwordx4 v[228:229], off
	v_lshl_add_u64 v[228:229], s[50:51], 0, v[134:135]
	s_mov_b32 m0, s57
	s_nop 0
	global_load_lds_dwordx4 v[228:229], off
	s_mov_b32 m0, s58
	s_nop 0
	global_load_lds_dwordx4 v[230:231], off
	s_waitcnt vmcnt(8)
	s_waitcnt lgkmcnt(0)
	s_setprio 1
	s_barrier
	v_mfma_f32_16x16x32_bf16 v[60:63], v[160:163], v[194:197], v[60:63]
	v_mfma_f32_16x16x32_bf16 v[60:63], v[164:167], v[198:201], v[60:63]
	v_mfma_f32_16x16x32_bf16 v[44:47], v[164:167], v[206:209], v[44:47]
	v_mfma_f32_16x16x32_bf16 v[44:47], v[160:163], v[202:205], v[44:47]
	v_mfma_f32_16x16x32_bf16 v[28:31], v[160:163], v[210:213], v[28:31]
	v_mfma_f32_16x16x32_bf16 v[28:31], v[164:167], v[214:217], v[28:31]
	v_mfma_f32_16x16x32_bf16 v[12:15], v[164:167], v[222:225], v[12:15]
	v_mfma_f32_16x16x32_bf16 v[12:15], v[160:163], v[218:221], v[12:15]
	v_mfma_f32_16x16x32_bf16 v[4:7], v[168:171], v[218:221], v[4:7]
	v_mfma_f32_16x16x32_bf16 v[4:7], v[172:175], v[222:225], v[4:7]
	v_mfma_f32_16x16x32_bf16 v[20:23], v[172:175], v[214:217], v[20:23]
	v_mfma_f32_16x16x32_bf16 v[20:23], v[168:171], v[210:213], v[20:23]
	v_mfma_f32_16x16x32_bf16 v[36:39], v[168:171], v[202:205], v[36:39]
	v_mfma_f32_16x16x32_bf16 v[36:39], v[172:175], v[206:209], v[36:39]
	v_mfma_f32_16x16x32_bf16 v[52:55], v[172:175], v[198:201], v[52:55]
	v_mfma_f32_16x16x32_bf16 v[52:55], v[168:171], v[194:197], v[52:55]
	s_setprio 0
	s_setprio 1
	v_mfma_f32_16x16x32_bf16 v[48:51], v[186:189], v[194:197], v[48:51]
	v_mfma_f32_16x16x32_bf16 v[48:51], v[190:193], v[198:201], v[48:51]
	v_mfma_f32_16x16x32_bf16 v[32:35], v[190:193], v[206:209], v[32:35]
	v_mfma_f32_16x16x32_bf16 v[32:35], v[186:189], v[202:205], v[32:35]
	v_mfma_f32_16x16x32_bf16 v[16:19], v[186:189], v[210:213], v[16:19]
	v_mfma_f32_16x16x32_bf16 v[16:19], v[190:193], v[214:217], v[16:19]
	v_mfma_f32_16x16x32_bf16 v[0:3], v[190:193], v[222:225], v[0:3]
	v_mfma_f32_16x16x32_bf16 v[0:3], v[186:189], v[218:221], v[0:3]
	v_mfma_f32_16x16x32_bf16 v[8:11], v[176:179], v[218:221], v[8:11]
	v_mfma_f32_16x16x32_bf16 v[8:11], v[180:183], v[222:225], v[8:11]
	v_mfma_f32_16x16x32_bf16 v[24:27], v[180:183], v[214:217], v[24:27]
	v_mfma_f32_16x16x32_bf16 v[24:27], v[176:179], v[210:213], v[24:27]
	v_mfma_f32_16x16x32_bf16 v[40:43], v[176:179], v[202:205], v[40:43]
	v_mfma_f32_16x16x32_bf16 v[40:43], v[180:183], v[206:209], v[40:43]
	v_mfma_f32_16x16x32_bf16 v[56:59], v[180:183], v[198:201], v[56:59]
	v_mfma_f32_16x16x32_bf16 v[56:59], v[176:179], v[194:197], v[56:59]
	s_barrier
	s_setprio 0
	s_add_i32 s76, 0, 0x18000
	v_add_u32_e32 v153, s76, v147
	s_add_i32 s77, 0, 0x1c000
	ds_read_b128 v[160:163], v153
	v_xor_b32_e32 v253, 64, v153
	ds_read_b128 v[164:167], v253
	ds_read_b128 v[168:171], v153 offset:2048
	ds_read_b128 v[172:175], v253 offset:2048
	v_add_u32_e32 v153, s77, v147
	ds_read_b128 v[176:179], v153
	v_xor_b32_e32 v253, 64, v153
	ds_read_b128 v[180:183], v253
	ds_read_b128 v[186:189], v153 offset:2048
	ds_read_b128 v[190:193], v253 offset:2048
	s_add_u32 s50, s50, 0x40000
	s_addc_u32 s51, s51, 0
	s_mov_b32 m0, s59
	v_lshl_add_u64 v[232:233], s[50:51], 0, v[134:135]
	ds_read_b128 v[194:197], v150 offset:32768
	v_xor_b32_e32 v253, 64, v150
	ds_read_b128 v[198:201], v253 offset:32768
	ds_read_b128 v[202:205], v150 offset:34816
	ds_read_b128 v[206:209], v253 offset:34816
	ds_read_b128 v[210:213], v150 offset:36864
	ds_read_b128 v[214:217], v253 offset:36864
	ds_read_b128 v[218:221], v150 offset:38912
	ds_read_b128 v[222:225], v253 offset:38912
	global_load_lds_dwordx4 v[232:233], off
	v_lshl_add_u64 v[232:233], s[50:51], 0, v[130:131]
	s_mov_b32 m0, s60
	s_nop 0
	global_load_lds_dwordx4 v[232:233], off
	s_waitcnt vmcnt(8)
	s_waitcnt lgkmcnt(0)
	s_setprio 1
	s_barrier
	v_mfma_f32_16x16x32_bf16 v[124:127], v[160:163], v[194:197], v[124:127]
	v_mfma_f32_16x16x32_bf16 v[124:127], v[164:167], v[198:201], v[124:127]
	v_mfma_f32_16x16x32_bf16 v[108:111], v[164:167], v[206:209], v[108:111]
	v_mfma_f32_16x16x32_bf16 v[108:111], v[160:163], v[202:205], v[108:111]
	v_mfma_f32_16x16x32_bf16 v[92:95], v[160:163], v[210:213], v[92:95]
	v_mfma_f32_16x16x32_bf16 v[92:95], v[164:167], v[214:217], v[92:95]
	v_mfma_f32_16x16x32_bf16 v[76:79], v[164:167], v[222:225], v[76:79]
	v_mfma_f32_16x16x32_bf16 v[76:79], v[160:163], v[218:221], v[76:79]
	v_mfma_f32_16x16x32_bf16 v[68:71], v[168:171], v[218:221], v[68:71]
	v_mfma_f32_16x16x32_bf16 v[68:71], v[172:175], v[222:225], v[68:71]
	v_mfma_f32_16x16x32_bf16 v[84:87], v[172:175], v[214:217], v[84:87]
	v_mfma_f32_16x16x32_bf16 v[84:87], v[168:171], v[210:213], v[84:87]
	v_mfma_f32_16x16x32_bf16 v[100:103], v[168:171], v[202:205], v[100:103]
	v_mfma_f32_16x16x32_bf16 v[100:103], v[172:175], v[206:209], v[100:103]
	v_mfma_f32_16x16x32_bf16 v[116:119], v[172:175], v[198:201], v[116:119]
	v_mfma_f32_16x16x32_bf16 v[116:119], v[168:171], v[194:197], v[116:119]
	s_setprio 0
	s_setprio 1
	v_mfma_f32_16x16x32_bf16 v[112:115], v[186:189], v[194:197], v[112:115]
	v_mfma_f32_16x16x32_bf16 v[112:115], v[190:193], v[198:201], v[112:115]
	v_mfma_f32_16x16x32_bf16 v[96:99], v[190:193], v[206:209], v[96:99]
	v_mfma_f32_16x16x32_bf16 v[96:99], v[186:189], v[202:205], v[96:99]
	v_mfma_f32_16x16x32_bf16 v[80:83], v[186:189], v[210:213], v[80:83]
	v_mfma_f32_16x16x32_bf16 v[80:83], v[190:193], v[214:217], v[80:83]
	v_mfma_f32_16x16x32_bf16 v[64:67], v[190:193], v[222:225], v[64:67]
	v_mfma_f32_16x16x32_bf16 v[64:67], v[186:189], v[218:221], v[64:67]
	v_mfma_f32_16x16x32_bf16 v[72:75], v[176:179], v[218:221], v[72:75]
	v_mfma_f32_16x16x32_bf16 v[72:75], v[180:183], v[222:225], v[72:75]
	v_mfma_f32_16x16x32_bf16 v[88:91], v[180:183], v[214:217], v[88:91]
	v_mfma_f32_16x16x32_bf16 v[88:91], v[176:179], v[210:213], v[88:91]
	v_mfma_f32_16x16x32_bf16 v[104:107], v[176:179], v[202:205], v[104:107]
	v_mfma_f32_16x16x32_bf16 v[104:107], v[180:183], v[206:209], v[104:107]
	v_mfma_f32_16x16x32_bf16 v[120:123], v[180:183], v[198:201], v[120:123]
	v_mfma_f32_16x16x32_bf16 v[120:123], v[176:179], v[194:197], v[120:123]
	s_barrier
	s_setprio 0
	s_add_i32 s50, s76, s54
	v_lshl_add_u64 v[154:155], v[154:155], 0, s[20:21]
	s_mov_b32 m0, s50
	ds_read_b128 v[194:197], v150 offset:49152
	v_xor_b32_e32 v253, 64, v150
	ds_read_b128 v[198:201], v253 offset:49152
	ds_read_b128 v[202:205], v150 offset:51200
	ds_read_b128 v[206:209], v253 offset:51200
	ds_read_b128 v[210:213], v150 offset:53248
	ds_read_b128 v[214:217], v253 offset:53248
	ds_read_b128 v[218:221], v150 offset:55296
	ds_read_b128 v[222:225], v253 offset:55296
	global_load_lds_dwordx4 v[154:155], off
	s_add_i32 m0, s50, 0x2000
	s_add_u32 s48, s48, 0x40080
	v_lshl_add_u64 v[154:155], v[226:227], 0, s[20:21]
	s_addc_u32 s49, s49, 0
	s_add_i32 s50, s77, s54
	global_load_lds_dwordx4 v[154:155], off
	v_lshl_add_u64 v[154:155], s[48:49], 0, v[132:133]
	s_mov_b32 m0, s50
	s_nop 0
	global_load_lds_dwordx4 v[154:155], off
	v_lshl_add_u64 v[154:155], s[48:49], 0, v[128:129]
	s_add_i32 m0, s50, 0x2000
	s_nop 0
	global_load_lds_dwordx4 v[154:155], off
	v_lshl_add_u64 v[154:155], v[228:229], 0, s[20:21]
	s_mov_b32 m0, s62
	s_nop 0
	global_load_lds_dwordx4 v[154:155], off
	v_lshl_add_u64 v[154:155], v[230:231], 0, s[20:21]
	s_mov_b32 m0, s63
	s_nop 0
	global_load_lds_dwordx4 v[154:155], off
	s_waitcnt vmcnt(8)
	s_waitcnt lgkmcnt(0)
	s_setprio 1
	s_barrier
	v_mfma_f32_16x16x32_bf16 v[60:63], v[160:163], v[194:197], v[60:63]
	v_mfma_f32_16x16x32_bf16 v[60:63], v[164:167], v[198:201], v[60:63]
	v_mfma_f32_16x16x32_bf16 v[44:47], v[164:167], v[206:209], v[44:47]
	v_mfma_f32_16x16x32_bf16 v[44:47], v[160:163], v[202:205], v[44:47]
	v_mfma_f32_16x16x32_bf16 v[28:31], v[160:163], v[210:213], v[28:31]
	v_mfma_f32_16x16x32_bf16 v[28:31], v[164:167], v[214:217], v[28:31]
	v_mfma_f32_16x16x32_bf16 v[12:15], v[164:167], v[222:225], v[12:15]
	v_mfma_f32_16x16x32_bf16 v[12:15], v[160:163], v[218:221], v[12:15]
	v_mfma_f32_16x16x32_bf16 v[4:7], v[168:171], v[218:221], v[4:7]
	v_mfma_f32_16x16x32_bf16 v[4:7], v[172:175], v[222:225], v[4:7]
	v_mfma_f32_16x16x32_bf16 v[20:23], v[172:175], v[214:217], v[20:23]
	v_mfma_f32_16x16x32_bf16 v[20:23], v[168:171], v[210:213], v[20:23]
	v_mfma_f32_16x16x32_bf16 v[36:39], v[168:171], v[202:205], v[36:39]
	v_mfma_f32_16x16x32_bf16 v[36:39], v[172:175], v[206:209], v[36:39]
	v_mfma_f32_16x16x32_bf16 v[52:55], v[172:175], v[198:201], v[52:55]
	v_mfma_f32_16x16x32_bf16 v[52:55], v[168:171], v[194:197], v[52:55]
	s_setprio 0
	s_setprio 1
	v_mfma_f32_16x16x32_bf16 v[48:51], v[186:189], v[194:197], v[48:51]
	v_mfma_f32_16x16x32_bf16 v[48:51], v[190:193], v[198:201], v[48:51]
	v_mfma_f32_16x16x32_bf16 v[32:35], v[190:193], v[206:209], v[32:35]
	v_mfma_f32_16x16x32_bf16 v[32:35], v[186:189], v[202:205], v[32:35]
	v_mfma_f32_16x16x32_bf16 v[16:19], v[186:189], v[210:213], v[16:19]
	v_mfma_f32_16x16x32_bf16 v[16:19], v[190:193], v[214:217], v[16:19]
	v_mfma_f32_16x16x32_bf16 v[0:3], v[190:193], v[222:225], v[0:3]
	v_mfma_f32_16x16x32_bf16 v[0:3], v[186:189], v[218:221], v[0:3]
	v_mfma_f32_16x16x32_bf16 v[8:11], v[176:179], v[218:221], v[8:11]
	v_mfma_f32_16x16x32_bf16 v[8:11], v[180:183], v[222:225], v[8:11]
	v_mfma_f32_16x16x32_bf16 v[24:27], v[180:183], v[214:217], v[24:27]
	v_mfma_f32_16x16x32_bf16 v[24:27], v[176:179], v[210:213], v[24:27]
	v_mfma_f32_16x16x32_bf16 v[40:43], v[176:179], v[202:205], v[40:43]
	v_mfma_f32_16x16x32_bf16 v[40:43], v[180:183], v[206:209], v[40:43]
	v_mfma_f32_16x16x32_bf16 v[56:59], v[180:183], v[198:201], v[56:59]
	v_mfma_f32_16x16x32_bf16 v[56:59], v[176:179], v[194:197], v[56:59]
	s_barrier
	s_setprio 0
	s_add_i32 s75, s75, 2
	s_add_u32 s73, s73, 0x100
	s_addc_u32 s74, s74, 0
	s_add_u32 s46, s46, 0x100
	s_addc_u32 s47, s47, 0
	s_cmp_gt_u32 s75, 13
	s_cbranch_scc1 .LBB0_529

.Llast_4:
	v_add_u32_e32 v153, s66, v147
	ds_read_b128 v[160:163], v153
	v_xor_b32_e32 v253, 64, v153
	ds_read_b128 v[164:167], v253
	ds_read_b128 v[168:171], v153 offset:2048
	ds_read_b128 v[172:175], v253 offset:2048
	v_add_u32_e32 v153, s67, v147
	ds_read_b128 v[176:179], v153
	v_xor_b32_e32 v253, 64, v153
	ds_read_b128 v[180:183], v253
	ds_read_b128 v[186:189], v153 offset:2048
	ds_read_b128 v[190:193], v253 offset:2048
	s_add_u32 s50, s46, 0xfffc0080
	s_addc_u32 s51, s47, -1
	s_and_b64 s[48:49], s[48:49], exec
	s_cselect_b32 s51, s29, s51
	s_cselect_b32 s50, s70, s50
	s_cselect_b32 s49, s71, s74
	s_cselect_b32 s48, s72, s73
	v_lshl_add_u64 v[154:155], s[46:47], 0, v[138:139]
	s_add_i32 m0, s57, 0xc000
	ds_read_b128 v[194:197], v150
	v_xor_b32_e32 v253, 64, v150
	ds_read_b128 v[198:201], v253
	ds_read_b128 v[202:205], v150 offset:2048
	ds_read_b128 v[206:209], v253 offset:2048
	ds_read_b128 v[210:213], v150 offset:4096
	ds_read_b128 v[214:217], v253 offset:4096
	ds_read_b128 v[218:221], v150 offset:6144
	ds_read_b128 v[222:225], v253 offset:6144
	global_load_lds_dwordx4 v[154:155], off
	v_lshl_add_u64 v[154:155], s[46:47], 0, v[136:137]
	s_add_i32 m0, s57, 0xe000
	s_nop 0
	global_load_lds_dwordx4 v[154:155], off
	s_waitcnt vmcnt(8)
	s_waitcnt lgkmcnt(0)
	s_setprio 1
	s_barrier
	v_mfma_f32_16x16x32_bf16 v[124:127], v[160:163], v[194:197], v[124:127]
	v_mfma_f32_16x16x32_bf16 v[124:127], v[164:167], v[198:201], v[124:127]
	v_mfma_f32_16x16x32_bf16 v[108:111], v[164:167], v[206:209], v[108:111]
	v_mfma_f32_16x16x32_bf16 v[108:111], v[160:163], v[202:205], v[108:111]
	v_mfma_f32_16x16x32_bf16 v[92:95], v[160:163], v[210:213], v[92:95]
	v_mfma_f32_16x16x32_bf16 v[92:95], v[164:167], v[214:217], v[92:95]
	v_mfma_f32_16x16x32_bf16 v[76:79], v[164:167], v[222:225], v[76:79]
	v_mfma_f32_16x16x32_bf16 v[76:79], v[160:163], v[218:221], v[76:79]
	v_mfma_f32_16x16x32_bf16 v[68:71], v[168:171], v[218:221], v[68:71]
	v_mfma_f32_16x16x32_bf16 v[68:71], v[172:175], v[222:225], v[68:71]
	v_mfma_f32_16x16x32_bf16 v[84:87], v[172:175], v[214:217], v[84:87]
	v_mfma_f32_16x16x32_bf16 v[84:87], v[168:171], v[210:213], v[84:87]
	v_mfma_f32_16x16x32_bf16 v[100:103], v[168:171], v[202:205], v[100:103]
	v_mfma_f32_16x16x32_bf16 v[100:103], v[172:175], v[206:209], v[100:103]
	v_mfma_f32_16x16x32_bf16 v[116:119], v[172:175], v[198:201], v[116:119]
	v_mfma_f32_16x16x32_bf16 v[116:119], v[168:171], v[194:197], v[116:119]
	s_setprio 0
	s_setprio 1
	v_mfma_f32_16x16x32_bf16 v[112:115], v[186:189], v[194:197], v[112:115]
	v_mfma_f32_16x16x32_bf16 v[112:115], v[190:193], v[198:201], v[112:115]
	v_mfma_f32_16x16x32_bf16 v[96:99], v[190:193], v[206:209], v[96:99]
	v_mfma_f32_16x16x32_bf16 v[96:99], v[186:189], v[202:205], v[96:99]
	v_mfma_f32_16x16x32_bf16 v[80:83], v[186:189], v[210:213], v[80:83]
	v_mfma_f32_16x16x32_bf16 v[80:83], v[190:193], v[214:217], v[80:83]
	v_mfma_f32_16x16x32_bf16 v[64:67], v[190:193], v[222:225], v[64:67]
	v_mfma_f32_16x16x32_bf16 v[64:67], v[186:189], v[218:221], v[64:67]
	v_mfma_f32_16x16x32_bf16 v[72:75], v[176:179], v[218:221], v[72:75]
	v_mfma_f32_16x16x32_bf16 v[72:75], v[180:183], v[222:225], v[72:75]
	v_mfma_f32_16x16x32_bf16 v[88:91], v[180:183], v[214:217], v[88:91]
	v_mfma_f32_16x16x32_bf16 v[88:91], v[176:179], v[210:213], v[88:91]
	v_mfma_f32_16x16x32_bf16 v[104:107], v[176:179], v[202:205], v[104:107]
	v_mfma_f32_16x16x32_bf16 v[104:107], v[180:183], v[206:209], v[104:107]
	v_mfma_f32_16x16x32_bf16 v[120:123], v[180:183], v[198:201], v[120:123]
	v_mfma_f32_16x16x32_bf16 v[120:123], v[176:179], v[194:197], v[120:123]
	s_barrier
	s_setprio 0
	s_add_i32 s76, s66, s54
	v_lshl_add_u64 v[154:155], s[48:49], 0, v[132:133]
	s_mov_b32 m0, s76
	ds_read_b128 v[194:197], v150 offset:16384
	v_xor_b32_e32 v253, 64, v150
	ds_read_b128 v[198:201], v253 offset:16384
	ds_read_b128 v[202:205], v150 offset:18432
	ds_read_b128 v[206:209], v253 offset:18432
	ds_read_b128 v[210:213], v150 offset:20480
	ds_read_b128 v[214:217], v253 offset:20480
	ds_read_b128 v[218:221], v150 offset:22528
	ds_read_b128 v[222:225], v253 offset:22528
	global_load_lds_dwordx4 v[154:155], off
	s_add_i32 m0, s76, 0x2000
	s_add_u32 s76, s48, 0x40000
	v_lshl_add_u64 v[226:227], s[48:49], 0, v[128:129]
	s_addc_u32 s77, s49, 0
	s_add_i32 s78, s67, s54
	global_load_lds_dwordx4 v[226:227], off
	v_lshl_add_u64 v[228:229], s[76:77], 0, v[132:133]
	s_mov_b32 m0, s78
	v_lshl_add_u64 v[230:231], s[50:51], 0, v[130:131]
	global_load_lds_dwordx4 v[228:229], off
	v_lshl_add_u64 v[228:229], s[76:77], 0, v[128:129]
	s_add_i32 m0, s78, 0x2000
	s_nop 0
	global_load_lds_dwordx4 v[228:229], off
	v_lshl_add_u64 v[228:229], s[50:51], 0, v[134:135]
	s_mov_b32 m0, s57
	s_nop 0
	global_load_lds_dwordx4 v[228:229], off
	s_mov_b32 m0, s58
	s_nop 0
	global_load_lds_dwordx4 v[230:231], off
	s_waitcnt vmcnt(8)
	s_waitcnt lgkmcnt(0)
	s_setprio 1
	s_barrier
	v_mfma_f32_16x16x32_bf16 v[60:63], v[160:163], v[194:197], v[60:63]
	v_mfma_f32_16x16x32_bf16 v[60:63], v[164:167], v[198:201], v[60:63]
	v_mfma_f32_16x16x32_bf16 v[44:47], v[164:167], v[206:209], v[44:47]
	v_mfma_f32_16x16x32_bf16 v[44:47], v[160:163], v[202:205], v[44:47]
	v_mfma_f32_16x16x32_bf16 v[28:31], v[160:163], v[210:213], v[28:31]
	v_mfma_f32_16x16x32_bf16 v[28:31], v[164:167], v[214:217], v[28:31]
	v_mfma_f32_16x16x32_bf16 v[12:15], v[164:167], v[222:225], v[12:15]
	v_mfma_f32_16x16x32_bf16 v[12:15], v[160:163], v[218:221], v[12:15]
	v_mfma_f32_16x16x32_bf16 v[4:7], v[168:171], v[218:221], v[4:7]
	v_mfma_f32_16x16x32_bf16 v[4:7], v[172:175], v[222:225], v[4:7]
	v_mfma_f32_16x16x32_bf16 v[20:23], v[172:175], v[214:217], v[20:23]
	v_mfma_f32_16x16x32_bf16 v[20:23], v[168:171], v[210:213], v[20:23]
	v_mfma_f32_16x16x32_bf16 v[36:39], v[168:171], v[202:205], v[36:39]
	v_mfma_f32_16x16x32_bf16 v[36:39], v[172:175], v[206:209], v[36:39]
	v_mfma_f32_16x16x32_bf16 v[52:55], v[172:175], v[198:201], v[52:55]
	v_mfma_f32_16x16x32_bf16 v[52:55], v[168:171], v[194:197], v[52:55]
	s_setprio 0
	s_setprio 1
	v_mfma_f32_16x16x32_bf16 v[48:51], v[186:189], v[194:197], v[48:51]
	v_mfma_f32_16x16x32_bf16 v[48:51], v[190:193], v[198:201], v[48:51]
	v_mfma_f32_16x16x32_bf16 v[32:35], v[190:193], v[206:209], v[32:35]
	v_mfma_f32_16x16x32_bf16 v[32:35], v[186:189], v[202:205], v[32:35]
	v_mfma_f32_16x16x32_bf16 v[16:19], v[186:189], v[210:213], v[16:19]
	v_mfma_f32_16x16x32_bf16 v[16:19], v[190:193], v[214:217], v[16:19]
	v_mfma_f32_16x16x32_bf16 v[0:3], v[190:193], v[222:225], v[0:3]
	v_mfma_f32_16x16x32_bf16 v[0:3], v[186:189], v[218:221], v[0:3]
	v_mfma_f32_16x16x32_bf16 v[8:11], v[176:179], v[218:221], v[8:11]
	v_mfma_f32_16x16x32_bf16 v[8:11], v[180:183], v[222:225], v[8:11]
	v_mfma_f32_16x16x32_bf16 v[24:27], v[180:183], v[214:217], v[24:27]
	v_mfma_f32_16x16x32_bf16 v[24:27], v[176:179], v[210:213], v[24:27]
	v_mfma_f32_16x16x32_bf16 v[40:43], v[176:179], v[202:205], v[40:43]
	v_mfma_f32_16x16x32_bf16 v[40:43], v[180:183], v[206:209], v[40:43]
	v_mfma_f32_16x16x32_bf16 v[56:59], v[180:183], v[198:201], v[56:59]
	v_mfma_f32_16x16x32_bf16 v[56:59], v[176:179], v[194:197], v[56:59]
	s_barrier
	s_setprio 0
	s_add_i32 s76, 0, 0x18000
	v_add_u32_e32 v153, s76, v147
	s_add_i32 s77, 0, 0x1c000
	ds_read_b128 v[160:163], v153
	v_xor_b32_e32 v253, 64, v153
	ds_read_b128 v[164:167], v253
	ds_read_b128 v[168:171], v153 offset:2048
	ds_read_b128 v[172:175], v253 offset:2048
	v_add_u32_e32 v153, s77, v147
	ds_read_b128 v[176:179], v153
	v_xor_b32_e32 v253, 64, v153
	ds_read_b128 v[180:183], v253
	ds_read_b128 v[186:189], v153 offset:2048
	ds_read_b128 v[190:193], v253 offset:2048
	s_add_u32 s50, s50, 0x40000
	s_addc_u32 s51, s51, 0
	s_mov_b32 m0, s59
	v_lshl_add_u64 v[232:233], s[50:51], 0, v[134:135]
	ds_read_b128 v[194:197], v150 offset:32768
	v_xor_b32_e32 v253, 64, v150
	ds_read_b128 v[198:201], v253 offset:32768
	ds_read_b128 v[202:205], v150 offset:34816
	ds_read_b128 v[206:209], v253 offset:34816
	ds_read_b128 v[210:213], v150 offset:36864
	ds_read_b128 v[214:217], v253 offset:36864
	ds_read_b128 v[218:221], v150 offset:38912
	ds_read_b128 v[222:225], v253 offset:38912
	global_load_lds_dwordx4 v[232:233], off
	v_lshl_add_u64 v[232:233], s[50:51], 0, v[130:131]
	s_mov_b32 m0, s60
	s_nop 0
	global_load_lds_dwordx4 v[232:233], off
	s_waitcnt vmcnt(8)
	s_waitcnt lgkmcnt(0)
	s_setprio 1
	s_barrier
	v_mfma_f32_16x16x32_bf16 v[124:127], v[160:163], v[194:197], v[124:127]
	v_mfma_f32_16x16x32_bf16 v[124:127], v[164:167], v[198:201], v[124:127]
	v_mfma_f32_16x16x32_bf16 v[108:111], v[164:167], v[206:209], v[108:111]
	v_mfma_f32_16x16x32_bf16 v[108:111], v[160:163], v[202:205], v[108:111]
	v_mfma_f32_16x16x32_bf16 v[92:95], v[160:163], v[210:213], v[92:95]
	v_mfma_f32_16x16x32_bf16 v[92:95], v[164:167], v[214:217], v[92:95]
	v_mfma_f32_16x16x32_bf16 v[76:79], v[164:167], v[222:225], v[76:79]
	v_mfma_f32_16x16x32_bf16 v[76:79], v[160:163], v[218:221], v[76:79]
	v_mfma_f32_16x16x32_bf16 v[68:71], v[168:171], v[218:221], v[68:71]
	v_mfma_f32_16x16x32_bf16 v[68:71], v[172:175], v[222:225], v[68:71]
	v_mfma_f32_16x16x32_bf16 v[84:87], v[172:175], v[214:217], v[84:87]
	v_mfma_f32_16x16x32_bf16 v[84:87], v[168:171], v[210:213], v[84:87]
	v_mfma_f32_16x16x32_bf16 v[100:103], v[168:171], v[202:205], v[100:103]
	v_mfma_f32_16x16x32_bf16 v[100:103], v[172:175], v[206:209], v[100:103]
	v_mfma_f32_16x16x32_bf16 v[116:119], v[172:175], v[198:201], v[116:119]
	v_mfma_f32_16x16x32_bf16 v[116:119], v[168:171], v[194:197], v[116:119]
	s_setprio 0
	s_setprio 1
	v_mfma_f32_16x16x32_bf16 v[112:115], v[186:189], v[194:197], v[112:115]
	v_mfma_f32_16x16x32_bf16 v[112:115], v[190:193], v[198:201], v[112:115]
	v_mfma_f32_16x16x32_bf16 v[96:99], v[190:193], v[206:209], v[96:99]
	v_mfma_f32_16x16x32_bf16 v[96:99], v[186:189], v[202:205], v[96:99]
	v_mfma_f32_16x16x32_bf16 v[80:83], v[186:189], v[210:213], v[80:83]
	v_mfma_f32_16x16x32_bf16 v[80:83], v[190:193], v[214:217], v[80:83]
	v_mfma_f32_16x16x32_bf16 v[64:67], v[190:193], v[222:225], v[64:67]
	v_mfma_f32_16x16x32_bf16 v[64:67], v[186:189], v[218:221], v[64:67]
	v_mfma_f32_16x16x32_bf16 v[72:75], v[176:179], v[218:221], v[72:75]
	v_mfma_f32_16x16x32_bf16 v[72:75], v[180:183], v[222:225], v[72:75]
	v_mfma_f32_16x16x32_bf16 v[88:91], v[180:183], v[214:217], v[88:91]
	v_mfma_f32_16x16x32_bf16 v[88:91], v[176:179], v[210:213], v[88:91]
	v_mfma_f32_16x16x32_bf16 v[104:107], v[176:179], v[202:205], v[104:107]
	v_mfma_f32_16x16x32_bf16 v[104:107], v[180:183], v[206:209], v[104:107]
	v_mfma_f32_16x16x32_bf16 v[120:123], v[180:183], v[198:201], v[120:123]
	v_mfma_f32_16x16x32_bf16 v[120:123], v[176:179], v[194:197], v[120:123]
	s_barrier
	s_setprio 0
	v_add_u32_e32 v234, 0x21000, v151
	ds_read_b128 v[236:239], v234
	ds_read_b128 v[240:243], v234 offset:256
	ds_read_b128 v[244:247], v234 offset:512
	ds_read_b128 v[248:251], v234 offset:768
	v_add_u32_e32 v235, s27, v146
	v_mul_u32_u24_e32 v235, 0x1600, v235
	v_lshl_or_b32 v234, s69, 7, v149
	v_lshl_add_u32 v235, v234, 1, v235
	s_add_i32 s50, s76, s54
	v_lshl_add_u64 v[154:155], v[154:155], 0, s[20:21]
	s_mov_b32 m0, s50
	ds_read_b128 v[194:197], v150 offset:49152
	v_xor_b32_e32 v253, 64, v150
	ds_read_b128 v[198:201], v253 offset:49152
	ds_read_b128 v[202:205], v150 offset:51200
	ds_read_b128 v[206:209], v253 offset:51200
	ds_read_b128 v[210:213], v150 offset:53248
	ds_read_b128 v[214:217], v253 offset:53248
	ds_read_b128 v[218:221], v150 offset:55296
	ds_read_b128 v[222:225], v253 offset:55296
	global_load_lds_dwordx4 v[154:155], off
	s_add_i32 m0, s50, 0x2000
	s_add_u32 s48, s48, 0x40080
	v_lshl_add_u64 v[154:155], v[226:227], 0, s[20:21]
	s_addc_u32 s49, s49, 0
	s_add_i32 s50, s77, s54
	global_load_lds_dwordx4 v[154:155], off
	v_lshl_add_u64 v[154:155], s[48:49], 0, v[132:133]
	s_mov_b32 m0, s50
	s_nop 0
	global_load_lds_dwordx4 v[154:155], off
	v_lshl_add_u64 v[154:155], s[48:49], 0, v[128:129]
	s_add_i32 m0, s50, 0x2000
	s_nop 0
	global_load_lds_dwordx4 v[154:155], off
	v_lshl_add_u64 v[154:155], v[228:229], 0, s[20:21]
	s_mov_b32 m0, s62
	s_nop 0
	global_load_lds_dwordx4 v[154:155], off
	v_lshl_add_u64 v[154:155], v[230:231], 0, s[20:21]
	s_mov_b32 m0, s63
	s_nop 0
	global_load_lds_dwordx4 v[154:155], off
	s_waitcnt lgkmcnt(8)
	v_add_f32_e32 v236, v236, v237
	v_add_f32_e32 v238, v238, v239
	v_add_f32_e32 v240, v240, v241
	v_add_f32_e32 v242, v242, v243
	v_add_f32_e32 v244, v244, v245
	v_add_f32_e32 v246, v246, v247
	v_add_f32_e32 v248, v248, v249
	v_add_f32_e32 v250, v250, v251
	v_add_f32_e32 v236, v236, v238
	v_add_f32_e32 v240, v240, v242
	v_add_f32_e32 v244, v244, v246
	v_add_f32_e32 v248, v248, v250
	v_fmamk_f32 v236, v236, 0x3a800000, v152
	v_fmamk_f32 v240, v240, 0x3a800000, v152
	v_fmamk_f32 v244, v244, 0x3a800000, v152
	v_fmamk_f32 v248, v248, 0x3a800000, v152
	v_rsq_f32_e32 v236, v236
	v_rsq_f32_e32 v240, v240
	v_rsq_f32_e32 v244, v244
	v_rsq_f32_e32 v248, v248
	v_mul_f32_e32 v252, 0xbfb8aa3b, v236
	v_mul_f32_e32 v254, v236, v236
	v_rcp_f32_e32 v254, v254
	v_pk_mul_f32 v[120:121], v[124:125], v[120:121]
	v_pk_mul_f32 v[122:123], v[126:127], v[122:123]
	v_pk_mul_f32 v[112:113], v[116:117], v[112:113]
	v_pk_mul_f32 v[114:115], v[118:119], v[114:115]
	v_pk_mul_f32 v[124:125], v[124:125], v[252:253] op_sel_hi:[1,0]
	v_pk_mul_f32 v[126:127], v[126:127], v[252:253] op_sel_hi:[1,0]
	v_pk_mul_f32 v[116:117], v[116:117], v[252:253] op_sel_hi:[1,0]
	v_pk_mul_f32 v[118:119], v[118:119], v[252:253] op_sel_hi:[1,0]
	v_exp_f32_e32 v124, v124
	v_exp_f32_e32 v125, v125
	v_exp_f32_e32 v126, v126
	v_exp_f32_e32 v127, v127
	v_exp_f32_e32 v116, v116
	v_exp_f32_e32 v117, v117
	v_exp_f32_e32 v118, v118
	v_exp_f32_e32 v119, v119
	v_pk_fma_f32 v[124:125], v[124:125], v[254:255], v[254:255] op_sel_hi:[1,0,0]
	v_pk_fma_f32 v[126:127], v[126:127], v[254:255], v[254:255] op_sel_hi:[1,0,0]
	v_pk_fma_f32 v[116:117], v[116:117], v[254:255], v[254:255] op_sel_hi:[1,0,0]
	v_pk_fma_f32 v[118:119], v[118:119], v[254:255], v[254:255] op_sel_hi:[1,0,0]
	v_rcp_f32_e32 v124, v124
	v_rcp_f32_e32 v125, v125
	v_rcp_f32_e32 v126, v126
	v_rcp_f32_e32 v127, v127
	v_rcp_f32_e32 v116, v116
	v_rcp_f32_e32 v117, v117
	v_rcp_f32_e32 v118, v118
	v_rcp_f32_e32 v119, v119
	v_pk_mul_f32 v[120:121], v[120:121], v[124:125]
	v_pk_mul_f32 v[122:123], v[122:123], v[126:127]
	v_pk_mul_f32 v[112:113], v[112:113], v[116:117]
	v_pk_mul_f32 v[114:115], v[114:115], v[118:119]
	v_cvt_pk_bf16_f32 v120, v120, v121
	v_cvt_pk_bf16_f32 v121, v122, v123
	v_cvt_pk_bf16_f32 v122, v112, v113
	v_cvt_pk_bf16_f32 v123, v114, v115
	global_store_dwordx4 v235, v[120:123], s[14:15]
	v_add_u32_e32 v234, 0x16000, v235
	v_mul_f32_e32 v252, 0xbfb8aa3b, v240
	v_mul_f32_e32 v254, v240, v240
	v_rcp_f32_e32 v254, v254
	v_pk_mul_f32 v[104:105], v[108:109], v[104:105]
	v_pk_mul_f32 v[106:107], v[110:111], v[106:107]
	v_pk_mul_f32 v[96:97], v[100:101], v[96:97]
	v_pk_mul_f32 v[98:99], v[102:103], v[98:99]
	v_pk_mul_f32 v[108:109], v[108:109], v[252:253] op_sel_hi:[1,0]
	v_pk_mul_f32 v[110:111], v[110:111], v[252:253] op_sel_hi:[1,0]
	v_pk_mul_f32 v[100:101], v[100:101], v[252:253] op_sel_hi:[1,0]
	v_pk_mul_f32 v[102:103], v[102:103], v[252:253] op_sel_hi:[1,0]
	v_exp_f32_e32 v108, v108
	v_exp_f32_e32 v109, v109
	v_exp_f32_e32 v110, v110
	v_exp_f32_e32 v111, v111
	v_exp_f32_e32 v100, v100
	v_exp_f32_e32 v101, v101
	v_exp_f32_e32 v102, v102
	v_exp_f32_e32 v103, v103
	v_pk_fma_f32 v[108:109], v[108:109], v[254:255], v[254:255] op_sel_hi:[1,0,0]
	v_pk_fma_f32 v[110:111], v[110:111], v[254:255], v[254:255] op_sel_hi:[1,0,0]
	v_pk_fma_f32 v[100:101], v[100:101], v[254:255], v[254:255] op_sel_hi:[1,0,0]
	v_pk_fma_f32 v[102:103], v[102:103], v[254:255], v[254:255] op_sel_hi:[1,0,0]
	v_rcp_f32_e32 v108, v108
	v_rcp_f32_e32 v109, v109
	v_rcp_f32_e32 v110, v110
	v_rcp_f32_e32 v111, v111
	v_rcp_f32_e32 v100, v100
	v_rcp_f32_e32 v101, v101
	v_rcp_f32_e32 v102, v102
	v_rcp_f32_e32 v103, v103
	v_pk_mul_f32 v[104:105], v[104:105], v[108:109]
	v_pk_mul_f32 v[106:107], v[106:107], v[110:111]
	v_pk_mul_f32 v[96:97], v[96:97], v[100:101]
	v_pk_mul_f32 v[98:99], v[98:99], v[102:103]
	v_cvt_pk_bf16_f32 v104, v104, v105
	v_cvt_pk_bf16_f32 v105, v106, v107
	v_cvt_pk_bf16_f32 v106, v96, v97
	v_cvt_pk_bf16_f32 v107, v98, v99
	global_store_dwordx4 v234, v[104:107], s[14:15]
	v_add_u32_e32 v235, 0x16000, v234
	v_mul_f32_e32 v252, 0xbfb8aa3b, v244
	v_mul_f32_e32 v254, v244, v244
	v_rcp_f32_e32 v254, v254
	v_pk_mul_f32 v[88:89], v[92:93], v[88:89]
	v_pk_mul_f32 v[90:91], v[94:95], v[90:91]
	v_pk_mul_f32 v[80:81], v[84:85], v[80:81]
	v_pk_mul_f32 v[82:83], v[86:87], v[82:83]
	v_pk_mul_f32 v[92:93], v[92:93], v[252:253] op_sel_hi:[1,0]
	v_pk_mul_f32 v[94:95], v[94:95], v[252:253] op_sel_hi:[1,0]
	v_pk_mul_f32 v[84:85], v[84:85], v[252:253] op_sel_hi:[1,0]
	v_pk_mul_f32 v[86:87], v[86:87], v[252:253] op_sel_hi:[1,0]
	v_exp_f32_e32 v92, v92
	v_exp_f32_e32 v93, v93
	v_exp_f32_e32 v94, v94
	v_exp_f32_e32 v95, v95
	v_exp_f32_e32 v84, v84
	v_exp_f32_e32 v85, v85
	v_exp_f32_e32 v86, v86
	v_exp_f32_e32 v87, v87
	v_pk_fma_f32 v[92:93], v[92:93], v[254:255], v[254:255] op_sel_hi:[1,0,0]
	v_pk_fma_f32 v[94:95], v[94:95], v[254:255], v[254:255] op_sel_hi:[1,0,0]
	v_pk_fma_f32 v[84:85], v[84:85], v[254:255], v[254:255] op_sel_hi:[1,0,0]
	v_pk_fma_f32 v[86:87], v[86:87], v[254:255], v[254:255] op_sel_hi:[1,0,0]
	v_rcp_f32_e32 v92, v92
	v_rcp_f32_e32 v93, v93
	v_rcp_f32_e32 v94, v94
	v_rcp_f32_e32 v95, v95
	v_rcp_f32_e32 v84, v84
	v_rcp_f32_e32 v85, v85
	v_rcp_f32_e32 v86, v86
	v_rcp_f32_e32 v87, v87
	v_pk_mul_f32 v[88:89], v[88:89], v[92:93]
	v_pk_mul_f32 v[90:91], v[90:91], v[94:95]
	v_pk_mul_f32 v[80:81], v[80:81], v[84:85]
	v_pk_mul_f32 v[82:83], v[82:83], v[86:87]
	v_cvt_pk_bf16_f32 v88, v88, v89
	v_cvt_pk_bf16_f32 v89, v90, v91
	v_cvt_pk_bf16_f32 v90, v80, v81
	v_cvt_pk_bf16_f32 v91, v82, v83
	global_store_dwordx4 v235, v[88:91], s[14:15]
	v_add_u32_e32 v234, 0x16000, v235
	v_mul_f32_e32 v252, 0xbfb8aa3b, v248
	v_mul_f32_e32 v254, v248, v248
	v_rcp_f32_e32 v254, v254
	v_pk_mul_f32 v[72:73], v[76:77], v[72:73]
	v_pk_mul_f32 v[74:75], v[78:79], v[74:75]
	v_pk_mul_f32 v[64:65], v[68:69], v[64:65]
	v_pk_mul_f32 v[66:67], v[70:71], v[66:67]
	v_pk_mul_f32 v[76:77], v[76:77], v[252:253] op_sel_hi:[1,0]
	v_pk_mul_f32 v[78:79], v[78:79], v[252:253] op_sel_hi:[1,0]
	v_pk_mul_f32 v[68:69], v[68:69], v[252:253] op_sel_hi:[1,0]
	v_pk_mul_f32 v[70:71], v[70:71], v[252:253] op_sel_hi:[1,0]
	v_exp_f32_e32 v76, v76
	v_exp_f32_e32 v77, v77
	v_exp_f32_e32 v78, v78
	v_exp_f32_e32 v79, v79
	v_exp_f32_e32 v68, v68
	v_exp_f32_e32 v69, v69
	v_exp_f32_e32 v70, v70
	v_exp_f32_e32 v71, v71
	v_pk_fma_f32 v[76:77], v[76:77], v[254:255], v[254:255] op_sel_hi:[1,0,0]
	v_pk_fma_f32 v[78:79], v[78:79], v[254:255], v[254:255] op_sel_hi:[1,0,0]
	v_pk_fma_f32 v[68:69], v[68:69], v[254:255], v[254:255] op_sel_hi:[1,0,0]
	v_pk_fma_f32 v[70:71], v[70:71], v[254:255], v[254:255] op_sel_hi:[1,0,0]
	v_rcp_f32_e32 v76, v76
	v_rcp_f32_e32 v77, v77
	v_rcp_f32_e32 v78, v78
	v_rcp_f32_e32 v79, v79
	v_rcp_f32_e32 v68, v68
	v_rcp_f32_e32 v69, v69
	v_rcp_f32_e32 v70, v70
	v_rcp_f32_e32 v71, v71
	v_pk_mul_f32 v[72:73], v[72:73], v[76:77]
	v_pk_mul_f32 v[74:75], v[74:75], v[78:79]
	v_pk_mul_f32 v[64:65], v[64:65], v[68:69]
	v_pk_mul_f32 v[66:67], v[66:67], v[70:71]
	v_cvt_pk_bf16_f32 v72, v72, v73
	v_cvt_pk_bf16_f32 v73, v74, v75
	v_cvt_pk_bf16_f32 v74, v64, v65
	v_cvt_pk_bf16_f32 v75, v66, v67
	global_store_dwordx4 v234, v[72:75], s[14:15]
	s_waitcnt vmcnt(12)
	s_waitcnt lgkmcnt(0)
	s_setprio 1
	s_barrier
	v_mfma_f32_16x16x32_bf16 v[60:63], v[160:163], v[194:197], v[60:63]
	v_mfma_f32_16x16x32_bf16 v[60:63], v[164:167], v[198:201], v[60:63]
	v_mfma_f32_16x16x32_bf16 v[44:47], v[164:167], v[206:209], v[44:47]
	v_mfma_f32_16x16x32_bf16 v[44:47], v[160:163], v[202:205], v[44:47]
	v_mfma_f32_16x16x32_bf16 v[28:31], v[160:163], v[210:213], v[28:31]
	v_mfma_f32_16x16x32_bf16 v[28:31], v[164:167], v[214:217], v[28:31]
	v_mfma_f32_16x16x32_bf16 v[12:15], v[164:167], v[222:225], v[12:15]
	v_mfma_f32_16x16x32_bf16 v[12:15], v[160:163], v[218:221], v[12:15]
	v_mfma_f32_16x16x32_bf16 v[4:7], v[168:171], v[218:221], v[4:7]
	v_mfma_f32_16x16x32_bf16 v[4:7], v[172:175], v[222:225], v[4:7]
	v_mfma_f32_16x16x32_bf16 v[20:23], v[172:175], v[214:217], v[20:23]
	v_mfma_f32_16x16x32_bf16 v[20:23], v[168:171], v[210:213], v[20:23]
	v_mfma_f32_16x16x32_bf16 v[36:39], v[168:171], v[202:205], v[36:39]
	v_mfma_f32_16x16x32_bf16 v[36:39], v[172:175], v[206:209], v[36:39]
	v_mfma_f32_16x16x32_bf16 v[52:55], v[172:175], v[198:201], v[52:55]
	v_mfma_f32_16x16x32_bf16 v[52:55], v[168:171], v[194:197], v[52:55]
	s_setprio 0
	s_setprio 1
	v_mfma_f32_16x16x32_bf16 v[48:51], v[186:189], v[194:197], v[48:51]
	v_mfma_f32_16x16x32_bf16 v[48:51], v[190:193], v[198:201], v[48:51]
	v_mfma_f32_16x16x32_bf16 v[32:35], v[190:193], v[206:209], v[32:35]
	v_mfma_f32_16x16x32_bf16 v[32:35], v[186:189], v[202:205], v[32:35]
	v_mfma_f32_16x16x32_bf16 v[16:19], v[186:189], v[210:213], v[16:19]
	v_mfma_f32_16x16x32_bf16 v[16:19], v[190:193], v[214:217], v[16:19]
	v_mfma_f32_16x16x32_bf16 v[0:3], v[190:193], v[222:225], v[0:3]
	v_mfma_f32_16x16x32_bf16 v[0:3], v[186:189], v[218:221], v[0:3]
	v_mfma_f32_16x16x32_bf16 v[8:11], v[176:179], v[218:221], v[8:11]
	v_mfma_f32_16x16x32_bf16 v[8:11], v[180:183], v[222:225], v[8:11]
	v_mfma_f32_16x16x32_bf16 v[24:27], v[180:183], v[214:217], v[24:27]
	v_mfma_f32_16x16x32_bf16 v[24:27], v[176:179], v[210:213], v[24:27]
	v_mfma_f32_16x16x32_bf16 v[40:43], v[176:179], v[202:205], v[40:43]
	v_mfma_f32_16x16x32_bf16 v[40:43], v[180:183], v[206:209], v[40:43]
	v_mfma_f32_16x16x32_bf16 v[56:59], v[180:183], v[198:201], v[56:59]
	v_mfma_f32_16x16x32_bf16 v[56:59], v[176:179], v[194:197], v[56:59]
	s_barrier
	s_setprio 0
	s_add_i32 s75, s75, 2
	s_add_u32 s73, s73, 0x100
	s_addc_u32 s74, s74, 0
	s_add_u32 s46, s46, 0x100
	s_addc_u32 s47, s47, 0

.LBB0_609:
	s_add_u32 s79, s56, 0x100
	s_addc_u32 s80, s57, 0
	s_mov_b32 s81, -2
	s_waitcnt lgkmcnt(0)
	s_cmp_eq_u32 s70, 1
	s_cbranch_scc1 .Lfa_5
	ds_read_b128 v[128:131], v189
	v_xor_b32_e32 v253, 64, v189
	ds_read_b128 v[132:135], v253
	ds_read_b128 v[136:139], v189 offset:2048
	ds_read_b128 v[140:143], v253 offset:2048
	ds_read_b128 v[144:147], v190
	v_xor_b32_e32 v253, 64, v190
	ds_read_b128 v[148:151], v253
	ds_read_b128 v[172:175], v190 offset:2048
	ds_read_b128 v[176:179], v253 offset:2048
	s_add_u32 s56, s54, 0x100
	s_addc_u32 s57, s55, 0
	s_cmp_eq_u32 s81, 40
	s_cselect_b32 s61, s17, s57
	s_cselect_b32 s60, s16, s56
	s_cselect_b32 s59, s53, s80
	s_cselect_b32 s58, s52, s79
	v_lshl_add_u64 v[222:223], s[54:55], 0, v[166:167]
	s_add_i32 m0, s66, 0xc000
	ds_read_b128 v[180:183], v191
	v_xor_b32_e32 v253, 64, v191
	ds_read_b128 v[194:197], v253
	ds_read_b128 v[198:201], v191 offset:2048
	ds_read_b128 v[202:205], v253 offset:2048
	ds_read_b128 v[206:209], v191 offset:4096
	ds_read_b128 v[210:213], v253 offset:4096
	ds_read_b128 v[214:217], v191 offset:6144
	ds_read_b128 v[218:221], v253 offset:6144
	global_load_lds_dwordx4 v[222:223], off
	v_lshl_add_u64 v[222:223], s[54:55], 0, v[164:165]
	s_add_i32 m0, s66, 0xe000
	s_nop 0
	global_load_lds_dwordx4 v[222:223], off
	s_waitcnt vmcnt(24)
	s_waitcnt lgkmcnt(0)
	s_setprio 1
	s_barrier
	v_mfma_f32_16x16x32_bf16 v[124:127], v[128:131], v[180:183], 0
	v_mfma_f32_16x16x32_bf16 v[120:123], v[136:139], v[180:183], 0
	v_mfma_f32_16x16x32_bf16 v[108:111], v[128:131], v[198:201], 0
	v_mfma_f32_16x16x32_bf16 v[104:107], v[136:139], v[198:201], 0
	v_mfma_f32_16x16x32_bf16 v[92:95], v[128:131], v[206:209], 0
	v_mfma_f32_16x16x32_bf16 v[88:91], v[136:139], v[206:209], 0
	v_mfma_f32_16x16x32_bf16 v[76:79], v[128:131], v[214:217], 0
	v_mfma_f32_16x16x32_bf16 v[72:75], v[136:139], v[214:217], 0
	v_mfma_f32_16x16x32_bf16 v[124:127], v[132:135], v[194:197], v[124:127]
	v_mfma_f32_16x16x32_bf16 v[120:123], v[140:143], v[194:197], v[120:123]
	v_mfma_f32_16x16x32_bf16 v[108:111], v[132:135], v[202:205], v[108:111]
	v_mfma_f32_16x16x32_bf16 v[104:107], v[140:143], v[202:205], v[104:107]
	v_mfma_f32_16x16x32_bf16 v[92:95], v[132:135], v[210:213], v[92:95]
	v_mfma_f32_16x16x32_bf16 v[88:91], v[140:143], v[210:213], v[88:91]
	v_mfma_f32_16x16x32_bf16 v[76:79], v[132:135], v[218:221], v[76:79]
	v_mfma_f32_16x16x32_bf16 v[72:75], v[140:143], v[218:221], v[72:75]
	s_setprio 0
	s_setprio 1
	v_mfma_f32_16x16x32_bf16 v[116:119], v[144:147], v[180:183], 0
	v_mfma_f32_16x16x32_bf16 v[112:115], v[172:175], v[180:183], 0
	v_mfma_f32_16x16x32_bf16 v[100:103], v[144:147], v[198:201], 0
	v_mfma_f32_16x16x32_bf16 v[96:99], v[172:175], v[198:201], 0
	v_mfma_f32_16x16x32_bf16 v[84:87], v[144:147], v[206:209], 0
	v_mfma_f32_16x16x32_bf16 v[80:83], v[172:175], v[206:209], 0
	v_mfma_f32_16x16x32_bf16 v[68:71], v[144:147], v[214:217], 0
	v_mfma_f32_16x16x32_bf16 v[64:67], v[172:175], v[214:217], 0
	v_mfma_f32_16x16x32_bf16 v[116:119], v[148:151], v[194:197], v[116:119]
	v_mfma_f32_16x16x32_bf16 v[112:115], v[176:179], v[194:197], v[112:115]
	v_mfma_f32_16x16x32_bf16 v[100:103], v[148:151], v[202:205], v[100:103]
	v_mfma_f32_16x16x32_bf16 v[96:99], v[176:179], v[202:205], v[96:99]
	v_mfma_f32_16x16x32_bf16 v[84:87], v[148:151], v[210:213], v[84:87]
	v_mfma_f32_16x16x32_bf16 v[80:83], v[176:179], v[210:213], v[80:83]
	v_mfma_f32_16x16x32_bf16 v[68:71], v[148:151], v[218:221], v[68:71]
	v_mfma_f32_16x16x32_bf16 v[64:67], v[176:179], v[218:221], v[64:67]
	s_barrier
	s_setprio 0
	s_add_i32 s54, s75, s65
	v_lshl_add_u64 v[222:223], s[58:59], 0, v[154:155]
	s_mov_b32 m0, s54
	ds_read_b128 v[180:183], v191 offset:16384
	v_xor_b32_e32 v253, 64, v191
	ds_read_b128 v[194:197], v253 offset:16384
	ds_read_b128 v[198:201], v191 offset:18432
	ds_read_b128 v[202:205], v253 offset:18432
	ds_read_b128 v[206:209], v191 offset:20480
	ds_read_b128 v[210:213], v253 offset:20480
	ds_read_b128 v[214:217], v191 offset:22528
	ds_read_b128 v[218:221], v253 offset:22528
	global_load_lds_dwordx4 v[222:223], off
	s_add_i32 m0, s54, 0x2000
	s_add_u32 s54, s58, 0xb0000
	v_lshl_add_u64 v[224:225], s[58:59], 0, v[162:163]
	s_addc_u32 s55, s59, 0
	s_add_i32 s82, s76, s65
	global_load_lds_dwordx4 v[224:225], off
	v_lshl_add_u64 v[226:227], s[54:55], 0, v[154:155]
	s_mov_b32 m0, s82
	v_lshl_add_u64 v[228:229], s[60:61], 0, v[160:161]
	global_load_lds_dwordx4 v[226:227], off
	v_lshl_add_u64 v[226:227], s[54:55], 0, v[162:163]
	s_add_i32 m0, s82, 0x2000
	s_nop 0
	global_load_lds_dwordx4 v[226:227], off
	v_lshl_add_u64 v[226:227], s[60:61], 0, v[152:153]
	s_mov_b32 m0, s66
	s_nop 0
	global_load_lds_dwordx4 v[226:227], off
	s_mov_b32 m0, s67
	s_nop 0
	global_load_lds_dwordx4 v[228:229], off
	s_waitcnt vmcnt(24)
	s_waitcnt lgkmcnt(0)
	s_setprio 1
	s_barrier
	v_mfma_f32_16x16x32_bf16 v[60:63], v[128:131], v[180:183], 0
	v_mfma_f32_16x16x32_bf16 v[56:59], v[136:139], v[180:183], 0
	v_mfma_f32_16x16x32_bf16 v[44:47], v[128:131], v[198:201], 0
	v_mfma_f32_16x16x32_bf16 v[40:43], v[136:139], v[198:201], 0
	v_mfma_f32_16x16x32_bf16 v[28:31], v[128:131], v[206:209], 0
	v_mfma_f32_16x16x32_bf16 v[24:27], v[136:139], v[206:209], 0
	v_mfma_f32_16x16x32_bf16 v[12:15], v[128:131], v[214:217], 0
	v_mfma_f32_16x16x32_bf16 v[8:11], v[136:139], v[214:217], 0
	v_mfma_f32_16x16x32_bf16 v[60:63], v[132:135], v[194:197], v[60:63]
	v_mfma_f32_16x16x32_bf16 v[56:59], v[140:143], v[194:197], v[56:59]
	v_mfma_f32_16x16x32_bf16 v[44:47], v[132:135], v[202:205], v[44:47]
	v_mfma_f32_16x16x32_bf16 v[40:43], v[140:143], v[202:205], v[40:43]
	v_mfma_f32_16x16x32_bf16 v[28:31], v[132:135], v[210:213], v[28:31]
	v_mfma_f32_16x16x32_bf16 v[24:27], v[140:143], v[210:213], v[24:27]
	v_mfma_f32_16x16x32_bf16 v[12:15], v[132:135], v[218:221], v[12:15]
	v_mfma_f32_16x16x32_bf16 v[8:11], v[140:143], v[218:221], v[8:11]
	s_setprio 0
	s_setprio 1
	v_mfma_f32_16x16x32_bf16 v[52:55], v[144:147], v[180:183], 0
	v_mfma_f32_16x16x32_bf16 v[48:51], v[172:175], v[180:183], 0
	v_mfma_f32_16x16x32_bf16 v[36:39], v[144:147], v[198:201], 0
	v_mfma_f32_16x16x32_bf16 v[32:35], v[172:175], v[198:201], 0
	v_mfma_f32_16x16x32_bf16 v[20:23], v[144:147], v[206:209], 0
	v_mfma_f32_16x16x32_bf16 v[16:19], v[172:175], v[206:209], 0
	v_mfma_f32_16x16x32_bf16 v[4:7], v[144:147], v[214:217], 0
	v_mfma_f32_16x16x32_bf16 v[0:3], v[172:175], v[214:217], 0
	v_mfma_f32_16x16x32_bf16 v[52:55], v[148:151], v[194:197], v[52:55]
	v_mfma_f32_16x16x32_bf16 v[48:51], v[176:179], v[194:197], v[48:51]
	v_mfma_f32_16x16x32_bf16 v[36:39], v[148:151], v[202:205], v[36:39]
	v_mfma_f32_16x16x32_bf16 v[32:35], v[176:179], v[202:205], v[32:35]
	v_mfma_f32_16x16x32_bf16 v[20:23], v[148:151], v[210:213], v[20:23]
	v_mfma_f32_16x16x32_bf16 v[16:19], v[176:179], v[210:213], v[16:19]
	v_mfma_f32_16x16x32_bf16 v[4:7], v[148:151], v[218:221], v[4:7]
	v_mfma_f32_16x16x32_bf16 v[0:3], v[176:179], v[218:221], v[0:3]
	s_barrier
	s_setprio 0
	s_add_i32 s82, 0, 0x18000
	s_add_i32 s83, 0, 0x1c000
	v_add_u32_e32 v140, s82, v186
	v_add_u32_e32 v176, s83, v186
	ds_read_b128 v[128:131], v140
	v_xor_b32_e32 v253, 64, v140
	ds_read_b128 v[132:135], v253
	ds_read_b128 v[136:139], v140 offset:2048
	ds_read_b128 v[140:143], v253 offset:2048
	ds_read_b128 v[144:147], v176
	v_xor_b32_e32 v253, 64, v176
	ds_read_b128 v[148:151], v253
	ds_read_b128 v[172:175], v176 offset:2048
	ds_read_b128 v[176:179], v253 offset:2048
	s_add_u32 s54, s60, 0xb0000
	s_addc_u32 s55, s61, 0
	s_mov_b32 m0, s68
	v_lshl_add_u64 v[230:231], s[54:55], 0, v[152:153]
	ds_read_b128 v[180:183], v191 offset:32768
	v_xor_b32_e32 v253, 64, v191
	ds_read_b128 v[194:197], v253 offset:32768
	ds_read_b128 v[198:201], v191 offset:34816
	ds_read_b128 v[202:205], v253 offset:34816
	ds_read_b128 v[206:209], v191 offset:36864
	ds_read_b128 v[210:213], v253 offset:36864
	ds_read_b128 v[214:217], v191 offset:38912
	ds_read_b128 v[218:221], v253 offset:38912
	global_load_lds_dwordx4 v[230:231], off
	v_lshl_add_u64 v[230:231], s[54:55], 0, v[160:161]
	s_mov_b32 m0, s69
	s_nop 0
	global_load_lds_dwordx4 v[230:231], off
	s_waitcnt vmcnt(8)
	s_waitcnt lgkmcnt(0)
	s_setprio 1
	s_barrier
	v_mfma_f32_16x16x32_bf16 v[124:127], v[128:131], v[180:183], v[124:127]
	v_mfma_f32_16x16x32_bf16 v[124:127], v[132:135], v[194:197], v[124:127]
	v_mfma_f32_16x16x32_bf16 v[108:111], v[132:135], v[202:205], v[108:111]
	v_mfma_f32_16x16x32_bf16 v[108:111], v[128:131], v[198:201], v[108:111]
	v_mfma_f32_16x16x32_bf16 v[92:95], v[128:131], v[206:209], v[92:95]
	v_mfma_f32_16x16x32_bf16 v[92:95], v[132:135], v[210:213], v[92:95]
	v_mfma_f32_16x16x32_bf16 v[76:79], v[132:135], v[218:221], v[76:79]
	v_mfma_f32_16x16x32_bf16 v[76:79], v[128:131], v[214:217], v[76:79]
	v_mfma_f32_16x16x32_bf16 v[72:75], v[136:139], v[214:217], v[72:75]
	v_mfma_f32_16x16x32_bf16 v[72:75], v[140:143], v[218:221], v[72:75]
	v_mfma_f32_16x16x32_bf16 v[88:91], v[140:143], v[210:213], v[88:91]
	v_mfma_f32_16x16x32_bf16 v[88:91], v[136:139], v[206:209], v[88:91]
	v_mfma_f32_16x16x32_bf16 v[104:107], v[136:139], v[198:201], v[104:107]
	v_mfma_f32_16x16x32_bf16 v[104:107], v[140:143], v[202:205], v[104:107]
	v_mfma_f32_16x16x32_bf16 v[120:123], v[140:143], v[194:197], v[120:123]
	v_mfma_f32_16x16x32_bf16 v[120:123], v[136:139], v[180:183], v[120:123]
	s_setprio 0
	s_setprio 1
	v_mfma_f32_16x16x32_bf16 v[112:115], v[172:175], v[180:183], v[112:115]
	v_mfma_f32_16x16x32_bf16 v[112:115], v[176:179], v[194:197], v[112:115]
	v_mfma_f32_16x16x32_bf16 v[96:99], v[176:179], v[202:205], v[96:99]
	v_mfma_f32_16x16x32_bf16 v[96:99], v[172:175], v[198:201], v[96:99]
	v_mfma_f32_16x16x32_bf16 v[80:83], v[172:175], v[206:209], v[80:83]
	v_mfma_f32_16x16x32_bf16 v[80:83], v[176:179], v[210:213], v[80:83]
	v_mfma_f32_16x16x32_bf16 v[64:67], v[176:179], v[218:221], v[64:67]
	v_mfma_f32_16x16x32_bf16 v[64:67], v[172:175], v[214:217], v[64:67]
	v_mfma_f32_16x16x32_bf16 v[68:71], v[144:147], v[214:217], v[68:71]
	v_mfma_f32_16x16x32_bf16 v[68:71], v[148:151], v[218:221], v[68:71]
	v_mfma_f32_16x16x32_bf16 v[84:87], v[148:151], v[210:213], v[84:87]
	v_mfma_f32_16x16x32_bf16 v[84:87], v[144:147], v[206:209], v[84:87]
	v_mfma_f32_16x16x32_bf16 v[100:103], v[144:147], v[198:201], v[100:103]
	v_mfma_f32_16x16x32_bf16 v[100:103], v[148:151], v[202:205], v[100:103]
	v_mfma_f32_16x16x32_bf16 v[116:119], v[148:151], v[194:197], v[116:119]
	v_mfma_f32_16x16x32_bf16 v[116:119], v[144:147], v[180:183], v[116:119]
	s_barrier
	s_setprio 0
	s_add_i32 s54, s82, s65
	v_lshl_add_u64 v[222:223], v[222:223], 0, s[28:29]
	s_mov_b32 m0, s54
	ds_read_b128 v[180:183], v191 offset:49152
	v_xor_b32_e32 v253, 64, v191
	ds_read_b128 v[194:197], v253 offset:49152
	ds_read_b128 v[198:201], v191 offset:51200
	ds_read_b128 v[202:205], v253 offset:51200
	ds_read_b128 v[206:209], v191 offset:53248
	ds_read_b128 v[210:213], v253 offset:53248
	ds_read_b128 v[214:217], v191 offset:55296
	ds_read_b128 v[218:221], v253 offset:55296
	global_load_lds_dwordx4 v[222:223], off
	s_add_i32 m0, s54, 0x2000
	s_add_u32 s54, s58, 0xb0080
	v_lshl_add_u64 v[222:223], v[224:225], 0, s[28:29]
	s_addc_u32 s55, s59, 0
	s_add_i32 s58, s83, s65
	global_load_lds_dwordx4 v[222:223], off
	v_lshl_add_u64 v[222:223], s[54:55], 0, v[154:155]
	s_mov_b32 m0, s58
	s_nop 0
	global_load_lds_dwordx4 v[222:223], off
	v_lshl_add_u64 v[222:223], s[54:55], 0, v[162:163]
	s_add_i32 m0, s58, 0x2000
	s_nop 0
	global_load_lds_dwordx4 v[222:223], off
	v_lshl_add_u64 v[222:223], v[226:227], 0, s[28:29]
	s_mov_b32 m0, s3
	s_nop 0
	global_load_lds_dwordx4 v[222:223], off
	v_lshl_add_u64 v[222:223], v[228:229], 0, s[28:29]
	s_mov_b32 m0, s71
	s_nop 0
	global_load_lds_dwordx4 v[222:223], off
	s_waitcnt vmcnt(8)
	s_waitcnt lgkmcnt(0)
	s_setprio 1
	s_barrier
	v_mfma_f32_16x16x32_bf16 v[60:63], v[128:131], v[180:183], v[60:63]
	v_mfma_f32_16x16x32_bf16 v[60:63], v[132:135], v[194:197], v[60:63]
	v_mfma_f32_16x16x32_bf16 v[44:47], v[132:135], v[202:205], v[44:47]
	v_mfma_f32_16x16x32_bf16 v[44:47], v[128:131], v[198:201], v[44:47]
	v_mfma_f32_16x16x32_bf16 v[28:31], v[128:131], v[206:209], v[28:31]
	v_mfma_f32_16x16x32_bf16 v[28:31], v[132:135], v[210:213], v[28:31]
	v_mfma_f32_16x16x32_bf16 v[12:15], v[132:135], v[218:221], v[12:15]
	v_mfma_f32_16x16x32_bf16 v[12:15], v[128:131], v[214:217], v[12:15]
	v_mfma_f32_16x16x32_bf16 v[8:11], v[136:139], v[214:217], v[8:11]
	v_mfma_f32_16x16x32_bf16 v[8:11], v[140:143], v[218:221], v[8:11]
	v_mfma_f32_16x16x32_bf16 v[24:27], v[140:143], v[210:213], v[24:27]
	v_mfma_f32_16x16x32_bf16 v[24:27], v[136:139], v[206:209], v[24:27]
	v_mfma_f32_16x16x32_bf16 v[40:43], v[136:139], v[198:201], v[40:43]
	v_mfma_f32_16x16x32_bf16 v[40:43], v[140:143], v[202:205], v[40:43]
	v_mfma_f32_16x16x32_bf16 v[56:59], v[140:143], v[194:197], v[56:59]
	v_mfma_f32_16x16x32_bf16 v[56:59], v[136:139], v[180:183], v[56:59]
	s_setprio 0
	s_setprio 1
	v_mfma_f32_16x16x32_bf16 v[48:51], v[172:175], v[180:183], v[48:51]
	v_mfma_f32_16x16x32_bf16 v[48:51], v[176:179], v[194:197], v[48:51]
	v_mfma_f32_16x16x32_bf16 v[32:35], v[176:179], v[202:205], v[32:35]
	v_mfma_f32_16x16x32_bf16 v[32:35], v[172:175], v[198:201], v[32:35]
	v_mfma_f32_16x16x32_bf16 v[16:19], v[172:175], v[206:209], v[16:19]
	v_mfma_f32_16x16x32_bf16 v[16:19], v[176:179], v[210:213], v[16:19]
	v_mfma_f32_16x16x32_bf16 v[0:3], v[176:179], v[218:221], v[0:3]
	v_mfma_f32_16x16x32_bf16 v[0:3], v[172:175], v[214:217], v[0:3]
	v_mfma_f32_16x16x32_bf16 v[4:7], v[144:147], v[214:217], v[4:7]
	v_mfma_f32_16x16x32_bf16 v[4:7], v[148:151], v[218:221], v[4:7]
	v_mfma_f32_16x16x32_bf16 v[20:23], v[148:151], v[210:213], v[20:23]
	v_mfma_f32_16x16x32_bf16 v[20:23], v[144:147], v[206:209], v[20:23]
	v_mfma_f32_16x16x32_bf16 v[36:39], v[144:147], v[198:201], v[36:39]
	v_mfma_f32_16x16x32_bf16 v[36:39], v[148:151], v[202:205], v[36:39]
	v_mfma_f32_16x16x32_bf16 v[52:55], v[148:151], v[194:197], v[52:55]
	v_mfma_f32_16x16x32_bf16 v[52:55], v[144:147], v[180:183], v[52:55]
	s_barrier
	s_setprio 0
	s_add_i32 s81, s81, 2
	s_add_u32 s79, s79, 0x100
	s_addc_u32 s80, s80, 0
	s_cmp_gt_u32 s81, 41
	s_mov_b64 s[54:55], s[56:57]
	s_branch .LBB0_610
.Lfa_5:
	ds_read_b128 v[128:131], v189
	v_xor_b32_e32 v253, 64, v189
	ds_read_b128 v[132:135], v253
	ds_read_b128 v[136:139], v189 offset:2048
	ds_read_b128 v[140:143], v253 offset:2048
	ds_read_b128 v[144:147], v190
	v_xor_b32_e32 v253, 64, v190
	ds_read_b128 v[148:151], v253
	ds_read_b128 v[172:175], v190 offset:2048
	ds_read_b128 v[176:179], v253 offset:2048
	s_add_u32 s56, s54, 0x100
	s_addc_u32 s57, s55, 0
	s_cmp_eq_u32 s81, 40
	s_cselect_b32 s61, s17, s57
	s_cselect_b32 s60, s16, s56
	s_cselect_b32 s59, s53, s80
	s_cselect_b32 s58, s52, s79
	v_lshl_add_u64 v[222:223], s[54:55], 0, v[166:167]
	s_add_i32 m0, s66, 0xc000
	ds_read_b128 v[180:183], v191
	v_xor_b32_e32 v253, 64, v191
	ds_read_b128 v[194:197], v253
	ds_read_b128 v[198:201], v191 offset:2048
	ds_read_b128 v[202:205], v253 offset:2048
	ds_read_b128 v[206:209], v191 offset:4096
	ds_read_b128 v[210:213], v253 offset:4096
	ds_read_b128 v[214:217], v191 offset:6144
	ds_read_b128 v[218:221], v253 offset:6144
	global_load_lds_dwordx4 v[222:223], off
	v_lshl_add_u64 v[222:223], s[54:55], 0, v[164:165]
	s_add_i32 m0, s66, 0xe000
	s_nop 0
	global_load_lds_dwordx4 v[222:223], off
	s_waitcnt vmcnt(8)
	s_waitcnt lgkmcnt(0)
	s_setprio 1
	s_barrier
	v_mfma_f32_16x16x32_bf16 v[124:127], v[128:131], v[180:183], 0
	v_mfma_f32_16x16x32_bf16 v[120:123], v[136:139], v[180:183], 0
	v_mfma_f32_16x16x32_bf16 v[108:111], v[128:131], v[198:201], 0
	v_mfma_f32_16x16x32_bf16 v[104:107], v[136:139], v[198:201], 0
	v_mfma_f32_16x16x32_bf16 v[92:95], v[128:131], v[206:209], 0
	v_mfma_f32_16x16x32_bf16 v[88:91], v[136:139], v[206:209], 0
	v_mfma_f32_16x16x32_bf16 v[76:79], v[128:131], v[214:217], 0
	v_mfma_f32_16x16x32_bf16 v[72:75], v[136:139], v[214:217], 0
	v_mfma_f32_16x16x32_bf16 v[124:127], v[132:135], v[194:197], v[124:127]
	v_mfma_f32_16x16x32_bf16 v[120:123], v[140:143], v[194:197], v[120:123]
	v_mfma_f32_16x16x32_bf16 v[108:111], v[132:135], v[202:205], v[108:111]
	v_mfma_f32_16x16x32_bf16 v[104:107], v[140:143], v[202:205], v[104:107]
	v_mfma_f32_16x16x32_bf16 v[92:95], v[132:135], v[210:213], v[92:95]
	v_mfma_f32_16x16x32_bf16 v[88:91], v[140:143], v[210:213], v[88:91]
	v_mfma_f32_16x16x32_bf16 v[76:79], v[132:135], v[218:221], v[76:79]
	v_mfma_f32_16x16x32_bf16 v[72:75], v[140:143], v[218:221], v[72:75]
	s_setprio 0
	s_setprio 1
	v_mfma_f32_16x16x32_bf16 v[116:119], v[144:147], v[180:183], 0
	v_mfma_f32_16x16x32_bf16 v[112:115], v[172:175], v[180:183], 0
	v_mfma_f32_16x16x32_bf16 v[100:103], v[144:147], v[198:201], 0
	v_mfma_f32_16x16x32_bf16 v[96:99], v[172:175], v[198:201], 0
	v_mfma_f32_16x16x32_bf16 v[84:87], v[144:147], v[206:209], 0
	v_mfma_f32_16x16x32_bf16 v[80:83], v[172:175], v[206:209], 0
	v_mfma_f32_16x16x32_bf16 v[68:71], v[144:147], v[214:217], 0
	v_mfma_f32_16x16x32_bf16 v[64:67], v[172:175], v[214:217], 0
	v_mfma_f32_16x16x32_bf16 v[116:119], v[148:151], v[194:197], v[116:119]
	v_mfma_f32_16x16x32_bf16 v[112:115], v[176:179], v[194:197], v[112:115]
	v_mfma_f32_16x16x32_bf16 v[100:103], v[148:151], v[202:205], v[100:103]
	v_mfma_f32_16x16x32_bf16 v[96:99], v[176:179], v[202:205], v[96:99]
	v_mfma_f32_16x16x32_bf16 v[84:87], v[148:151], v[210:213], v[84:87]
	v_mfma_f32_16x16x32_bf16 v[80:83], v[176:179], v[210:213], v[80:83]
	v_mfma_f32_16x16x32_bf16 v[68:71], v[148:151], v[218:221], v[68:71]
	v_mfma_f32_16x16x32_bf16 v[64:67], v[176:179], v[218:221], v[64:67]
	s_barrier
	s_setprio 0
	s_add_i32 s54, s75, s65
	v_lshl_add_u64 v[222:223], s[58:59], 0, v[154:155]
	s_mov_b32 m0, s54
	ds_read_b128 v[180:183], v191 offset:16384
	v_xor_b32_e32 v253, 64, v191
	ds_read_b128 v[194:197], v253 offset:16384
	ds_read_b128 v[198:201], v191 offset:18432
	ds_read_b128 v[202:205], v253 offset:18432
	ds_read_b128 v[206:209], v191 offset:20480
	ds_read_b128 v[210:213], v253 offset:20480
	ds_read_b128 v[214:217], v191 offset:22528
	ds_read_b128 v[218:221], v253 offset:22528
	global_load_lds_dwordx4 v[222:223], off
	s_add_i32 m0, s54, 0x2000
	s_add_u32 s54, s58, 0xb0000
	v_lshl_add_u64 v[224:225], s[58:59], 0, v[162:163]
	s_addc_u32 s55, s59, 0
	s_add_i32 s82, s76, s65
	global_load_lds_dwordx4 v[224:225], off
	v_lshl_add_u64 v[226:227], s[54:55], 0, v[154:155]
	s_mov_b32 m0, s82
	v_lshl_add_u64 v[228:229], s[60:61], 0, v[160:161]
	global_load_lds_dwordx4 v[226:227], off
	v_lshl_add_u64 v[226:227], s[54:55], 0, v[162:163]
	s_add_i32 m0, s82, 0x2000
	s_nop 0
	global_load_lds_dwordx4 v[226:227], off
	v_lshl_add_u64 v[226:227], s[60:61], 0, v[152:153]
	s_mov_b32 m0, s66
	s_nop 0
	global_load_lds_dwordx4 v[226:227], off
	s_mov_b32 m0, s67
	s_nop 0
	global_load_lds_dwordx4 v[228:229], off
	s_waitcnt vmcnt(8)
	s_waitcnt lgkmcnt(0)
	s_setprio 1
	s_barrier
	v_mfma_f32_16x16x32_bf16 v[60:63], v[128:131], v[180:183], 0
	v_mfma_f32_16x16x32_bf16 v[56:59], v[136:139], v[180:183], 0
	v_mfma_f32_16x16x32_bf16 v[44:47], v[128:131], v[198:201], 0
	v_mfma_f32_16x16x32_bf16 v[40:43], v[136:139], v[198:201], 0
	v_mfma_f32_16x16x32_bf16 v[28:31], v[128:131], v[206:209], 0
	v_mfma_f32_16x16x32_bf16 v[24:27], v[136:139], v[206:209], 0
	v_mfma_f32_16x16x32_bf16 v[12:15], v[128:131], v[214:217], 0
	v_mfma_f32_16x16x32_bf16 v[8:11], v[136:139], v[214:217], 0
	v_mfma_f32_16x16x32_bf16 v[60:63], v[132:135], v[194:197], v[60:63]
	v_mfma_f32_16x16x32_bf16 v[56:59], v[140:143], v[194:197], v[56:59]
	v_mfma_f32_16x16x32_bf16 v[44:47], v[132:135], v[202:205], v[44:47]
	v_mfma_f32_16x16x32_bf16 v[40:43], v[140:143], v[202:205], v[40:43]
	v_mfma_f32_16x16x32_bf16 v[28:31], v[132:135], v[210:213], v[28:31]
	v_mfma_f32_16x16x32_bf16 v[24:27], v[140:143], v[210:213], v[24:27]
	v_mfma_f32_16x16x32_bf16 v[12:15], v[132:135], v[218:221], v[12:15]
	v_mfma_f32_16x16x32_bf16 v[8:11], v[140:143], v[218:221], v[8:11]
	s_setprio 0
	s_setprio 1
	v_mfma_f32_16x16x32_bf16 v[52:55], v[144:147], v[180:183], 0
	v_mfma_f32_16x16x32_bf16 v[48:51], v[172:175], v[180:183], 0
	v_mfma_f32_16x16x32_bf16 v[36:39], v[144:147], v[198:201], 0
	v_mfma_f32_16x16x32_bf16 v[32:35], v[172:175], v[198:201], 0
	v_mfma_f32_16x16x32_bf16 v[20:23], v[144:147], v[206:209], 0
	v_mfma_f32_16x16x32_bf16 v[16:19], v[172:175], v[206:209], 0
	v_mfma_f32_16x16x32_bf16 v[4:7], v[144:147], v[214:217], 0
	v_mfma_f32_16x16x32_bf16 v[0:3], v[172:175], v[214:217], 0
	v_mfma_f32_16x16x32_bf16 v[52:55], v[148:151], v[194:197], v[52:55]
	v_mfma_f32_16x16x32_bf16 v[48:51], v[176:179], v[194:197], v[48:51]
	v_mfma_f32_16x16x32_bf16 v[36:39], v[148:151], v[202:205], v[36:39]
	v_mfma_f32_16x16x32_bf16 v[32:35], v[176:179], v[202:205], v[32:35]
	v_mfma_f32_16x16x32_bf16 v[20:23], v[148:151], v[210:213], v[20:23]
	v_mfma_f32_16x16x32_bf16 v[16:19], v[176:179], v[210:213], v[16:19]
	v_mfma_f32_16x16x32_bf16 v[4:7], v[148:151], v[218:221], v[4:7]
	v_mfma_f32_16x16x32_bf16 v[0:3], v[176:179], v[218:221], v[0:3]
	s_barrier
	s_setprio 0
	s_add_i32 s82, 0, 0x18000
	s_add_i32 s83, 0, 0x1c000
	v_add_u32_e32 v140, s82, v186
	v_add_u32_e32 v176, s83, v186
	ds_read_b128 v[128:131], v140
	v_xor_b32_e32 v253, 64, v140
	ds_read_b128 v[132:135], v253
	ds_read_b128 v[136:139], v140 offset:2048
	ds_read_b128 v[140:143], v253 offset:2048
	ds_read_b128 v[144:147], v176
	v_xor_b32_e32 v253, 64, v176
	ds_read_b128 v[148:151], v253
	ds_read_b128 v[172:175], v176 offset:2048
	ds_read_b128 v[176:179], v253 offset:2048
	s_add_u32 s54, s60, 0xb0000
	s_addc_u32 s55, s61, 0
	s_mov_b32 m0, s68
	v_lshl_add_u64 v[230:231], s[54:55], 0, v[152:153]
	ds_read_b128 v[180:183], v191 offset:32768
	v_xor_b32_e32 v253, 64, v191
	ds_read_b128 v[194:197], v253 offset:32768
	ds_read_b128 v[198:201], v191 offset:34816
	ds_read_b128 v[202:205], v253 offset:34816
	ds_read_b128 v[206:209], v191 offset:36864
	ds_read_b128 v[210:213], v253 offset:36864
	ds_read_b128 v[214:217], v191 offset:38912
	ds_read_b128 v[218:221], v253 offset:38912
	global_load_lds_dwordx4 v[230:231], off
	v_lshl_add_u64 v[230:231], s[54:55], 0, v[160:161]
	s_mov_b32 m0, s69
	s_nop 0
	global_load_lds_dwordx4 v[230:231], off
	s_waitcnt vmcnt(8)
	s_waitcnt lgkmcnt(0)
	s_setprio 1
	s_barrier
	v_mfma_f32_16x16x32_bf16 v[124:127], v[128:131], v[180:183], v[124:127]
	v_mfma_f32_16x16x32_bf16 v[124:127], v[132:135], v[194:197], v[124:127]
	v_mfma_f32_16x16x32_bf16 v[108:111], v[132:135], v[202:205], v[108:111]
	v_mfma_f32_16x16x32_bf16 v[108:111], v[128:131], v[198:201], v[108:111]
	v_mfma_f32_16x16x32_bf16 v[92:95], v[128:131], v[206:209], v[92:95]
	v_mfma_f32_16x16x32_bf16 v[92:95], v[132:135], v[210:213], v[92:95]
	v_mfma_f32_16x16x32_bf16 v[76:79], v[132:135], v[218:221], v[76:79]
	v_mfma_f32_16x16x32_bf16 v[76:79], v[128:131], v[214:217], v[76:79]
	v_mfma_f32_16x16x32_bf16 v[72:75], v[136:139], v[214:217], v[72:75]
	v_mfma_f32_16x16x32_bf16 v[72:75], v[140:143], v[218:221], v[72:75]
	v_mfma_f32_16x16x32_bf16 v[88:91], v[140:143], v[210:213], v[88:91]
	v_mfma_f32_16x16x32_bf16 v[88:91], v[136:139], v[206:209], v[88:91]
	v_mfma_f32_16x16x32_bf16 v[104:107], v[136:139], v[198:201], v[104:107]
	v_mfma_f32_16x16x32_bf16 v[104:107], v[140:143], v[202:205], v[104:107]
	v_mfma_f32_16x16x32_bf16 v[120:123], v[140:143], v[194:197], v[120:123]
	v_mfma_f32_16x16x32_bf16 v[120:123], v[136:139], v[180:183], v[120:123]
	s_setprio 0
	s_setprio 1
	v_mfma_f32_16x16x32_bf16 v[112:115], v[172:175], v[180:183], v[112:115]
	v_mfma_f32_16x16x32_bf16 v[112:115], v[176:179], v[194:197], v[112:115]
	v_mfma_f32_16x16x32_bf16 v[96:99], v[176:179], v[202:205], v[96:99]
	v_mfma_f32_16x16x32_bf16 v[96:99], v[172:175], v[198:201], v[96:99]
	v_mfma_f32_16x16x32_bf16 v[80:83], v[172:175], v[206:209], v[80:83]
	v_mfma_f32_16x16x32_bf16 v[80:83], v[176:179], v[210:213], v[80:83]
	v_mfma_f32_16x16x32_bf16 v[64:67], v[176:179], v[218:221], v[64:67]
	v_mfma_f32_16x16x32_bf16 v[64:67], v[172:175], v[214:217], v[64:67]
	v_mfma_f32_16x16x32_bf16 v[68:71], v[144:147], v[214:217], v[68:71]
	v_mfma_f32_16x16x32_bf16 v[68:71], v[148:151], v[218:221], v[68:71]
	v_mfma_f32_16x16x32_bf16 v[84:87], v[148:151], v[210:213], v[84:87]
	v_mfma_f32_16x16x32_bf16 v[84:87], v[144:147], v[206:209], v[84:87]
	v_mfma_f32_16x16x32_bf16 v[100:103], v[144:147], v[198:201], v[100:103]
	v_mfma_f32_16x16x32_bf16 v[100:103], v[148:151], v[202:205], v[100:103]
	v_mfma_f32_16x16x32_bf16 v[116:119], v[148:151], v[194:197], v[116:119]
	v_mfma_f32_16x16x32_bf16 v[116:119], v[144:147], v[180:183], v[116:119]
	s_barrier
	s_setprio 0
	s_add_i32 s54, s82, s65
	v_lshl_add_u64 v[222:223], v[222:223], 0, s[28:29]
	s_mov_b32 m0, s54
	ds_read_b128 v[180:183], v191 offset:49152
	v_xor_b32_e32 v253, 64, v191
	ds_read_b128 v[194:197], v253 offset:49152
	ds_read_b128 v[198:201], v191 offset:51200
	ds_read_b128 v[202:205], v253 offset:51200
	ds_read_b128 v[206:209], v191 offset:53248
	ds_read_b128 v[210:213], v253 offset:53248
	ds_read_b128 v[214:217], v191 offset:55296
	ds_read_b128 v[218:221], v253 offset:55296
	global_load_lds_dwordx4 v[222:223], off
	s_add_i32 m0, s54, 0x2000
	s_add_u32 s54, s58, 0xb0080
	v_lshl_add_u64 v[222:223], v[224:225], 0, s[28:29]
	s_addc_u32 s55, s59, 0
	s_add_i32 s58, s83, s65
	global_load_lds_dwordx4 v[222:223], off
	v_lshl_add_u64 v[222:223], s[54:55], 0, v[154:155]
	s_mov_b32 m0, s58
	s_nop 0
	global_load_lds_dwordx4 v[222:223], off
	v_lshl_add_u64 v[222:223], s[54:55], 0, v[162:163]
	s_add_i32 m0, s58, 0x2000
	s_nop 0
	global_load_lds_dwordx4 v[222:223], off
	v_lshl_add_u64 v[222:223], v[226:227], 0, s[28:29]
	s_mov_b32 m0, s3
	s_nop 0
	global_load_lds_dwordx4 v[222:223], off
	v_lshl_add_u64 v[222:223], v[228:229], 0, s[28:29]
	s_mov_b32 m0, s71
	s_nop 0
	global_load_lds_dwordx4 v[222:223], off
	s_waitcnt vmcnt(8)
	s_waitcnt lgkmcnt(0)
	s_setprio 1
	s_barrier
	v_mfma_f32_16x16x32_bf16 v[60:63], v[128:131], v[180:183], v[60:63]
	v_mfma_f32_16x16x32_bf16 v[60:63], v[132:135], v[194:197], v[60:63]
	v_mfma_f32_16x16x32_bf16 v[44:47], v[132:135], v[202:205], v[44:47]
	v_mfma_f32_16x16x32_bf16 v[44:47], v[128:131], v[198:201], v[44:47]
	v_mfma_f32_16x16x32_bf16 v[28:31], v[128:131], v[206:209], v[28:31]
	v_mfma_f32_16x16x32_bf16 v[28:31], v[132:135], v[210:213], v[28:31]
	v_mfma_f32_16x16x32_bf16 v[12:15], v[132:135], v[218:221], v[12:15]
	v_mfma_f32_16x16x32_bf16 v[12:15], v[128:131], v[214:217], v[12:15]
	v_mfma_f32_16x16x32_bf16 v[8:11], v[136:139], v[214:217], v[8:11]
	v_mfma_f32_16x16x32_bf16 v[8:11], v[140:143], v[218:221], v[8:11]
	v_mfma_f32_16x16x32_bf16 v[24:27], v[140:143], v[210:213], v[24:27]
	v_mfma_f32_16x16x32_bf16 v[24:27], v[136:139], v[206:209], v[24:27]
	v_mfma_f32_16x16x32_bf16 v[40:43], v[136:139], v[198:201], v[40:43]
	v_mfma_f32_16x16x32_bf16 v[40:43], v[140:143], v[202:205], v[40:43]
	v_mfma_f32_16x16x32_bf16 v[56:59], v[140:143], v[194:197], v[56:59]
	v_mfma_f32_16x16x32_bf16 v[56:59], v[136:139], v[180:183], v[56:59]
	s_setprio 0
	s_setprio 1
	v_mfma_f32_16x16x32_bf16 v[48:51], v[172:175], v[180:183], v[48:51]
	v_mfma_f32_16x16x32_bf16 v[48:51], v[176:179], v[194:197], v[48:51]
	v_mfma_f32_16x16x32_bf16 v[32:35], v[176:179], v[202:205], v[32:35]
	v_mfma_f32_16x16x32_bf16 v[32:35], v[172:175], v[198:201], v[32:35]
	v_mfma_f32_16x16x32_bf16 v[16:19], v[172:175], v[206:209], v[16:19]
	v_mfma_f32_16x16x32_bf16 v[16:19], v[176:179], v[210:213], v[16:19]
	v_mfma_f32_16x16x32_bf16 v[0:3], v[176:179], v[218:221], v[0:3]
	v_mfma_f32_16x16x32_bf16 v[0:3], v[172:175], v[214:217], v[0:3]
	v_mfma_f32_16x16x32_bf16 v[4:7], v[144:147], v[214:217], v[4:7]
	v_mfma_f32_16x16x32_bf16 v[4:7], v[148:151], v[218:221], v[4:7]
	v_mfma_f32_16x16x32_bf16 v[20:23], v[148:151], v[210:213], v[20:23]
	v_mfma_f32_16x16x32_bf16 v[20:23], v[144:147], v[206:209], v[20:23]
	v_mfma_f32_16x16x32_bf16 v[36:39], v[144:147], v[198:201], v[36:39]
	v_mfma_f32_16x16x32_bf16 v[36:39], v[148:151], v[202:205], v[36:39]
	v_mfma_f32_16x16x32_bf16 v[52:55], v[148:151], v[194:197], v[52:55]
	v_mfma_f32_16x16x32_bf16 v[52:55], v[144:147], v[180:183], v[52:55]
	s_barrier
	s_setprio 0
	s_add_i32 s81, s81, 2
	s_add_u32 s79, s79, 0x100
	s_addc_u32 s80, s80, 0
	s_cmp_gt_u32 s81, 41
	s_mov_b64 s[54:55], s[56:57]
.LBB0_610:
	ds_read_b128 v[128:131], v189
	v_xor_b32_e32 v253, 64, v189
	ds_read_b128 v[132:135], v253
	ds_read_b128 v[136:139], v189 offset:2048
	ds_read_b128 v[140:143], v253 offset:2048
	ds_read_b128 v[144:147], v190
	v_xor_b32_e32 v253, 64, v190
	ds_read_b128 v[148:151], v253
	ds_read_b128 v[172:175], v190 offset:2048
	ds_read_b128 v[176:179], v253 offset:2048
	s_add_u32 s56, s54, 0x100
	s_addc_u32 s57, s55, 0
	s_cmp_eq_u32 s81, 40
	s_cselect_b32 s61, s17, s57
	s_cselect_b32 s60, s16, s56
	s_cselect_b32 s59, s53, s80
	s_cselect_b32 s58, s52, s79
	v_lshl_add_u64 v[222:223], s[54:55], 0, v[166:167]
	s_add_i32 m0, s66, 0xc000
	ds_read_b128 v[180:183], v191
	v_xor_b32_e32 v253, 64, v191
	ds_read_b128 v[194:197], v253
	ds_read_b128 v[198:201], v191 offset:2048
	ds_read_b128 v[202:205], v253 offset:2048
	ds_read_b128 v[206:209], v191 offset:4096
	ds_read_b128 v[210:213], v253 offset:4096
	ds_read_b128 v[214:217], v191 offset:6144
	ds_read_b128 v[218:221], v253 offset:6144
	global_load_lds_dwordx4 v[222:223], off
	v_lshl_add_u64 v[222:223], s[54:55], 0, v[164:165]
	s_add_i32 m0, s66, 0xe000
	s_nop 0
	global_load_lds_dwordx4 v[222:223], off
	s_waitcnt vmcnt(8)
	s_waitcnt lgkmcnt(0)
	s_setprio 1
	s_barrier
	v_mfma_f32_16x16x32_bf16 v[124:127], v[128:131], v[180:183], v[124:127]
	v_mfma_f32_16x16x32_bf16 v[124:127], v[132:135], v[194:197], v[124:127]
	v_mfma_f32_16x16x32_bf16 v[108:111], v[132:135], v[202:205], v[108:111]
	v_mfma_f32_16x16x32_bf16 v[108:111], v[128:131], v[198:201], v[108:111]
	v_mfma_f32_16x16x32_bf16 v[92:95], v[128:131], v[206:209], v[92:95]
	v_mfma_f32_16x16x32_bf16 v[92:95], v[132:135], v[210:213], v[92:95]
	v_mfma_f32_16x16x32_bf16 v[76:79], v[132:135], v[218:221], v[76:79]
	v_mfma_f32_16x16x32_bf16 v[76:79], v[128:131], v[214:217], v[76:79]
	v_mfma_f32_16x16x32_bf16 v[72:75], v[136:139], v[214:217], v[72:75]
	v_mfma_f32_16x16x32_bf16 v[72:75], v[140:143], v[218:221], v[72:75]
	v_mfma_f32_16x16x32_bf16 v[88:91], v[140:143], v[210:213], v[88:91]
	v_mfma_f32_16x16x32_bf16 v[88:91], v[136:139], v[206:209], v[88:91]
	v_mfma_f32_16x16x32_bf16 v[104:107], v[136:139], v[198:201], v[104:107]
	v_mfma_f32_16x16x32_bf16 v[104:107], v[140:143], v[202:205], v[104:107]
	v_mfma_f32_16x16x32_bf16 v[120:123], v[140:143], v[194:197], v[120:123]
	v_mfma_f32_16x16x32_bf16 v[120:123], v[136:139], v[180:183], v[120:123]
	s_setprio 0
	s_setprio 1
	v_mfma_f32_16x16x32_bf16 v[112:115], v[172:175], v[180:183], v[112:115]
	v_mfma_f32_16x16x32_bf16 v[112:115], v[176:179], v[194:197], v[112:115]
	v_mfma_f32_16x16x32_bf16 v[96:99], v[176:179], v[202:205], v[96:99]
	v_mfma_f32_16x16x32_bf16 v[96:99], v[172:175], v[198:201], v[96:99]
	v_mfma_f32_16x16x32_bf16 v[80:83], v[172:175], v[206:209], v[80:83]
	v_mfma_f32_16x16x32_bf16 v[80:83], v[176:179], v[210:213], v[80:83]
	v_mfma_f32_16x16x32_bf16 v[64:67], v[176:179], v[218:221], v[64:67]
	v_mfma_f32_16x16x32_bf16 v[64:67], v[172:175], v[214:217], v[64:67]
	v_mfma_f32_16x16x32_bf16 v[68:71], v[144:147], v[214:217], v[68:71]
	v_mfma_f32_16x16x32_bf16 v[68:71], v[148:151], v[218:221], v[68:71]
	v_mfma_f32_16x16x32_bf16 v[84:87], v[148:151], v[210:213], v[84:87]
	v_mfma_f32_16x16x32_bf16 v[84:87], v[144:147], v[206:209], v[84:87]
	v_mfma_f32_16x16x32_bf16 v[100:103], v[144:147], v[198:201], v[100:103]
	v_mfma_f32_16x16x32_bf16 v[100:103], v[148:151], v[202:205], v[100:103]
	v_mfma_f32_16x16x32_bf16 v[116:119], v[148:151], v[194:197], v[116:119]
	v_mfma_f32_16x16x32_bf16 v[116:119], v[144:147], v[180:183], v[116:119]
	s_barrier
	s_setprio 0
	s_add_i32 s54, s75, s65
	v_lshl_add_u64 v[222:223], s[58:59], 0, v[154:155]
	s_mov_b32 m0, s54
	ds_read_b128 v[180:183], v191 offset:16384
	v_xor_b32_e32 v253, 64, v191
	ds_read_b128 v[194:197], v253 offset:16384
	ds_read_b128 v[198:201], v191 offset:18432
	ds_read_b128 v[202:205], v253 offset:18432
	ds_read_b128 v[206:209], v191 offset:20480
	ds_read_b128 v[210:213], v253 offset:20480
	ds_read_b128 v[214:217], v191 offset:22528
	ds_read_b128 v[218:221], v253 offset:22528
	global_load_lds_dwordx4 v[222:223], off
	s_add_i32 m0, s54, 0x2000
	s_add_u32 s54, s58, 0xb0000
	v_lshl_add_u64 v[224:225], s[58:59], 0, v[162:163]
	s_addc_u32 s55, s59, 0
	s_add_i32 s82, s76, s65
	global_load_lds_dwordx4 v[224:225], off
	v_lshl_add_u64 v[226:227], s[54:55], 0, v[154:155]
	s_mov_b32 m0, s82
	v_lshl_add_u64 v[228:229], s[60:61], 0, v[160:161]
	global_load_lds_dwordx4 v[226:227], off
	v_lshl_add_u64 v[226:227], s[54:55], 0, v[162:163]
	s_add_i32 m0, s82, 0x2000
	s_nop 0
	global_load_lds_dwordx4 v[226:227], off
	v_lshl_add_u64 v[226:227], s[60:61], 0, v[152:153]
	s_mov_b32 m0, s66
	s_nop 0
	global_load_lds_dwordx4 v[226:227], off
	s_mov_b32 m0, s67
	s_nop 0
	global_load_lds_dwordx4 v[228:229], off
	s_waitcnt vmcnt(8)
	s_waitcnt lgkmcnt(0)
	s_setprio 1
	s_barrier
	v_mfma_f32_16x16x32_bf16 v[60:63], v[128:131], v[180:183], v[60:63]
	v_mfma_f32_16x16x32_bf16 v[60:63], v[132:135], v[194:197], v[60:63]
	v_mfma_f32_16x16x32_bf16 v[44:47], v[132:135], v[202:205], v[44:47]
	v_mfma_f32_16x16x32_bf16 v[44:47], v[128:131], v[198:201], v[44:47]
	v_mfma_f32_16x16x32_bf16 v[28:31], v[128:131], v[206:209], v[28:31]
	v_mfma_f32_16x16x32_bf16 v[28:31], v[132:135], v[210:213], v[28:31]
	v_mfma_f32_16x16x32_bf16 v[12:15], v[132:135], v[218:221], v[12:15]
	v_mfma_f32_16x16x32_bf16 v[12:15], v[128:131], v[214:217], v[12:15]
	v_mfma_f32_16x16x32_bf16 v[8:11], v[136:139], v[214:217], v[8:11]
	v_mfma_f32_16x16x32_bf16 v[8:11], v[140:143], v[218:221], v[8:11]
	v_mfma_f32_16x16x32_bf16 v[24:27], v[140:143], v[210:213], v[24:27]
	v_mfma_f32_16x16x32_bf16 v[24:27], v[136:139], v[206:209], v[24:27]
	v_mfma_f32_16x16x32_bf16 v[40:43], v[136:139], v[198:201], v[40:43]
	v_mfma_f32_16x16x32_bf16 v[40:43], v[140:143], v[202:205], v[40:43]
	v_mfma_f32_16x16x32_bf16 v[56:59], v[140:143], v[194:197], v[56:59]
	v_mfma_f32_16x16x32_bf16 v[56:59], v[136:139], v[180:183], v[56:59]
	s_setprio 0
	s_setprio 1
	v_mfma_f32_16x16x32_bf16 v[48:51], v[172:175], v[180:183], v[48:51]
	v_mfma_f32_16x16x32_bf16 v[48:51], v[176:179], v[194:197], v[48:51]
	v_mfma_f32_16x16x32_bf16 v[32:35], v[176:179], v[202:205], v[32:35]
	v_mfma_f32_16x16x32_bf16 v[32:35], v[172:175], v[198:201], v[32:35]
	v_mfma_f32_16x16x32_bf16 v[16:19], v[172:175], v[206:209], v[16:19]
	v_mfma_f32_16x16x32_bf16 v[16:19], v[176:179], v[210:213], v[16:19]
	v_mfma_f32_16x16x32_bf16 v[0:3], v[176:179], v[218:221], v[0:3]
	v_mfma_f32_16x16x32_bf16 v[0:3], v[172:175], v[214:217], v[0:3]
	v_mfma_f32_16x16x32_bf16 v[4:7], v[144:147], v[214:217], v[4:7]
	v_mfma_f32_16x16x32_bf16 v[4:7], v[148:151], v[218:221], v[4:7]
	v_mfma_f32_16x16x32_bf16 v[20:23], v[148:151], v[210:213], v[20:23]
	v_mfma_f32_16x16x32_bf16 v[20:23], v[144:147], v[206:209], v[20:23]
	v_mfma_f32_16x16x32_bf16 v[36:39], v[144:147], v[198:201], v[36:39]
	v_mfma_f32_16x16x32_bf16 v[36:39], v[148:151], v[202:205], v[36:39]
	v_mfma_f32_16x16x32_bf16 v[52:55], v[148:151], v[194:197], v[52:55]
	v_mfma_f32_16x16x32_bf16 v[52:55], v[144:147], v[180:183], v[52:55]
	s_barrier
	s_setprio 0
	s_add_i32 s82, 0, 0x18000
	s_add_i32 s83, 0, 0x1c000
	v_add_u32_e32 v140, s82, v186
	v_add_u32_e32 v176, s83, v186
	ds_read_b128 v[128:131], v140
	v_xor_b32_e32 v253, 64, v140
	ds_read_b128 v[132:135], v253
	ds_read_b128 v[136:139], v140 offset:2048
	ds_read_b128 v[140:143], v253 offset:2048
	ds_read_b128 v[144:147], v176
	v_xor_b32_e32 v253, 64, v176
	ds_read_b128 v[148:151], v253
	ds_read_b128 v[172:175], v176 offset:2048
	ds_read_b128 v[176:179], v253 offset:2048
	s_add_u32 s54, s60, 0xb0000
	s_addc_u32 s55, s61, 0
	s_mov_b32 m0, s68
	v_lshl_add_u64 v[230:231], s[54:55], 0, v[152:153]
	ds_read_b128 v[180:183], v191 offset:32768
	v_xor_b32_e32 v253, 64, v191
	ds_read_b128 v[194:197], v253 offset:32768
	ds_read_b128 v[198:201], v191 offset:34816
	ds_read_b128 v[202:205], v253 offset:34816
	ds_read_b128 v[206:209], v191 offset:36864
	ds_read_b128 v[210:213], v253 offset:36864
	ds_read_b128 v[214:217], v191 offset:38912
	ds_read_b128 v[218:221], v253 offset:38912
	global_load_lds_dwordx4 v[230:231], off
	v_lshl_add_u64 v[230:231], s[54:55], 0, v[160:161]
	s_mov_b32 m0, s69
	s_nop 0
	global_load_lds_dwordx4 v[230:231], off
	s_waitcnt vmcnt(8)
	s_waitcnt lgkmcnt(0)
	s_setprio 1
	s_barrier
	v_mfma_f32_16x16x32_bf16 v[124:127], v[128:131], v[180:183], v[124:127]
	v_mfma_f32_16x16x32_bf16 v[124:127], v[132:135], v[194:197], v[124:127]
	v_mfma_f32_16x16x32_bf16 v[108:111], v[132:135], v[202:205], v[108:111]
	v_mfma_f32_16x16x32_bf16 v[108:111], v[128:131], v[198:201], v[108:111]
	v_mfma_f32_16x16x32_bf16 v[92:95], v[128:131], v[206:209], v[92:95]
	v_mfma_f32_16x16x32_bf16 v[92:95], v[132:135], v[210:213], v[92:95]
	v_mfma_f32_16x16x32_bf16 v[76:79], v[132:135], v[218:221], v[76:79]
	v_mfma_f32_16x16x32_bf16 v[76:79], v[128:131], v[214:217], v[76:79]
	v_mfma_f32_16x16x32_bf16 v[72:75], v[136:139], v[214:217], v[72:75]
	v_mfma_f32_16x16x32_bf16 v[72:75], v[140:143], v[218:221], v[72:75]
	v_mfma_f32_16x16x32_bf16 v[88:91], v[140:143], v[210:213], v[88:91]
	v_mfma_f32_16x16x32_bf16 v[88:91], v[136:139], v[206:209], v[88:91]
	v_mfma_f32_16x16x32_bf16 v[104:107], v[136:139], v[198:201], v[104:107]
	v_mfma_f32_16x16x32_bf16 v[104:107], v[140:143], v[202:205], v[104:107]
	v_mfma_f32_16x16x32_bf16 v[120:123], v[140:143], v[194:197], v[120:123]
	v_mfma_f32_16x16x32_bf16 v[120:123], v[136:139], v[180:183], v[120:123]
	s_setprio 0
	s_setprio 1
	v_mfma_f32_16x16x32_bf16 v[112:115], v[172:175], v[180:183], v[112:115]
	v_mfma_f32_16x16x32_bf16 v[112:115], v[176:179], v[194:197], v[112:115]
	v_mfma_f32_16x16x32_bf16 v[96:99], v[176:179], v[202:205], v[96:99]
	v_mfma_f32_16x16x32_bf16 v[96:99], v[172:175], v[198:201], v[96:99]
	v_mfma_f32_16x16x32_bf16 v[80:83], v[172:175], v[206:209], v[80:83]
	v_mfma_f32_16x16x32_bf16 v[80:83], v[176:179], v[210:213], v[80:83]
	v_mfma_f32_16x16x32_bf16 v[64:67], v[176:179], v[218:221], v[64:67]
	v_mfma_f32_16x16x32_bf16 v[64:67], v[172:175], v[214:217], v[64:67]
	v_mfma_f32_16x16x32_bf16 v[68:71], v[144:147], v[214:217], v[68:71]
	v_mfma_f32_16x16x32_bf16 v[68:71], v[148:151], v[218:221], v[68:71]
	v_mfma_f32_16x16x32_bf16 v[84:87], v[148:151], v[210:213], v[84:87]
	v_mfma_f32_16x16x32_bf16 v[84:87], v[144:147], v[206:209], v[84:87]
	v_mfma_f32_16x16x32_bf16 v[100:103], v[144:147], v[198:201], v[100:103]
	v_mfma_f32_16x16x32_bf16 v[100:103], v[148:151], v[202:205], v[100:103]
	v_mfma_f32_16x16x32_bf16 v[116:119], v[148:151], v[194:197], v[116:119]
	v_mfma_f32_16x16x32_bf16 v[116:119], v[144:147], v[180:183], v[116:119]
	s_barrier
	s_setprio 0
	s_add_i32 s54, s82, s65
	v_lshl_add_u64 v[222:223], v[222:223], 0, s[28:29]
	s_mov_b32 m0, s54
	ds_read_b128 v[180:183], v191 offset:49152
	v_xor_b32_e32 v253, 64, v191
	ds_read_b128 v[194:197], v253 offset:49152
	ds_read_b128 v[198:201], v191 offset:51200
	ds_read_b128 v[202:205], v253 offset:51200
	ds_read_b128 v[206:209], v191 offset:53248
	ds_read_b128 v[210:213], v253 offset:53248
	ds_read_b128 v[214:217], v191 offset:55296
	ds_read_b128 v[218:221], v253 offset:55296
	global_load_lds_dwordx4 v[222:223], off
	s_add_i32 m0, s54, 0x2000
	s_add_u32 s54, s58, 0xb0080
	v_lshl_add_u64 v[222:223], v[224:225], 0, s[28:29]
	s_addc_u32 s55, s59, 0
	s_add_i32 s58, s83, s65
	global_load_lds_dwordx4 v[222:223], off
	v_lshl_add_u64 v[222:223], s[54:55], 0, v[154:155]
	s_mov_b32 m0, s58
	s_nop 0
	global_load_lds_dwordx4 v[222:223], off
	v_lshl_add_u64 v[222:223], s[54:55], 0, v[162:163]
	s_add_i32 m0, s58, 0x2000
	s_nop 0
	global_load_lds_dwordx4 v[222:223], off
	v_lshl_add_u64 v[222:223], v[226:227], 0, s[28:29]
	s_mov_b32 m0, s3
	s_nop 0
	global_load_lds_dwordx4 v[222:223], off
	v_lshl_add_u64 v[222:223], v[228:229], 0, s[28:29]
	s_mov_b32 m0, s71
	s_nop 0
	global_load_lds_dwordx4 v[222:223], off
	s_waitcnt vmcnt(8)
	s_waitcnt lgkmcnt(0)
	s_setprio 1
	s_barrier
	v_mfma_f32_16x16x32_bf16 v[60:63], v[128:131], v[180:183], v[60:63]
	v_mfma_f32_16x16x32_bf16 v[60:63], v[132:135], v[194:197], v[60:63]
	v_mfma_f32_16x16x32_bf16 v[44:47], v[132:135], v[202:205], v[44:47]
	v_mfma_f32_16x16x32_bf16 v[44:47], v[128:131], v[198:201], v[44:47]
	v_mfma_f32_16x16x32_bf16 v[28:31], v[128:131], v[206:209], v[28:31]
	v_mfma_f32_16x16x32_bf16 v[28:31], v[132:135], v[210:213], v[28:31]
	v_mfma_f32_16x16x32_bf16 v[12:15], v[132:135], v[218:221], v[12:15]
	v_mfma_f32_16x16x32_bf16 v[12:15], v[128:131], v[214:217], v[12:15]
	v_mfma_f32_16x16x32_bf16 v[8:11], v[136:139], v[214:217], v[8:11]
	v_mfma_f32_16x16x32_bf16 v[8:11], v[140:143], v[218:221], v[8:11]
	v_mfma_f32_16x16x32_bf16 v[24:27], v[140:143], v[210:213], v[24:27]
	v_mfma_f32_16x16x32_bf16 v[24:27], v[136:139], v[206:209], v[24:27]
	v_mfma_f32_16x16x32_bf16 v[40:43], v[136:139], v[198:201], v[40:43]
	v_mfma_f32_16x16x32_bf16 v[40:43], v[140:143], v[202:205], v[40:43]
	v_mfma_f32_16x16x32_bf16 v[56:59], v[140:143], v[194:197], v[56:59]
	v_mfma_f32_16x16x32_bf16 v[56:59], v[136:139], v[180:183], v[56:59]
	s_setprio 0
	s_setprio 1
	v_mfma_f32_16x16x32_bf16 v[48:51], v[172:175], v[180:183], v[48:51]
	v_mfma_f32_16x16x32_bf16 v[48:51], v[176:179], v[194:197], v[48:51]
	v_mfma_f32_16x16x32_bf16 v[32:35], v[176:179], v[202:205], v[32:35]
	v_mfma_f32_16x16x32_bf16 v[32:35], v[172:175], v[198:201], v[32:35]
	v_mfma_f32_16x16x32_bf16 v[16:19], v[172:175], v[206:209], v[16:19]
	v_mfma_f32_16x16x32_bf16 v[16:19], v[176:179], v[210:213], v[16:19]
	v_mfma_f32_16x16x32_bf16 v[0:3], v[176:179], v[218:221], v[0:3]
	v_mfma_f32_16x16x32_bf16 v[0:3], v[172:175], v[214:217], v[0:3]
	v_mfma_f32_16x16x32_bf16 v[4:7], v[144:147], v[214:217], v[4:7]
	v_mfma_f32_16x16x32_bf16 v[4:7], v[148:151], v[218:221], v[4:7]
	v_mfma_f32_16x16x32_bf16 v[20:23], v[148:151], v[210:213], v[20:23]
	v_mfma_f32_16x16x32_bf16 v[20:23], v[144:147], v[206:209], v[20:23]
	v_mfma_f32_16x16x32_bf16 v[36:39], v[144:147], v[198:201], v[36:39]
	v_mfma_f32_16x16x32_bf16 v[36:39], v[148:151], v[202:205], v[36:39]
	v_mfma_f32_16x16x32_bf16 v[52:55], v[148:151], v[194:197], v[52:55]
	v_mfma_f32_16x16x32_bf16 v[52:55], v[144:147], v[180:183], v[52:55]
	s_barrier
	s_setprio 0
	s_add_i32 s81, s81, 2
	s_add_u32 s79, s79, 0x100
	s_addc_u32 s80, s80, 0
	s_cmp_gt_u32 s81, 41
	s_mov_b64 s[54:55], s[56:57]
	s_cbranch_scc0 .LBB0_610
	s_and_b64 vcc, exec, s[30:31]
	s_cbranch_vccz .LBB0_613
	s_barrier

.LBB0_873:
	s_ashr_i32 s49, s48, 31
	s_lshl_b64 s[50:51], s[48:49], 19
	s_add_u32 s50, s35, s50
	s_addc_u32 s51, s60, s51
	s_and_b64 s[52:53], s[10:11], exec
	s_cselect_b32 s49, s51, s59
	s_cselect_b32 s80, s50, s58
	s_ashr_i32 s47, s46, 31
	s_lshl_b64 s[52:53], s[46:47], 19
	s_add_u32 s52, s61, s52
	s_addc_u32 s53, s62, s53
	s_and_b64 s[82:83], s[10:11], exec
	s_cselect_b32 s81, s53, s57
	s_cselect_b32 s82, s52, s56
	s_lshl_b32 s47, s54, 8
	v_add_u32_e32 v0, s47, v151
	s_add_u32 s83, s56, 0x100
	v_ashrrev_i32_e32 v1, 31, v0
	s_addc_u32 s84, s57, 0
	v_lshl_add_u64 v[144:145], v[0:1], 4, s[20:21]
	s_add_u32 s54, s58, 0x40080
	s_addc_u32 s55, s59, 0
	s_mov_b32 s85, -2
	s_mov_b64 s[56:57], 0
	s_cmp_eq_u32 s68, 1
	s_cbranch_scc1 .Lfa_8
	v_add_u32_e32 v146, s73, v149
	ds_read_b128 v[162:165], v146
	v_xor_b32_e32 v253, 64, v146
	ds_read_b128 v[166:169], v253
	ds_read_b128 v[170:173], v146 offset:2048
	ds_read_b128 v[174:177], v253 offset:2048
	v_add_u32_e32 v146, s74, v149
	ds_read_b128 v[178:181], v146
	v_xor_b32_e32 v253, 64, v146
	ds_read_b128 v[186:189], v253
	ds_read_b128 v[190:193], v146 offset:2048
	ds_read_b128 v[194:197], v253 offset:2048
	s_add_u32 s58, s54, 0xfffc0080
	s_addc_u32 s59, s55, -1
	s_and_b64 s[56:57], s[56:57], exec
	s_cselect_b32 s59, s49, s59
	s_cselect_b32 s58, s80, s58
	s_cselect_b32 s57, s81, s84
	s_cselect_b32 s56, s82, s83
	v_lshl_add_u64 v[182:183], s[54:55], 0, v[138:139]
	s_add_i32 m0, s64, 0xc000
	ds_read_b128 v[198:201], v154
	v_xor_b32_e32 v253, 64, v154
	ds_read_b128 v[202:205], v253
	ds_read_b128 v[206:209], v154 offset:2048
	ds_read_b128 v[210:213], v253 offset:2048
	ds_read_b128 v[214:217], v154 offset:4096
	ds_read_b128 v[218:221], v253 offset:4096
	ds_read_b128 v[222:225], v154 offset:6144
	ds_read_b128 v[226:229], v253 offset:6144
	global_load_lds_dwordx4 v[182:183], off
	v_lshl_add_u64 v[182:183], s[54:55], 0, v[136:137]
	s_add_i32 m0, s64, 0xe000
	s_nop 0
	global_load_lds_dwordx4 v[182:183], off
	s_waitcnt vmcnt(24)
	s_waitcnt lgkmcnt(0)
	s_setprio 1
	s_barrier
	v_mfma_f32_16x16x32_bf16 v[124:127], v[162:165], v[198:201], 0
	v_mfma_f32_16x16x32_bf16 v[120:123], v[170:173], v[198:201], 0
	v_mfma_f32_16x16x32_bf16 v[112:115], v[162:165], v[206:209], 0
	v_mfma_f32_16x16x32_bf16 v[104:107], v[170:173], v[206:209], 0
	v_mfma_f32_16x16x32_bf16 v[96:99], v[162:165], v[214:217], 0
	v_mfma_f32_16x16x32_bf16 v[88:91], v[170:173], v[214:217], 0
	v_mfma_f32_16x16x32_bf16 v[80:83], v[162:165], v[222:225], 0
	v_mfma_f32_16x16x32_bf16 v[72:75], v[170:173], v[222:225], 0
	v_mfma_f32_16x16x32_bf16 v[124:127], v[166:169], v[202:205], v[124:127]
	v_mfma_f32_16x16x32_bf16 v[120:123], v[174:177], v[202:205], v[120:123]
	v_mfma_f32_16x16x32_bf16 v[112:115], v[166:169], v[210:213], v[112:115]
	v_mfma_f32_16x16x32_bf16 v[104:107], v[174:177], v[210:213], v[104:107]
	v_mfma_f32_16x16x32_bf16 v[96:99], v[166:169], v[218:221], v[96:99]
	v_mfma_f32_16x16x32_bf16 v[88:91], v[174:177], v[218:221], v[88:91]
	v_mfma_f32_16x16x32_bf16 v[80:83], v[166:169], v[226:229], v[80:83]
	v_mfma_f32_16x16x32_bf16 v[72:75], v[174:177], v[226:229], v[72:75]
	s_setprio 0
	s_setprio 1
	v_mfma_f32_16x16x32_bf16 v[116:119], v[178:181], v[198:201], 0
	v_mfma_f32_16x16x32_bf16 v[108:111], v[190:193], v[198:201], 0
	v_mfma_f32_16x16x32_bf16 v[100:103], v[178:181], v[206:209], 0
	v_mfma_f32_16x16x32_bf16 v[92:95], v[190:193], v[206:209], 0
	v_mfma_f32_16x16x32_bf16 v[84:87], v[178:181], v[214:217], 0
	v_mfma_f32_16x16x32_bf16 v[76:79], v[190:193], v[214:217], 0
	v_mfma_f32_16x16x32_bf16 v[68:71], v[178:181], v[222:225], 0
	v_mfma_f32_16x16x32_bf16 v[64:67], v[190:193], v[222:225], 0
	v_mfma_f32_16x16x32_bf16 v[116:119], v[186:189], v[202:205], v[116:119]
	v_mfma_f32_16x16x32_bf16 v[108:111], v[194:197], v[202:205], v[108:111]
	v_mfma_f32_16x16x32_bf16 v[100:103], v[186:189], v[210:213], v[100:103]
	v_mfma_f32_16x16x32_bf16 v[92:95], v[194:197], v[210:213], v[92:95]
	v_mfma_f32_16x16x32_bf16 v[84:87], v[186:189], v[218:221], v[84:87]
	v_mfma_f32_16x16x32_bf16 v[76:79], v[194:197], v[218:221], v[76:79]
	v_mfma_f32_16x16x32_bf16 v[68:71], v[186:189], v[226:229], v[68:71]
	v_mfma_f32_16x16x32_bf16 v[64:67], v[194:197], v[226:229], v[64:67]
	s_barrier
	s_setprio 0
	s_add_i32 s86, s73, s63
	v_lshl_add_u64 v[182:183], s[56:57], 0, v[130:131]
	s_mov_b32 m0, s86
	ds_read_b128 v[198:201], v154 offset:16384
	v_xor_b32_e32 v253, 64, v154
	ds_read_b128 v[202:205], v253 offset:16384
	ds_read_b128 v[206:209], v154 offset:18432
	ds_read_b128 v[210:213], v253 offset:18432
	ds_read_b128 v[214:217], v154 offset:20480
	ds_read_b128 v[218:221], v253 offset:20480
	ds_read_b128 v[222:225], v154 offset:22528
	ds_read_b128 v[226:229], v253 offset:22528
	global_load_lds_dwordx4 v[182:183], off
	s_add_i32 m0, s86, 0x2000
	s_add_u32 s86, s56, 0x40000
	v_lshl_add_u64 v[230:231], s[56:57], 0, v[134:135]
	s_addc_u32 s87, s57, 0
	s_add_i32 s88, s74, s63
	global_load_lds_dwordx4 v[230:231], off
	v_lshl_add_u64 v[232:233], s[86:87], 0, v[130:131]
	s_mov_b32 m0, s88
	v_lshl_add_u64 v[234:235], s[58:59], 0, v[132:133]
	global_load_lds_dwordx4 v[232:233], off
	v_lshl_add_u64 v[232:233], s[86:87], 0, v[134:135]
	s_add_i32 m0, s88, 0x2000
	s_nop 0
	global_load_lds_dwordx4 v[232:233], off
	v_lshl_add_u64 v[232:233], s[58:59], 0, v[128:129]
	s_mov_b32 m0, s64
	s_nop 0
	global_load_lds_dwordx4 v[232:233], off
	s_mov_b32 m0, s65
	s_nop 0
	global_load_lds_dwordx4 v[234:235], off
	s_waitcnt vmcnt(24)
	s_waitcnt lgkmcnt(0)
	s_setprio 1
	s_barrier
	v_mfma_f32_16x16x32_bf16 v[60:63], v[162:165], v[198:201], 0
	v_mfma_f32_16x16x32_bf16 v[56:59], v[170:173], v[198:201], 0
	v_mfma_f32_16x16x32_bf16 v[48:51], v[162:165], v[206:209], 0
	v_mfma_f32_16x16x32_bf16 v[40:43], v[170:173], v[206:209], 0
	v_mfma_f32_16x16x32_bf16 v[32:35], v[162:165], v[214:217], 0
	v_mfma_f32_16x16x32_bf16 v[24:27], v[170:173], v[214:217], 0
	v_mfma_f32_16x16x32_bf16 v[16:19], v[162:165], v[222:225], 0
	v_mfma_f32_16x16x32_bf16 v[8:11], v[170:173], v[222:225], 0
	v_mfma_f32_16x16x32_bf16 v[60:63], v[166:169], v[202:205], v[60:63]
	v_mfma_f32_16x16x32_bf16 v[56:59], v[174:177], v[202:205], v[56:59]
	v_mfma_f32_16x16x32_bf16 v[48:51], v[166:169], v[210:213], v[48:51]
	v_mfma_f32_16x16x32_bf16 v[40:43], v[174:177], v[210:213], v[40:43]
	v_mfma_f32_16x16x32_bf16 v[32:35], v[166:169], v[218:221], v[32:35]
	v_mfma_f32_16x16x32_bf16 v[24:27], v[174:177], v[218:221], v[24:27]
	v_mfma_f32_16x16x32_bf16 v[16:19], v[166:169], v[226:229], v[16:19]
	v_mfma_f32_16x16x32_bf16 v[8:11], v[174:177], v[226:229], v[8:11]
	s_setprio 0
	s_setprio 1
	v_mfma_f32_16x16x32_bf16 v[52:55], v[178:181], v[198:201], 0
	v_mfma_f32_16x16x32_bf16 v[44:47], v[190:193], v[198:201], 0
	v_mfma_f32_16x16x32_bf16 v[36:39], v[178:181], v[206:209], 0
	v_mfma_f32_16x16x32_bf16 v[28:31], v[190:193], v[206:209], 0
	v_mfma_f32_16x16x32_bf16 v[20:23], v[178:181], v[214:217], 0
	v_mfma_f32_16x16x32_bf16 v[12:15], v[190:193], v[214:217], 0
	v_mfma_f32_16x16x32_bf16 v[4:7], v[178:181], v[222:225], 0
	v_mfma_f32_16x16x32_bf16 v[0:3], v[190:193], v[222:225], 0
	v_mfma_f32_16x16x32_bf16 v[52:55], v[186:189], v[202:205], v[52:55]
	v_mfma_f32_16x16x32_bf16 v[44:47], v[194:197], v[202:205], v[44:47]
	v_mfma_f32_16x16x32_bf16 v[36:39], v[186:189], v[210:213], v[36:39]
	v_mfma_f32_16x16x32_bf16 v[28:31], v[194:197], v[210:213], v[28:31]
	v_mfma_f32_16x16x32_bf16 v[20:23], v[186:189], v[218:221], v[20:23]
	v_mfma_f32_16x16x32_bf16 v[12:15], v[194:197], v[218:221], v[12:15]
	v_mfma_f32_16x16x32_bf16 v[4:7], v[186:189], v[226:229], v[4:7]
	v_mfma_f32_16x16x32_bf16 v[0:3], v[194:197], v[226:229], v[0:3]
	s_barrier
	s_setprio 0
	s_add_i32 s86, 0, 0x18000
	v_add_u32_e32 v146, s86, v149
	s_add_i32 s87, 0, 0x1c000
	ds_read_b128 v[162:165], v146
	v_xor_b32_e32 v253, 64, v146
	ds_read_b128 v[166:169], v253
	ds_read_b128 v[170:173], v146 offset:2048
	ds_read_b128 v[174:177], v253 offset:2048
	v_add_u32_e32 v146, s87, v149
	ds_read_b128 v[178:181], v146
	v_xor_b32_e32 v253, 64, v146
	ds_read_b128 v[186:189], v253
	ds_read_b128 v[190:193], v146 offset:2048
	ds_read_b128 v[194:197], v253 offset:2048
	s_add_u32 s58, s58, 0x40000
	s_addc_u32 s59, s59, 0
	s_mov_b32 m0, s66
	v_lshl_add_u64 v[236:237], s[58:59], 0, v[128:129]
	ds_read_b128 v[198:201], v154 offset:32768
	v_xor_b32_e32 v253, 64, v154
	ds_read_b128 v[202:205], v253 offset:32768
	ds_read_b128 v[206:209], v154 offset:34816
	ds_read_b128 v[210:213], v253 offset:34816
	ds_read_b128 v[214:217], v154 offset:36864
	ds_read_b128 v[218:221], v253 offset:36864
	ds_read_b128 v[222:225], v154 offset:38912
	ds_read_b128 v[226:229], v253 offset:38912
	global_load_lds_dwordx4 v[236:237], off
	v_lshl_add_u64 v[236:237], s[58:59], 0, v[132:133]
	s_mov_b32 m0, s67
	s_nop 0
	global_load_lds_dwordx4 v[236:237], off
	s_waitcnt vmcnt(8)
	s_waitcnt lgkmcnt(0)
	s_setprio 1
	s_barrier
	v_mfma_f32_16x16x32_bf16 v[124:127], v[162:165], v[198:201], v[124:127]
	v_mfma_f32_16x16x32_bf16 v[124:127], v[166:169], v[202:205], v[124:127]
	v_mfma_f32_16x16x32_bf16 v[112:115], v[166:169], v[210:213], v[112:115]
	v_mfma_f32_16x16x32_bf16 v[112:115], v[162:165], v[206:209], v[112:115]
	v_mfma_f32_16x16x32_bf16 v[96:99], v[162:165], v[214:217], v[96:99]
	v_mfma_f32_16x16x32_bf16 v[96:99], v[166:169], v[218:221], v[96:99]
	v_mfma_f32_16x16x32_bf16 v[80:83], v[166:169], v[226:229], v[80:83]
	v_mfma_f32_16x16x32_bf16 v[80:83], v[162:165], v[222:225], v[80:83]
	v_mfma_f32_16x16x32_bf16 v[72:75], v[170:173], v[222:225], v[72:75]
	v_mfma_f32_16x16x32_bf16 v[72:75], v[174:177], v[226:229], v[72:75]
	v_mfma_f32_16x16x32_bf16 v[88:91], v[174:177], v[218:221], v[88:91]
	v_mfma_f32_16x16x32_bf16 v[88:91], v[170:173], v[214:217], v[88:91]
	v_mfma_f32_16x16x32_bf16 v[104:107], v[170:173], v[206:209], v[104:107]
	v_mfma_f32_16x16x32_bf16 v[104:107], v[174:177], v[210:213], v[104:107]
	v_mfma_f32_16x16x32_bf16 v[120:123], v[174:177], v[202:205], v[120:123]
	v_mfma_f32_16x16x32_bf16 v[120:123], v[170:173], v[198:201], v[120:123]
	s_setprio 0
	s_setprio 1
	v_mfma_f32_16x16x32_bf16 v[108:111], v[190:193], v[198:201], v[108:111]
	v_mfma_f32_16x16x32_bf16 v[108:111], v[194:197], v[202:205], v[108:111]
	v_mfma_f32_16x16x32_bf16 v[92:95], v[194:197], v[210:213], v[92:95]
	v_mfma_f32_16x16x32_bf16 v[92:95], v[190:193], v[206:209], v[92:95]
	v_mfma_f32_16x16x32_bf16 v[76:79], v[190:193], v[214:217], v[76:79]
	v_mfma_f32_16x16x32_bf16 v[76:79], v[194:197], v[218:221], v[76:79]
	v_mfma_f32_16x16x32_bf16 v[64:67], v[194:197], v[226:229], v[64:67]
	v_mfma_f32_16x16x32_bf16 v[64:67], v[190:193], v[222:225], v[64:67]
	v_mfma_f32_16x16x32_bf16 v[68:71], v[178:181], v[222:225], v[68:71]
	v_mfma_f32_16x16x32_bf16 v[68:71], v[186:189], v[226:229], v[68:71]
	v_mfma_f32_16x16x32_bf16 v[84:87], v[186:189], v[218:221], v[84:87]
	v_mfma_f32_16x16x32_bf16 v[84:87], v[178:181], v[214:217], v[84:87]
	v_mfma_f32_16x16x32_bf16 v[100:103], v[178:181], v[206:209], v[100:103]
	v_mfma_f32_16x16x32_bf16 v[100:103], v[186:189], v[210:213], v[100:103]
	v_mfma_f32_16x16x32_bf16 v[116:119], v[186:189], v[202:205], v[116:119]
	v_mfma_f32_16x16x32_bf16 v[116:119], v[178:181], v[198:201], v[116:119]
	s_barrier
	s_setprio 0
	s_add_i32 s58, s86, s63
	v_lshl_add_u64 v[182:183], v[182:183], 0, s[22:23]
	s_mov_b32 m0, s58
	ds_read_b128 v[198:201], v154 offset:49152
	v_xor_b32_e32 v253, 64, v154
	ds_read_b128 v[202:205], v253 offset:49152
	ds_read_b128 v[206:209], v154 offset:51200
	ds_read_b128 v[210:213], v253 offset:51200
	ds_read_b128 v[214:217], v154 offset:53248
	ds_read_b128 v[218:221], v253 offset:53248
	ds_read_b128 v[222:225], v154 offset:55296
	ds_read_b128 v[226:229], v253 offset:55296
	global_load_lds_dwordx4 v[182:183], off
	s_add_i32 m0, s58, 0x2000
	s_add_u32 s56, s56, 0x40080
	v_lshl_add_u64 v[182:183], v[230:231], 0, s[22:23]
	s_addc_u32 s57, s57, 0
	s_add_i32 s58, s87, s63
	global_load_lds_dwordx4 v[182:183], off
	v_lshl_add_u64 v[182:183], s[56:57], 0, v[130:131]
	s_mov_b32 m0, s58
	s_nop 0
	global_load_lds_dwordx4 v[182:183], off
	v_lshl_add_u64 v[182:183], s[56:57], 0, v[134:135]
	s_add_i32 m0, s58, 0x2000
	s_nop 0
	global_load_lds_dwordx4 v[182:183], off
	v_lshl_add_u64 v[182:183], v[232:233], 0, s[22:23]
	s_mov_b32 m0, s69
	s_nop 0
	global_load_lds_dwordx4 v[182:183], off
	v_lshl_add_u64 v[182:183], v[234:235], 0, s[22:23]
	s_mov_b32 m0, s70
	s_nop 0
	global_load_lds_dwordx4 v[182:183], off
	s_waitcnt vmcnt(8)
	s_waitcnt lgkmcnt(0)
	s_setprio 1
	s_barrier
	v_mfma_f32_16x16x32_bf16 v[60:63], v[162:165], v[198:201], v[60:63]
	v_mfma_f32_16x16x32_bf16 v[60:63], v[166:169], v[202:205], v[60:63]
	v_mfma_f32_16x16x32_bf16 v[48:51], v[166:169], v[210:213], v[48:51]
	v_mfma_f32_16x16x32_bf16 v[48:51], v[162:165], v[206:209], v[48:51]
	v_mfma_f32_16x16x32_bf16 v[32:35], v[162:165], v[214:217], v[32:35]
	v_mfma_f32_16x16x32_bf16 v[32:35], v[166:169], v[218:221], v[32:35]
	v_mfma_f32_16x16x32_bf16 v[16:19], v[166:169], v[226:229], v[16:19]
	v_mfma_f32_16x16x32_bf16 v[16:19], v[162:165], v[222:225], v[16:19]
	v_mfma_f32_16x16x32_bf16 v[8:11], v[170:173], v[222:225], v[8:11]
	v_mfma_f32_16x16x32_bf16 v[8:11], v[174:177], v[226:229], v[8:11]
	v_mfma_f32_16x16x32_bf16 v[24:27], v[174:177], v[218:221], v[24:27]
	v_mfma_f32_16x16x32_bf16 v[24:27], v[170:173], v[214:217], v[24:27]
	v_mfma_f32_16x16x32_bf16 v[40:43], v[170:173], v[206:209], v[40:43]
	v_mfma_f32_16x16x32_bf16 v[40:43], v[174:177], v[210:213], v[40:43]
	v_mfma_f32_16x16x32_bf16 v[56:59], v[174:177], v[202:205], v[56:59]
	v_mfma_f32_16x16x32_bf16 v[56:59], v[170:173], v[198:201], v[56:59]
	s_setprio 0
	s_setprio 1
	v_mfma_f32_16x16x32_bf16 v[44:47], v[190:193], v[198:201], v[44:47]
	v_mfma_f32_16x16x32_bf16 v[44:47], v[194:197], v[202:205], v[44:47]
	v_mfma_f32_16x16x32_bf16 v[28:31], v[194:197], v[210:213], v[28:31]
	v_mfma_f32_16x16x32_bf16 v[28:31], v[190:193], v[206:209], v[28:31]
	v_mfma_f32_16x16x32_bf16 v[12:15], v[190:193], v[214:217], v[12:15]
	v_mfma_f32_16x16x32_bf16 v[12:15], v[194:197], v[218:221], v[12:15]
	v_mfma_f32_16x16x32_bf16 v[0:3], v[194:197], v[226:229], v[0:3]
	v_mfma_f32_16x16x32_bf16 v[0:3], v[190:193], v[222:225], v[0:3]
	v_mfma_f32_16x16x32_bf16 v[4:7], v[178:181], v[222:225], v[4:7]
	v_mfma_f32_16x16x32_bf16 v[4:7], v[186:189], v[226:229], v[4:7]
	v_mfma_f32_16x16x32_bf16 v[20:23], v[186:189], v[218:221], v[20:23]
	v_mfma_f32_16x16x32_bf16 v[20:23], v[178:181], v[214:217], v[20:23]
	v_mfma_f32_16x16x32_bf16 v[36:39], v[178:181], v[206:209], v[36:39]
	v_mfma_f32_16x16x32_bf16 v[36:39], v[186:189], v[210:213], v[36:39]
	v_mfma_f32_16x16x32_bf16 v[52:55], v[186:189], v[202:205], v[52:55]
	v_mfma_f32_16x16x32_bf16 v[52:55], v[178:181], v[198:201], v[52:55]
	s_barrier
	s_setprio 0
	s_add_i32 s85, s85, 2
	s_add_u32 s83, s83, 0x100
	s_addc_u32 s84, s84, 0
	s_add_u32 s54, s54, 0x100
	s_addc_u32 s55, s55, 0
	s_branch .LBB0_875
.Lfa_8:
	v_add_u32_e32 v146, s73, v149
	ds_read_b128 v[162:165], v146
	v_xor_b32_e32 v253, 64, v146
	ds_read_b128 v[166:169], v253
	ds_read_b128 v[170:173], v146 offset:2048
	ds_read_b128 v[174:177], v253 offset:2048
	v_add_u32_e32 v146, s74, v149
	ds_read_b128 v[178:181], v146
	v_xor_b32_e32 v253, 64, v146
	ds_read_b128 v[186:189], v253
	ds_read_b128 v[190:193], v146 offset:2048
	ds_read_b128 v[194:197], v253 offset:2048
	s_add_u32 s58, s54, 0xfffc0080
	s_addc_u32 s59, s55, -1
	s_and_b64 s[56:57], s[56:57], exec
	s_cselect_b32 s59, s49, s59
	s_cselect_b32 s58, s80, s58
	s_cselect_b32 s57, s81, s84
	s_cselect_b32 s56, s82, s83
	v_lshl_add_u64 v[182:183], s[54:55], 0, v[138:139]
	s_add_i32 m0, s64, 0xc000
	ds_read_b128 v[198:201], v154
	v_xor_b32_e32 v253, 64, v154
	ds_read_b128 v[202:205], v253
	ds_read_b128 v[206:209], v154 offset:2048
	ds_read_b128 v[210:213], v253 offset:2048
	ds_read_b128 v[214:217], v154 offset:4096
	ds_read_b128 v[218:221], v253 offset:4096
	ds_read_b128 v[222:225], v154 offset:6144
	ds_read_b128 v[226:229], v253 offset:6144
	global_load_lds_dwordx4 v[182:183], off
	v_lshl_add_u64 v[182:183], s[54:55], 0, v[136:137]
	s_add_i32 m0, s64, 0xe000
	s_nop 0
	global_load_lds_dwordx4 v[182:183], off
	s_waitcnt vmcnt(8)
	s_waitcnt lgkmcnt(0)
	s_setprio 1
	s_barrier
	v_mfma_f32_16x16x32_bf16 v[124:127], v[162:165], v[198:201], 0
	v_mfma_f32_16x16x32_bf16 v[120:123], v[170:173], v[198:201], 0
	v_mfma_f32_16x16x32_bf16 v[112:115], v[162:165], v[206:209], 0
	v_mfma_f32_16x16x32_bf16 v[104:107], v[170:173], v[206:209], 0
	v_mfma_f32_16x16x32_bf16 v[96:99], v[162:165], v[214:217], 0
	v_mfma_f32_16x16x32_bf16 v[88:91], v[170:173], v[214:217], 0
	v_mfma_f32_16x16x32_bf16 v[80:83], v[162:165], v[222:225], 0
	v_mfma_f32_16x16x32_bf16 v[72:75], v[170:173], v[222:225], 0
	v_mfma_f32_16x16x32_bf16 v[124:127], v[166:169], v[202:205], v[124:127]
	v_mfma_f32_16x16x32_bf16 v[120:123], v[174:177], v[202:205], v[120:123]
	v_mfma_f32_16x16x32_bf16 v[112:115], v[166:169], v[210:213], v[112:115]
	v_mfma_f32_16x16x32_bf16 v[104:107], v[174:177], v[210:213], v[104:107]
	v_mfma_f32_16x16x32_bf16 v[96:99], v[166:169], v[218:221], v[96:99]
	v_mfma_f32_16x16x32_bf16 v[88:91], v[174:177], v[218:221], v[88:91]
	v_mfma_f32_16x16x32_bf16 v[80:83], v[166:169], v[226:229], v[80:83]
	v_mfma_f32_16x16x32_bf16 v[72:75], v[174:177], v[226:229], v[72:75]
	s_setprio 0
	s_setprio 1
	v_mfma_f32_16x16x32_bf16 v[116:119], v[178:181], v[198:201], 0
	v_mfma_f32_16x16x32_bf16 v[108:111], v[190:193], v[198:201], 0
	v_mfma_f32_16x16x32_bf16 v[100:103], v[178:181], v[206:209], 0
	v_mfma_f32_16x16x32_bf16 v[92:95], v[190:193], v[206:209], 0
	v_mfma_f32_16x16x32_bf16 v[84:87], v[178:181], v[214:217], 0
	v_mfma_f32_16x16x32_bf16 v[76:79], v[190:193], v[214:217], 0
	v_mfma_f32_16x16x32_bf16 v[68:71], v[178:181], v[222:225], 0
	v_mfma_f32_16x16x32_bf16 v[64:67], v[190:193], v[222:225], 0
	v_mfma_f32_16x16x32_bf16 v[116:119], v[186:189], v[202:205], v[116:119]
	v_mfma_f32_16x16x32_bf16 v[108:111], v[194:197], v[202:205], v[108:111]
	v_mfma_f32_16x16x32_bf16 v[100:103], v[186:189], v[210:213], v[100:103]
	v_mfma_f32_16x16x32_bf16 v[92:95], v[194:197], v[210:213], v[92:95]
	v_mfma_f32_16x16x32_bf16 v[84:87], v[186:189], v[218:221], v[84:87]
	v_mfma_f32_16x16x32_bf16 v[76:79], v[194:197], v[218:221], v[76:79]
	v_mfma_f32_16x16x32_bf16 v[68:71], v[186:189], v[226:229], v[68:71]
	v_mfma_f32_16x16x32_bf16 v[64:67], v[194:197], v[226:229], v[64:67]
	s_barrier
	s_setprio 0
	s_add_i32 s86, s73, s63
	v_lshl_add_u64 v[182:183], s[56:57], 0, v[130:131]
	s_mov_b32 m0, s86
	ds_read_b128 v[198:201], v154 offset:16384
	v_xor_b32_e32 v253, 64, v154
	ds_read_b128 v[202:205], v253 offset:16384
	ds_read_b128 v[206:209], v154 offset:18432
	ds_read_b128 v[210:213], v253 offset:18432
	ds_read_b128 v[214:217], v154 offset:20480
	ds_read_b128 v[218:221], v253 offset:20480
	ds_read_b128 v[222:225], v154 offset:22528
	ds_read_b128 v[226:229], v253 offset:22528
	global_load_lds_dwordx4 v[182:183], off
	s_add_i32 m0, s86, 0x2000
	s_add_u32 s86, s56, 0x40000
	v_lshl_add_u64 v[230:231], s[56:57], 0, v[134:135]
	s_addc_u32 s87, s57, 0
	s_add_i32 s88, s74, s63
	global_load_lds_dwordx4 v[230:231], off
	v_lshl_add_u64 v[232:233], s[86:87], 0, v[130:131]
	s_mov_b32 m0, s88
	v_lshl_add_u64 v[234:235], s[58:59], 0, v[132:133]
	global_load_lds_dwordx4 v[232:233], off
	v_lshl_add_u64 v[232:233], s[86:87], 0, v[134:135]
	s_add_i32 m0, s88, 0x2000
	s_nop 0
	global_load_lds_dwordx4 v[232:233], off
	v_lshl_add_u64 v[232:233], s[58:59], 0, v[128:129]
	s_mov_b32 m0, s64
	s_nop 0
	global_load_lds_dwordx4 v[232:233], off
	s_mov_b32 m0, s65
	s_nop 0
	global_load_lds_dwordx4 v[234:235], off
	s_waitcnt vmcnt(8)
	s_waitcnt lgkmcnt(0)
	s_setprio 1
	s_barrier
	v_mfma_f32_16x16x32_bf16 v[60:63], v[162:165], v[198:201], 0
	v_mfma_f32_16x16x32_bf16 v[56:59], v[170:173], v[198:201], 0
	v_mfma_f32_16x16x32_bf16 v[48:51], v[162:165], v[206:209], 0
	v_mfma_f32_16x16x32_bf16 v[40:43], v[170:173], v[206:209], 0
	v_mfma_f32_16x16x32_bf16 v[32:35], v[162:165], v[214:217], 0
	v_mfma_f32_16x16x32_bf16 v[24:27], v[170:173], v[214:217], 0
	v_mfma_f32_16x16x32_bf16 v[16:19], v[162:165], v[222:225], 0
	v_mfma_f32_16x16x32_bf16 v[8:11], v[170:173], v[222:225], 0
	v_mfma_f32_16x16x32_bf16 v[60:63], v[166:169], v[202:205], v[60:63]
	v_mfma_f32_16x16x32_bf16 v[56:59], v[174:177], v[202:205], v[56:59]
	v_mfma_f32_16x16x32_bf16 v[48:51], v[166:169], v[210:213], v[48:51]
	v_mfma_f32_16x16x32_bf16 v[40:43], v[174:177], v[210:213], v[40:43]
	v_mfma_f32_16x16x32_bf16 v[32:35], v[166:169], v[218:221], v[32:35]
	v_mfma_f32_16x16x32_bf16 v[24:27], v[174:177], v[218:221], v[24:27]
	v_mfma_f32_16x16x32_bf16 v[16:19], v[166:169], v[226:229], v[16:19]
	v_mfma_f32_16x16x32_bf16 v[8:11], v[174:177], v[226:229], v[8:11]
	s_setprio 0
	s_setprio 1
	v_mfma_f32_16x16x32_bf16 v[52:55], v[178:181], v[198:201], 0
	v_mfma_f32_16x16x32_bf16 v[44:47], v[190:193], v[198:201], 0
	v_mfma_f32_16x16x32_bf16 v[36:39], v[178:181], v[206:209], 0
	v_mfma_f32_16x16x32_bf16 v[28:31], v[190:193], v[206:209], 0
	v_mfma_f32_16x16x32_bf16 v[20:23], v[178:181], v[214:217], 0
	v_mfma_f32_16x16x32_bf16 v[12:15], v[190:193], v[214:217], 0
	v_mfma_f32_16x16x32_bf16 v[4:7], v[178:181], v[222:225], 0
	v_mfma_f32_16x16x32_bf16 v[0:3], v[190:193], v[222:225], 0
	v_mfma_f32_16x16x32_bf16 v[52:55], v[186:189], v[202:205], v[52:55]
	v_mfma_f32_16x16x32_bf16 v[44:47], v[194:197], v[202:205], v[44:47]
	v_mfma_f32_16x16x32_bf16 v[36:39], v[186:189], v[210:213], v[36:39]
	v_mfma_f32_16x16x32_bf16 v[28:31], v[194:197], v[210:213], v[28:31]
	v_mfma_f32_16x16x32_bf16 v[20:23], v[186:189], v[218:221], v[20:23]
	v_mfma_f32_16x16x32_bf16 v[12:15], v[194:197], v[218:221], v[12:15]
	v_mfma_f32_16x16x32_bf16 v[4:7], v[186:189], v[226:229], v[4:7]
	v_mfma_f32_16x16x32_bf16 v[0:3], v[194:197], v[226:229], v[0:3]
	s_barrier
	s_setprio 0
	s_add_i32 s86, 0, 0x18000
	v_add_u32_e32 v146, s86, v149
	s_add_i32 s87, 0, 0x1c000
	ds_read_b128 v[162:165], v146
	v_xor_b32_e32 v253, 64, v146
	ds_read_b128 v[166:169], v253
	ds_read_b128 v[170:173], v146 offset:2048
	ds_read_b128 v[174:177], v253 offset:2048
	v_add_u32_e32 v146, s87, v149
	ds_read_b128 v[178:181], v146
	v_xor_b32_e32 v253, 64, v146
	ds_read_b128 v[186:189], v253
	ds_read_b128 v[190:193], v146 offset:2048
	ds_read_b128 v[194:197], v253 offset:2048
	s_add_u32 s58, s58, 0x40000
	s_addc_u32 s59, s59, 0
	s_mov_b32 m0, s66
	v_lshl_add_u64 v[236:237], s[58:59], 0, v[128:129]
	ds_read_b128 v[198:201], v154 offset:32768
	v_xor_b32_e32 v253, 64, v154
	ds_read_b128 v[202:205], v253 offset:32768
	ds_read_b128 v[206:209], v154 offset:34816
	ds_read_b128 v[210:213], v253 offset:34816
	ds_read_b128 v[214:217], v154 offset:36864
	ds_read_b128 v[218:221], v253 offset:36864
	ds_read_b128 v[222:225], v154 offset:38912
	ds_read_b128 v[226:229], v253 offset:38912
	global_load_lds_dwordx4 v[236:237], off
	v_lshl_add_u64 v[236:237], s[58:59], 0, v[132:133]
	s_mov_b32 m0, s67
	s_nop 0
	global_load_lds_dwordx4 v[236:237], off
	s_waitcnt vmcnt(8)
	s_waitcnt lgkmcnt(0)
	s_setprio 1
	s_barrier
	v_mfma_f32_16x16x32_bf16 v[124:127], v[162:165], v[198:201], v[124:127]
	v_mfma_f32_16x16x32_bf16 v[124:127], v[166:169], v[202:205], v[124:127]
	v_mfma_f32_16x16x32_bf16 v[112:115], v[166:169], v[210:213], v[112:115]
	v_mfma_f32_16x16x32_bf16 v[112:115], v[162:165], v[206:209], v[112:115]
	v_mfma_f32_16x16x32_bf16 v[96:99], v[162:165], v[214:217], v[96:99]
	v_mfma_f32_16x16x32_bf16 v[96:99], v[166:169], v[218:221], v[96:99]
	v_mfma_f32_16x16x32_bf16 v[80:83], v[166:169], v[226:229], v[80:83]
	v_mfma_f32_16x16x32_bf16 v[80:83], v[162:165], v[222:225], v[80:83]
	v_mfma_f32_16x16x32_bf16 v[72:75], v[170:173], v[222:225], v[72:75]
	v_mfma_f32_16x16x32_bf16 v[72:75], v[174:177], v[226:229], v[72:75]
	v_mfma_f32_16x16x32_bf16 v[88:91], v[174:177], v[218:221], v[88:91]
	v_mfma_f32_16x16x32_bf16 v[88:91], v[170:173], v[214:217], v[88:91]
	v_mfma_f32_16x16x32_bf16 v[104:107], v[170:173], v[206:209], v[104:107]
	v_mfma_f32_16x16x32_bf16 v[104:107], v[174:177], v[210:213], v[104:107]
	v_mfma_f32_16x16x32_bf16 v[120:123], v[174:177], v[202:205], v[120:123]
	v_mfma_f32_16x16x32_bf16 v[120:123], v[170:173], v[198:201], v[120:123]
	s_setprio 0
	s_setprio 1
	v_mfma_f32_16x16x32_bf16 v[108:111], v[190:193], v[198:201], v[108:111]
	v_mfma_f32_16x16x32_bf16 v[108:111], v[194:197], v[202:205], v[108:111]
	v_mfma_f32_16x16x32_bf16 v[92:95], v[194:197], v[210:213], v[92:95]
	v_mfma_f32_16x16x32_bf16 v[92:95], v[190:193], v[206:209], v[92:95]
	v_mfma_f32_16x16x32_bf16 v[76:79], v[190:193], v[214:217], v[76:79]
	v_mfma_f32_16x16x32_bf16 v[76:79], v[194:197], v[218:221], v[76:79]
	v_mfma_f32_16x16x32_bf16 v[64:67], v[194:197], v[226:229], v[64:67]
	v_mfma_f32_16x16x32_bf16 v[64:67], v[190:193], v[222:225], v[64:67]
	v_mfma_f32_16x16x32_bf16 v[68:71], v[178:181], v[222:225], v[68:71]
	v_mfma_f32_16x16x32_bf16 v[68:71], v[186:189], v[226:229], v[68:71]
	v_mfma_f32_16x16x32_bf16 v[84:87], v[186:189], v[218:221], v[84:87]
	v_mfma_f32_16x16x32_bf16 v[84:87], v[178:181], v[214:217], v[84:87]
	v_mfma_f32_16x16x32_bf16 v[100:103], v[178:181], v[206:209], v[100:103]
	v_mfma_f32_16x16x32_bf16 v[100:103], v[186:189], v[210:213], v[100:103]
	v_mfma_f32_16x16x32_bf16 v[116:119], v[186:189], v[202:205], v[116:119]
	v_mfma_f32_16x16x32_bf16 v[116:119], v[178:181], v[198:201], v[116:119]
	s_barrier
	s_setprio 0
	s_add_i32 s58, s86, s63
	v_lshl_add_u64 v[182:183], v[182:183], 0, s[22:23]
	s_mov_b32 m0, s58
	ds_read_b128 v[198:201], v154 offset:49152
	v_xor_b32_e32 v253, 64, v154
	ds_read_b128 v[202:205], v253 offset:49152
	ds_read_b128 v[206:209], v154 offset:51200
	ds_read_b128 v[210:213], v253 offset:51200
	ds_read_b128 v[214:217], v154 offset:53248
	ds_read_b128 v[218:221], v253 offset:53248
	ds_read_b128 v[222:225], v154 offset:55296
	ds_read_b128 v[226:229], v253 offset:55296
	global_load_lds_dwordx4 v[182:183], off
	s_add_i32 m0, s58, 0x2000
	s_add_u32 s56, s56, 0x40080
	v_lshl_add_u64 v[182:183], v[230:231], 0, s[22:23]
	s_addc_u32 s57, s57, 0
	s_add_i32 s58, s87, s63
	global_load_lds_dwordx4 v[182:183], off
	v_lshl_add_u64 v[182:183], s[56:57], 0, v[130:131]
	s_mov_b32 m0, s58
	s_nop 0
	global_load_lds_dwordx4 v[182:183], off
	v_lshl_add_u64 v[182:183], s[56:57], 0, v[134:135]
	s_add_i32 m0, s58, 0x2000
	s_nop 0
	global_load_lds_dwordx4 v[182:183], off
	v_lshl_add_u64 v[182:183], v[232:233], 0, s[22:23]
	s_mov_b32 m0, s69
	s_nop 0
	global_load_lds_dwordx4 v[182:183], off
	v_lshl_add_u64 v[182:183], v[234:235], 0, s[22:23]
	s_mov_b32 m0, s70
	s_nop 0
	global_load_lds_dwordx4 v[182:183], off
	s_waitcnt vmcnt(8)
	s_waitcnt lgkmcnt(0)
	s_setprio 1
	s_barrier
	v_mfma_f32_16x16x32_bf16 v[60:63], v[162:165], v[198:201], v[60:63]
	v_mfma_f32_16x16x32_bf16 v[60:63], v[166:169], v[202:205], v[60:63]
	v_mfma_f32_16x16x32_bf16 v[48:51], v[166:169], v[210:213], v[48:51]
	v_mfma_f32_16x16x32_bf16 v[48:51], v[162:165], v[206:209], v[48:51]
	v_mfma_f32_16x16x32_bf16 v[32:35], v[162:165], v[214:217], v[32:35]
	v_mfma_f32_16x16x32_bf16 v[32:35], v[166:169], v[218:221], v[32:35]
	v_mfma_f32_16x16x32_bf16 v[16:19], v[166:169], v[226:229], v[16:19]
	v_mfma_f32_16x16x32_bf16 v[16:19], v[162:165], v[222:225], v[16:19]
	v_mfma_f32_16x16x32_bf16 v[8:11], v[170:173], v[222:225], v[8:11]
	v_mfma_f32_16x16x32_bf16 v[8:11], v[174:177], v[226:229], v[8:11]
	v_mfma_f32_16x16x32_bf16 v[24:27], v[174:177], v[218:221], v[24:27]
	v_mfma_f32_16x16x32_bf16 v[24:27], v[170:173], v[214:217], v[24:27]
	v_mfma_f32_16x16x32_bf16 v[40:43], v[170:173], v[206:209], v[40:43]
	v_mfma_f32_16x16x32_bf16 v[40:43], v[174:177], v[210:213], v[40:43]
	v_mfma_f32_16x16x32_bf16 v[56:59], v[174:177], v[202:205], v[56:59]
	v_mfma_f32_16x16x32_bf16 v[56:59], v[170:173], v[198:201], v[56:59]
	s_setprio 0
	s_setprio 1
	v_mfma_f32_16x16x32_bf16 v[44:47], v[190:193], v[198:201], v[44:47]
	v_mfma_f32_16x16x32_bf16 v[44:47], v[194:197], v[202:205], v[44:47]
	v_mfma_f32_16x16x32_bf16 v[28:31], v[194:197], v[210:213], v[28:31]
	v_mfma_f32_16x16x32_bf16 v[28:31], v[190:193], v[206:209], v[28:31]
	v_mfma_f32_16x16x32_bf16 v[12:15], v[190:193], v[214:217], v[12:15]
	v_mfma_f32_16x16x32_bf16 v[12:15], v[194:197], v[218:221], v[12:15]
	v_mfma_f32_16x16x32_bf16 v[0:3], v[194:197], v[226:229], v[0:3]
	v_mfma_f32_16x16x32_bf16 v[0:3], v[190:193], v[222:225], v[0:3]
	v_mfma_f32_16x16x32_bf16 v[4:7], v[178:181], v[222:225], v[4:7]
	v_mfma_f32_16x16x32_bf16 v[4:7], v[186:189], v[226:229], v[4:7]
	v_mfma_f32_16x16x32_bf16 v[20:23], v[186:189], v[218:221], v[20:23]
	v_mfma_f32_16x16x32_bf16 v[20:23], v[178:181], v[214:217], v[20:23]
	v_mfma_f32_16x16x32_bf16 v[36:39], v[178:181], v[206:209], v[36:39]
	v_mfma_f32_16x16x32_bf16 v[36:39], v[186:189], v[210:213], v[36:39]
	v_mfma_f32_16x16x32_bf16 v[52:55], v[186:189], v[202:205], v[52:55]
	v_mfma_f32_16x16x32_bf16 v[52:55], v[178:181], v[198:201], v[52:55]
	s_barrier
	s_setprio 0
	s_add_i32 s85, s85, 2
	s_add_u32 s83, s83, 0x100
	s_addc_u32 s84, s84, 0
	s_add_u32 s54, s54, 0x100
	s_addc_u32 s55, s55, 0
	s_branch .LBB0_875
.LBB0_874:
	v_add_u32_e32 v146, s73, v149
	ds_read_b128 v[162:165], v146
	v_xor_b32_e32 v253, 64, v146
	ds_read_b128 v[166:169], v253
	ds_read_b128 v[170:173], v146 offset:2048
	ds_read_b128 v[174:177], v253 offset:2048
	v_add_u32_e32 v146, s74, v149
	ds_read_b128 v[178:181], v146
	v_xor_b32_e32 v253, 64, v146
	ds_read_b128 v[186:189], v253
	ds_read_b128 v[190:193], v146 offset:2048
	ds_read_b128 v[194:197], v253 offset:2048
	s_add_u32 s58, s54, 0xfffc0080
	s_addc_u32 s59, s55, -1
	s_and_b64 s[56:57], s[56:57], exec
	s_cselect_b32 s59, s49, s59
	s_cselect_b32 s58, s80, s58
	s_cselect_b32 s57, s81, s84
	s_cselect_b32 s56, s82, s83
	v_lshl_add_u64 v[182:183], s[54:55], 0, v[138:139]
	s_add_i32 m0, s64, 0xc000
	ds_read_b128 v[198:201], v154
	v_xor_b32_e32 v253, 64, v154
	ds_read_b128 v[202:205], v253
	ds_read_b128 v[206:209], v154 offset:2048
	ds_read_b128 v[210:213], v253 offset:2048
	ds_read_b128 v[214:217], v154 offset:4096
	ds_read_b128 v[218:221], v253 offset:4096
	ds_read_b128 v[222:225], v154 offset:6144
	ds_read_b128 v[226:229], v253 offset:6144
	global_load_lds_dwordx4 v[182:183], off
	v_lshl_add_u64 v[182:183], s[54:55], 0, v[136:137]
	s_add_i32 m0, s64, 0xe000
	s_nop 0
	global_load_lds_dwordx4 v[182:183], off
	s_waitcnt vmcnt(8)
	s_waitcnt lgkmcnt(0)
	s_setprio 1
	s_barrier
	v_mfma_f32_16x16x32_bf16 v[124:127], v[162:165], v[198:201], v[124:127]
	v_mfma_f32_16x16x32_bf16 v[124:127], v[166:169], v[202:205], v[124:127]
	v_mfma_f32_16x16x32_bf16 v[112:115], v[166:169], v[210:213], v[112:115]
	v_mfma_f32_16x16x32_bf16 v[112:115], v[162:165], v[206:209], v[112:115]
	v_mfma_f32_16x16x32_bf16 v[96:99], v[162:165], v[214:217], v[96:99]
	v_mfma_f32_16x16x32_bf16 v[96:99], v[166:169], v[218:221], v[96:99]
	v_mfma_f32_16x16x32_bf16 v[80:83], v[166:169], v[226:229], v[80:83]
	v_mfma_f32_16x16x32_bf16 v[80:83], v[162:165], v[222:225], v[80:83]
	v_mfma_f32_16x16x32_bf16 v[72:75], v[170:173], v[222:225], v[72:75]
	v_mfma_f32_16x16x32_bf16 v[72:75], v[174:177], v[226:229], v[72:75]
	v_mfma_f32_16x16x32_bf16 v[88:91], v[174:177], v[218:221], v[88:91]
	v_mfma_f32_16x16x32_bf16 v[88:91], v[170:173], v[214:217], v[88:91]
	v_mfma_f32_16x16x32_bf16 v[104:107], v[170:173], v[206:209], v[104:107]
	v_mfma_f32_16x16x32_bf16 v[104:107], v[174:177], v[210:213], v[104:107]
	v_mfma_f32_16x16x32_bf16 v[120:123], v[174:177], v[202:205], v[120:123]
	v_mfma_f32_16x16x32_bf16 v[120:123], v[170:173], v[198:201], v[120:123]
	s_setprio 0
	s_setprio 1
	v_mfma_f32_16x16x32_bf16 v[108:111], v[190:193], v[198:201], v[108:111]
	v_mfma_f32_16x16x32_bf16 v[108:111], v[194:197], v[202:205], v[108:111]
	v_mfma_f32_16x16x32_bf16 v[92:95], v[194:197], v[210:213], v[92:95]
	v_mfma_f32_16x16x32_bf16 v[92:95], v[190:193], v[206:209], v[92:95]
	v_mfma_f32_16x16x32_bf16 v[76:79], v[190:193], v[214:217], v[76:79]
	v_mfma_f32_16x16x32_bf16 v[76:79], v[194:197], v[218:221], v[76:79]
	v_mfma_f32_16x16x32_bf16 v[64:67], v[194:197], v[226:229], v[64:67]
	v_mfma_f32_16x16x32_bf16 v[64:67], v[190:193], v[222:225], v[64:67]
	v_mfma_f32_16x16x32_bf16 v[68:71], v[178:181], v[222:225], v[68:71]
	v_mfma_f32_16x16x32_bf16 v[68:71], v[186:189], v[226:229], v[68:71]
	v_mfma_f32_16x16x32_bf16 v[84:87], v[186:189], v[218:221], v[84:87]
	v_mfma_f32_16x16x32_bf16 v[84:87], v[178:181], v[214:217], v[84:87]
	v_mfma_f32_16x16x32_bf16 v[100:103], v[178:181], v[206:209], v[100:103]
	v_mfma_f32_16x16x32_bf16 v[100:103], v[186:189], v[210:213], v[100:103]
	v_mfma_f32_16x16x32_bf16 v[116:119], v[186:189], v[202:205], v[116:119]
	v_mfma_f32_16x16x32_bf16 v[116:119], v[178:181], v[198:201], v[116:119]
	s_barrier
	s_setprio 0
	s_add_i32 s86, s73, s63
	v_lshl_add_u64 v[182:183], s[56:57], 0, v[130:131]
	s_mov_b32 m0, s86
	ds_read_b128 v[198:201], v154 offset:16384
	v_xor_b32_e32 v253, 64, v154
	ds_read_b128 v[202:205], v253 offset:16384
	ds_read_b128 v[206:209], v154 offset:18432
	ds_read_b128 v[210:213], v253 offset:18432
	ds_read_b128 v[214:217], v154 offset:20480
	ds_read_b128 v[218:221], v253 offset:20480
	ds_read_b128 v[222:225], v154 offset:22528
	ds_read_b128 v[226:229], v253 offset:22528
	global_load_lds_dwordx4 v[182:183], off
	s_add_i32 m0, s86, 0x2000
	s_add_u32 s86, s56, 0x40000
	v_lshl_add_u64 v[230:231], s[56:57], 0, v[134:135]
	s_addc_u32 s87, s57, 0
	s_add_i32 s88, s74, s63
	global_load_lds_dwordx4 v[230:231], off
	v_lshl_add_u64 v[232:233], s[86:87], 0, v[130:131]
	s_mov_b32 m0, s88
	v_lshl_add_u64 v[234:235], s[58:59], 0, v[132:133]
	global_load_lds_dwordx4 v[232:233], off
	v_lshl_add_u64 v[232:233], s[86:87], 0, v[134:135]
	s_add_i32 m0, s88, 0x2000
	s_nop 0
	global_load_lds_dwordx4 v[232:233], off
	v_lshl_add_u64 v[232:233], s[58:59], 0, v[128:129]
	s_mov_b32 m0, s64
	s_nop 0
	global_load_lds_dwordx4 v[232:233], off
	s_mov_b32 m0, s65
	s_nop 0
	global_load_lds_dwordx4 v[234:235], off
	s_waitcnt vmcnt(8)
	s_waitcnt lgkmcnt(0)
	s_setprio 1
	s_barrier
	v_mfma_f32_16x16x32_bf16 v[60:63], v[162:165], v[198:201], v[60:63]
	v_mfma_f32_16x16x32_bf16 v[60:63], v[166:169], v[202:205], v[60:63]
	v_mfma_f32_16x16x32_bf16 v[48:51], v[166:169], v[210:213], v[48:51]
	v_mfma_f32_16x16x32_bf16 v[48:51], v[162:165], v[206:209], v[48:51]
	v_mfma_f32_16x16x32_bf16 v[32:35], v[162:165], v[214:217], v[32:35]
	v_mfma_f32_16x16x32_bf16 v[32:35], v[166:169], v[218:221], v[32:35]
	v_mfma_f32_16x16x32_bf16 v[16:19], v[166:169], v[226:229], v[16:19]
	v_mfma_f32_16x16x32_bf16 v[16:19], v[162:165], v[222:225], v[16:19]
	v_mfma_f32_16x16x32_bf16 v[8:11], v[170:173], v[222:225], v[8:11]
	v_mfma_f32_16x16x32_bf16 v[8:11], v[174:177], v[226:229], v[8:11]
	v_mfma_f32_16x16x32_bf16 v[24:27], v[174:177], v[218:221], v[24:27]
	v_mfma_f32_16x16x32_bf16 v[24:27], v[170:173], v[214:217], v[24:27]
	v_mfma_f32_16x16x32_bf16 v[40:43], v[170:173], v[206:209], v[40:43]
	v_mfma_f32_16x16x32_bf16 v[40:43], v[174:177], v[210:213], v[40:43]
	v_mfma_f32_16x16x32_bf16 v[56:59], v[174:177], v[202:205], v[56:59]
	v_mfma_f32_16x16x32_bf16 v[56:59], v[170:173], v[198:201], v[56:59]
	s_setprio 0
	s_setprio 1
	v_mfma_f32_16x16x32_bf16 v[44:47], v[190:193], v[198:201], v[44:47]
	v_mfma_f32_16x16x32_bf16 v[44:47], v[194:197], v[202:205], v[44:47]
	v_mfma_f32_16x16x32_bf16 v[28:31], v[194:197], v[210:213], v[28:31]
	v_mfma_f32_16x16x32_bf16 v[28:31], v[190:193], v[206:209], v[28:31]
	v_mfma_f32_16x16x32_bf16 v[12:15], v[190:193], v[214:217], v[12:15]
	v_mfma_f32_16x16x32_bf16 v[12:15], v[194:197], v[218:221], v[12:15]
	v_mfma_f32_16x16x32_bf16 v[0:3], v[194:197], v[226:229], v[0:3]
	v_mfma_f32_16x16x32_bf16 v[0:3], v[190:193], v[222:225], v[0:3]
	v_mfma_f32_16x16x32_bf16 v[4:7], v[178:181], v[222:225], v[4:7]
	v_mfma_f32_16x16x32_bf16 v[4:7], v[186:189], v[226:229], v[4:7]
	v_mfma_f32_16x16x32_bf16 v[20:23], v[186:189], v[218:221], v[20:23]
	v_mfma_f32_16x16x32_bf16 v[20:23], v[178:181], v[214:217], v[20:23]
	v_mfma_f32_16x16x32_bf16 v[36:39], v[178:181], v[206:209], v[36:39]
	v_mfma_f32_16x16x32_bf16 v[36:39], v[186:189], v[210:213], v[36:39]
	v_mfma_f32_16x16x32_bf16 v[52:55], v[186:189], v[202:205], v[52:55]
	v_mfma_f32_16x16x32_bf16 v[52:55], v[178:181], v[198:201], v[52:55]
	s_barrier
	s_setprio 0
	s_add_i32 s86, 0, 0x18000
	v_add_u32_e32 v146, s86, v149
	s_add_i32 s87, 0, 0x1c000
	ds_read_b128 v[162:165], v146
	v_xor_b32_e32 v253, 64, v146
	ds_read_b128 v[166:169], v253
	ds_read_b128 v[170:173], v146 offset:2048
	ds_read_b128 v[174:177], v253 offset:2048
	v_add_u32_e32 v146, s87, v149
	ds_read_b128 v[178:181], v146
	v_xor_b32_e32 v253, 64, v146
	ds_read_b128 v[186:189], v253
	ds_read_b128 v[190:193], v146 offset:2048
	ds_read_b128 v[194:197], v253 offset:2048
	s_add_u32 s58, s58, 0x40000
	s_addc_u32 s59, s59, 0
	s_mov_b32 m0, s66
	v_lshl_add_u64 v[236:237], s[58:59], 0, v[128:129]
	ds_read_b128 v[198:201], v154 offset:32768
	v_xor_b32_e32 v253, 64, v154
	ds_read_b128 v[202:205], v253 offset:32768
	ds_read_b128 v[206:209], v154 offset:34816
	ds_read_b128 v[210:213], v253 offset:34816
	ds_read_b128 v[214:217], v154 offset:36864
	ds_read_b128 v[218:221], v253 offset:36864
	ds_read_b128 v[222:225], v154 offset:38912
	ds_read_b128 v[226:229], v253 offset:38912
	global_load_lds_dwordx4 v[236:237], off
	v_lshl_add_u64 v[236:237], s[58:59], 0, v[132:133]
	s_mov_b32 m0, s67
	s_nop 0
	global_load_lds_dwordx4 v[236:237], off
	s_waitcnt vmcnt(8)
	s_waitcnt lgkmcnt(0)
	s_setprio 1
	s_barrier
	v_mfma_f32_16x16x32_bf16 v[124:127], v[162:165], v[198:201], v[124:127]
	v_mfma_f32_16x16x32_bf16 v[124:127], v[166:169], v[202:205], v[124:127]
	v_mfma_f32_16x16x32_bf16 v[112:115], v[166:169], v[210:213], v[112:115]
	v_mfma_f32_16x16x32_bf16 v[112:115], v[162:165], v[206:209], v[112:115]
	v_mfma_f32_16x16x32_bf16 v[96:99], v[162:165], v[214:217], v[96:99]
	v_mfma_f32_16x16x32_bf16 v[96:99], v[166:169], v[218:221], v[96:99]
	v_mfma_f32_16x16x32_bf16 v[80:83], v[166:169], v[226:229], v[80:83]
	v_mfma_f32_16x16x32_bf16 v[80:83], v[162:165], v[222:225], v[80:83]
	v_mfma_f32_16x16x32_bf16 v[72:75], v[170:173], v[222:225], v[72:75]
	v_mfma_f32_16x16x32_bf16 v[72:75], v[174:177], v[226:229], v[72:75]
	v_mfma_f32_16x16x32_bf16 v[88:91], v[174:177], v[218:221], v[88:91]
	v_mfma_f32_16x16x32_bf16 v[88:91], v[170:173], v[214:217], v[88:91]
	v_mfma_f32_16x16x32_bf16 v[104:107], v[170:173], v[206:209], v[104:107]
	v_mfma_f32_16x16x32_bf16 v[104:107], v[174:177], v[210:213], v[104:107]
	v_mfma_f32_16x16x32_bf16 v[120:123], v[174:177], v[202:205], v[120:123]
	v_mfma_f32_16x16x32_bf16 v[120:123], v[170:173], v[198:201], v[120:123]
	s_setprio 0
	s_setprio 1
	v_mfma_f32_16x16x32_bf16 v[108:111], v[190:193], v[198:201], v[108:111]
	v_mfma_f32_16x16x32_bf16 v[108:111], v[194:197], v[202:205], v[108:111]
	v_mfma_f32_16x16x32_bf16 v[92:95], v[194:197], v[210:213], v[92:95]
	v_mfma_f32_16x16x32_bf16 v[92:95], v[190:193], v[206:209], v[92:95]
	v_mfma_f32_16x16x32_bf16 v[76:79], v[190:193], v[214:217], v[76:79]
	v_mfma_f32_16x16x32_bf16 v[76:79], v[194:197], v[218:221], v[76:79]
	v_mfma_f32_16x16x32_bf16 v[64:67], v[194:197], v[226:229], v[64:67]
	v_mfma_f32_16x16x32_bf16 v[64:67], v[190:193], v[222:225], v[64:67]
	v_mfma_f32_16x16x32_bf16 v[68:71], v[178:181], v[222:225], v[68:71]
	v_mfma_f32_16x16x32_bf16 v[68:71], v[186:189], v[226:229], v[68:71]
	v_mfma_f32_16x16x32_bf16 v[84:87], v[186:189], v[218:221], v[84:87]
	v_mfma_f32_16x16x32_bf16 v[84:87], v[178:181], v[214:217], v[84:87]
	v_mfma_f32_16x16x32_bf16 v[100:103], v[178:181], v[206:209], v[100:103]
	v_mfma_f32_16x16x32_bf16 v[100:103], v[186:189], v[210:213], v[100:103]
	v_mfma_f32_16x16x32_bf16 v[116:119], v[186:189], v[202:205], v[116:119]
	v_mfma_f32_16x16x32_bf16 v[116:119], v[178:181], v[198:201], v[116:119]
	s_barrier
	s_setprio 0
	s_add_i32 s58, s86, s63
	v_lshl_add_u64 v[182:183], v[182:183], 0, s[22:23]
	s_mov_b32 m0, s58
	ds_read_b128 v[198:201], v154 offset:49152
	v_xor_b32_e32 v253, 64, v154
	ds_read_b128 v[202:205], v253 offset:49152
	ds_read_b128 v[206:209], v154 offset:51200
	ds_read_b128 v[210:213], v253 offset:51200
	ds_read_b128 v[214:217], v154 offset:53248
	ds_read_b128 v[218:221], v253 offset:53248
	ds_read_b128 v[222:225], v154 offset:55296
	ds_read_b128 v[226:229], v253 offset:55296
	global_load_lds_dwordx4 v[182:183], off
	s_add_i32 m0, s58, 0x2000
	s_add_u32 s56, s56, 0x40080
	v_lshl_add_u64 v[182:183], v[230:231], 0, s[22:23]
	s_addc_u32 s57, s57, 0
	s_add_i32 s58, s87, s63
	global_load_lds_dwordx4 v[182:183], off
	v_lshl_add_u64 v[182:183], s[56:57], 0, v[130:131]
	s_mov_b32 m0, s58
	s_nop 0
	global_load_lds_dwordx4 v[182:183], off
	v_lshl_add_u64 v[182:183], s[56:57], 0, v[134:135]
	s_add_i32 m0, s58, 0x2000
	s_nop 0
	global_load_lds_dwordx4 v[182:183], off
	v_lshl_add_u64 v[182:183], v[232:233], 0, s[22:23]
	s_mov_b32 m0, s69
	s_nop 0
	global_load_lds_dwordx4 v[182:183], off
	v_lshl_add_u64 v[182:183], v[234:235], 0, s[22:23]
	s_mov_b32 m0, s70
	s_nop 0
	global_load_lds_dwordx4 v[182:183], off
	s_waitcnt vmcnt(8)
	s_waitcnt lgkmcnt(0)
	s_setprio 1
	s_barrier
	v_mfma_f32_16x16x32_bf16 v[60:63], v[162:165], v[198:201], v[60:63]
	v_mfma_f32_16x16x32_bf16 v[60:63], v[166:169], v[202:205], v[60:63]
	v_mfma_f32_16x16x32_bf16 v[48:51], v[166:169], v[210:213], v[48:51]
	v_mfma_f32_16x16x32_bf16 v[48:51], v[162:165], v[206:209], v[48:51]
	v_mfma_f32_16x16x32_bf16 v[32:35], v[162:165], v[214:217], v[32:35]
	v_mfma_f32_16x16x32_bf16 v[32:35], v[166:169], v[218:221], v[32:35]
	v_mfma_f32_16x16x32_bf16 v[16:19], v[166:169], v[226:229], v[16:19]
	v_mfma_f32_16x16x32_bf16 v[16:19], v[162:165], v[222:225], v[16:19]
	v_mfma_f32_16x16x32_bf16 v[8:11], v[170:173], v[222:225], v[8:11]
	v_mfma_f32_16x16x32_bf16 v[8:11], v[174:177], v[226:229], v[8:11]
	v_mfma_f32_16x16x32_bf16 v[24:27], v[174:177], v[218:221], v[24:27]
	v_mfma_f32_16x16x32_bf16 v[24:27], v[170:173], v[214:217], v[24:27]
	v_mfma_f32_16x16x32_bf16 v[40:43], v[170:173], v[206:209], v[40:43]
	v_mfma_f32_16x16x32_bf16 v[40:43], v[174:177], v[210:213], v[40:43]
	v_mfma_f32_16x16x32_bf16 v[56:59], v[174:177], v[202:205], v[56:59]
	v_mfma_f32_16x16x32_bf16 v[56:59], v[170:173], v[198:201], v[56:59]
	s_setprio 0
	s_setprio 1
	v_mfma_f32_16x16x32_bf16 v[44:47], v[190:193], v[198:201], v[44:47]
	v_mfma_f32_16x16x32_bf16 v[44:47], v[194:197], v[202:205], v[44:47]
	v_mfma_f32_16x16x32_bf16 v[28:31], v[194:197], v[210:213], v[28:31]
	v_mfma_f32_16x16x32_bf16 v[28:31], v[190:193], v[206:209], v[28:31]
	v_mfma_f32_16x16x32_bf16 v[12:15], v[190:193], v[214:217], v[12:15]
	v_mfma_f32_16x16x32_bf16 v[12:15], v[194:197], v[218:221], v[12:15]
	v_mfma_f32_16x16x32_bf16 v[0:3], v[194:197], v[226:229], v[0:3]
	v_mfma_f32_16x16x32_bf16 v[0:3], v[190:193], v[222:225], v[0:3]
	v_mfma_f32_16x16x32_bf16 v[4:7], v[178:181], v[222:225], v[4:7]
	v_mfma_f32_16x16x32_bf16 v[4:7], v[186:189], v[226:229], v[4:7]
	v_mfma_f32_16x16x32_bf16 v[20:23], v[186:189], v[218:221], v[20:23]
	v_mfma_f32_16x16x32_bf16 v[20:23], v[178:181], v[214:217], v[20:23]
	v_mfma_f32_16x16x32_bf16 v[36:39], v[178:181], v[206:209], v[36:39]
	v_mfma_f32_16x16x32_bf16 v[36:39], v[186:189], v[210:213], v[36:39]
	v_mfma_f32_16x16x32_bf16 v[52:55], v[186:189], v[202:205], v[52:55]
	v_mfma_f32_16x16x32_bf16 v[52:55], v[178:181], v[198:201], v[52:55]
	s_barrier
	s_setprio 0
	s_add_i32 s85, s85, 2
	s_add_u32 s83, s83, 0x100
	s_addc_u32 s84, s84, 0
	s_add_u32 s54, s54, 0x100
	s_addc_u32 s55, s55, 0
	s_cmp_gt_u32 s85, 13
	s_cbranch_scc1 .LBB0_877

.LBB0_1010:
	s_ashr_i32 s51, s50, 31
	s_lshl_b64 s[52:53], s[50:51], 19
	s_add_u32 s52, s33, s52
	s_addc_u32 s53, s35, s53
	s_and_b64 s[54:55], s[12:13], exec
	s_cselect_b32 s15, s53, s61
	s_cselect_b32 s51, s52, s60
	s_ashr_i32 s49, s48, 31
	s_lshl_b64 s[54:55], s[48:49], 19
	s_add_u32 s54, s64, s54
	s_addc_u32 s55, s65, s55
	s_and_b64 s[62:63], s[12:13], exec
	s_cselect_b32 s49, s55, s59
	s_cselect_b32 s57, s54, s58
	s_add_u32 s78, s58, 0x100
	s_addc_u32 s79, s59, 0
	s_add_u32 s58, s60, 0x40080
	s_addc_u32 s59, s61, 0
	s_mov_b32 s80, -2
	s_waitcnt lgkmcnt(0)
	s_cmp_eq_u32 s71, 1
	s_cbranch_scc1 .Lfa_9
	ds_read_b128 v[128:131], v188
	v_xor_b32_e32 v253, 64, v188
	ds_read_b128 v[132:135], v253
	ds_read_b128 v[136:139], v188 offset:2048
	ds_read_b128 v[140:143], v253 offset:2048
	ds_read_b128 v[144:147], v189
	v_xor_b32_e32 v253, 64, v189
	ds_read_b128 v[148:151], v253
	ds_read_b128 v[172:175], v189 offset:2048
	ds_read_b128 v[176:179], v253 offset:2048
	s_add_u32 s60, s58, 0xfffc0080
	s_addc_u32 s61, s59, -1
	s_cmp_eq_u32 s80, 12
	s_cselect_b32 s63, s15, s61
	s_cselect_b32 s62, s51, s60
	s_cselect_b32 s61, s49, s79
	s_cselect_b32 s60, s57, s78
	v_lshl_add_u64 v[220:221], s[58:59], 0, v[166:167]
	s_add_i32 m0, s67, 0xc000
	ds_read_b128 v[180:183], v190
	v_xor_b32_e32 v253, 64, v190
	ds_read_b128 v[192:195], v253
	ds_read_b128 v[196:199], v190 offset:2048
	ds_read_b128 v[200:203], v253 offset:2048
	ds_read_b128 v[204:207], v190 offset:4096
	ds_read_b128 v[208:211], v253 offset:4096
	ds_read_b128 v[212:215], v190 offset:6144
	ds_read_b128 v[216:219], v253 offset:6144
	global_load_lds_dwordx4 v[220:221], off
	v_lshl_add_u64 v[220:221], s[58:59], 0, v[164:165]
	s_add_i32 m0, s67, 0xe000
	s_nop 0
	global_load_lds_dwordx4 v[220:221], off
	s_waitcnt vmcnt(24)
	s_waitcnt lgkmcnt(0)
	s_setprio 1
	s_barrier
	v_mfma_f32_16x16x32_bf16 v[124:127], v[128:131], v[180:183], 0
	v_mfma_f32_16x16x32_bf16 v[120:123], v[136:139], v[180:183], 0
	v_mfma_f32_16x16x32_bf16 v[108:111], v[128:131], v[196:199], 0
	v_mfma_f32_16x16x32_bf16 v[104:107], v[136:139], v[196:199], 0
	v_mfma_f32_16x16x32_bf16 v[92:95], v[128:131], v[204:207], 0
	v_mfma_f32_16x16x32_bf16 v[88:91], v[136:139], v[204:207], 0
	v_mfma_f32_16x16x32_bf16 v[76:79], v[128:131], v[212:215], 0
	v_mfma_f32_16x16x32_bf16 v[72:75], v[136:139], v[212:215], 0
	v_mfma_f32_16x16x32_bf16 v[124:127], v[132:135], v[192:195], v[124:127]
	v_mfma_f32_16x16x32_bf16 v[120:123], v[140:143], v[192:195], v[120:123]
	v_mfma_f32_16x16x32_bf16 v[108:111], v[132:135], v[200:203], v[108:111]
	v_mfma_f32_16x16x32_bf16 v[104:107], v[140:143], v[200:203], v[104:107]
	v_mfma_f32_16x16x32_bf16 v[92:95], v[132:135], v[208:211], v[92:95]
	v_mfma_f32_16x16x32_bf16 v[88:91], v[140:143], v[208:211], v[88:91]
	v_mfma_f32_16x16x32_bf16 v[76:79], v[132:135], v[216:219], v[76:79]
	v_mfma_f32_16x16x32_bf16 v[72:75], v[140:143], v[216:219], v[72:75]
	s_setprio 0
	s_setprio 1
	v_mfma_f32_16x16x32_bf16 v[116:119], v[144:147], v[180:183], 0
	v_mfma_f32_16x16x32_bf16 v[112:115], v[172:175], v[180:183], 0
	v_mfma_f32_16x16x32_bf16 v[100:103], v[144:147], v[196:199], 0
	v_mfma_f32_16x16x32_bf16 v[96:99], v[172:175], v[196:199], 0
	v_mfma_f32_16x16x32_bf16 v[84:87], v[144:147], v[204:207], 0
	v_mfma_f32_16x16x32_bf16 v[80:83], v[172:175], v[204:207], 0
	v_mfma_f32_16x16x32_bf16 v[68:71], v[144:147], v[212:215], 0
	v_mfma_f32_16x16x32_bf16 v[64:67], v[172:175], v[212:215], 0
	v_mfma_f32_16x16x32_bf16 v[116:119], v[148:151], v[192:195], v[116:119]
	v_mfma_f32_16x16x32_bf16 v[112:115], v[176:179], v[192:195], v[112:115]
	v_mfma_f32_16x16x32_bf16 v[100:103], v[148:151], v[200:203], v[100:103]
	v_mfma_f32_16x16x32_bf16 v[96:99], v[176:179], v[200:203], v[96:99]
	v_mfma_f32_16x16x32_bf16 v[84:87], v[148:151], v[208:211], v[84:87]
	v_mfma_f32_16x16x32_bf16 v[80:83], v[176:179], v[208:211], v[80:83]
	v_mfma_f32_16x16x32_bf16 v[68:71], v[148:151], v[216:219], v[68:71]
	v_mfma_f32_16x16x32_bf16 v[64:67], v[176:179], v[216:219], v[64:67]
	s_barrier
	s_setprio 0
	s_add_i32 s81, s76, s66
	v_lshl_add_u64 v[220:221], s[60:61], 0, v[154:155]
	s_mov_b32 m0, s81
	ds_read_b128 v[180:183], v190 offset:16384
	v_xor_b32_e32 v253, 64, v190
	ds_read_b128 v[192:195], v253 offset:16384
	ds_read_b128 v[196:199], v190 offset:18432
	ds_read_b128 v[200:203], v253 offset:18432
	ds_read_b128 v[204:207], v190 offset:20480
	ds_read_b128 v[208:211], v253 offset:20480
	ds_read_b128 v[212:215], v190 offset:22528
	ds_read_b128 v[216:219], v253 offset:22528
	global_load_lds_dwordx4 v[220:221], off
	s_add_i32 m0, s81, 0x2000
	s_add_u32 s82, s60, 0x40000
	v_lshl_add_u64 v[222:223], s[60:61], 0, v[162:163]
	s_addc_u32 s83, s61, 0
	s_add_i32 s81, s77, s66
	global_load_lds_dwordx4 v[222:223], off
	v_lshl_add_u64 v[224:225], s[82:83], 0, v[154:155]
	s_mov_b32 m0, s81
	v_lshl_add_u64 v[226:227], s[62:63], 0, v[160:161]
	global_load_lds_dwordx4 v[224:225], off
	v_lshl_add_u64 v[224:225], s[82:83], 0, v[162:163]
	s_add_i32 m0, s81, 0x2000
	s_nop 0
	global_load_lds_dwordx4 v[224:225], off
	v_lshl_add_u64 v[224:225], s[62:63], 0, v[152:153]
	s_mov_b32 m0, s67
	s_nop 0
	global_load_lds_dwordx4 v[224:225], off
	s_mov_b32 m0, s68
	s_nop 0
	global_load_lds_dwordx4 v[226:227], off
	s_waitcnt vmcnt(24)
	s_waitcnt lgkmcnt(0)
	s_setprio 1
	s_barrier
	v_mfma_f32_16x16x32_bf16 v[60:63], v[128:131], v[180:183], 0
	v_mfma_f32_16x16x32_bf16 v[56:59], v[136:139], v[180:183], 0
	v_mfma_f32_16x16x32_bf16 v[44:47], v[128:131], v[196:199], 0
	v_mfma_f32_16x16x32_bf16 v[40:43], v[136:139], v[196:199], 0
	v_mfma_f32_16x16x32_bf16 v[28:31], v[128:131], v[204:207], 0
	v_mfma_f32_16x16x32_bf16 v[24:27], v[136:139], v[204:207], 0
	v_mfma_f32_16x16x32_bf16 v[12:15], v[128:131], v[212:215], 0
	v_mfma_f32_16x16x32_bf16 v[8:11], v[136:139], v[212:215], 0
	v_mfma_f32_16x16x32_bf16 v[60:63], v[132:135], v[192:195], v[60:63]
	v_mfma_f32_16x16x32_bf16 v[56:59], v[140:143], v[192:195], v[56:59]
	v_mfma_f32_16x16x32_bf16 v[44:47], v[132:135], v[200:203], v[44:47]
	v_mfma_f32_16x16x32_bf16 v[40:43], v[140:143], v[200:203], v[40:43]
	v_mfma_f32_16x16x32_bf16 v[28:31], v[132:135], v[208:211], v[28:31]
	v_mfma_f32_16x16x32_bf16 v[24:27], v[140:143], v[208:211], v[24:27]
	v_mfma_f32_16x16x32_bf16 v[12:15], v[132:135], v[216:219], v[12:15]
	v_mfma_f32_16x16x32_bf16 v[8:11], v[140:143], v[216:219], v[8:11]
	s_setprio 0
	s_setprio 1
	v_mfma_f32_16x16x32_bf16 v[52:55], v[144:147], v[180:183], 0
	v_mfma_f32_16x16x32_bf16 v[48:51], v[172:175], v[180:183], 0
	v_mfma_f32_16x16x32_bf16 v[36:39], v[144:147], v[196:199], 0
	v_mfma_f32_16x16x32_bf16 v[32:35], v[172:175], v[196:199], 0
	v_mfma_f32_16x16x32_bf16 v[20:23], v[144:147], v[204:207], 0
	v_mfma_f32_16x16x32_bf16 v[16:19], v[172:175], v[204:207], 0
	v_mfma_f32_16x16x32_bf16 v[4:7], v[144:147], v[212:215], 0
	v_mfma_f32_16x16x32_bf16 v[0:3], v[172:175], v[212:215], 0
	v_mfma_f32_16x16x32_bf16 v[52:55], v[148:151], v[192:195], v[52:55]
	v_mfma_f32_16x16x32_bf16 v[48:51], v[176:179], v[192:195], v[48:51]
	v_mfma_f32_16x16x32_bf16 v[36:39], v[148:151], v[200:203], v[36:39]
	v_mfma_f32_16x16x32_bf16 v[32:35], v[176:179], v[200:203], v[32:35]
	v_mfma_f32_16x16x32_bf16 v[20:23], v[148:151], v[208:211], v[20:23]
	v_mfma_f32_16x16x32_bf16 v[16:19], v[176:179], v[208:211], v[16:19]
	v_mfma_f32_16x16x32_bf16 v[4:7], v[148:151], v[216:219], v[4:7]
	v_mfma_f32_16x16x32_bf16 v[0:3], v[176:179], v[216:219], v[0:3]
	s_barrier
	s_setprio 0
	s_add_i32 s81, 0, 0x18000
	s_add_i32 s82, 0, 0x1c000
	v_add_u32_e32 v140, s81, v185
	v_add_u32_e32 v176, s82, v185
	ds_read_b128 v[128:131], v140
	v_xor_b32_e32 v253, 64, v140
	ds_read_b128 v[132:135], v253
	ds_read_b128 v[136:139], v140 offset:2048
	ds_read_b128 v[140:143], v253 offset:2048
	ds_read_b128 v[144:147], v176
	v_xor_b32_e32 v253, 64, v176
	ds_read_b128 v[148:151], v253
	ds_read_b128 v[172:175], v176 offset:2048
	ds_read_b128 v[176:179], v253 offset:2048
	s_add_u32 s62, s62, 0x40000
	s_addc_u32 s63, s63, 0
	s_mov_b32 m0, s69
	v_lshl_add_u64 v[228:229], s[62:63], 0, v[152:153]
	ds_read_b128 v[180:183], v190 offset:32768
	v_xor_b32_e32 v253, 64, v190
	ds_read_b128 v[192:195], v253 offset:32768
	ds_read_b128 v[196:199], v190 offset:34816
	ds_read_b128 v[200:203], v253 offset:34816
	ds_read_b128 v[204:207], v190 offset:36864
	ds_read_b128 v[208:211], v253 offset:36864
	ds_read_b128 v[212:215], v190 offset:38912
	ds_read_b128 v[216:219], v253 offset:38912
	global_load_lds_dwordx4 v[228:229], off
	v_lshl_add_u64 v[228:229], s[62:63], 0, v[160:161]
	s_mov_b32 m0, s70
	s_nop 0
	global_load_lds_dwordx4 v[228:229], off
	s_waitcnt vmcnt(8)
	s_waitcnt lgkmcnt(0)
	s_setprio 1
	s_barrier
	v_mfma_f32_16x16x32_bf16 v[124:127], v[128:131], v[180:183], v[124:127]
	v_mfma_f32_16x16x32_bf16 v[124:127], v[132:135], v[192:195], v[124:127]
	v_mfma_f32_16x16x32_bf16 v[108:111], v[132:135], v[200:203], v[108:111]
	v_mfma_f32_16x16x32_bf16 v[108:111], v[128:131], v[196:199], v[108:111]
	v_mfma_f32_16x16x32_bf16 v[92:95], v[128:131], v[204:207], v[92:95]
	v_mfma_f32_16x16x32_bf16 v[92:95], v[132:135], v[208:211], v[92:95]
	v_mfma_f32_16x16x32_bf16 v[76:79], v[132:135], v[216:219], v[76:79]
	v_mfma_f32_16x16x32_bf16 v[76:79], v[128:131], v[212:215], v[76:79]
	v_mfma_f32_16x16x32_bf16 v[72:75], v[136:139], v[212:215], v[72:75]
	v_mfma_f32_16x16x32_bf16 v[72:75], v[140:143], v[216:219], v[72:75]
	v_mfma_f32_16x16x32_bf16 v[88:91], v[140:143], v[208:211], v[88:91]
	v_mfma_f32_16x16x32_bf16 v[88:91], v[136:139], v[204:207], v[88:91]
	v_mfma_f32_16x16x32_bf16 v[104:107], v[136:139], v[196:199], v[104:107]
	v_mfma_f32_16x16x32_bf16 v[104:107], v[140:143], v[200:203], v[104:107]
	v_mfma_f32_16x16x32_bf16 v[120:123], v[140:143], v[192:195], v[120:123]
	v_mfma_f32_16x16x32_bf16 v[120:123], v[136:139], v[180:183], v[120:123]
	s_setprio 0
	s_setprio 1
	v_mfma_f32_16x16x32_bf16 v[112:115], v[172:175], v[180:183], v[112:115]
	v_mfma_f32_16x16x32_bf16 v[112:115], v[176:179], v[192:195], v[112:115]
	v_mfma_f32_16x16x32_bf16 v[96:99], v[176:179], v[200:203], v[96:99]
	v_mfma_f32_16x16x32_bf16 v[96:99], v[172:175], v[196:199], v[96:99]
	v_mfma_f32_16x16x32_bf16 v[80:83], v[172:175], v[204:207], v[80:83]
	v_mfma_f32_16x16x32_bf16 v[80:83], v[176:179], v[208:211], v[80:83]
	v_mfma_f32_16x16x32_bf16 v[64:67], v[176:179], v[216:219], v[64:67]
	v_mfma_f32_16x16x32_bf16 v[64:67], v[172:175], v[212:215], v[64:67]
	v_mfma_f32_16x16x32_bf16 v[68:71], v[144:147], v[212:215], v[68:71]
	v_mfma_f32_16x16x32_bf16 v[68:71], v[148:151], v[216:219], v[68:71]
	v_mfma_f32_16x16x32_bf16 v[84:87], v[148:151], v[208:211], v[84:87]
	v_mfma_f32_16x16x32_bf16 v[84:87], v[144:147], v[204:207], v[84:87]
	v_mfma_f32_16x16x32_bf16 v[100:103], v[144:147], v[196:199], v[100:103]
	v_mfma_f32_16x16x32_bf16 v[100:103], v[148:151], v[200:203], v[100:103]
	v_mfma_f32_16x16x32_bf16 v[116:119], v[148:151], v[192:195], v[116:119]
	v_mfma_f32_16x16x32_bf16 v[116:119], v[144:147], v[180:183], v[116:119]
	s_barrier
	s_setprio 0
	s_add_i32 s62, s81, s66
	v_lshl_add_u64 v[220:221], v[220:221], 0, s[26:27]
	s_mov_b32 m0, s62
	ds_read_b128 v[180:183], v190 offset:49152
	v_xor_b32_e32 v253, 64, v190
	ds_read_b128 v[192:195], v253 offset:49152
	ds_read_b128 v[196:199], v190 offset:51200
	ds_read_b128 v[200:203], v253 offset:51200
	ds_read_b128 v[204:207], v190 offset:53248
	ds_read_b128 v[208:211], v253 offset:53248
	ds_read_b128 v[212:215], v190 offset:55296
	ds_read_b128 v[216:219], v253 offset:55296
	global_load_lds_dwordx4 v[220:221], off
	s_add_i32 m0, s62, 0x2000
	s_add_u32 s60, s60, 0x40080
	v_lshl_add_u64 v[220:221], v[222:223], 0, s[26:27]
	s_addc_u32 s61, s61, 0
	s_add_i32 s62, s82, s66
	global_load_lds_dwordx4 v[220:221], off
	v_lshl_add_u64 v[220:221], s[60:61], 0, v[154:155]
	s_mov_b32 m0, s62
	s_nop 0
	global_load_lds_dwordx4 v[220:221], off
	v_lshl_add_u64 v[220:221], s[60:61], 0, v[162:163]
	s_add_i32 m0, s62, 0x2000
	s_nop 0
	global_load_lds_dwordx4 v[220:221], off
	v_lshl_add_u64 v[220:221], v[224:225], 0, s[26:27]
	s_mov_b32 m0, s3
	s_nop 0
	global_load_lds_dwordx4 v[220:221], off
	v_lshl_add_u64 v[220:221], v[226:227], 0, s[26:27]
	s_mov_b32 m0, s72
	s_nop 0
	global_load_lds_dwordx4 v[220:221], off
	s_waitcnt vmcnt(8)
	s_waitcnt lgkmcnt(0)
	s_setprio 1
	s_barrier
	v_mfma_f32_16x16x32_bf16 v[60:63], v[128:131], v[180:183], v[60:63]
	v_mfma_f32_16x16x32_bf16 v[60:63], v[132:135], v[192:195], v[60:63]
	v_mfma_f32_16x16x32_bf16 v[44:47], v[132:135], v[200:203], v[44:47]
	v_mfma_f32_16x16x32_bf16 v[44:47], v[128:131], v[196:199], v[44:47]
	v_mfma_f32_16x16x32_bf16 v[28:31], v[128:131], v[204:207], v[28:31]
	v_mfma_f32_16x16x32_bf16 v[28:31], v[132:135], v[208:211], v[28:31]
	v_mfma_f32_16x16x32_bf16 v[12:15], v[132:135], v[216:219], v[12:15]
	v_mfma_f32_16x16x32_bf16 v[12:15], v[128:131], v[212:215], v[12:15]
	v_mfma_f32_16x16x32_bf16 v[8:11], v[136:139], v[212:215], v[8:11]
	v_mfma_f32_16x16x32_bf16 v[8:11], v[140:143], v[216:219], v[8:11]
	v_mfma_f32_16x16x32_bf16 v[24:27], v[140:143], v[208:211], v[24:27]
	v_mfma_f32_16x16x32_bf16 v[24:27], v[136:139], v[204:207], v[24:27]
	v_mfma_f32_16x16x32_bf16 v[40:43], v[136:139], v[196:199], v[40:43]
	v_mfma_f32_16x16x32_bf16 v[40:43], v[140:143], v[200:203], v[40:43]
	v_mfma_f32_16x16x32_bf16 v[56:59], v[140:143], v[192:195], v[56:59]
	v_mfma_f32_16x16x32_bf16 v[56:59], v[136:139], v[180:183], v[56:59]
	s_setprio 0
	s_setprio 1
	v_mfma_f32_16x16x32_bf16 v[48:51], v[172:175], v[180:183], v[48:51]
	v_mfma_f32_16x16x32_bf16 v[48:51], v[176:179], v[192:195], v[48:51]
	v_mfma_f32_16x16x32_bf16 v[32:35], v[176:179], v[200:203], v[32:35]
	v_mfma_f32_16x16x32_bf16 v[32:35], v[172:175], v[196:199], v[32:35]
	v_mfma_f32_16x16x32_bf16 v[16:19], v[172:175], v[204:207], v[16:19]
	v_mfma_f32_16x16x32_bf16 v[16:19], v[176:179], v[208:211], v[16:19]
	v_mfma_f32_16x16x32_bf16 v[0:3], v[176:179], v[216:219], v[0:3]
	v_mfma_f32_16x16x32_bf16 v[0:3], v[172:175], v[212:215], v[0:3]
	v_mfma_f32_16x16x32_bf16 v[4:7], v[144:147], v[212:215], v[4:7]
	v_mfma_f32_16x16x32_bf16 v[4:7], v[148:151], v[216:219], v[4:7]
	v_mfma_f32_16x16x32_bf16 v[20:23], v[148:151], v[208:211], v[20:23]
	v_mfma_f32_16x16x32_bf16 v[20:23], v[144:147], v[204:207], v[20:23]
	v_mfma_f32_16x16x32_bf16 v[36:39], v[144:147], v[196:199], v[36:39]
	v_mfma_f32_16x16x32_bf16 v[36:39], v[148:151], v[200:203], v[36:39]
	v_mfma_f32_16x16x32_bf16 v[52:55], v[148:151], v[192:195], v[52:55]
	v_mfma_f32_16x16x32_bf16 v[52:55], v[144:147], v[180:183], v[52:55]
	s_barrier
	s_setprio 0
	s_add_i32 s80, s80, 2
	s_add_u32 s78, s78, 0x100
	s_addc_u32 s79, s79, 0
	s_add_u32 s58, s58, 0x100
	s_addc_u32 s59, s59, 0
	s_cmp_gt_u32 s80, 13
	s_branch .LBB0_1011
.Lfa_9:
	ds_read_b128 v[128:131], v188
	v_xor_b32_e32 v253, 64, v188
	ds_read_b128 v[132:135], v253
	ds_read_b128 v[136:139], v188 offset:2048
	ds_read_b128 v[140:143], v253 offset:2048
	ds_read_b128 v[144:147], v189
	v_xor_b32_e32 v253, 64, v189
	ds_read_b128 v[148:151], v253
	ds_read_b128 v[172:175], v189 offset:2048
	ds_read_b128 v[176:179], v253 offset:2048
	s_add_u32 s60, s58, 0xfffc0080
	s_addc_u32 s61, s59, -1
	s_cmp_eq_u32 s80, 12
	s_cselect_b32 s63, s15, s61
	s_cselect_b32 s62, s51, s60
	s_cselect_b32 s61, s49, s79
	s_cselect_b32 s60, s57, s78
	v_lshl_add_u64 v[220:221], s[58:59], 0, v[166:167]
	s_add_i32 m0, s67, 0xc000
	ds_read_b128 v[180:183], v190
	v_xor_b32_e32 v253, 64, v190
	ds_read_b128 v[192:195], v253
	ds_read_b128 v[196:199], v190 offset:2048
	ds_read_b128 v[200:203], v253 offset:2048
	ds_read_b128 v[204:207], v190 offset:4096
	ds_read_b128 v[208:211], v253 offset:4096
	ds_read_b128 v[212:215], v190 offset:6144
	ds_read_b128 v[216:219], v253 offset:6144
	global_load_lds_dwordx4 v[220:221], off
	v_lshl_add_u64 v[220:221], s[58:59], 0, v[164:165]
	s_add_i32 m0, s67, 0xe000
	s_nop 0
	global_load_lds_dwordx4 v[220:221], off
	s_waitcnt vmcnt(8)
	s_waitcnt lgkmcnt(0)
	s_setprio 1
	s_barrier
	v_mfma_f32_16x16x32_bf16 v[124:127], v[128:131], v[180:183], 0
	v_mfma_f32_16x16x32_bf16 v[120:123], v[136:139], v[180:183], 0
	v_mfma_f32_16x16x32_bf16 v[108:111], v[128:131], v[196:199], 0
	v_mfma_f32_16x16x32_bf16 v[104:107], v[136:139], v[196:199], 0
	v_mfma_f32_16x16x32_bf16 v[92:95], v[128:131], v[204:207], 0
	v_mfma_f32_16x16x32_bf16 v[88:91], v[136:139], v[204:207], 0
	v_mfma_f32_16x16x32_bf16 v[76:79], v[128:131], v[212:215], 0
	v_mfma_f32_16x16x32_bf16 v[72:75], v[136:139], v[212:215], 0
	v_mfma_f32_16x16x32_bf16 v[124:127], v[132:135], v[192:195], v[124:127]
	v_mfma_f32_16x16x32_bf16 v[120:123], v[140:143], v[192:195], v[120:123]
	v_mfma_f32_16x16x32_bf16 v[108:111], v[132:135], v[200:203], v[108:111]
	v_mfma_f32_16x16x32_bf16 v[104:107], v[140:143], v[200:203], v[104:107]
	v_mfma_f32_16x16x32_bf16 v[92:95], v[132:135], v[208:211], v[92:95]
	v_mfma_f32_16x16x32_bf16 v[88:91], v[140:143], v[208:211], v[88:91]
	v_mfma_f32_16x16x32_bf16 v[76:79], v[132:135], v[216:219], v[76:79]
	v_mfma_f32_16x16x32_bf16 v[72:75], v[140:143], v[216:219], v[72:75]
	s_setprio 0
	s_setprio 1
	v_mfma_f32_16x16x32_bf16 v[116:119], v[144:147], v[180:183], 0
	v_mfma_f32_16x16x32_bf16 v[112:115], v[172:175], v[180:183], 0
	v_mfma_f32_16x16x32_bf16 v[100:103], v[144:147], v[196:199], 0
	v_mfma_f32_16x16x32_bf16 v[96:99], v[172:175], v[196:199], 0
	v_mfma_f32_16x16x32_bf16 v[84:87], v[144:147], v[204:207], 0
	v_mfma_f32_16x16x32_bf16 v[80:83], v[172:175], v[204:207], 0
	v_mfma_f32_16x16x32_bf16 v[68:71], v[144:147], v[212:215], 0
	v_mfma_f32_16x16x32_bf16 v[64:67], v[172:175], v[212:215], 0
	v_mfma_f32_16x16x32_bf16 v[116:119], v[148:151], v[192:195], v[116:119]
	v_mfma_f32_16x16x32_bf16 v[112:115], v[176:179], v[192:195], v[112:115]
	v_mfma_f32_16x16x32_bf16 v[100:103], v[148:151], v[200:203], v[100:103]
	v_mfma_f32_16x16x32_bf16 v[96:99], v[176:179], v[200:203], v[96:99]
	v_mfma_f32_16x16x32_bf16 v[84:87], v[148:151], v[208:211], v[84:87]
	v_mfma_f32_16x16x32_bf16 v[80:83], v[176:179], v[208:211], v[80:83]
	v_mfma_f32_16x16x32_bf16 v[68:71], v[148:151], v[216:219], v[68:71]
	v_mfma_f32_16x16x32_bf16 v[64:67], v[176:179], v[216:219], v[64:67]
	s_barrier
	s_setprio 0
	s_add_i32 s81, s76, s66
	v_lshl_add_u64 v[220:221], s[60:61], 0, v[154:155]
	s_mov_b32 m0, s81
	ds_read_b128 v[180:183], v190 offset:16384
	v_xor_b32_e32 v253, 64, v190
	ds_read_b128 v[192:195], v253 offset:16384
	ds_read_b128 v[196:199], v190 offset:18432
	ds_read_b128 v[200:203], v253 offset:18432
	ds_read_b128 v[204:207], v190 offset:20480
	ds_read_b128 v[208:211], v253 offset:20480
	ds_read_b128 v[212:215], v190 offset:22528
	ds_read_b128 v[216:219], v253 offset:22528
	global_load_lds_dwordx4 v[220:221], off
	s_add_i32 m0, s81, 0x2000
	s_add_u32 s82, s60, 0x40000
	v_lshl_add_u64 v[222:223], s[60:61], 0, v[162:163]
	s_addc_u32 s83, s61, 0
	s_add_i32 s81, s77, s66
	global_load_lds_dwordx4 v[222:223], off
	v_lshl_add_u64 v[224:225], s[82:83], 0, v[154:155]
	s_mov_b32 m0, s81
	v_lshl_add_u64 v[226:227], s[62:63], 0, v[160:161]
	global_load_lds_dwordx4 v[224:225], off
	v_lshl_add_u64 v[224:225], s[82:83], 0, v[162:163]
	s_add_i32 m0, s81, 0x2000
	s_nop 0
	global_load_lds_dwordx4 v[224:225], off
	v_lshl_add_u64 v[224:225], s[62:63], 0, v[152:153]
	s_mov_b32 m0, s67
	s_nop 0
	global_load_lds_dwordx4 v[224:225], off
	s_mov_b32 m0, s68
	s_nop 0
	global_load_lds_dwordx4 v[226:227], off
	s_waitcnt vmcnt(8)
	s_waitcnt lgkmcnt(0)
	s_setprio 1
	s_barrier
	v_mfma_f32_16x16x32_bf16 v[60:63], v[128:131], v[180:183], 0
	v_mfma_f32_16x16x32_bf16 v[56:59], v[136:139], v[180:183], 0
	v_mfma_f32_16x16x32_bf16 v[44:47], v[128:131], v[196:199], 0
	v_mfma_f32_16x16x32_bf16 v[40:43], v[136:139], v[196:199], 0
	v_mfma_f32_16x16x32_bf16 v[28:31], v[128:131], v[204:207], 0
	v_mfma_f32_16x16x32_bf16 v[24:27], v[136:139], v[204:207], 0
	v_mfma_f32_16x16x32_bf16 v[12:15], v[128:131], v[212:215], 0
	v_mfma_f32_16x16x32_bf16 v[8:11], v[136:139], v[212:215], 0
	v_mfma_f32_16x16x32_bf16 v[60:63], v[132:135], v[192:195], v[60:63]
	v_mfma_f32_16x16x32_bf16 v[56:59], v[140:143], v[192:195], v[56:59]
	v_mfma_f32_16x16x32_bf16 v[44:47], v[132:135], v[200:203], v[44:47]
	v_mfma_f32_16x16x32_bf16 v[40:43], v[140:143], v[200:203], v[40:43]
	v_mfma_f32_16x16x32_bf16 v[28:31], v[132:135], v[208:211], v[28:31]
	v_mfma_f32_16x16x32_bf16 v[24:27], v[140:143], v[208:211], v[24:27]
	v_mfma_f32_16x16x32_bf16 v[12:15], v[132:135], v[216:219], v[12:15]
	v_mfma_f32_16x16x32_bf16 v[8:11], v[140:143], v[216:219], v[8:11]
	s_setprio 0
	s_setprio 1
	v_mfma_f32_16x16x32_bf16 v[52:55], v[144:147], v[180:183], 0
	v_mfma_f32_16x16x32_bf16 v[48:51], v[172:175], v[180:183], 0
	v_mfma_f32_16x16x32_bf16 v[36:39], v[144:147], v[196:199], 0
	v_mfma_f32_16x16x32_bf16 v[32:35], v[172:175], v[196:199], 0
	v_mfma_f32_16x16x32_bf16 v[20:23], v[144:147], v[204:207], 0
	v_mfma_f32_16x16x32_bf16 v[16:19], v[172:175], v[204:207], 0
	v_mfma_f32_16x16x32_bf16 v[4:7], v[144:147], v[212:215], 0
	v_mfma_f32_16x16x32_bf16 v[0:3], v[172:175], v[212:215], 0
	v_mfma_f32_16x16x32_bf16 v[52:55], v[148:151], v[192:195], v[52:55]
	v_mfma_f32_16x16x32_bf16 v[48:51], v[176:179], v[192:195], v[48:51]
	v_mfma_f32_16x16x32_bf16 v[36:39], v[148:151], v[200:203], v[36:39]
	v_mfma_f32_16x16x32_bf16 v[32:35], v[176:179], v[200:203], v[32:35]
	v_mfma_f32_16x16x32_bf16 v[20:23], v[148:151], v[208:211], v[20:23]
	v_mfma_f32_16x16x32_bf16 v[16:19], v[176:179], v[208:211], v[16:19]
	v_mfma_f32_16x16x32_bf16 v[4:7], v[148:151], v[216:219], v[4:7]
	v_mfma_f32_16x16x32_bf16 v[0:3], v[176:179], v[216:219], v[0:3]
	s_barrier
	s_setprio 0
	s_add_i32 s81, 0, 0x18000
	s_add_i32 s82, 0, 0x1c000
	v_add_u32_e32 v140, s81, v185
	v_add_u32_e32 v176, s82, v185
	ds_read_b128 v[128:131], v140
	v_xor_b32_e32 v253, 64, v140
	ds_read_b128 v[132:135], v253
	ds_read_b128 v[136:139], v140 offset:2048
	ds_read_b128 v[140:143], v253 offset:2048
	ds_read_b128 v[144:147], v176
	v_xor_b32_e32 v253, 64, v176
	ds_read_b128 v[148:151], v253
	ds_read_b128 v[172:175], v176 offset:2048
	ds_read_b128 v[176:179], v253 offset:2048
	s_add_u32 s62, s62, 0x40000
	s_addc_u32 s63, s63, 0
	s_mov_b32 m0, s69
	v_lshl_add_u64 v[228:229], s[62:63], 0, v[152:153]
	ds_read_b128 v[180:183], v190 offset:32768
	v_xor_b32_e32 v253, 64, v190
	ds_read_b128 v[192:195], v253 offset:32768
	ds_read_b128 v[196:199], v190 offset:34816
	ds_read_b128 v[200:203], v253 offset:34816
	ds_read_b128 v[204:207], v190 offset:36864
	ds_read_b128 v[208:211], v253 offset:36864
	ds_read_b128 v[212:215], v190 offset:38912
	ds_read_b128 v[216:219], v253 offset:38912
	global_load_lds_dwordx4 v[228:229], off
	v_lshl_add_u64 v[228:229], s[62:63], 0, v[160:161]
	s_mov_b32 m0, s70
	s_nop 0
	global_load_lds_dwordx4 v[228:229], off
	s_waitcnt vmcnt(8)
	s_waitcnt lgkmcnt(0)
	s_setprio 1
	s_barrier
	v_mfma_f32_16x16x32_bf16 v[124:127], v[128:131], v[180:183], v[124:127]
	v_mfma_f32_16x16x32_bf16 v[124:127], v[132:135], v[192:195], v[124:127]
	v_mfma_f32_16x16x32_bf16 v[108:111], v[132:135], v[200:203], v[108:111]
	v_mfma_f32_16x16x32_bf16 v[108:111], v[128:131], v[196:199], v[108:111]
	v_mfma_f32_16x16x32_bf16 v[92:95], v[128:131], v[204:207], v[92:95]
	v_mfma_f32_16x16x32_bf16 v[92:95], v[132:135], v[208:211], v[92:95]
	v_mfma_f32_16x16x32_bf16 v[76:79], v[132:135], v[216:219], v[76:79]
	v_mfma_f32_16x16x32_bf16 v[76:79], v[128:131], v[212:215], v[76:79]
	v_mfma_f32_16x16x32_bf16 v[72:75], v[136:139], v[212:215], v[72:75]
	v_mfma_f32_16x16x32_bf16 v[72:75], v[140:143], v[216:219], v[72:75]
	v_mfma_f32_16x16x32_bf16 v[88:91], v[140:143], v[208:211], v[88:91]
	v_mfma_f32_16x16x32_bf16 v[88:91], v[136:139], v[204:207], v[88:91]
	v_mfma_f32_16x16x32_bf16 v[104:107], v[136:139], v[196:199], v[104:107]
	v_mfma_f32_16x16x32_bf16 v[104:107], v[140:143], v[200:203], v[104:107]
	v_mfma_f32_16x16x32_bf16 v[120:123], v[140:143], v[192:195], v[120:123]
	v_mfma_f32_16x16x32_bf16 v[120:123], v[136:139], v[180:183], v[120:123]
	s_setprio 0
	s_setprio 1
	v_mfma_f32_16x16x32_bf16 v[112:115], v[172:175], v[180:183], v[112:115]
	v_mfma_f32_16x16x32_bf16 v[112:115], v[176:179], v[192:195], v[112:115]
	v_mfma_f32_16x16x32_bf16 v[96:99], v[176:179], v[200:203], v[96:99]
	v_mfma_f32_16x16x32_bf16 v[96:99], v[172:175], v[196:199], v[96:99]
	v_mfma_f32_16x16x32_bf16 v[80:83], v[172:175], v[204:207], v[80:83]
	v_mfma_f32_16x16x32_bf16 v[80:83], v[176:179], v[208:211], v[80:83]
	v_mfma_f32_16x16x32_bf16 v[64:67], v[176:179], v[216:219], v[64:67]
	v_mfma_f32_16x16x32_bf16 v[64:67], v[172:175], v[212:215], v[64:67]
	v_mfma_f32_16x16x32_bf16 v[68:71], v[144:147], v[212:215], v[68:71]
	v_mfma_f32_16x16x32_bf16 v[68:71], v[148:151], v[216:219], v[68:71]
	v_mfma_f32_16x16x32_bf16 v[84:87], v[148:151], v[208:211], v[84:87]
	v_mfma_f32_16x16x32_bf16 v[84:87], v[144:147], v[204:207], v[84:87]
	v_mfma_f32_16x16x32_bf16 v[100:103], v[144:147], v[196:199], v[100:103]
	v_mfma_f32_16x16x32_bf16 v[100:103], v[148:151], v[200:203], v[100:103]
	v_mfma_f32_16x16x32_bf16 v[116:119], v[148:151], v[192:195], v[116:119]
	v_mfma_f32_16x16x32_bf16 v[116:119], v[144:147], v[180:183], v[116:119]
	s_barrier
	s_setprio 0
	s_add_i32 s62, s81, s66
	v_lshl_add_u64 v[220:221], v[220:221], 0, s[26:27]
	s_mov_b32 m0, s62
	ds_read_b128 v[180:183], v190 offset:49152
	v_xor_b32_e32 v253, 64, v190
	ds_read_b128 v[192:195], v253 offset:49152
	ds_read_b128 v[196:199], v190 offset:51200
	ds_read_b128 v[200:203], v253 offset:51200
	ds_read_b128 v[204:207], v190 offset:53248
	ds_read_b128 v[208:211], v253 offset:53248
	ds_read_b128 v[212:215], v190 offset:55296
	ds_read_b128 v[216:219], v253 offset:55296
	global_load_lds_dwordx4 v[220:221], off
	s_add_i32 m0, s62, 0x2000
	s_add_u32 s60, s60, 0x40080
	v_lshl_add_u64 v[220:221], v[222:223], 0, s[26:27]
	s_addc_u32 s61, s61, 0
	s_add_i32 s62, s82, s66
	global_load_lds_dwordx4 v[220:221], off
	v_lshl_add_u64 v[220:221], s[60:61], 0, v[154:155]
	s_mov_b32 m0, s62
	s_nop 0
	global_load_lds_dwordx4 v[220:221], off
	v_lshl_add_u64 v[220:221], s[60:61], 0, v[162:163]
	s_add_i32 m0, s62, 0x2000
	s_nop 0
	global_load_lds_dwordx4 v[220:221], off
	v_lshl_add_u64 v[220:221], v[224:225], 0, s[26:27]
	s_mov_b32 m0, s3
	s_nop 0
	global_load_lds_dwordx4 v[220:221], off
	v_lshl_add_u64 v[220:221], v[226:227], 0, s[26:27]
	s_mov_b32 m0, s72
	s_nop 0
	global_load_lds_dwordx4 v[220:221], off
	s_waitcnt vmcnt(8)
	s_waitcnt lgkmcnt(0)
	s_setprio 1
	s_barrier
	v_mfma_f32_16x16x32_bf16 v[60:63], v[128:131], v[180:183], v[60:63]
	v_mfma_f32_16x16x32_bf16 v[60:63], v[132:135], v[192:195], v[60:63]
	v_mfma_f32_16x16x32_bf16 v[44:47], v[132:135], v[200:203], v[44:47]
	v_mfma_f32_16x16x32_bf16 v[44:47], v[128:131], v[196:199], v[44:47]
	v_mfma_f32_16x16x32_bf16 v[28:31], v[128:131], v[204:207], v[28:31]
	v_mfma_f32_16x16x32_bf16 v[28:31], v[132:135], v[208:211], v[28:31]
	v_mfma_f32_16x16x32_bf16 v[12:15], v[132:135], v[216:219], v[12:15]
	v_mfma_f32_16x16x32_bf16 v[12:15], v[128:131], v[212:215], v[12:15]
	v_mfma_f32_16x16x32_bf16 v[8:11], v[136:139], v[212:215], v[8:11]
	v_mfma_f32_16x16x32_bf16 v[8:11], v[140:143], v[216:219], v[8:11]
	v_mfma_f32_16x16x32_bf16 v[24:27], v[140:143], v[208:211], v[24:27]
	v_mfma_f32_16x16x32_bf16 v[24:27], v[136:139], v[204:207], v[24:27]
	v_mfma_f32_16x16x32_bf16 v[40:43], v[136:139], v[196:199], v[40:43]
	v_mfma_f32_16x16x32_bf16 v[40:43], v[140:143], v[200:203], v[40:43]
	v_mfma_f32_16x16x32_bf16 v[56:59], v[140:143], v[192:195], v[56:59]
	v_mfma_f32_16x16x32_bf16 v[56:59], v[136:139], v[180:183], v[56:59]
	s_setprio 0
	s_setprio 1
	v_mfma_f32_16x16x32_bf16 v[48:51], v[172:175], v[180:183], v[48:51]
	v_mfma_f32_16x16x32_bf16 v[48:51], v[176:179], v[192:195], v[48:51]
	v_mfma_f32_16x16x32_bf16 v[32:35], v[176:179], v[200:203], v[32:35]
	v_mfma_f32_16x16x32_bf16 v[32:35], v[172:175], v[196:199], v[32:35]
	v_mfma_f32_16x16x32_bf16 v[16:19], v[172:175], v[204:207], v[16:19]
	v_mfma_f32_16x16x32_bf16 v[16:19], v[176:179], v[208:211], v[16:19]
	v_mfma_f32_16x16x32_bf16 v[0:3], v[176:179], v[216:219], v[0:3]
	v_mfma_f32_16x16x32_bf16 v[0:3], v[172:175], v[212:215], v[0:3]
	v_mfma_f32_16x16x32_bf16 v[4:7], v[144:147], v[212:215], v[4:7]
	v_mfma_f32_16x16x32_bf16 v[4:7], v[148:151], v[216:219], v[4:7]
	v_mfma_f32_16x16x32_bf16 v[20:23], v[148:151], v[208:211], v[20:23]
	v_mfma_f32_16x16x32_bf16 v[20:23], v[144:147], v[204:207], v[20:23]
	v_mfma_f32_16x16x32_bf16 v[36:39], v[144:147], v[196:199], v[36:39]
	v_mfma_f32_16x16x32_bf16 v[36:39], v[148:151], v[200:203], v[36:39]
	v_mfma_f32_16x16x32_bf16 v[52:55], v[148:151], v[192:195], v[52:55]
	v_mfma_f32_16x16x32_bf16 v[52:55], v[144:147], v[180:183], v[52:55]
	s_barrier
	s_setprio 0
	s_add_i32 s80, s80, 2
	s_add_u32 s78, s78, 0x100
	s_addc_u32 s79, s79, 0
	s_add_u32 s58, s58, 0x100
	s_addc_u32 s59, s59, 0
	s_cmp_gt_u32 s80, 13
.LBB0_1011:
	ds_read_b128 v[128:131], v188
	v_xor_b32_e32 v253, 64, v188
	ds_read_b128 v[132:135], v253
	ds_read_b128 v[136:139], v188 offset:2048
	ds_read_b128 v[140:143], v253 offset:2048
	ds_read_b128 v[144:147], v189
	v_xor_b32_e32 v253, 64, v189
	ds_read_b128 v[148:151], v253
	ds_read_b128 v[172:175], v189 offset:2048
	ds_read_b128 v[176:179], v253 offset:2048
	s_add_u32 s60, s58, 0xfffc0080
	s_addc_u32 s61, s59, -1
	s_cmp_eq_u32 s80, 12
	s_cselect_b32 s63, s15, s61
	s_cselect_b32 s62, s51, s60
	s_cselect_b32 s61, s49, s79
	s_cselect_b32 s60, s57, s78
	v_lshl_add_u64 v[220:221], s[58:59], 0, v[166:167]
	s_add_i32 m0, s67, 0xc000
	ds_read_b128 v[180:183], v190
	v_xor_b32_e32 v253, 64, v190
	ds_read_b128 v[192:195], v253
	ds_read_b128 v[196:199], v190 offset:2048
	ds_read_b128 v[200:203], v253 offset:2048
	ds_read_b128 v[204:207], v190 offset:4096
	ds_read_b128 v[208:211], v253 offset:4096
	ds_read_b128 v[212:215], v190 offset:6144
	ds_read_b128 v[216:219], v253 offset:6144
	global_load_lds_dwordx4 v[220:221], off
	v_lshl_add_u64 v[220:221], s[58:59], 0, v[164:165]
	s_add_i32 m0, s67, 0xe000
	s_nop 0
	global_load_lds_dwordx4 v[220:221], off
	s_waitcnt vmcnt(8)
	s_waitcnt lgkmcnt(0)
	s_setprio 1
	s_barrier
	v_mfma_f32_16x16x32_bf16 v[124:127], v[128:131], v[180:183], v[124:127]
	v_mfma_f32_16x16x32_bf16 v[124:127], v[132:135], v[192:195], v[124:127]
	v_mfma_f32_16x16x32_bf16 v[108:111], v[132:135], v[200:203], v[108:111]
	v_mfma_f32_16x16x32_bf16 v[108:111], v[128:131], v[196:199], v[108:111]
	v_mfma_f32_16x16x32_bf16 v[92:95], v[128:131], v[204:207], v[92:95]
	v_mfma_f32_16x16x32_bf16 v[92:95], v[132:135], v[208:211], v[92:95]
	v_mfma_f32_16x16x32_bf16 v[76:79], v[132:135], v[216:219], v[76:79]
	v_mfma_f32_16x16x32_bf16 v[76:79], v[128:131], v[212:215], v[76:79]
	v_mfma_f32_16x16x32_bf16 v[72:75], v[136:139], v[212:215], v[72:75]
	v_mfma_f32_16x16x32_bf16 v[72:75], v[140:143], v[216:219], v[72:75]
	v_mfma_f32_16x16x32_bf16 v[88:91], v[140:143], v[208:211], v[88:91]
	v_mfma_f32_16x16x32_bf16 v[88:91], v[136:139], v[204:207], v[88:91]
	v_mfma_f32_16x16x32_bf16 v[104:107], v[136:139], v[196:199], v[104:107]
	v_mfma_f32_16x16x32_bf16 v[104:107], v[140:143], v[200:203], v[104:107]
	v_mfma_f32_16x16x32_bf16 v[120:123], v[140:143], v[192:195], v[120:123]
	v_mfma_f32_16x16x32_bf16 v[120:123], v[136:139], v[180:183], v[120:123]
	s_setprio 0
	s_setprio 1
	v_mfma_f32_16x16x32_bf16 v[112:115], v[172:175], v[180:183], v[112:115]
	v_mfma_f32_16x16x32_bf16 v[112:115], v[176:179], v[192:195], v[112:115]
	v_mfma_f32_16x16x32_bf16 v[96:99], v[176:179], v[200:203], v[96:99]
	v_mfma_f32_16x16x32_bf16 v[96:99], v[172:175], v[196:199], v[96:99]
	v_mfma_f32_16x16x32_bf16 v[80:83], v[172:175], v[204:207], v[80:83]
	v_mfma_f32_16x16x32_bf16 v[80:83], v[176:179], v[208:211], v[80:83]
	v_mfma_f32_16x16x32_bf16 v[64:67], v[176:179], v[216:219], v[64:67]
	v_mfma_f32_16x16x32_bf16 v[64:67], v[172:175], v[212:215], v[64:67]
	v_mfma_f32_16x16x32_bf16 v[68:71], v[144:147], v[212:215], v[68:71]
	v_mfma_f32_16x16x32_bf16 v[68:71], v[148:151], v[216:219], v[68:71]
	v_mfma_f32_16x16x32_bf16 v[84:87], v[148:151], v[208:211], v[84:87]
	v_mfma_f32_16x16x32_bf16 v[84:87], v[144:147], v[204:207], v[84:87]
	v_mfma_f32_16x16x32_bf16 v[100:103], v[144:147], v[196:199], v[100:103]
	v_mfma_f32_16x16x32_bf16 v[100:103], v[148:151], v[200:203], v[100:103]
	v_mfma_f32_16x16x32_bf16 v[116:119], v[148:151], v[192:195], v[116:119]
	v_mfma_f32_16x16x32_bf16 v[116:119], v[144:147], v[180:183], v[116:119]
	s_barrier
	s_setprio 0
	s_add_i32 s81, s76, s66
	v_lshl_add_u64 v[220:221], s[60:61], 0, v[154:155]
	s_mov_b32 m0, s81
	ds_read_b128 v[180:183], v190 offset:16384
	v_xor_b32_e32 v253, 64, v190
	ds_read_b128 v[192:195], v253 offset:16384
	ds_read_b128 v[196:199], v190 offset:18432
	ds_read_b128 v[200:203], v253 offset:18432
	ds_read_b128 v[204:207], v190 offset:20480
	ds_read_b128 v[208:211], v253 offset:20480
	ds_read_b128 v[212:215], v190 offset:22528
	ds_read_b128 v[216:219], v253 offset:22528
	global_load_lds_dwordx4 v[220:221], off
	s_add_i32 m0, s81, 0x2000
	s_add_u32 s82, s60, 0x40000
	v_lshl_add_u64 v[222:223], s[60:61], 0, v[162:163]
	s_addc_u32 s83, s61, 0
	s_add_i32 s81, s77, s66
	global_load_lds_dwordx4 v[222:223], off
	v_lshl_add_u64 v[224:225], s[82:83], 0, v[154:155]
	s_mov_b32 m0, s81
	v_lshl_add_u64 v[226:227], s[62:63], 0, v[160:161]
	global_load_lds_dwordx4 v[224:225], off
	v_lshl_add_u64 v[224:225], s[82:83], 0, v[162:163]
	s_add_i32 m0, s81, 0x2000
	s_nop 0
	global_load_lds_dwordx4 v[224:225], off
	v_lshl_add_u64 v[224:225], s[62:63], 0, v[152:153]
	s_mov_b32 m0, s67
	s_nop 0
	global_load_lds_dwordx4 v[224:225], off
	s_mov_b32 m0, s68
	s_nop 0
	global_load_lds_dwordx4 v[226:227], off
	s_waitcnt vmcnt(8)
	s_waitcnt lgkmcnt(0)
	s_setprio 1
	s_barrier
	v_mfma_f32_16x16x32_bf16 v[60:63], v[128:131], v[180:183], v[60:63]
	v_mfma_f32_16x16x32_bf16 v[60:63], v[132:135], v[192:195], v[60:63]
	v_mfma_f32_16x16x32_bf16 v[44:47], v[132:135], v[200:203], v[44:47]
	v_mfma_f32_16x16x32_bf16 v[44:47], v[128:131], v[196:199], v[44:47]
	v_mfma_f32_16x16x32_bf16 v[28:31], v[128:131], v[204:207], v[28:31]
	v_mfma_f32_16x16x32_bf16 v[28:31], v[132:135], v[208:211], v[28:31]
	v_mfma_f32_16x16x32_bf16 v[12:15], v[132:135], v[216:219], v[12:15]
	v_mfma_f32_16x16x32_bf16 v[12:15], v[128:131], v[212:215], v[12:15]
	v_mfma_f32_16x16x32_bf16 v[8:11], v[136:139], v[212:215], v[8:11]
	v_mfma_f32_16x16x32_bf16 v[8:11], v[140:143], v[216:219], v[8:11]
	v_mfma_f32_16x16x32_bf16 v[24:27], v[140:143], v[208:211], v[24:27]
	v_mfma_f32_16x16x32_bf16 v[24:27], v[136:139], v[204:207], v[24:27]
	v_mfma_f32_16x16x32_bf16 v[40:43], v[136:139], v[196:199], v[40:43]
	v_mfma_f32_16x16x32_bf16 v[40:43], v[140:143], v[200:203], v[40:43]
	v_mfma_f32_16x16x32_bf16 v[56:59], v[140:143], v[192:195], v[56:59]
	v_mfma_f32_16x16x32_bf16 v[56:59], v[136:139], v[180:183], v[56:59]
	s_setprio 0
	s_setprio 1
	v_mfma_f32_16x16x32_bf16 v[48:51], v[172:175], v[180:183], v[48:51]
	v_mfma_f32_16x16x32_bf16 v[48:51], v[176:179], v[192:195], v[48:51]
	v_mfma_f32_16x16x32_bf16 v[32:35], v[176:179], v[200:203], v[32:35]
	v_mfma_f32_16x16x32_bf16 v[32:35], v[172:175], v[196:199], v[32:35]
	v_mfma_f32_16x16x32_bf16 v[16:19], v[172:175], v[204:207], v[16:19]
	v_mfma_f32_16x16x32_bf16 v[16:19], v[176:179], v[208:211], v[16:19]
	v_mfma_f32_16x16x32_bf16 v[0:3], v[176:179], v[216:219], v[0:3]
	v_mfma_f32_16x16x32_bf16 v[0:3], v[172:175], v[212:215], v[0:3]
	v_mfma_f32_16x16x32_bf16 v[4:7], v[144:147], v[212:215], v[4:7]
	v_mfma_f32_16x16x32_bf16 v[4:7], v[148:151], v[216:219], v[4:7]
	v_mfma_f32_16x16x32_bf16 v[20:23], v[148:151], v[208:211], v[20:23]
	v_mfma_f32_16x16x32_bf16 v[20:23], v[144:147], v[204:207], v[20:23]
	v_mfma_f32_16x16x32_bf16 v[36:39], v[144:147], v[196:199], v[36:39]
	v_mfma_f32_16x16x32_bf16 v[36:39], v[148:151], v[200:203], v[36:39]
	v_mfma_f32_16x16x32_bf16 v[52:55], v[148:151], v[192:195], v[52:55]
	v_mfma_f32_16x16x32_bf16 v[52:55], v[144:147], v[180:183], v[52:55]
	s_barrier
	s_setprio 0
	s_add_i32 s81, 0, 0x18000
	s_add_i32 s82, 0, 0x1c000
	v_add_u32_e32 v140, s81, v185
	v_add_u32_e32 v176, s82, v185
	ds_read_b128 v[128:131], v140
	v_xor_b32_e32 v253, 64, v140
	ds_read_b128 v[132:135], v253
	ds_read_b128 v[136:139], v140 offset:2048
	ds_read_b128 v[140:143], v253 offset:2048
	ds_read_b128 v[144:147], v176
	v_xor_b32_e32 v253, 64, v176
	ds_read_b128 v[148:151], v253
	ds_read_b128 v[172:175], v176 offset:2048
	ds_read_b128 v[176:179], v253 offset:2048
	s_add_u32 s62, s62, 0x40000
	s_addc_u32 s63, s63, 0
	s_mov_b32 m0, s69
	v_lshl_add_u64 v[228:229], s[62:63], 0, v[152:153]
	ds_read_b128 v[180:183], v190 offset:32768
	v_xor_b32_e32 v253, 64, v190
	ds_read_b128 v[192:195], v253 offset:32768
	ds_read_b128 v[196:199], v190 offset:34816
	ds_read_b128 v[200:203], v253 offset:34816
	ds_read_b128 v[204:207], v190 offset:36864
	ds_read_b128 v[208:211], v253 offset:36864
	ds_read_b128 v[212:215], v190 offset:38912
	ds_read_b128 v[216:219], v253 offset:38912
	global_load_lds_dwordx4 v[228:229], off
	v_lshl_add_u64 v[228:229], s[62:63], 0, v[160:161]
	s_mov_b32 m0, s70
	s_nop 0
	global_load_lds_dwordx4 v[228:229], off
	s_waitcnt vmcnt(8)
	s_waitcnt lgkmcnt(0)
	s_setprio 1
	s_barrier
	v_mfma_f32_16x16x32_bf16 v[124:127], v[128:131], v[180:183], v[124:127]
	v_mfma_f32_16x16x32_bf16 v[124:127], v[132:135], v[192:195], v[124:127]
	v_mfma_f32_16x16x32_bf16 v[108:111], v[132:135], v[200:203], v[108:111]
	v_mfma_f32_16x16x32_bf16 v[108:111], v[128:131], v[196:199], v[108:111]
	v_mfma_f32_16x16x32_bf16 v[92:95], v[128:131], v[204:207], v[92:95]
	v_mfma_f32_16x16x32_bf16 v[92:95], v[132:135], v[208:211], v[92:95]
	v_mfma_f32_16x16x32_bf16 v[76:79], v[132:135], v[216:219], v[76:79]
	v_mfma_f32_16x16x32_bf16 v[76:79], v[128:131], v[212:215], v[76:79]
	v_mfma_f32_16x16x32_bf16 v[72:75], v[136:139], v[212:215], v[72:75]
	v_mfma_f32_16x16x32_bf16 v[72:75], v[140:143], v[216:219], v[72:75]
	v_mfma_f32_16x16x32_bf16 v[88:91], v[140:143], v[208:211], v[88:91]
	v_mfma_f32_16x16x32_bf16 v[88:91], v[136:139], v[204:207], v[88:91]
	v_mfma_f32_16x16x32_bf16 v[104:107], v[136:139], v[196:199], v[104:107]
	v_mfma_f32_16x16x32_bf16 v[104:107], v[140:143], v[200:203], v[104:107]
	v_mfma_f32_16x16x32_bf16 v[120:123], v[140:143], v[192:195], v[120:123]
	v_mfma_f32_16x16x32_bf16 v[120:123], v[136:139], v[180:183], v[120:123]
	s_setprio 0
	s_setprio 1
	v_mfma_f32_16x16x32_bf16 v[112:115], v[172:175], v[180:183], v[112:115]
	v_mfma_f32_16x16x32_bf16 v[112:115], v[176:179], v[192:195], v[112:115]
	v_mfma_f32_16x16x32_bf16 v[96:99], v[176:179], v[200:203], v[96:99]
	v_mfma_f32_16x16x32_bf16 v[96:99], v[172:175], v[196:199], v[96:99]
	v_mfma_f32_16x16x32_bf16 v[80:83], v[172:175], v[204:207], v[80:83]
	v_mfma_f32_16x16x32_bf16 v[80:83], v[176:179], v[208:211], v[80:83]
	v_mfma_f32_16x16x32_bf16 v[64:67], v[176:179], v[216:219], v[64:67]
	v_mfma_f32_16x16x32_bf16 v[64:67], v[172:175], v[212:215], v[64:67]
	v_mfma_f32_16x16x32_bf16 v[68:71], v[144:147], v[212:215], v[68:71]
	v_mfma_f32_16x16x32_bf16 v[68:71], v[148:151], v[216:219], v[68:71]
	v_mfma_f32_16x16x32_bf16 v[84:87], v[148:151], v[208:211], v[84:87]
	v_mfma_f32_16x16x32_bf16 v[84:87], v[144:147], v[204:207], v[84:87]
	v_mfma_f32_16x16x32_bf16 v[100:103], v[144:147], v[196:199], v[100:103]
	v_mfma_f32_16x16x32_bf16 v[100:103], v[148:151], v[200:203], v[100:103]
	v_mfma_f32_16x16x32_bf16 v[116:119], v[148:151], v[192:195], v[116:119]
	v_mfma_f32_16x16x32_bf16 v[116:119], v[144:147], v[180:183], v[116:119]
	s_barrier
	s_setprio 0
	s_add_i32 s62, s81, s66
	v_lshl_add_u64 v[220:221], v[220:221], 0, s[26:27]
	s_mov_b32 m0, s62
	ds_read_b128 v[180:183], v190 offset:49152
	v_xor_b32_e32 v253, 64, v190
	ds_read_b128 v[192:195], v253 offset:49152
	ds_read_b128 v[196:199], v190 offset:51200
	ds_read_b128 v[200:203], v253 offset:51200
	ds_read_b128 v[204:207], v190 offset:53248
	ds_read_b128 v[208:211], v253 offset:53248
	ds_read_b128 v[212:215], v190 offset:55296
	ds_read_b128 v[216:219], v253 offset:55296
	global_load_lds_dwordx4 v[220:221], off
	s_add_i32 m0, s62, 0x2000
	s_add_u32 s60, s60, 0x40080
	v_lshl_add_u64 v[220:221], v[222:223], 0, s[26:27]
	s_addc_u32 s61, s61, 0
	s_add_i32 s62, s82, s66
	global_load_lds_dwordx4 v[220:221], off
	v_lshl_add_u64 v[220:221], s[60:61], 0, v[154:155]
	s_mov_b32 m0, s62
	s_nop 0
	global_load_lds_dwordx4 v[220:221], off
	v_lshl_add_u64 v[220:221], s[60:61], 0, v[162:163]
	s_add_i32 m0, s62, 0x2000
	s_nop 0
	global_load_lds_dwordx4 v[220:221], off
	v_lshl_add_u64 v[220:221], v[224:225], 0, s[26:27]
	s_mov_b32 m0, s3
	s_nop 0
	global_load_lds_dwordx4 v[220:221], off
	v_lshl_add_u64 v[220:221], v[226:227], 0, s[26:27]
	s_mov_b32 m0, s72
	s_nop 0
	global_load_lds_dwordx4 v[220:221], off
	s_waitcnt vmcnt(8)
	s_waitcnt lgkmcnt(0)
	s_setprio 1
	s_barrier
	v_mfma_f32_16x16x32_bf16 v[60:63], v[128:131], v[180:183], v[60:63]
	v_mfma_f32_16x16x32_bf16 v[60:63], v[132:135], v[192:195], v[60:63]
	v_mfma_f32_16x16x32_bf16 v[44:47], v[132:135], v[200:203], v[44:47]
	v_mfma_f32_16x16x32_bf16 v[44:47], v[128:131], v[196:199], v[44:47]
	v_mfma_f32_16x16x32_bf16 v[28:31], v[128:131], v[204:207], v[28:31]
	v_mfma_f32_16x16x32_bf16 v[28:31], v[132:135], v[208:211], v[28:31]
	v_mfma_f32_16x16x32_bf16 v[12:15], v[132:135], v[216:219], v[12:15]
	v_mfma_f32_16x16x32_bf16 v[12:15], v[128:131], v[212:215], v[12:15]
	v_mfma_f32_16x16x32_bf16 v[8:11], v[136:139], v[212:215], v[8:11]
	v_mfma_f32_16x16x32_bf16 v[8:11], v[140:143], v[216:219], v[8:11]
	v_mfma_f32_16x16x32_bf16 v[24:27], v[140:143], v[208:211], v[24:27]
	v_mfma_f32_16x16x32_bf16 v[24:27], v[136:139], v[204:207], v[24:27]
	v_mfma_f32_16x16x32_bf16 v[40:43], v[136:139], v[196:199], v[40:43]
	v_mfma_f32_16x16x32_bf16 v[40:43], v[140:143], v[200:203], v[40:43]
	v_mfma_f32_16x16x32_bf16 v[56:59], v[140:143], v[192:195], v[56:59]
	v_mfma_f32_16x16x32_bf16 v[56:59], v[136:139], v[180:183], v[56:59]
	s_setprio 0
	s_setprio 1
	v_mfma_f32_16x16x32_bf16 v[48:51], v[172:175], v[180:183], v[48:51]
	v_mfma_f32_16x16x32_bf16 v[48:51], v[176:179], v[192:195], v[48:51]
	v_mfma_f32_16x16x32_bf16 v[32:35], v[176:179], v[200:203], v[32:35]
	v_mfma_f32_16x16x32_bf16 v[32:35], v[172:175], v[196:199], v[32:35]
	v_mfma_f32_16x16x32_bf16 v[16:19], v[172:175], v[204:207], v[16:19]
	v_mfma_f32_16x16x32_bf16 v[16:19], v[176:179], v[208:211], v[16:19]
	v_mfma_f32_16x16x32_bf16 v[0:3], v[176:179], v[216:219], v[0:3]
	v_mfma_f32_16x16x32_bf16 v[0:3], v[172:175], v[212:215], v[0:3]
	v_mfma_f32_16x16x32_bf16 v[4:7], v[144:147], v[212:215], v[4:7]
	v_mfma_f32_16x16x32_bf16 v[4:7], v[148:151], v[216:219], v[4:7]
	v_mfma_f32_16x16x32_bf16 v[20:23], v[148:151], v[208:211], v[20:23]
	v_mfma_f32_16x16x32_bf16 v[20:23], v[144:147], v[204:207], v[20:23]
	v_mfma_f32_16x16x32_bf16 v[36:39], v[144:147], v[196:199], v[36:39]
	v_mfma_f32_16x16x32_bf16 v[36:39], v[148:151], v[200:203], v[36:39]
	v_mfma_f32_16x16x32_bf16 v[52:55], v[148:151], v[192:195], v[52:55]
	v_mfma_f32_16x16x32_bf16 v[52:55], v[144:147], v[180:183], v[52:55]
	s_barrier
	s_setprio 0
	s_add_i32 s80, s80, 2
	s_add_u32 s78, s78, 0x100
	s_addc_u32 s79, s79, 0
	s_add_u32 s58, s58, 0x100
	s_addc_u32 s59, s59, 0
	s_cmp_gt_u32 s80, 13
	s_cbranch_scc0 .LBB0_1011
	s_and_b64 vcc, exec, s[28:29]
	s_cbranch_vccz .LBB0_1014
	s_barrier

.LBB0_1096:
	s_ashr_i32 s25, s24, 31
	s_lshl_b64 s[26:27], s[24:25], 19
	s_add_u32 s26, s3, s26
	s_addc_u32 s27, s33, s27
	s_and_b64 s[28:29], s[6:7], exec
	s_cselect_b32 s25, s27, s47
	s_cselect_b32 s65, s26, s46
	s_ashr_i32 s23, s22, 31
	s_lshl_b64 s[28:29], s[22:23], 19
	s_add_u32 s28, s35, s28
	s_addc_u32 s29, s48, s29
	s_and_b64 s[66:67], s[6:7], exec
	s_cselect_b32 s66, s29, s45
	s_cselect_b32 s67, s28, s44
	s_lshl_b32 s23, s30, 8
	v_add_u32_e32 v0, s23, v148
	s_add_u32 s68, s44, 0x100
	v_ashrrev_i32_e32 v1, 31, v0
	s_addc_u32 s69, s45, 0
	v_lshl_add_u64 v[144:145], v[0:1], 4, s[12:13]
	s_add_u32 s30, s46, 0x40080
	s_addc_u32 s31, s47, 0
	s_mov_b32 s70, -2
	s_mov_b64 s[44:45], 0
	s_cmp_eq_u32 s56, 1
	s_cbranch_scc1 .Lfa_10
	v_add_u32_e32 v153, s61, v147
	ds_read_b128 v[160:163], v153
	v_xor_b32_e32 v253, 64, v153
	ds_read_b128 v[164:167], v253
	ds_read_b128 v[168:171], v153 offset:2048
	ds_read_b128 v[172:175], v253 offset:2048
	v_add_u32_e32 v153, s62, v147
	ds_read_b128 v[176:179], v153
	v_xor_b32_e32 v253, 64, v153
	ds_read_b128 v[180:183], v253
	ds_read_b128 v[184:187], v153 offset:2048
	ds_read_b128 v[188:191], v253 offset:2048
	s_add_u32 s46, s30, 0xfffc0080
	s_addc_u32 s47, s31, -1
	s_and_b64 s[44:45], s[44:45], exec
	s_cselect_b32 s47, s25, s47
	s_cselect_b32 s46, s65, s46
	s_cselect_b32 s45, s66, s69
	s_cselect_b32 s44, s67, s68
	v_lshl_add_u64 v[154:155], s[30:31], 0, v[138:139]
	s_add_i32 m0, s52, 0xc000
	ds_read_b128 v[192:195], v150
	v_xor_b32_e32 v253, 64, v150
	ds_read_b128 v[196:199], v253
	ds_read_b128 v[200:203], v150 offset:2048
	ds_read_b128 v[204:207], v253 offset:2048
	ds_read_b128 v[208:211], v150 offset:4096
	ds_read_b128 v[212:215], v253 offset:4096
	ds_read_b128 v[216:219], v150 offset:6144
	ds_read_b128 v[220:223], v253 offset:6144
	global_load_lds_dwordx4 v[154:155], off
	v_lshl_add_u64 v[154:155], s[30:31], 0, v[136:137]
	s_add_i32 m0, s52, 0xe000
	s_nop 0
	global_load_lds_dwordx4 v[154:155], off
	s_waitcnt vmcnt(16)
	s_waitcnt lgkmcnt(0)
	s_setprio 1
	s_barrier
	v_mfma_f32_16x16x32_bf16 v[124:127], v[160:163], v[192:195], 0
	v_mfma_f32_16x16x32_bf16 v[116:119], v[168:171], v[192:195], 0
	v_mfma_f32_16x16x32_bf16 v[108:111], v[160:163], v[200:203], 0
	v_mfma_f32_16x16x32_bf16 v[100:103], v[168:171], v[200:203], 0
	v_mfma_f32_16x16x32_bf16 v[92:95], v[160:163], v[208:211], 0
	v_mfma_f32_16x16x32_bf16 v[84:87], v[168:171], v[208:211], 0
	v_mfma_f32_16x16x32_bf16 v[76:79], v[160:163], v[216:219], 0
	v_mfma_f32_16x16x32_bf16 v[68:71], v[168:171], v[216:219], 0
	v_mfma_f32_16x16x32_bf16 v[124:127], v[164:167], v[196:199], v[124:127]
	v_mfma_f32_16x16x32_bf16 v[116:119], v[172:175], v[196:199], v[116:119]
	v_mfma_f32_16x16x32_bf16 v[108:111], v[164:167], v[204:207], v[108:111]
	v_mfma_f32_16x16x32_bf16 v[100:103], v[172:175], v[204:207], v[100:103]
	v_mfma_f32_16x16x32_bf16 v[92:95], v[164:167], v[212:215], v[92:95]
	v_mfma_f32_16x16x32_bf16 v[84:87], v[172:175], v[212:215], v[84:87]
	v_mfma_f32_16x16x32_bf16 v[76:79], v[164:167], v[220:223], v[76:79]
	v_mfma_f32_16x16x32_bf16 v[68:71], v[172:175], v[220:223], v[68:71]
	s_setprio 0
	s_setprio 1
	v_mfma_f32_16x16x32_bf16 v[120:123], v[176:179], v[192:195], 0
	v_mfma_f32_16x16x32_bf16 v[112:115], v[184:187], v[192:195], 0
	v_mfma_f32_16x16x32_bf16 v[104:107], v[176:179], v[200:203], 0
	v_mfma_f32_16x16x32_bf16 v[96:99], v[184:187], v[200:203], 0
	v_mfma_f32_16x16x32_bf16 v[88:91], v[176:179], v[208:211], 0
	v_mfma_f32_16x16x32_bf16 v[80:83], v[184:187], v[208:211], 0
	v_mfma_f32_16x16x32_bf16 v[72:75], v[176:179], v[216:219], 0
	v_mfma_f32_16x16x32_bf16 v[64:67], v[184:187], v[216:219], 0
	v_mfma_f32_16x16x32_bf16 v[120:123], v[180:183], v[196:199], v[120:123]
	v_mfma_f32_16x16x32_bf16 v[112:115], v[188:191], v[196:199], v[112:115]
	v_mfma_f32_16x16x32_bf16 v[104:107], v[180:183], v[204:207], v[104:107]
	v_mfma_f32_16x16x32_bf16 v[96:99], v[188:191], v[204:207], v[96:99]
	v_mfma_f32_16x16x32_bf16 v[88:91], v[180:183], v[212:215], v[88:91]
	v_mfma_f32_16x16x32_bf16 v[80:83], v[188:191], v[212:215], v[80:83]
	v_mfma_f32_16x16x32_bf16 v[72:75], v[180:183], v[220:223], v[72:75]
	v_mfma_f32_16x16x32_bf16 v[64:67], v[188:191], v[220:223], v[64:67]
	s_barrier
	s_setprio 0
	s_add_i32 s71, s61, s49
	v_lshl_add_u64 v[154:155], s[44:45], 0, v[132:133]
	s_mov_b32 m0, s71
	ds_read_b128 v[192:195], v150 offset:16384
	v_xor_b32_e32 v253, 64, v150
	ds_read_b128 v[196:199], v253 offset:16384
	ds_read_b128 v[200:203], v150 offset:18432
	ds_read_b128 v[204:207], v253 offset:18432
	ds_read_b128 v[208:211], v150 offset:20480
	ds_read_b128 v[212:215], v253 offset:20480
	ds_read_b128 v[216:219], v150 offset:22528
	ds_read_b128 v[220:223], v253 offset:22528
	global_load_lds_dwordx4 v[154:155], off
	s_add_i32 m0, s71, 0x2000
	s_add_u32 s72, s44, 0x40000
	v_lshl_add_u64 v[224:225], s[44:45], 0, v[128:129]
	s_addc_u32 s73, s45, 0
	s_add_i32 s71, s62, s49
	global_load_lds_dwordx4 v[224:225], off
	v_lshl_add_u64 v[226:227], s[72:73], 0, v[132:133]
	s_mov_b32 m0, s71
	v_lshl_add_u64 v[228:229], s[46:47], 0, v[130:131]
	global_load_lds_dwordx4 v[226:227], off
	v_lshl_add_u64 v[226:227], s[72:73], 0, v[128:129]
	s_add_i32 m0, s71, 0x2000
	s_nop 0
	global_load_lds_dwordx4 v[226:227], off
	v_lshl_add_u64 v[226:227], s[46:47], 0, v[134:135]
	s_mov_b32 m0, s52
	s_nop 0
	global_load_lds_dwordx4 v[226:227], off
	s_mov_b32 m0, s53
	s_nop 0
	global_load_lds_dwordx4 v[228:229], off
	s_waitcnt vmcnt(16)
	s_waitcnt lgkmcnt(0)
	s_setprio 1
	s_barrier
	v_mfma_f32_16x16x32_bf16 v[60:63], v[160:163], v[192:195], 0
	v_mfma_f32_16x16x32_bf16 v[52:55], v[168:171], v[192:195], 0
	v_mfma_f32_16x16x32_bf16 v[44:47], v[160:163], v[200:203], 0
	v_mfma_f32_16x16x32_bf16 v[36:39], v[168:171], v[200:203], 0
	v_mfma_f32_16x16x32_bf16 v[28:31], v[160:163], v[208:211], 0
	v_mfma_f32_16x16x32_bf16 v[20:23], v[168:171], v[208:211], 0
	v_mfma_f32_16x16x32_bf16 v[12:15], v[160:163], v[216:219], 0
	v_mfma_f32_16x16x32_bf16 v[4:7], v[168:171], v[216:219], 0
	v_mfma_f32_16x16x32_bf16 v[60:63], v[164:167], v[196:199], v[60:63]
	v_mfma_f32_16x16x32_bf16 v[52:55], v[172:175], v[196:199], v[52:55]
	v_mfma_f32_16x16x32_bf16 v[44:47], v[164:167], v[204:207], v[44:47]
	v_mfma_f32_16x16x32_bf16 v[36:39], v[172:175], v[204:207], v[36:39]
	v_mfma_f32_16x16x32_bf16 v[28:31], v[164:167], v[212:215], v[28:31]
	v_mfma_f32_16x16x32_bf16 v[20:23], v[172:175], v[212:215], v[20:23]
	v_mfma_f32_16x16x32_bf16 v[12:15], v[164:167], v[220:223], v[12:15]
	v_mfma_f32_16x16x32_bf16 v[4:7], v[172:175], v[220:223], v[4:7]
	s_setprio 0
	s_setprio 1
	v_mfma_f32_16x16x32_bf16 v[56:59], v[176:179], v[192:195], 0
	v_mfma_f32_16x16x32_bf16 v[48:51], v[184:187], v[192:195], 0
	v_mfma_f32_16x16x32_bf16 v[40:43], v[176:179], v[200:203], 0
	v_mfma_f32_16x16x32_bf16 v[32:35], v[184:187], v[200:203], 0
	v_mfma_f32_16x16x32_bf16 v[24:27], v[176:179], v[208:211], 0
	v_mfma_f32_16x16x32_bf16 v[16:19], v[184:187], v[208:211], 0
	v_mfma_f32_16x16x32_bf16 v[8:11], v[176:179], v[216:219], 0
	v_mfma_f32_16x16x32_bf16 v[0:3], v[184:187], v[216:219], 0
	v_mfma_f32_16x16x32_bf16 v[56:59], v[180:183], v[196:199], v[56:59]
	v_mfma_f32_16x16x32_bf16 v[48:51], v[188:191], v[196:199], v[48:51]
	v_mfma_f32_16x16x32_bf16 v[40:43], v[180:183], v[204:207], v[40:43]
	v_mfma_f32_16x16x32_bf16 v[32:35], v[188:191], v[204:207], v[32:35]
	v_mfma_f32_16x16x32_bf16 v[24:27], v[180:183], v[212:215], v[24:27]
	v_mfma_f32_16x16x32_bf16 v[16:19], v[188:191], v[212:215], v[16:19]
	v_mfma_f32_16x16x32_bf16 v[8:11], v[180:183], v[220:223], v[8:11]
	v_mfma_f32_16x16x32_bf16 v[0:3], v[188:191], v[220:223], v[0:3]
	s_barrier
	s_setprio 0
	s_add_i32 s71, 0, 0x18000
	v_add_u32_e32 v153, s71, v147
	s_add_i32 s72, 0, 0x1c000
	ds_read_b128 v[160:163], v153
	v_xor_b32_e32 v253, 64, v153
	ds_read_b128 v[164:167], v253
	ds_read_b128 v[168:171], v153 offset:2048
	ds_read_b128 v[172:175], v253 offset:2048
	v_add_u32_e32 v153, s72, v147
	ds_read_b128 v[176:179], v153
	v_xor_b32_e32 v253, 64, v153
	ds_read_b128 v[180:183], v253
	ds_read_b128 v[184:187], v153 offset:2048
	ds_read_b128 v[188:191], v253 offset:2048
	s_add_u32 s46, s46, 0x40000
	s_addc_u32 s47, s47, 0
	s_mov_b32 m0, s54
	v_lshl_add_u64 v[230:231], s[46:47], 0, v[134:135]
	ds_read_b128 v[192:195], v150 offset:32768
	v_xor_b32_e32 v253, 64, v150
	ds_read_b128 v[196:199], v253 offset:32768
	ds_read_b128 v[200:203], v150 offset:34816
	ds_read_b128 v[204:207], v253 offset:34816
	ds_read_b128 v[208:211], v150 offset:36864
	ds_read_b128 v[212:215], v253 offset:36864
	ds_read_b128 v[216:219], v150 offset:38912
	ds_read_b128 v[220:223], v253 offset:38912
	global_load_lds_dwordx4 v[230:231], off
	v_lshl_add_u64 v[230:231], s[46:47], 0, v[130:131]
	s_mov_b32 m0, s55
	s_nop 0
	global_load_lds_dwordx4 v[230:231], off
	s_waitcnt vmcnt(8)
	s_waitcnt lgkmcnt(0)
	s_setprio 1
	s_barrier
	v_mfma_f32_16x16x32_bf16 v[124:127], v[160:163], v[192:195], v[124:127]
	v_mfma_f32_16x16x32_bf16 v[124:127], v[164:167], v[196:199], v[124:127]
	v_mfma_f32_16x16x32_bf16 v[108:111], v[164:167], v[204:207], v[108:111]
	v_mfma_f32_16x16x32_bf16 v[108:111], v[160:163], v[200:203], v[108:111]
	v_mfma_f32_16x16x32_bf16 v[92:95], v[160:163], v[208:211], v[92:95]
	v_mfma_f32_16x16x32_bf16 v[92:95], v[164:167], v[212:215], v[92:95]
	v_mfma_f32_16x16x32_bf16 v[76:79], v[164:167], v[220:223], v[76:79]
	v_mfma_f32_16x16x32_bf16 v[76:79], v[160:163], v[216:219], v[76:79]
	v_mfma_f32_16x16x32_bf16 v[68:71], v[168:171], v[216:219], v[68:71]
	v_mfma_f32_16x16x32_bf16 v[68:71], v[172:175], v[220:223], v[68:71]
	v_mfma_f32_16x16x32_bf16 v[84:87], v[172:175], v[212:215], v[84:87]
	v_mfma_f32_16x16x32_bf16 v[84:87], v[168:171], v[208:211], v[84:87]
	v_mfma_f32_16x16x32_bf16 v[100:103], v[168:171], v[200:203], v[100:103]
	v_mfma_f32_16x16x32_bf16 v[100:103], v[172:175], v[204:207], v[100:103]
	v_mfma_f32_16x16x32_bf16 v[116:119], v[172:175], v[196:199], v[116:119]
	v_mfma_f32_16x16x32_bf16 v[116:119], v[168:171], v[192:195], v[116:119]
	s_setprio 0
	s_setprio 1
	v_mfma_f32_16x16x32_bf16 v[112:115], v[184:187], v[192:195], v[112:115]
	v_mfma_f32_16x16x32_bf16 v[112:115], v[188:191], v[196:199], v[112:115]
	v_mfma_f32_16x16x32_bf16 v[96:99], v[188:191], v[204:207], v[96:99]
	v_mfma_f32_16x16x32_bf16 v[96:99], v[184:187], v[200:203], v[96:99]
	v_mfma_f32_16x16x32_bf16 v[80:83], v[184:187], v[208:211], v[80:83]
	v_mfma_f32_16x16x32_bf16 v[80:83], v[188:191], v[212:215], v[80:83]
	v_mfma_f32_16x16x32_bf16 v[64:67], v[188:191], v[220:223], v[64:67]
	v_mfma_f32_16x16x32_bf16 v[64:67], v[184:187], v[216:219], v[64:67]
	v_mfma_f32_16x16x32_bf16 v[72:75], v[176:179], v[216:219], v[72:75]
	v_mfma_f32_16x16x32_bf16 v[72:75], v[180:183], v[220:223], v[72:75]
	v_mfma_f32_16x16x32_bf16 v[88:91], v[180:183], v[212:215], v[88:91]
	v_mfma_f32_16x16x32_bf16 v[88:91], v[176:179], v[208:211], v[88:91]
	v_mfma_f32_16x16x32_bf16 v[104:107], v[176:179], v[200:203], v[104:107]
	v_mfma_f32_16x16x32_bf16 v[104:107], v[180:183], v[204:207], v[104:107]
	v_mfma_f32_16x16x32_bf16 v[120:123], v[180:183], v[196:199], v[120:123]
	v_mfma_f32_16x16x32_bf16 v[120:123], v[176:179], v[192:195], v[120:123]
	s_barrier
	s_setprio 0
	s_add_i32 s46, s71, s49
	v_lshl_add_u64 v[154:155], v[154:155], 0, s[14:15]
	s_mov_b32 m0, s46
	ds_read_b128 v[192:195], v150 offset:49152
	v_xor_b32_e32 v253, 64, v150
	ds_read_b128 v[196:199], v253 offset:49152
	ds_read_b128 v[200:203], v150 offset:51200
	ds_read_b128 v[204:207], v253 offset:51200
	ds_read_b128 v[208:211], v150 offset:53248
	ds_read_b128 v[212:215], v253 offset:53248
	ds_read_b128 v[216:219], v150 offset:55296
	ds_read_b128 v[220:223], v253 offset:55296
	global_load_lds_dwordx4 v[154:155], off
	s_add_i32 m0, s46, 0x2000
	s_add_u32 s44, s44, 0x40080
	v_lshl_add_u64 v[154:155], v[224:225], 0, s[14:15]
	s_addc_u32 s45, s45, 0
	s_add_i32 s46, s72, s49
	global_load_lds_dwordx4 v[154:155], off
	v_lshl_add_u64 v[154:155], s[44:45], 0, v[132:133]
	s_mov_b32 m0, s46
	s_nop 0
	global_load_lds_dwordx4 v[154:155], off
	v_lshl_add_u64 v[154:155], s[44:45], 0, v[128:129]
	s_add_i32 m0, s46, 0x2000
	s_nop 0
	global_load_lds_dwordx4 v[154:155], off
	v_lshl_add_u64 v[154:155], v[226:227], 0, s[14:15]
	s_mov_b32 m0, s57
	s_nop 0
	global_load_lds_dwordx4 v[154:155], off
	v_lshl_add_u64 v[154:155], v[228:229], 0, s[14:15]
	s_mov_b32 m0, s58
	s_nop 0
	global_load_lds_dwordx4 v[154:155], off
	s_waitcnt vmcnt(8)
	s_waitcnt lgkmcnt(0)
	s_setprio 1
	s_barrier
	v_mfma_f32_16x16x32_bf16 v[60:63], v[160:163], v[192:195], v[60:63]
	v_mfma_f32_16x16x32_bf16 v[60:63], v[164:167], v[196:199], v[60:63]
	v_mfma_f32_16x16x32_bf16 v[44:47], v[164:167], v[204:207], v[44:47]
	v_mfma_f32_16x16x32_bf16 v[44:47], v[160:163], v[200:203], v[44:47]
	v_mfma_f32_16x16x32_bf16 v[28:31], v[160:163], v[208:211], v[28:31]
	v_mfma_f32_16x16x32_bf16 v[28:31], v[164:167], v[212:215], v[28:31]
	v_mfma_f32_16x16x32_bf16 v[12:15], v[164:167], v[220:223], v[12:15]
	v_mfma_f32_16x16x32_bf16 v[12:15], v[160:163], v[216:219], v[12:15]
	v_mfma_f32_16x16x32_bf16 v[4:7], v[168:171], v[216:219], v[4:7]
	v_mfma_f32_16x16x32_bf16 v[4:7], v[172:175], v[220:223], v[4:7]
	v_mfma_f32_16x16x32_bf16 v[20:23], v[172:175], v[212:215], v[20:23]
	v_mfma_f32_16x16x32_bf16 v[20:23], v[168:171], v[208:211], v[20:23]
	v_mfma_f32_16x16x32_bf16 v[36:39], v[168:171], v[200:203], v[36:39]
	v_mfma_f32_16x16x32_bf16 v[36:39], v[172:175], v[204:207], v[36:39]
	v_mfma_f32_16x16x32_bf16 v[52:55], v[172:175], v[196:199], v[52:55]
	v_mfma_f32_16x16x32_bf16 v[52:55], v[168:171], v[192:195], v[52:55]
	s_setprio 0
	s_setprio 1
	v_mfma_f32_16x16x32_bf16 v[48:51], v[184:187], v[192:195], v[48:51]
	v_mfma_f32_16x16x32_bf16 v[48:51], v[188:191], v[196:199], v[48:51]
	v_mfma_f32_16x16x32_bf16 v[32:35], v[188:191], v[204:207], v[32:35]
	v_mfma_f32_16x16x32_bf16 v[32:35], v[184:187], v[200:203], v[32:35]
	v_mfma_f32_16x16x32_bf16 v[16:19], v[184:187], v[208:211], v[16:19]
	v_mfma_f32_16x16x32_bf16 v[16:19], v[188:191], v[212:215], v[16:19]
	v_mfma_f32_16x16x32_bf16 v[0:3], v[188:191], v[220:223], v[0:3]
	v_mfma_f32_16x16x32_bf16 v[0:3], v[184:187], v[216:219], v[0:3]
	v_mfma_f32_16x16x32_bf16 v[8:11], v[176:179], v[216:219], v[8:11]
	v_mfma_f32_16x16x32_bf16 v[8:11], v[180:183], v[220:223], v[8:11]
	v_mfma_f32_16x16x32_bf16 v[24:27], v[180:183], v[212:215], v[24:27]
	v_mfma_f32_16x16x32_bf16 v[24:27], v[176:179], v[208:211], v[24:27]
	v_mfma_f32_16x16x32_bf16 v[40:43], v[176:179], v[200:203], v[40:43]
	v_mfma_f32_16x16x32_bf16 v[40:43], v[180:183], v[204:207], v[40:43]
	v_mfma_f32_16x16x32_bf16 v[56:59], v[180:183], v[196:199], v[56:59]
	v_mfma_f32_16x16x32_bf16 v[56:59], v[176:179], v[192:195], v[56:59]
	s_barrier
	s_setprio 0
	s_add_i32 s70, s70, 2
	s_add_u32 s68, s68, 0x100
	s_addc_u32 s69, s69, 0
	s_add_u32 s30, s30, 0x100
	s_addc_u32 s31, s31, 0
	s_branch .LBB0_1098
.Lfa_10:
	v_add_u32_e32 v153, s61, v147
	ds_read_b128 v[160:163], v153
	v_xor_b32_e32 v253, 64, v153
	ds_read_b128 v[164:167], v253
	ds_read_b128 v[168:171], v153 offset:2048
	ds_read_b128 v[172:175], v253 offset:2048
	v_add_u32_e32 v153, s62, v147
	ds_read_b128 v[176:179], v153
	v_xor_b32_e32 v253, 64, v153
	ds_read_b128 v[180:183], v253
	ds_read_b128 v[184:187], v153 offset:2048
	ds_read_b128 v[188:191], v253 offset:2048
	s_add_u32 s46, s30, 0xfffc0080
	s_addc_u32 s47, s31, -1
	s_and_b64 s[44:45], s[44:45], exec
	s_cselect_b32 s47, s25, s47
	s_cselect_b32 s46, s65, s46
	s_cselect_b32 s45, s66, s69
	s_cselect_b32 s44, s67, s68
	v_lshl_add_u64 v[154:155], s[30:31], 0, v[138:139]
	s_add_i32 m0, s52, 0xc000
	ds_read_b128 v[192:195], v150
	v_xor_b32_e32 v253, 64, v150
	ds_read_b128 v[196:199], v253
	ds_read_b128 v[200:203], v150 offset:2048
	ds_read_b128 v[204:207], v253 offset:2048
	ds_read_b128 v[208:211], v150 offset:4096
	ds_read_b128 v[212:215], v253 offset:4096
	ds_read_b128 v[216:219], v150 offset:6144
	ds_read_b128 v[220:223], v253 offset:6144
	global_load_lds_dwordx4 v[154:155], off
	v_lshl_add_u64 v[154:155], s[30:31], 0, v[136:137]
	s_add_i32 m0, s52, 0xe000
	s_nop 0
	global_load_lds_dwordx4 v[154:155], off
	s_waitcnt vmcnt(8)
	s_waitcnt lgkmcnt(0)
	s_setprio 1
	s_barrier
	v_mfma_f32_16x16x32_bf16 v[124:127], v[160:163], v[192:195], 0
	v_mfma_f32_16x16x32_bf16 v[116:119], v[168:171], v[192:195], 0
	v_mfma_f32_16x16x32_bf16 v[108:111], v[160:163], v[200:203], 0
	v_mfma_f32_16x16x32_bf16 v[100:103], v[168:171], v[200:203], 0
	v_mfma_f32_16x16x32_bf16 v[92:95], v[160:163], v[208:211], 0
	v_mfma_f32_16x16x32_bf16 v[84:87], v[168:171], v[208:211], 0
	v_mfma_f32_16x16x32_bf16 v[76:79], v[160:163], v[216:219], 0
	v_mfma_f32_16x16x32_bf16 v[68:71], v[168:171], v[216:219], 0
	v_mfma_f32_16x16x32_bf16 v[124:127], v[164:167], v[196:199], v[124:127]
	v_mfma_f32_16x16x32_bf16 v[116:119], v[172:175], v[196:199], v[116:119]
	v_mfma_f32_16x16x32_bf16 v[108:111], v[164:167], v[204:207], v[108:111]
	v_mfma_f32_16x16x32_bf16 v[100:103], v[172:175], v[204:207], v[100:103]
	v_mfma_f32_16x16x32_bf16 v[92:95], v[164:167], v[212:215], v[92:95]
	v_mfma_f32_16x16x32_bf16 v[84:87], v[172:175], v[212:215], v[84:87]
	v_mfma_f32_16x16x32_bf16 v[76:79], v[164:167], v[220:223], v[76:79]
	v_mfma_f32_16x16x32_bf16 v[68:71], v[172:175], v[220:223], v[68:71]
	s_setprio 0
	s_setprio 1
	v_mfma_f32_16x16x32_bf16 v[120:123], v[176:179], v[192:195], 0
	v_mfma_f32_16x16x32_bf16 v[112:115], v[184:187], v[192:195], 0
	v_mfma_f32_16x16x32_bf16 v[104:107], v[176:179], v[200:203], 0
	v_mfma_f32_16x16x32_bf16 v[96:99], v[184:187], v[200:203], 0
	v_mfma_f32_16x16x32_bf16 v[88:91], v[176:179], v[208:211], 0
	v_mfma_f32_16x16x32_bf16 v[80:83], v[184:187], v[208:211], 0
	v_mfma_f32_16x16x32_bf16 v[72:75], v[176:179], v[216:219], 0
	v_mfma_f32_16x16x32_bf16 v[64:67], v[184:187], v[216:219], 0
	v_mfma_f32_16x16x32_bf16 v[120:123], v[180:183], v[196:199], v[120:123]
	v_mfma_f32_16x16x32_bf16 v[112:115], v[188:191], v[196:199], v[112:115]
	v_mfma_f32_16x16x32_bf16 v[104:107], v[180:183], v[204:207], v[104:107]
	v_mfma_f32_16x16x32_bf16 v[96:99], v[188:191], v[204:207], v[96:99]
	v_mfma_f32_16x16x32_bf16 v[88:91], v[180:183], v[212:215], v[88:91]
	v_mfma_f32_16x16x32_bf16 v[80:83], v[188:191], v[212:215], v[80:83]
	v_mfma_f32_16x16x32_bf16 v[72:75], v[180:183], v[220:223], v[72:75]
	v_mfma_f32_16x16x32_bf16 v[64:67], v[188:191], v[220:223], v[64:67]
	s_barrier
	s_setprio 0
	s_add_i32 s71, s61, s49
	v_lshl_add_u64 v[154:155], s[44:45], 0, v[132:133]
	s_mov_b32 m0, s71
	ds_read_b128 v[192:195], v150 offset:16384
	v_xor_b32_e32 v253, 64, v150
	ds_read_b128 v[196:199], v253 offset:16384
	ds_read_b128 v[200:203], v150 offset:18432
	ds_read_b128 v[204:207], v253 offset:18432
	ds_read_b128 v[208:211], v150 offset:20480
	ds_read_b128 v[212:215], v253 offset:20480
	ds_read_b128 v[216:219], v150 offset:22528
	ds_read_b128 v[220:223], v253 offset:22528
	global_load_lds_dwordx4 v[154:155], off
	s_add_i32 m0, s71, 0x2000
	s_add_u32 s72, s44, 0x40000
	v_lshl_add_u64 v[224:225], s[44:45], 0, v[128:129]
	s_addc_u32 s73, s45, 0
	s_add_i32 s71, s62, s49
	global_load_lds_dwordx4 v[224:225], off
	v_lshl_add_u64 v[226:227], s[72:73], 0, v[132:133]
	s_mov_b32 m0, s71
	v_lshl_add_u64 v[228:229], s[46:47], 0, v[130:131]
	global_load_lds_dwordx4 v[226:227], off
	v_lshl_add_u64 v[226:227], s[72:73], 0, v[128:129]
	s_add_i32 m0, s71, 0x2000
	s_nop 0
	global_load_lds_dwordx4 v[226:227], off
	v_lshl_add_u64 v[226:227], s[46:47], 0, v[134:135]
	s_mov_b32 m0, s52
	s_nop 0
	global_load_lds_dwordx4 v[226:227], off
	s_mov_b32 m0, s53
	s_nop 0
	global_load_lds_dwordx4 v[228:229], off
	s_waitcnt vmcnt(8)
	s_waitcnt lgkmcnt(0)
	s_setprio 1
	s_barrier
	v_mfma_f32_16x16x32_bf16 v[60:63], v[160:163], v[192:195], 0
	v_mfma_f32_16x16x32_bf16 v[52:55], v[168:171], v[192:195], 0
	v_mfma_f32_16x16x32_bf16 v[44:47], v[160:163], v[200:203], 0
	v_mfma_f32_16x16x32_bf16 v[36:39], v[168:171], v[200:203], 0
	v_mfma_f32_16x16x32_bf16 v[28:31], v[160:163], v[208:211], 0
	v_mfma_f32_16x16x32_bf16 v[20:23], v[168:171], v[208:211], 0
	v_mfma_f32_16x16x32_bf16 v[12:15], v[160:163], v[216:219], 0
	v_mfma_f32_16x16x32_bf16 v[4:7], v[168:171], v[216:219], 0
	v_mfma_f32_16x16x32_bf16 v[60:63], v[164:167], v[196:199], v[60:63]
	v_mfma_f32_16x16x32_bf16 v[52:55], v[172:175], v[196:199], v[52:55]
	v_mfma_f32_16x16x32_bf16 v[44:47], v[164:167], v[204:207], v[44:47]
	v_mfma_f32_16x16x32_bf16 v[36:39], v[172:175], v[204:207], v[36:39]
	v_mfma_f32_16x16x32_bf16 v[28:31], v[164:167], v[212:215], v[28:31]
	v_mfma_f32_16x16x32_bf16 v[20:23], v[172:175], v[212:215], v[20:23]
	v_mfma_f32_16x16x32_bf16 v[12:15], v[164:167], v[220:223], v[12:15]
	v_mfma_f32_16x16x32_bf16 v[4:7], v[172:175], v[220:223], v[4:7]
	s_setprio 0
	s_setprio 1
	v_mfma_f32_16x16x32_bf16 v[56:59], v[176:179], v[192:195], 0
	v_mfma_f32_16x16x32_bf16 v[48:51], v[184:187], v[192:195], 0
	v_mfma_f32_16x16x32_bf16 v[40:43], v[176:179], v[200:203], 0
	v_mfma_f32_16x16x32_bf16 v[32:35], v[184:187], v[200:203], 0
	v_mfma_f32_16x16x32_bf16 v[24:27], v[176:179], v[208:211], 0
	v_mfma_f32_16x16x32_bf16 v[16:19], v[184:187], v[208:211], 0
	v_mfma_f32_16x16x32_bf16 v[8:11], v[176:179], v[216:219], 0
	v_mfma_f32_16x16x32_bf16 v[0:3], v[184:187], v[216:219], 0
	v_mfma_f32_16x16x32_bf16 v[56:59], v[180:183], v[196:199], v[56:59]
	v_mfma_f32_16x16x32_bf16 v[48:51], v[188:191], v[196:199], v[48:51]
	v_mfma_f32_16x16x32_bf16 v[40:43], v[180:183], v[204:207], v[40:43]
	v_mfma_f32_16x16x32_bf16 v[32:35], v[188:191], v[204:207], v[32:35]
	v_mfma_f32_16x16x32_bf16 v[24:27], v[180:183], v[212:215], v[24:27]
	v_mfma_f32_16x16x32_bf16 v[16:19], v[188:191], v[212:215], v[16:19]
	v_mfma_f32_16x16x32_bf16 v[8:11], v[180:183], v[220:223], v[8:11]
	v_mfma_f32_16x16x32_bf16 v[0:3], v[188:191], v[220:223], v[0:3]
	s_barrier
	s_setprio 0
	s_add_i32 s71, 0, 0x18000
	v_add_u32_e32 v153, s71, v147
	s_add_i32 s72, 0, 0x1c000
	ds_read_b128 v[160:163], v153
	v_xor_b32_e32 v253, 64, v153
	ds_read_b128 v[164:167], v253
	ds_read_b128 v[168:171], v153 offset:2048
	ds_read_b128 v[172:175], v253 offset:2048
	v_add_u32_e32 v153, s72, v147
	ds_read_b128 v[176:179], v153
	v_xor_b32_e32 v253, 64, v153
	ds_read_b128 v[180:183], v253
	ds_read_b128 v[184:187], v153 offset:2048
	ds_read_b128 v[188:191], v253 offset:2048
	s_add_u32 s46, s46, 0x40000
	s_addc_u32 s47, s47, 0
	s_mov_b32 m0, s54
	v_lshl_add_u64 v[230:231], s[46:47], 0, v[134:135]
	ds_read_b128 v[192:195], v150 offset:32768
	v_xor_b32_e32 v253, 64, v150
	ds_read_b128 v[196:199], v253 offset:32768
	ds_read_b128 v[200:203], v150 offset:34816
	ds_read_b128 v[204:207], v253 offset:34816
	ds_read_b128 v[208:211], v150 offset:36864
	ds_read_b128 v[212:215], v253 offset:36864
	ds_read_b128 v[216:219], v150 offset:38912
	ds_read_b128 v[220:223], v253 offset:38912
	global_load_lds_dwordx4 v[230:231], off
	v_lshl_add_u64 v[230:231], s[46:47], 0, v[130:131]
	s_mov_b32 m0, s55
	s_nop 0
	global_load_lds_dwordx4 v[230:231], off
	s_waitcnt vmcnt(8)
	s_waitcnt lgkmcnt(0)
	s_setprio 1
	s_barrier
	v_mfma_f32_16x16x32_bf16 v[124:127], v[160:163], v[192:195], v[124:127]
	v_mfma_f32_16x16x32_bf16 v[124:127], v[164:167], v[196:199], v[124:127]
	v_mfma_f32_16x16x32_bf16 v[108:111], v[164:167], v[204:207], v[108:111]
	v_mfma_f32_16x16x32_bf16 v[108:111], v[160:163], v[200:203], v[108:111]
	v_mfma_f32_16x16x32_bf16 v[92:95], v[160:163], v[208:211], v[92:95]
	v_mfma_f32_16x16x32_bf16 v[92:95], v[164:167], v[212:215], v[92:95]
	v_mfma_f32_16x16x32_bf16 v[76:79], v[164:167], v[220:223], v[76:79]
	v_mfma_f32_16x16x32_bf16 v[76:79], v[160:163], v[216:219], v[76:79]
	v_mfma_f32_16x16x32_bf16 v[68:71], v[168:171], v[216:219], v[68:71]
	v_mfma_f32_16x16x32_bf16 v[68:71], v[172:175], v[220:223], v[68:71]
	v_mfma_f32_16x16x32_bf16 v[84:87], v[172:175], v[212:215], v[84:87]
	v_mfma_f32_16x16x32_bf16 v[84:87], v[168:171], v[208:211], v[84:87]
	v_mfma_f32_16x16x32_bf16 v[100:103], v[168:171], v[200:203], v[100:103]
	v_mfma_f32_16x16x32_bf16 v[100:103], v[172:175], v[204:207], v[100:103]
	v_mfma_f32_16x16x32_bf16 v[116:119], v[172:175], v[196:199], v[116:119]
	v_mfma_f32_16x16x32_bf16 v[116:119], v[168:171], v[192:195], v[116:119]
	s_setprio 0
	s_setprio 1
	v_mfma_f32_16x16x32_bf16 v[112:115], v[184:187], v[192:195], v[112:115]
	v_mfma_f32_16x16x32_bf16 v[112:115], v[188:191], v[196:199], v[112:115]
	v_mfma_f32_16x16x32_bf16 v[96:99], v[188:191], v[204:207], v[96:99]
	v_mfma_f32_16x16x32_bf16 v[96:99], v[184:187], v[200:203], v[96:99]
	v_mfma_f32_16x16x32_bf16 v[80:83], v[184:187], v[208:211], v[80:83]
	v_mfma_f32_16x16x32_bf16 v[80:83], v[188:191], v[212:215], v[80:83]
	v_mfma_f32_16x16x32_bf16 v[64:67], v[188:191], v[220:223], v[64:67]
	v_mfma_f32_16x16x32_bf16 v[64:67], v[184:187], v[216:219], v[64:67]
	v_mfma_f32_16x16x32_bf16 v[72:75], v[176:179], v[216:219], v[72:75]
	v_mfma_f32_16x16x32_bf16 v[72:75], v[180:183], v[220:223], v[72:75]
	v_mfma_f32_16x16x32_bf16 v[88:91], v[180:183], v[212:215], v[88:91]
	v_mfma_f32_16x16x32_bf16 v[88:91], v[176:179], v[208:211], v[88:91]
	v_mfma_f32_16x16x32_bf16 v[104:107], v[176:179], v[200:203], v[104:107]
	v_mfma_f32_16x16x32_bf16 v[104:107], v[180:183], v[204:207], v[104:107]
	v_mfma_f32_16x16x32_bf16 v[120:123], v[180:183], v[196:199], v[120:123]
	v_mfma_f32_16x16x32_bf16 v[120:123], v[176:179], v[192:195], v[120:123]
	s_barrier
	s_setprio 0
	s_add_i32 s46, s71, s49
	v_lshl_add_u64 v[154:155], v[154:155], 0, s[14:15]
	s_mov_b32 m0, s46
	ds_read_b128 v[192:195], v150 offset:49152
	v_xor_b32_e32 v253, 64, v150
	ds_read_b128 v[196:199], v253 offset:49152
	ds_read_b128 v[200:203], v150 offset:51200
	ds_read_b128 v[204:207], v253 offset:51200
	ds_read_b128 v[208:211], v150 offset:53248
	ds_read_b128 v[212:215], v253 offset:53248
	ds_read_b128 v[216:219], v150 offset:55296
	ds_read_b128 v[220:223], v253 offset:55296
	global_load_lds_dwordx4 v[154:155], off
	s_add_i32 m0, s46, 0x2000
	s_add_u32 s44, s44, 0x40080
	v_lshl_add_u64 v[154:155], v[224:225], 0, s[14:15]
	s_addc_u32 s45, s45, 0
	s_add_i32 s46, s72, s49
	global_load_lds_dwordx4 v[154:155], off
	v_lshl_add_u64 v[154:155], s[44:45], 0, v[132:133]
	s_mov_b32 m0, s46
	s_nop 0
	global_load_lds_dwordx4 v[154:155], off
	v_lshl_add_u64 v[154:155], s[44:45], 0, v[128:129]
	s_add_i32 m0, s46, 0x2000
	s_nop 0
	global_load_lds_dwordx4 v[154:155], off
	v_lshl_add_u64 v[154:155], v[226:227], 0, s[14:15]
	s_mov_b32 m0, s57
	s_nop 0
	global_load_lds_dwordx4 v[154:155], off
	v_lshl_add_u64 v[154:155], v[228:229], 0, s[14:15]
	s_mov_b32 m0, s58
	s_nop 0
	global_load_lds_dwordx4 v[154:155], off
	s_waitcnt vmcnt(8)
	s_waitcnt lgkmcnt(0)
	s_setprio 1
	s_barrier
	v_mfma_f32_16x16x32_bf16 v[60:63], v[160:163], v[192:195], v[60:63]
	v_mfma_f32_16x16x32_bf16 v[60:63], v[164:167], v[196:199], v[60:63]
	v_mfma_f32_16x16x32_bf16 v[44:47], v[164:167], v[204:207], v[44:47]
	v_mfma_f32_16x16x32_bf16 v[44:47], v[160:163], v[200:203], v[44:47]
	v_mfma_f32_16x16x32_bf16 v[28:31], v[160:163], v[208:211], v[28:31]
	v_mfma_f32_16x16x32_bf16 v[28:31], v[164:167], v[212:215], v[28:31]
	v_mfma_f32_16x16x32_bf16 v[12:15], v[164:167], v[220:223], v[12:15]
	v_mfma_f32_16x16x32_bf16 v[12:15], v[160:163], v[216:219], v[12:15]
	v_mfma_f32_16x16x32_bf16 v[4:7], v[168:171], v[216:219], v[4:7]
	v_mfma_f32_16x16x32_bf16 v[4:7], v[172:175], v[220:223], v[4:7]
	v_mfma_f32_16x16x32_bf16 v[20:23], v[172:175], v[212:215], v[20:23]
	v_mfma_f32_16x16x32_bf16 v[20:23], v[168:171], v[208:211], v[20:23]
	v_mfma_f32_16x16x32_bf16 v[36:39], v[168:171], v[200:203], v[36:39]
	v_mfma_f32_16x16x32_bf16 v[36:39], v[172:175], v[204:207], v[36:39]
	v_mfma_f32_16x16x32_bf16 v[52:55], v[172:175], v[196:199], v[52:55]
	v_mfma_f32_16x16x32_bf16 v[52:55], v[168:171], v[192:195], v[52:55]
	s_setprio 0
	s_setprio 1
	v_mfma_f32_16x16x32_bf16 v[48:51], v[184:187], v[192:195], v[48:51]
	v_mfma_f32_16x16x32_bf16 v[48:51], v[188:191], v[196:199], v[48:51]
	v_mfma_f32_16x16x32_bf16 v[32:35], v[188:191], v[204:207], v[32:35]
	v_mfma_f32_16x16x32_bf16 v[32:35], v[184:187], v[200:203], v[32:35]
	v_mfma_f32_16x16x32_bf16 v[16:19], v[184:187], v[208:211], v[16:19]
	v_mfma_f32_16x16x32_bf16 v[16:19], v[188:191], v[212:215], v[16:19]
	v_mfma_f32_16x16x32_bf16 v[0:3], v[188:191], v[220:223], v[0:3]
	v_mfma_f32_16x16x32_bf16 v[0:3], v[184:187], v[216:219], v[0:3]
	v_mfma_f32_16x16x32_bf16 v[8:11], v[176:179], v[216:219], v[8:11]
	v_mfma_f32_16x16x32_bf16 v[8:11], v[180:183], v[220:223], v[8:11]
	v_mfma_f32_16x16x32_bf16 v[24:27], v[180:183], v[212:215], v[24:27]
	v_mfma_f32_16x16x32_bf16 v[24:27], v[176:179], v[208:211], v[24:27]
	v_mfma_f32_16x16x32_bf16 v[40:43], v[176:179], v[200:203], v[40:43]
	v_mfma_f32_16x16x32_bf16 v[40:43], v[180:183], v[204:207], v[40:43]
	v_mfma_f32_16x16x32_bf16 v[56:59], v[180:183], v[196:199], v[56:59]
	v_mfma_f32_16x16x32_bf16 v[56:59], v[176:179], v[192:195], v[56:59]
	s_barrier
	s_setprio 0
	s_add_i32 s70, s70, 2
	s_add_u32 s68, s68, 0x100
	s_addc_u32 s69, s69, 0
	s_add_u32 s30, s30, 0x100
	s_addc_u32 s31, s31, 0
	s_branch .LBB0_1098
.LBB0_1097:
	v_add_u32_e32 v153, s61, v147
	ds_read_b128 v[160:163], v153
	v_xor_b32_e32 v253, 64, v153
	ds_read_b128 v[164:167], v253
	ds_read_b128 v[168:171], v153 offset:2048
	ds_read_b128 v[172:175], v253 offset:2048
	v_add_u32_e32 v153, s62, v147
	ds_read_b128 v[176:179], v153
	v_xor_b32_e32 v253, 64, v153
	ds_read_b128 v[180:183], v253
	ds_read_b128 v[184:187], v153 offset:2048
	ds_read_b128 v[188:191], v253 offset:2048
	s_add_u32 s46, s30, 0xfffc0080
	s_addc_u32 s47, s31, -1
	s_and_b64 s[44:45], s[44:45], exec
	s_cselect_b32 s47, s25, s47
	s_cselect_b32 s46, s65, s46
	s_cselect_b32 s45, s66, s69
	s_cselect_b32 s44, s67, s68
	v_lshl_add_u64 v[154:155], s[30:31], 0, v[138:139]
	s_add_i32 m0, s52, 0xc000
	ds_read_b128 v[192:195], v150
	v_xor_b32_e32 v253, 64, v150
	ds_read_b128 v[196:199], v253
	ds_read_b128 v[200:203], v150 offset:2048
	ds_read_b128 v[204:207], v253 offset:2048
	ds_read_b128 v[208:211], v150 offset:4096
	ds_read_b128 v[212:215], v253 offset:4096
	ds_read_b128 v[216:219], v150 offset:6144
	ds_read_b128 v[220:223], v253 offset:6144
	global_load_lds_dwordx4 v[154:155], off
	v_lshl_add_u64 v[154:155], s[30:31], 0, v[136:137]
	s_add_i32 m0, s52, 0xe000
	s_nop 0
	global_load_lds_dwordx4 v[154:155], off
	s_waitcnt vmcnt(8)
	s_waitcnt lgkmcnt(0)
	s_setprio 1
	s_barrier
	v_mfma_f32_16x16x32_bf16 v[124:127], v[160:163], v[192:195], v[124:127]
	v_mfma_f32_16x16x32_bf16 v[124:127], v[164:167], v[196:199], v[124:127]
	v_mfma_f32_16x16x32_bf16 v[108:111], v[164:167], v[204:207], v[108:111]
	v_mfma_f32_16x16x32_bf16 v[108:111], v[160:163], v[200:203], v[108:111]
	v_mfma_f32_16x16x32_bf16 v[92:95], v[160:163], v[208:211], v[92:95]
	v_mfma_f32_16x16x32_bf16 v[92:95], v[164:167], v[212:215], v[92:95]
	v_mfma_f32_16x16x32_bf16 v[76:79], v[164:167], v[220:223], v[76:79]
	v_mfma_f32_16x16x32_bf16 v[76:79], v[160:163], v[216:219], v[76:79]
	v_mfma_f32_16x16x32_bf16 v[68:71], v[168:171], v[216:219], v[68:71]
	v_mfma_f32_16x16x32_bf16 v[68:71], v[172:175], v[220:223], v[68:71]
	v_mfma_f32_16x16x32_bf16 v[84:87], v[172:175], v[212:215], v[84:87]
	v_mfma_f32_16x16x32_bf16 v[84:87], v[168:171], v[208:211], v[84:87]
	v_mfma_f32_16x16x32_bf16 v[100:103], v[168:171], v[200:203], v[100:103]
	v_mfma_f32_16x16x32_bf16 v[100:103], v[172:175], v[204:207], v[100:103]
	v_mfma_f32_16x16x32_bf16 v[116:119], v[172:175], v[196:199], v[116:119]
	v_mfma_f32_16x16x32_bf16 v[116:119], v[168:171], v[192:195], v[116:119]
	s_setprio 0
	s_setprio 1
	v_mfma_f32_16x16x32_bf16 v[112:115], v[184:187], v[192:195], v[112:115]
	v_mfma_f32_16x16x32_bf16 v[112:115], v[188:191], v[196:199], v[112:115]
	v_mfma_f32_16x16x32_bf16 v[96:99], v[188:191], v[204:207], v[96:99]
	v_mfma_f32_16x16x32_bf16 v[96:99], v[184:187], v[200:203], v[96:99]
	v_mfma_f32_16x16x32_bf16 v[80:83], v[184:187], v[208:211], v[80:83]
	v_mfma_f32_16x16x32_bf16 v[80:83], v[188:191], v[212:215], v[80:83]
	v_mfma_f32_16x16x32_bf16 v[64:67], v[188:191], v[220:223], v[64:67]
	v_mfma_f32_16x16x32_bf16 v[64:67], v[184:187], v[216:219], v[64:67]
	v_mfma_f32_16x16x32_bf16 v[72:75], v[176:179], v[216:219], v[72:75]
	v_mfma_f32_16x16x32_bf16 v[72:75], v[180:183], v[220:223], v[72:75]
	v_mfma_f32_16x16x32_bf16 v[88:91], v[180:183], v[212:215], v[88:91]
	v_mfma_f32_16x16x32_bf16 v[88:91], v[176:179], v[208:211], v[88:91]
	v_mfma_f32_16x16x32_bf16 v[104:107], v[176:179], v[200:203], v[104:107]
	v_mfma_f32_16x16x32_bf16 v[104:107], v[180:183], v[204:207], v[104:107]
	v_mfma_f32_16x16x32_bf16 v[120:123], v[180:183], v[196:199], v[120:123]
	v_mfma_f32_16x16x32_bf16 v[120:123], v[176:179], v[192:195], v[120:123]
	s_barrier
	s_setprio 0
	s_add_i32 s71, s61, s49
	v_lshl_add_u64 v[154:155], s[44:45], 0, v[132:133]
	s_mov_b32 m0, s71
	ds_read_b128 v[192:195], v150 offset:16384
	v_xor_b32_e32 v253, 64, v150
	ds_read_b128 v[196:199], v253 offset:16384
	ds_read_b128 v[200:203], v150 offset:18432
	ds_read_b128 v[204:207], v253 offset:18432
	ds_read_b128 v[208:211], v150 offset:20480
	ds_read_b128 v[212:215], v253 offset:20480
	ds_read_b128 v[216:219], v150 offset:22528
	ds_read_b128 v[220:223], v253 offset:22528
	global_load_lds_dwordx4 v[154:155], off
	s_add_i32 m0, s71, 0x2000
	s_add_u32 s72, s44, 0x40000
	v_lshl_add_u64 v[224:225], s[44:45], 0, v[128:129]
	s_addc_u32 s73, s45, 0
	s_add_i32 s71, s62, s49
	global_load_lds_dwordx4 v[224:225], off
	v_lshl_add_u64 v[226:227], s[72:73], 0, v[132:133]
	s_mov_b32 m0, s71
	v_lshl_add_u64 v[228:229], s[46:47], 0, v[130:131]
	global_load_lds_dwordx4 v[226:227], off
	v_lshl_add_u64 v[226:227], s[72:73], 0, v[128:129]
	s_add_i32 m0, s71, 0x2000
	s_nop 0
	global_load_lds_dwordx4 v[226:227], off
	v_lshl_add_u64 v[226:227], s[46:47], 0, v[134:135]
	s_mov_b32 m0, s52
	s_nop 0
	global_load_lds_dwordx4 v[226:227], off
	s_mov_b32 m0, s53
	s_nop 0
	global_load_lds_dwordx4 v[228:229], off
	s_waitcnt vmcnt(8)
	s_waitcnt lgkmcnt(0)
	s_setprio 1
	s_barrier
	v_mfma_f32_16x16x32_bf16 v[60:63], v[160:163], v[192:195], v[60:63]
	v_mfma_f32_16x16x32_bf16 v[60:63], v[164:167], v[196:199], v[60:63]
	v_mfma_f32_16x16x32_bf16 v[44:47], v[164:167], v[204:207], v[44:47]
	v_mfma_f32_16x16x32_bf16 v[44:47], v[160:163], v[200:203], v[44:47]
	v_mfma_f32_16x16x32_bf16 v[28:31], v[160:163], v[208:211], v[28:31]
	v_mfma_f32_16x16x32_bf16 v[28:31], v[164:167], v[212:215], v[28:31]
	v_mfma_f32_16x16x32_bf16 v[12:15], v[164:167], v[220:223], v[12:15]
	v_mfma_f32_16x16x32_bf16 v[12:15], v[160:163], v[216:219], v[12:15]
	v_mfma_f32_16x16x32_bf16 v[4:7], v[168:171], v[216:219], v[4:7]
	v_mfma_f32_16x16x32_bf16 v[4:7], v[172:175], v[220:223], v[4:7]
	v_mfma_f32_16x16x32_bf16 v[20:23], v[172:175], v[212:215], v[20:23]
	v_mfma_f32_16x16x32_bf16 v[20:23], v[168:171], v[208:211], v[20:23]
	v_mfma_f32_16x16x32_bf16 v[36:39], v[168:171], v[200:203], v[36:39]
	v_mfma_f32_16x16x32_bf16 v[36:39], v[172:175], v[204:207], v[36:39]
	v_mfma_f32_16x16x32_bf16 v[52:55], v[172:175], v[196:199], v[52:55]
	v_mfma_f32_16x16x32_bf16 v[52:55], v[168:171], v[192:195], v[52:55]
	s_setprio 0
	s_setprio 1
	v_mfma_f32_16x16x32_bf16 v[48:51], v[184:187], v[192:195], v[48:51]
	v_mfma_f32_16x16x32_bf16 v[48:51], v[188:191], v[196:199], v[48:51]
	v_mfma_f32_16x16x32_bf16 v[32:35], v[188:191], v[204:207], v[32:35]
	v_mfma_f32_16x16x32_bf16 v[32:35], v[184:187], v[200:203], v[32:35]
	v_mfma_f32_16x16x32_bf16 v[16:19], v[184:187], v[208:211], v[16:19]
	v_mfma_f32_16x16x32_bf16 v[16:19], v[188:191], v[212:215], v[16:19]
	v_mfma_f32_16x16x32_bf16 v[0:3], v[188:191], v[220:223], v[0:3]
	v_mfma_f32_16x16x32_bf16 v[0:3], v[184:187], v[216:219], v[0:3]
	v_mfma_f32_16x16x32_bf16 v[8:11], v[176:179], v[216:219], v[8:11]
	v_mfma_f32_16x16x32_bf16 v[8:11], v[180:183], v[220:223], v[8:11]
	v_mfma_f32_16x16x32_bf16 v[24:27], v[180:183], v[212:215], v[24:27]
	v_mfma_f32_16x16x32_bf16 v[24:27], v[176:179], v[208:211], v[24:27]
	v_mfma_f32_16x16x32_bf16 v[40:43], v[176:179], v[200:203], v[40:43]
	v_mfma_f32_16x16x32_bf16 v[40:43], v[180:183], v[204:207], v[40:43]
	v_mfma_f32_16x16x32_bf16 v[56:59], v[180:183], v[196:199], v[56:59]
	v_mfma_f32_16x16x32_bf16 v[56:59], v[176:179], v[192:195], v[56:59]
	s_barrier
	s_setprio 0
	s_add_i32 s71, 0, 0x18000
	v_add_u32_e32 v153, s71, v147
	s_add_i32 s72, 0, 0x1c000
	ds_read_b128 v[160:163], v153
	v_xor_b32_e32 v253, 64, v153
	ds_read_b128 v[164:167], v253
	ds_read_b128 v[168:171], v153 offset:2048
	ds_read_b128 v[172:175], v253 offset:2048
	v_add_u32_e32 v153, s72, v147
	ds_read_b128 v[176:179], v153
	v_xor_b32_e32 v253, 64, v153
	ds_read_b128 v[180:183], v253
	ds_read_b128 v[184:187], v153 offset:2048
	ds_read_b128 v[188:191], v253 offset:2048
	s_add_u32 s46, s46, 0x40000
	s_addc_u32 s47, s47, 0
	s_mov_b32 m0, s54
	v_lshl_add_u64 v[230:231], s[46:47], 0, v[134:135]
	ds_read_b128 v[192:195], v150 offset:32768
	v_xor_b32_e32 v253, 64, v150
	ds_read_b128 v[196:199], v253 offset:32768
	ds_read_b128 v[200:203], v150 offset:34816
	ds_read_b128 v[204:207], v253 offset:34816
	ds_read_b128 v[208:211], v150 offset:36864
	ds_read_b128 v[212:215], v253 offset:36864
	ds_read_b128 v[216:219], v150 offset:38912
	ds_read_b128 v[220:223], v253 offset:38912
	global_load_lds_dwordx4 v[230:231], off
	v_lshl_add_u64 v[230:231], s[46:47], 0, v[130:131]
	s_mov_b32 m0, s55
	s_nop 0
	global_load_lds_dwordx4 v[230:231], off
	s_waitcnt vmcnt(8)
	s_waitcnt lgkmcnt(0)
	s_setprio 1
	s_barrier
	v_mfma_f32_16x16x32_bf16 v[124:127], v[160:163], v[192:195], v[124:127]
	v_mfma_f32_16x16x32_bf16 v[124:127], v[164:167], v[196:199], v[124:127]
	v_mfma_f32_16x16x32_bf16 v[108:111], v[164:167], v[204:207], v[108:111]
	v_mfma_f32_16x16x32_bf16 v[108:111], v[160:163], v[200:203], v[108:111]
	v_mfma_f32_16x16x32_bf16 v[92:95], v[160:163], v[208:211], v[92:95]
	v_mfma_f32_16x16x32_bf16 v[92:95], v[164:167], v[212:215], v[92:95]
	v_mfma_f32_16x16x32_bf16 v[76:79], v[164:167], v[220:223], v[76:79]
	v_mfma_f32_16x16x32_bf16 v[76:79], v[160:163], v[216:219], v[76:79]
	v_mfma_f32_16x16x32_bf16 v[68:71], v[168:171], v[216:219], v[68:71]
	v_mfma_f32_16x16x32_bf16 v[68:71], v[172:175], v[220:223], v[68:71]
	v_mfma_f32_16x16x32_bf16 v[84:87], v[172:175], v[212:215], v[84:87]
	v_mfma_f32_16x16x32_bf16 v[84:87], v[168:171], v[208:211], v[84:87]
	v_mfma_f32_16x16x32_bf16 v[100:103], v[168:171], v[200:203], v[100:103]
	v_mfma_f32_16x16x32_bf16 v[100:103], v[172:175], v[204:207], v[100:103]
	v_mfma_f32_16x16x32_bf16 v[116:119], v[172:175], v[196:199], v[116:119]
	v_mfma_f32_16x16x32_bf16 v[116:119], v[168:171], v[192:195], v[116:119]
	s_setprio 0
	s_setprio 1
	v_mfma_f32_16x16x32_bf16 v[112:115], v[184:187], v[192:195], v[112:115]
	v_mfma_f32_16x16x32_bf16 v[112:115], v[188:191], v[196:199], v[112:115]
	v_mfma_f32_16x16x32_bf16 v[96:99], v[188:191], v[204:207], v[96:99]
	v_mfma_f32_16x16x32_bf16 v[96:99], v[184:187], v[200:203], v[96:99]
	v_mfma_f32_16x16x32_bf16 v[80:83], v[184:187], v[208:211], v[80:83]
	v_mfma_f32_16x16x32_bf16 v[80:83], v[188:191], v[212:215], v[80:83]
	v_mfma_f32_16x16x32_bf16 v[64:67], v[188:191], v[220:223], v[64:67]
	v_mfma_f32_16x16x32_bf16 v[64:67], v[184:187], v[216:219], v[64:67]
	v_mfma_f32_16x16x32_bf16 v[72:75], v[176:179], v[216:219], v[72:75]
	v_mfma_f32_16x16x32_bf16 v[72:75], v[180:183], v[220:223], v[72:75]
	v_mfma_f32_16x16x32_bf16 v[88:91], v[180:183], v[212:215], v[88:91]
	v_mfma_f32_16x16x32_bf16 v[88:91], v[176:179], v[208:211], v[88:91]
	v_mfma_f32_16x16x32_bf16 v[104:107], v[176:179], v[200:203], v[104:107]
	v_mfma_f32_16x16x32_bf16 v[104:107], v[180:183], v[204:207], v[104:107]
	v_mfma_f32_16x16x32_bf16 v[120:123], v[180:183], v[196:199], v[120:123]
	v_mfma_f32_16x16x32_bf16 v[120:123], v[176:179], v[192:195], v[120:123]
	s_barrier
	s_setprio 0
	s_add_i32 s46, s71, s49
	v_lshl_add_u64 v[154:155], v[154:155], 0, s[14:15]
	s_mov_b32 m0, s46
	ds_read_b128 v[192:195], v150 offset:49152
	v_xor_b32_e32 v253, 64, v150
	ds_read_b128 v[196:199], v253 offset:49152
	ds_read_b128 v[200:203], v150 offset:51200
	ds_read_b128 v[204:207], v253 offset:51200
	ds_read_b128 v[208:211], v150 offset:53248
	ds_read_b128 v[212:215], v253 offset:53248
	ds_read_b128 v[216:219], v150 offset:55296
	ds_read_b128 v[220:223], v253 offset:55296
	global_load_lds_dwordx4 v[154:155], off
	s_add_i32 m0, s46, 0x2000
	s_add_u32 s44, s44, 0x40080
	v_lshl_add_u64 v[154:155], v[224:225], 0, s[14:15]
	s_addc_u32 s45, s45, 0
	s_add_i32 s46, s72, s49
	global_load_lds_dwordx4 v[154:155], off
	v_lshl_add_u64 v[154:155], s[44:45], 0, v[132:133]
	s_mov_b32 m0, s46
	s_nop 0
	global_load_lds_dwordx4 v[154:155], off
	v_lshl_add_u64 v[154:155], s[44:45], 0, v[128:129]
	s_add_i32 m0, s46, 0x2000
	s_nop 0
	global_load_lds_dwordx4 v[154:155], off
	v_lshl_add_u64 v[154:155], v[226:227], 0, s[14:15]
	s_mov_b32 m0, s57
	s_nop 0
	global_load_lds_dwordx4 v[154:155], off
	v_lshl_add_u64 v[154:155], v[228:229], 0, s[14:15]
	s_mov_b32 m0, s58
	s_nop 0
	global_load_lds_dwordx4 v[154:155], off
	s_waitcnt vmcnt(8)
	s_waitcnt lgkmcnt(0)
	s_setprio 1
	s_barrier
	v_mfma_f32_16x16x32_bf16 v[60:63], v[160:163], v[192:195], v[60:63]
	v_mfma_f32_16x16x32_bf16 v[60:63], v[164:167], v[196:199], v[60:63]
	v_mfma_f32_16x16x32_bf16 v[44:47], v[164:167], v[204:207], v[44:47]
	v_mfma_f32_16x16x32_bf16 v[44:47], v[160:163], v[200:203], v[44:47]
	v_mfma_f32_16x16x32_bf16 v[28:31], v[160:163], v[208:211], v[28:31]
	v_mfma_f32_16x16x32_bf16 v[28:31], v[164:167], v[212:215], v[28:31]
	v_mfma_f32_16x16x32_bf16 v[12:15], v[164:167], v[220:223], v[12:15]
	v_mfma_f32_16x16x32_bf16 v[12:15], v[160:163], v[216:219], v[12:15]
	v_mfma_f32_16x16x32_bf16 v[4:7], v[168:171], v[216:219], v[4:7]
	v_mfma_f32_16x16x32_bf16 v[4:7], v[172:175], v[220:223], v[4:7]
	v_mfma_f32_16x16x32_bf16 v[20:23], v[172:175], v[212:215], v[20:23]
	v_mfma_f32_16x16x32_bf16 v[20:23], v[168:171], v[208:211], v[20:23]
	v_mfma_f32_16x16x32_bf16 v[36:39], v[168:171], v[200:203], v[36:39]
	v_mfma_f32_16x16x32_bf16 v[36:39], v[172:175], v[204:207], v[36:39]
	v_mfma_f32_16x16x32_bf16 v[52:55], v[172:175], v[196:199], v[52:55]
	v_mfma_f32_16x16x32_bf16 v[52:55], v[168:171], v[192:195], v[52:55]
	s_setprio 0
	s_setprio 1
	v_mfma_f32_16x16x32_bf16 v[48:51], v[184:187], v[192:195], v[48:51]
	v_mfma_f32_16x16x32_bf16 v[48:51], v[188:191], v[196:199], v[48:51]
	v_mfma_f32_16x16x32_bf16 v[32:35], v[188:191], v[204:207], v[32:35]
	v_mfma_f32_16x16x32_bf16 v[32:35], v[184:187], v[200:203], v[32:35]
	v_mfma_f32_16x16x32_bf16 v[16:19], v[184:187], v[208:211], v[16:19]
	v_mfma_f32_16x16x32_bf16 v[16:19], v[188:191], v[212:215], v[16:19]
	v_mfma_f32_16x16x32_bf16 v[0:3], v[188:191], v[220:223], v[0:3]
	v_mfma_f32_16x16x32_bf16 v[0:3], v[184:187], v[216:219], v[0:3]
	v_mfma_f32_16x16x32_bf16 v[8:11], v[176:179], v[216:219], v[8:11]
	v_mfma_f32_16x16x32_bf16 v[8:11], v[180:183], v[220:223], v[8:11]
	v_mfma_f32_16x16x32_bf16 v[24:27], v[180:183], v[212:215], v[24:27]
	v_mfma_f32_16x16x32_bf16 v[24:27], v[176:179], v[208:211], v[24:27]
	v_mfma_f32_16x16x32_bf16 v[40:43], v[176:179], v[200:203], v[40:43]
	v_mfma_f32_16x16x32_bf16 v[40:43], v[180:183], v[204:207], v[40:43]
	v_mfma_f32_16x16x32_bf16 v[56:59], v[180:183], v[196:199], v[56:59]
	v_mfma_f32_16x16x32_bf16 v[56:59], v[176:179], v[192:195], v[56:59]
	s_barrier
	s_setprio 0
	s_add_i32 s70, s70, 2
	s_add_u32 s68, s68, 0x100
	s_addc_u32 s69, s69, 0
	s_add_u32 s30, s30, 0x100
	s_addc_u32 s31, s31, 0
	s_cmp_gt_u32 s70, 13
	s_cbranch_scc1 .LBB0_1100

.Llast_10:
	v_add_u32_e32 v153, s61, v147
	ds_read_b128 v[160:163], v153
	v_xor_b32_e32 v253, 64, v153
	ds_read_b128 v[164:167], v253
	ds_read_b128 v[168:171], v153 offset:2048
	ds_read_b128 v[172:175], v253 offset:2048
	v_add_u32_e32 v153, s62, v147
	ds_read_b128 v[176:179], v153
	v_xor_b32_e32 v253, 64, v153
	ds_read_b128 v[180:183], v253
	ds_read_b128 v[184:187], v153 offset:2048
	ds_read_b128 v[188:191], v253 offset:2048
	s_add_u32 s46, s30, 0xfffc0080
	s_addc_u32 s47, s31, -1
	s_and_b64 s[44:45], s[44:45], exec
	s_cselect_b32 s47, s25, s47
	s_cselect_b32 s46, s65, s46
	s_cselect_b32 s45, s66, s69
	s_cselect_b32 s44, s67, s68
	v_lshl_add_u64 v[154:155], s[30:31], 0, v[138:139]
	s_add_i32 m0, s52, 0xc000
	ds_read_b128 v[192:195], v150
	v_xor_b32_e32 v253, 64, v150
	ds_read_b128 v[196:199], v253
	ds_read_b128 v[200:203], v150 offset:2048
	ds_read_b128 v[204:207], v253 offset:2048
	ds_read_b128 v[208:211], v150 offset:4096
	ds_read_b128 v[212:215], v253 offset:4096
	ds_read_b128 v[216:219], v150 offset:6144
	ds_read_b128 v[220:223], v253 offset:6144
	global_load_lds_dwordx4 v[154:155], off
	v_lshl_add_u64 v[154:155], s[30:31], 0, v[136:137]
	s_add_i32 m0, s52, 0xe000
	s_nop 0
	global_load_lds_dwordx4 v[154:155], off
	s_waitcnt vmcnt(8)
	s_waitcnt lgkmcnt(0)
	s_setprio 1
	s_barrier
	v_mfma_f32_16x16x32_bf16 v[124:127], v[160:163], v[192:195], v[124:127]
	v_mfma_f32_16x16x32_bf16 v[124:127], v[164:167], v[196:199], v[124:127]
	v_mfma_f32_16x16x32_bf16 v[108:111], v[164:167], v[204:207], v[108:111]
	v_mfma_f32_16x16x32_bf16 v[108:111], v[160:163], v[200:203], v[108:111]
	v_mfma_f32_16x16x32_bf16 v[92:95], v[160:163], v[208:211], v[92:95]
	v_mfma_f32_16x16x32_bf16 v[92:95], v[164:167], v[212:215], v[92:95]
	v_mfma_f32_16x16x32_bf16 v[76:79], v[164:167], v[220:223], v[76:79]
	v_mfma_f32_16x16x32_bf16 v[76:79], v[160:163], v[216:219], v[76:79]
	v_mfma_f32_16x16x32_bf16 v[68:71], v[168:171], v[216:219], v[68:71]
	v_mfma_f32_16x16x32_bf16 v[68:71], v[172:175], v[220:223], v[68:71]
	v_mfma_f32_16x16x32_bf16 v[84:87], v[172:175], v[212:215], v[84:87]
	v_mfma_f32_16x16x32_bf16 v[84:87], v[168:171], v[208:211], v[84:87]
	v_mfma_f32_16x16x32_bf16 v[100:103], v[168:171], v[200:203], v[100:103]
	v_mfma_f32_16x16x32_bf16 v[100:103], v[172:175], v[204:207], v[100:103]
	v_mfma_f32_16x16x32_bf16 v[116:119], v[172:175], v[196:199], v[116:119]
	v_mfma_f32_16x16x32_bf16 v[116:119], v[168:171], v[192:195], v[116:119]
	s_setprio 0
	s_setprio 1
	v_mfma_f32_16x16x32_bf16 v[112:115], v[184:187], v[192:195], v[112:115]
	v_mfma_f32_16x16x32_bf16 v[112:115], v[188:191], v[196:199], v[112:115]
	v_mfma_f32_16x16x32_bf16 v[96:99], v[188:191], v[204:207], v[96:99]
	v_mfma_f32_16x16x32_bf16 v[96:99], v[184:187], v[200:203], v[96:99]
	v_mfma_f32_16x16x32_bf16 v[80:83], v[184:187], v[208:211], v[80:83]
	v_mfma_f32_16x16x32_bf16 v[80:83], v[188:191], v[212:215], v[80:83]
	v_mfma_f32_16x16x32_bf16 v[64:67], v[188:191], v[220:223], v[64:67]
	v_mfma_f32_16x16x32_bf16 v[64:67], v[184:187], v[216:219], v[64:67]
	v_mfma_f32_16x16x32_bf16 v[72:75], v[176:179], v[216:219], v[72:75]
	v_mfma_f32_16x16x32_bf16 v[72:75], v[180:183], v[220:223], v[72:75]
	v_mfma_f32_16x16x32_bf16 v[88:91], v[180:183], v[212:215], v[88:91]
	v_mfma_f32_16x16x32_bf16 v[88:91], v[176:179], v[208:211], v[88:91]
	v_mfma_f32_16x16x32_bf16 v[104:107], v[176:179], v[200:203], v[104:107]
	v_mfma_f32_16x16x32_bf16 v[104:107], v[180:183], v[204:207], v[104:107]
	v_mfma_f32_16x16x32_bf16 v[120:123], v[180:183], v[196:199], v[120:123]
	v_mfma_f32_16x16x32_bf16 v[120:123], v[176:179], v[192:195], v[120:123]
	s_barrier
	s_setprio 0
	s_add_i32 s71, s61, s49
	v_lshl_add_u64 v[154:155], s[44:45], 0, v[132:133]
	s_mov_b32 m0, s71
	ds_read_b128 v[192:195], v150 offset:16384
	v_xor_b32_e32 v253, 64, v150
	ds_read_b128 v[196:199], v253 offset:16384
	ds_read_b128 v[200:203], v150 offset:18432
	ds_read_b128 v[204:207], v253 offset:18432
	ds_read_b128 v[208:211], v150 offset:20480
	ds_read_b128 v[212:215], v253 offset:20480
	ds_read_b128 v[216:219], v150 offset:22528
	ds_read_b128 v[220:223], v253 offset:22528
	global_load_lds_dwordx4 v[154:155], off
	s_add_i32 m0, s71, 0x2000
	s_add_u32 s72, s44, 0x40000
	v_lshl_add_u64 v[224:225], s[44:45], 0, v[128:129]
	s_addc_u32 s73, s45, 0
	s_add_i32 s71, s62, s49
	global_load_lds_dwordx4 v[224:225], off
	v_lshl_add_u64 v[226:227], s[72:73], 0, v[132:133]
	s_mov_b32 m0, s71
	v_lshl_add_u64 v[228:229], s[46:47], 0, v[130:131]
	global_load_lds_dwordx4 v[226:227], off
	v_lshl_add_u64 v[226:227], s[72:73], 0, v[128:129]
	s_add_i32 m0, s71, 0x2000
	s_nop 0
	global_load_lds_dwordx4 v[226:227], off
	v_lshl_add_u64 v[226:227], s[46:47], 0, v[134:135]
	s_mov_b32 m0, s52
	s_nop 0
	global_load_lds_dwordx4 v[226:227], off
	s_mov_b32 m0, s53
	s_nop 0
	global_load_lds_dwordx4 v[228:229], off
	s_waitcnt vmcnt(8)
	s_waitcnt lgkmcnt(0)
	s_setprio 1
	s_barrier
	v_mfma_f32_16x16x32_bf16 v[60:63], v[160:163], v[192:195], v[60:63]
	v_mfma_f32_16x16x32_bf16 v[60:63], v[164:167], v[196:199], v[60:63]
	v_mfma_f32_16x16x32_bf16 v[44:47], v[164:167], v[204:207], v[44:47]
	v_mfma_f32_16x16x32_bf16 v[44:47], v[160:163], v[200:203], v[44:47]
	v_mfma_f32_16x16x32_bf16 v[28:31], v[160:163], v[208:211], v[28:31]
	v_mfma_f32_16x16x32_bf16 v[28:31], v[164:167], v[212:215], v[28:31]
	v_mfma_f32_16x16x32_bf16 v[12:15], v[164:167], v[220:223], v[12:15]
	v_mfma_f32_16x16x32_bf16 v[12:15], v[160:163], v[216:219], v[12:15]
	v_mfma_f32_16x16x32_bf16 v[4:7], v[168:171], v[216:219], v[4:7]
	v_mfma_f32_16x16x32_bf16 v[4:7], v[172:175], v[220:223], v[4:7]
	v_mfma_f32_16x16x32_bf16 v[20:23], v[172:175], v[212:215], v[20:23]
	v_mfma_f32_16x16x32_bf16 v[20:23], v[168:171], v[208:211], v[20:23]
	v_mfma_f32_16x16x32_bf16 v[36:39], v[168:171], v[200:203], v[36:39]
	v_mfma_f32_16x16x32_bf16 v[36:39], v[172:175], v[204:207], v[36:39]
	v_mfma_f32_16x16x32_bf16 v[52:55], v[172:175], v[196:199], v[52:55]
	v_mfma_f32_16x16x32_bf16 v[52:55], v[168:171], v[192:195], v[52:55]
	s_setprio 0
	s_setprio 1
	v_mfma_f32_16x16x32_bf16 v[48:51], v[184:187], v[192:195], v[48:51]
	v_mfma_f32_16x16x32_bf16 v[48:51], v[188:191], v[196:199], v[48:51]
	v_mfma_f32_16x16x32_bf16 v[32:35], v[188:191], v[204:207], v[32:35]
	v_mfma_f32_16x16x32_bf16 v[32:35], v[184:187], v[200:203], v[32:35]
	v_mfma_f32_16x16x32_bf16 v[16:19], v[184:187], v[208:211], v[16:19]
	v_mfma_f32_16x16x32_bf16 v[16:19], v[188:191], v[212:215], v[16:19]
	v_mfma_f32_16x16x32_bf16 v[0:3], v[188:191], v[220:223], v[0:3]
	v_mfma_f32_16x16x32_bf16 v[0:3], v[184:187], v[216:219], v[0:3]
	v_mfma_f32_16x16x32_bf16 v[8:11], v[176:179], v[216:219], v[8:11]
	v_mfma_f32_16x16x32_bf16 v[8:11], v[180:183], v[220:223], v[8:11]
	v_mfma_f32_16x16x32_bf16 v[24:27], v[180:183], v[212:215], v[24:27]
	v_mfma_f32_16x16x32_bf16 v[24:27], v[176:179], v[208:211], v[24:27]
	v_mfma_f32_16x16x32_bf16 v[40:43], v[176:179], v[200:203], v[40:43]
	v_mfma_f32_16x16x32_bf16 v[40:43], v[180:183], v[204:207], v[40:43]
	v_mfma_f32_16x16x32_bf16 v[56:59], v[180:183], v[196:199], v[56:59]
	v_mfma_f32_16x16x32_bf16 v[56:59], v[176:179], v[192:195], v[56:59]
	s_barrier
	s_setprio 0
	s_add_i32 s71, 0, 0x18000
	v_add_u32_e32 v153, s71, v147
	s_add_i32 s72, 0, 0x1c000
	ds_read_b128 v[160:163], v153
	v_xor_b32_e32 v253, 64, v153
	ds_read_b128 v[164:167], v253
	ds_read_b128 v[168:171], v153 offset:2048
	ds_read_b128 v[172:175], v253 offset:2048
	v_add_u32_e32 v153, s72, v147
	ds_read_b128 v[176:179], v153
	v_xor_b32_e32 v253, 64, v153
	ds_read_b128 v[180:183], v253
	ds_read_b128 v[184:187], v153 offset:2048
	ds_read_b128 v[188:191], v253 offset:2048
	s_add_u32 s46, s46, 0x40000
	s_addc_u32 s47, s47, 0
	s_mov_b32 m0, s54
	v_lshl_add_u64 v[230:231], s[46:47], 0, v[134:135]
	ds_read_b128 v[192:195], v150 offset:32768
	v_xor_b32_e32 v253, 64, v150
	ds_read_b128 v[196:199], v253 offset:32768
	ds_read_b128 v[200:203], v150 offset:34816
	ds_read_b128 v[204:207], v253 offset:34816
	ds_read_b128 v[208:211], v150 offset:36864
	ds_read_b128 v[212:215], v253 offset:36864
	ds_read_b128 v[216:219], v150 offset:38912
	ds_read_b128 v[220:223], v253 offset:38912
	global_load_lds_dwordx4 v[230:231], off
	v_lshl_add_u64 v[230:231], s[46:47], 0, v[130:131]
	s_mov_b32 m0, s55
	s_nop 0
	global_load_lds_dwordx4 v[230:231], off
	s_waitcnt vmcnt(8)
	s_waitcnt lgkmcnt(0)
	s_setprio 1
	s_barrier
	v_mfma_f32_16x16x32_bf16 v[124:127], v[160:163], v[192:195], v[124:127]
	v_mfma_f32_16x16x32_bf16 v[124:127], v[164:167], v[196:199], v[124:127]
	v_mfma_f32_16x16x32_bf16 v[108:111], v[164:167], v[204:207], v[108:111]
	v_mfma_f32_16x16x32_bf16 v[108:111], v[160:163], v[200:203], v[108:111]
	v_mfma_f32_16x16x32_bf16 v[92:95], v[160:163], v[208:211], v[92:95]
	v_mfma_f32_16x16x32_bf16 v[92:95], v[164:167], v[212:215], v[92:95]
	v_mfma_f32_16x16x32_bf16 v[76:79], v[164:167], v[220:223], v[76:79]
	v_mfma_f32_16x16x32_bf16 v[76:79], v[160:163], v[216:219], v[76:79]
	v_mfma_f32_16x16x32_bf16 v[68:71], v[168:171], v[216:219], v[68:71]
	v_mfma_f32_16x16x32_bf16 v[68:71], v[172:175], v[220:223], v[68:71]
	v_mfma_f32_16x16x32_bf16 v[84:87], v[172:175], v[212:215], v[84:87]
	v_mfma_f32_16x16x32_bf16 v[84:87], v[168:171], v[208:211], v[84:87]
	v_mfma_f32_16x16x32_bf16 v[100:103], v[168:171], v[200:203], v[100:103]
	v_mfma_f32_16x16x32_bf16 v[100:103], v[172:175], v[204:207], v[100:103]
	v_mfma_f32_16x16x32_bf16 v[116:119], v[172:175], v[196:199], v[116:119]
	v_mfma_f32_16x16x32_bf16 v[116:119], v[168:171], v[192:195], v[116:119]
	s_setprio 0
	s_setprio 1
	v_mfma_f32_16x16x32_bf16 v[112:115], v[184:187], v[192:195], v[112:115]
	v_mfma_f32_16x16x32_bf16 v[112:115], v[188:191], v[196:199], v[112:115]
	v_mfma_f32_16x16x32_bf16 v[96:99], v[188:191], v[204:207], v[96:99]
	v_mfma_f32_16x16x32_bf16 v[96:99], v[184:187], v[200:203], v[96:99]
	v_mfma_f32_16x16x32_bf16 v[80:83], v[184:187], v[208:211], v[80:83]
	v_mfma_f32_16x16x32_bf16 v[80:83], v[188:191], v[212:215], v[80:83]
	v_mfma_f32_16x16x32_bf16 v[64:67], v[188:191], v[220:223], v[64:67]
	v_mfma_f32_16x16x32_bf16 v[64:67], v[184:187], v[216:219], v[64:67]
	v_mfma_f32_16x16x32_bf16 v[72:75], v[176:179], v[216:219], v[72:75]
	v_mfma_f32_16x16x32_bf16 v[72:75], v[180:183], v[220:223], v[72:75]
	v_mfma_f32_16x16x32_bf16 v[88:91], v[180:183], v[212:215], v[88:91]
	v_mfma_f32_16x16x32_bf16 v[88:91], v[176:179], v[208:211], v[88:91]
	v_mfma_f32_16x16x32_bf16 v[104:107], v[176:179], v[200:203], v[104:107]
	v_mfma_f32_16x16x32_bf16 v[104:107], v[180:183], v[204:207], v[104:107]
	v_mfma_f32_16x16x32_bf16 v[120:123], v[180:183], v[196:199], v[120:123]
	v_mfma_f32_16x16x32_bf16 v[120:123], v[176:179], v[192:195], v[120:123]
	s_barrier
	s_setprio 0
	v_add_u32_e32 v234, 0x21000, v151
	ds_read_b128 v[236:239], v234
	ds_read_b128 v[240:243], v234 offset:256
	ds_read_b128 v[244:247], v234 offset:512
	ds_read_b128 v[248:251], v234 offset:768
	v_add_u32_e32 v235, s23, v146
	v_mul_u32_u24_e32 v235, 0x1600, v235
	v_lshl_or_b32 v234, s64, 7, v149
	v_lshl_add_u32 v235, v234, 1, v235
	s_add_i32 s46, s71, s49
	v_lshl_add_u64 v[154:155], v[154:155], 0, s[14:15]
	s_mov_b32 m0, s46
	ds_read_b128 v[192:195], v150 offset:49152
	v_xor_b32_e32 v253, 64, v150
	ds_read_b128 v[196:199], v253 offset:49152
	ds_read_b128 v[200:203], v150 offset:51200
	ds_read_b128 v[204:207], v253 offset:51200
	ds_read_b128 v[208:211], v150 offset:53248
	ds_read_b128 v[212:215], v253 offset:53248
	ds_read_b128 v[216:219], v150 offset:55296
	ds_read_b128 v[220:223], v253 offset:55296
	global_load_lds_dwordx4 v[154:155], off
	s_add_i32 m0, s46, 0x2000
	s_add_u32 s44, s44, 0x40080
	v_lshl_add_u64 v[154:155], v[224:225], 0, s[14:15]
	s_addc_u32 s45, s45, 0
	s_add_i32 s46, s72, s49
	global_load_lds_dwordx4 v[154:155], off
	v_lshl_add_u64 v[154:155], s[44:45], 0, v[132:133]
	s_mov_b32 m0, s46
	s_nop 0
	global_load_lds_dwordx4 v[154:155], off
	v_lshl_add_u64 v[154:155], s[44:45], 0, v[128:129]
	s_add_i32 m0, s46, 0x2000
	s_nop 0
	global_load_lds_dwordx4 v[154:155], off
	v_lshl_add_u64 v[154:155], v[226:227], 0, s[14:15]
	s_mov_b32 m0, s57
	s_nop 0
	global_load_lds_dwordx4 v[154:155], off
	v_lshl_add_u64 v[154:155], v[228:229], 0, s[14:15]
	s_mov_b32 m0, s58
	s_nop 0
	global_load_lds_dwordx4 v[154:155], off
	s_waitcnt lgkmcnt(8)
	v_add_f32_e32 v236, v236, v237
	v_add_f32_e32 v238, v238, v239
	v_add_f32_e32 v240, v240, v241
	v_add_f32_e32 v242, v242, v243
	v_add_f32_e32 v244, v244, v245
	v_add_f32_e32 v246, v246, v247
	v_add_f32_e32 v248, v248, v249
	v_add_f32_e32 v250, v250, v251
	v_add_f32_e32 v236, v236, v238
	v_add_f32_e32 v240, v240, v242
	v_add_f32_e32 v244, v244, v246
	v_add_f32_e32 v248, v248, v250
	v_fmamk_f32 v236, v236, 0x3a800000, v152
	v_fmamk_f32 v240, v240, 0x3a800000, v152
	v_fmamk_f32 v244, v244, 0x3a800000, v152
	v_fmamk_f32 v248, v248, 0x3a800000, v152
	v_rsq_f32_e32 v236, v236
	v_rsq_f32_e32 v240, v240
	v_rsq_f32_e32 v244, v244
	v_rsq_f32_e32 v248, v248
	v_mul_f32_e32 v252, 0xbfb8aa3b, v236
	v_mul_f32_e32 v254, v236, v236
	v_rcp_f32_e32 v254, v254
	v_pk_mul_f32 v[120:121], v[124:125], v[120:121]
	v_pk_mul_f32 v[122:123], v[126:127], v[122:123]
	v_pk_mul_f32 v[112:113], v[116:117], v[112:113]
	v_pk_mul_f32 v[114:115], v[118:119], v[114:115]
	v_pk_mul_f32 v[124:125], v[124:125], v[252:253] op_sel_hi:[1,0]
	v_pk_mul_f32 v[126:127], v[126:127], v[252:253] op_sel_hi:[1,0]
	v_pk_mul_f32 v[116:117], v[116:117], v[252:253] op_sel_hi:[1,0]
	v_pk_mul_f32 v[118:119], v[118:119], v[252:253] op_sel_hi:[1,0]
	v_exp_f32_e32 v124, v124
	v_exp_f32_e32 v125, v125
	v_exp_f32_e32 v126, v126
	v_exp_f32_e32 v127, v127
	v_exp_f32_e32 v116, v116
	v_exp_f32_e32 v117, v117
	v_exp_f32_e32 v118, v118
	v_exp_f32_e32 v119, v119
	v_pk_fma_f32 v[124:125], v[124:125], v[254:255], v[254:255] op_sel_hi:[1,0,0]
	v_pk_fma_f32 v[126:127], v[126:127], v[254:255], v[254:255] op_sel_hi:[1,0,0]
	v_pk_fma_f32 v[116:117], v[116:117], v[254:255], v[254:255] op_sel_hi:[1,0,0]
	v_pk_fma_f32 v[118:119], v[118:119], v[254:255], v[254:255] op_sel_hi:[1,0,0]
	v_rcp_f32_e32 v124, v124
	v_rcp_f32_e32 v125, v125
	v_rcp_f32_e32 v126, v126
	v_rcp_f32_e32 v127, v127
	v_rcp_f32_e32 v116, v116
	v_rcp_f32_e32 v117, v117
	v_rcp_f32_e32 v118, v118
	v_rcp_f32_e32 v119, v119
	v_pk_mul_f32 v[120:121], v[120:121], v[124:125]
	v_pk_mul_f32 v[122:123], v[122:123], v[126:127]
	v_pk_mul_f32 v[112:113], v[112:113], v[116:117]
	v_pk_mul_f32 v[114:115], v[114:115], v[118:119]
	v_cvt_pk_bf16_f32 v120, v120, v121
	v_cvt_pk_bf16_f32 v121, v122, v123
	v_cvt_pk_bf16_f32 v122, v112, v113
	v_cvt_pk_bf16_f32 v123, v114, v115
	global_store_dwordx4 v235, v[120:123], s[10:11]
	v_add_u32_e32 v234, 0x16000, v235
	v_mul_f32_e32 v252, 0xbfb8aa3b, v240
	v_mul_f32_e32 v254, v240, v240
	v_rcp_f32_e32 v254, v254
	v_pk_mul_f32 v[104:105], v[108:109], v[104:105]
	v_pk_mul_f32 v[106:107], v[110:111], v[106:107]
	v_pk_mul_f32 v[96:97], v[100:101], v[96:97]
	v_pk_mul_f32 v[98:99], v[102:103], v[98:99]
	v_pk_mul_f32 v[108:109], v[108:109], v[252:253] op_sel_hi:[1,0]
	v_pk_mul_f32 v[110:111], v[110:111], v[252:253] op_sel_hi:[1,0]
	v_pk_mul_f32 v[100:101], v[100:101], v[252:253] op_sel_hi:[1,0]
	v_pk_mul_f32 v[102:103], v[102:103], v[252:253] op_sel_hi:[1,0]
	v_exp_f32_e32 v108, v108
	v_exp_f32_e32 v109, v109
	v_exp_f32_e32 v110, v110
	v_exp_f32_e32 v111, v111
	v_exp_f32_e32 v100, v100
	v_exp_f32_e32 v101, v101
	v_exp_f32_e32 v102, v102
	v_exp_f32_e32 v103, v103
	v_pk_fma_f32 v[108:109], v[108:109], v[254:255], v[254:255] op_sel_hi:[1,0,0]
	v_pk_fma_f32 v[110:111], v[110:111], v[254:255], v[254:255] op_sel_hi:[1,0,0]
	v_pk_fma_f32 v[100:101], v[100:101], v[254:255], v[254:255] op_sel_hi:[1,0,0]
	v_pk_fma_f32 v[102:103], v[102:103], v[254:255], v[254:255] op_sel_hi:[1,0,0]
	v_rcp_f32_e32 v108, v108
	v_rcp_f32_e32 v109, v109
	v_rcp_f32_e32 v110, v110
	v_rcp_f32_e32 v111, v111
	v_rcp_f32_e32 v100, v100
	v_rcp_f32_e32 v101, v101
	v_rcp_f32_e32 v102, v102
	v_rcp_f32_e32 v103, v103
	v_pk_mul_f32 v[104:105], v[104:105], v[108:109]
	v_pk_mul_f32 v[106:107], v[106:107], v[110:111]
	v_pk_mul_f32 v[96:97], v[96:97], v[100:101]
	v_pk_mul_f32 v[98:99], v[98:99], v[102:103]
	v_cvt_pk_bf16_f32 v104, v104, v105
	v_cvt_pk_bf16_f32 v105, v106, v107
	v_cvt_pk_bf16_f32 v106, v96, v97
	v_cvt_pk_bf16_f32 v107, v98, v99
	global_store_dwordx4 v234, v[104:107], s[10:11]
	v_add_u32_e32 v235, 0x16000, v234
	v_mul_f32_e32 v252, 0xbfb8aa3b, v244
	v_mul_f32_e32 v254, v244, v244
	v_rcp_f32_e32 v254, v254
	v_pk_mul_f32 v[88:89], v[92:93], v[88:89]
	v_pk_mul_f32 v[90:91], v[94:95], v[90:91]
	v_pk_mul_f32 v[80:81], v[84:85], v[80:81]
	v_pk_mul_f32 v[82:83], v[86:87], v[82:83]
	v_pk_mul_f32 v[92:93], v[92:93], v[252:253] op_sel_hi:[1,0]
	v_pk_mul_f32 v[94:95], v[94:95], v[252:253] op_sel_hi:[1,0]
	v_pk_mul_f32 v[84:85], v[84:85], v[252:253] op_sel_hi:[1,0]
	v_pk_mul_f32 v[86:87], v[86:87], v[252:253] op_sel_hi:[1,0]
	v_exp_f32_e32 v92, v92
	v_exp_f32_e32 v93, v93
	v_exp_f32_e32 v94, v94
	v_exp_f32_e32 v95, v95
	v_exp_f32_e32 v84, v84
	v_exp_f32_e32 v85, v85
	v_exp_f32_e32 v86, v86
	v_exp_f32_e32 v87, v87
	v_pk_fma_f32 v[92:93], v[92:93], v[254:255], v[254:255] op_sel_hi:[1,0,0]
	v_pk_fma_f32 v[94:95], v[94:95], v[254:255], v[254:255] op_sel_hi:[1,0,0]
	v_pk_fma_f32 v[84:85], v[84:85], v[254:255], v[254:255] op_sel_hi:[1,0,0]
	v_pk_fma_f32 v[86:87], v[86:87], v[254:255], v[254:255] op_sel_hi:[1,0,0]
	v_rcp_f32_e32 v92, v92
	v_rcp_f32_e32 v93, v93
	v_rcp_f32_e32 v94, v94
	v_rcp_f32_e32 v95, v95
	v_rcp_f32_e32 v84, v84
	v_rcp_f32_e32 v85, v85
	v_rcp_f32_e32 v86, v86
	v_rcp_f32_e32 v87, v87
	v_pk_mul_f32 v[88:89], v[88:89], v[92:93]
	v_pk_mul_f32 v[90:91], v[90:91], v[94:95]
	v_pk_mul_f32 v[80:81], v[80:81], v[84:85]
	v_pk_mul_f32 v[82:83], v[82:83], v[86:87]
	v_cvt_pk_bf16_f32 v88, v88, v89
	v_cvt_pk_bf16_f32 v89, v90, v91
	v_cvt_pk_bf16_f32 v90, v80, v81
	v_cvt_pk_bf16_f32 v91, v82, v83
	global_store_dwordx4 v235, v[88:91], s[10:11]
	v_add_u32_e32 v234, 0x16000, v235
	v_mul_f32_e32 v252, 0xbfb8aa3b, v248
	v_mul_f32_e32 v254, v248, v248
	v_rcp_f32_e32 v254, v254
	v_pk_mul_f32 v[72:73], v[76:77], v[72:73]
	v_pk_mul_f32 v[74:75], v[78:79], v[74:75]
	v_pk_mul_f32 v[64:65], v[68:69], v[64:65]
	v_pk_mul_f32 v[66:67], v[70:71], v[66:67]
	v_pk_mul_f32 v[76:77], v[76:77], v[252:253] op_sel_hi:[1,0]
	v_pk_mul_f32 v[78:79], v[78:79], v[252:253] op_sel_hi:[1,0]
	v_pk_mul_f32 v[68:69], v[68:69], v[252:253] op_sel_hi:[1,0]
	v_pk_mul_f32 v[70:71], v[70:71], v[252:253] op_sel_hi:[1,0]
	v_exp_f32_e32 v76, v76
	v_exp_f32_e32 v77, v77
	v_exp_f32_e32 v78, v78
	v_exp_f32_e32 v79, v79
	v_exp_f32_e32 v68, v68
	v_exp_f32_e32 v69, v69
	v_exp_f32_e32 v70, v70
	v_exp_f32_e32 v71, v71
	v_pk_fma_f32 v[76:77], v[76:77], v[254:255], v[254:255] op_sel_hi:[1,0,0]
	v_pk_fma_f32 v[78:79], v[78:79], v[254:255], v[254:255] op_sel_hi:[1,0,0]
	v_pk_fma_f32 v[68:69], v[68:69], v[254:255], v[254:255] op_sel_hi:[1,0,0]
	v_pk_fma_f32 v[70:71], v[70:71], v[254:255], v[254:255] op_sel_hi:[1,0,0]
	v_rcp_f32_e32 v76, v76
	v_rcp_f32_e32 v77, v77
	v_rcp_f32_e32 v78, v78
	v_rcp_f32_e32 v79, v79
	v_rcp_f32_e32 v68, v68
	v_rcp_f32_e32 v69, v69
	v_rcp_f32_e32 v70, v70
	v_rcp_f32_e32 v71, v71
	v_pk_mul_f32 v[72:73], v[72:73], v[76:77]
	v_pk_mul_f32 v[74:75], v[74:75], v[78:79]
	v_pk_mul_f32 v[64:65], v[64:65], v[68:69]
	v_pk_mul_f32 v[66:67], v[66:67], v[70:71]
	v_cvt_pk_bf16_f32 v72, v72, v73
	v_cvt_pk_bf16_f32 v73, v74, v75
	v_cvt_pk_bf16_f32 v74, v64, v65
	v_cvt_pk_bf16_f32 v75, v66, v67
	global_store_dwordx4 v234, v[72:75], s[10:11]
	s_waitcnt vmcnt(12)
	s_waitcnt lgkmcnt(0)
	s_setprio 1
	s_barrier
	v_mfma_f32_16x16x32_bf16 v[60:63], v[160:163], v[192:195], v[60:63]
	v_mfma_f32_16x16x32_bf16 v[60:63], v[164:167], v[196:199], v[60:63]
	v_mfma_f32_16x16x32_bf16 v[44:47], v[164:167], v[204:207], v[44:47]
	v_mfma_f32_16x16x32_bf16 v[44:47], v[160:163], v[200:203], v[44:47]
	v_mfma_f32_16x16x32_bf16 v[28:31], v[160:163], v[208:211], v[28:31]
	v_mfma_f32_16x16x32_bf16 v[28:31], v[164:167], v[212:215], v[28:31]
	v_mfma_f32_16x16x32_bf16 v[12:15], v[164:167], v[220:223], v[12:15]
	v_mfma_f32_16x16x32_bf16 v[12:15], v[160:163], v[216:219], v[12:15]
	v_mfma_f32_16x16x32_bf16 v[4:7], v[168:171], v[216:219], v[4:7]
	v_mfma_f32_16x16x32_bf16 v[4:7], v[172:175], v[220:223], v[4:7]
	v_mfma_f32_16x16x32_bf16 v[20:23], v[172:175], v[212:215], v[20:23]
	v_mfma_f32_16x16x32_bf16 v[20:23], v[168:171], v[208:211], v[20:23]
	v_mfma_f32_16x16x32_bf16 v[36:39], v[168:171], v[200:203], v[36:39]
	v_mfma_f32_16x16x32_bf16 v[36:39], v[172:175], v[204:207], v[36:39]
	v_mfma_f32_16x16x32_bf16 v[52:55], v[172:175], v[196:199], v[52:55]
	v_mfma_f32_16x16x32_bf16 v[52:55], v[168:171], v[192:195], v[52:55]
	s_setprio 0
	s_setprio 1
	v_mfma_f32_16x16x32_bf16 v[48:51], v[184:187], v[192:195], v[48:51]
	v_mfma_f32_16x16x32_bf16 v[48:51], v[188:191], v[196:199], v[48:51]
	v_mfma_f32_16x16x32_bf16 v[32:35], v[188:191], v[204:207], v[32:35]
	v_mfma_f32_16x16x32_bf16 v[32:35], v[184:187], v[200:203], v[32:35]
	v_mfma_f32_16x16x32_bf16 v[16:19], v[184:187], v[208:211], v[16:19]
	v_mfma_f32_16x16x32_bf16 v[16:19], v[188:191], v[212:215], v[16:19]
	v_mfma_f32_16x16x32_bf16 v[0:3], v[188:191], v[220:223], v[0:3]
	v_mfma_f32_16x16x32_bf16 v[0:3], v[184:187], v[216:219], v[0:3]
	v_mfma_f32_16x16x32_bf16 v[8:11], v[176:179], v[216:219], v[8:11]
	v_mfma_f32_16x16x32_bf16 v[8:11], v[180:183], v[220:223], v[8:11]
	v_mfma_f32_16x16x32_bf16 v[24:27], v[180:183], v[212:215], v[24:27]
	v_mfma_f32_16x16x32_bf16 v[24:27], v[176:179], v[208:211], v[24:27]
	v_mfma_f32_16x16x32_bf16 v[40:43], v[176:179], v[200:203], v[40:43]
	v_mfma_f32_16x16x32_bf16 v[40:43], v[180:183], v[204:207], v[40:43]
	v_mfma_f32_16x16x32_bf16 v[56:59], v[180:183], v[196:199], v[56:59]
	v_mfma_f32_16x16x32_bf16 v[56:59], v[176:179], v[192:195], v[56:59]
	s_barrier
	s_setprio 0
	s_add_i32 s70, s70, 2
	s_add_u32 s68, s68, 0x100
	s_addc_u32 s69, s69, 0
	s_add_u32 s30, s30, 0x100
	s_addc_u32 s31, s31, 0

.LBB0_1180:
	s_add_u32 s72, s50, 0x100
	s_addc_u32 s73, s51, 0
	s_mov_b32 s74, -2
	s_waitcnt lgkmcnt(0)
	s_cmp_eq_u32 s63, 1
	s_cbranch_scc1 .Lfa_11
	ds_read_b128 v[128:131], v188
	v_xor_b32_e32 v253, 64, v188
	ds_read_b128 v[132:135], v253
	ds_read_b128 v[136:139], v188 offset:2048
	ds_read_b128 v[140:143], v253 offset:2048
	ds_read_b128 v[144:147], v189
	v_xor_b32_e32 v253, 64, v189
	ds_read_b128 v[148:151], v253
	ds_read_b128 v[172:175], v189 offset:2048
	ds_read_b128 v[176:179], v253 offset:2048
	s_add_u32 s50, s48, 0x100
	s_addc_u32 s51, s49, 0
	s_cmp_eq_u32 s74, 40
	s_cselect_b32 s55, s11, s51
	s_cselect_b32 s54, s10, s50
	s_cselect_b32 s53, s47, s73
	s_cselect_b32 s52, s46, s72
	v_lshl_add_u64 v[220:221], s[48:49], 0, v[166:167]
	s_add_i32 m0, s59, 0xc000
	ds_read_b128 v[180:183], v190
	v_xor_b32_e32 v253, 64, v190
	ds_read_b128 v[192:195], v253
	ds_read_b128 v[196:199], v190 offset:2048
	ds_read_b128 v[200:203], v253 offset:2048
	ds_read_b128 v[204:207], v190 offset:4096
	ds_read_b128 v[208:211], v253 offset:4096
	ds_read_b128 v[212:215], v190 offset:6144
	ds_read_b128 v[216:219], v253 offset:6144
	global_load_lds_dwordx4 v[220:221], off
	v_lshl_add_u64 v[220:221], s[48:49], 0, v[164:165]
	s_add_i32 m0, s59, 0xe000
	s_nop 0
	global_load_lds_dwordx4 v[220:221], off
	s_waitcnt vmcnt(24)
	s_waitcnt lgkmcnt(0)
	s_setprio 1
	s_barrier
	v_mfma_f32_16x16x32_bf16 v[124:127], v[128:131], v[180:183], 0
	v_mfma_f32_16x16x32_bf16 v[120:123], v[136:139], v[180:183], 0
	v_mfma_f32_16x16x32_bf16 v[108:111], v[128:131], v[196:199], 0
	v_mfma_f32_16x16x32_bf16 v[104:107], v[136:139], v[196:199], 0
	v_mfma_f32_16x16x32_bf16 v[92:95], v[128:131], v[204:207], 0
	v_mfma_f32_16x16x32_bf16 v[88:91], v[136:139], v[204:207], 0
	v_mfma_f32_16x16x32_bf16 v[76:79], v[128:131], v[212:215], 0
	v_mfma_f32_16x16x32_bf16 v[72:75], v[136:139], v[212:215], 0
	v_mfma_f32_16x16x32_bf16 v[124:127], v[132:135], v[192:195], v[124:127]
	v_mfma_f32_16x16x32_bf16 v[120:123], v[140:143], v[192:195], v[120:123]
	v_mfma_f32_16x16x32_bf16 v[108:111], v[132:135], v[200:203], v[108:111]
	v_mfma_f32_16x16x32_bf16 v[104:107], v[140:143], v[200:203], v[104:107]
	v_mfma_f32_16x16x32_bf16 v[92:95], v[132:135], v[208:211], v[92:95]
	v_mfma_f32_16x16x32_bf16 v[88:91], v[140:143], v[208:211], v[88:91]
	v_mfma_f32_16x16x32_bf16 v[76:79], v[132:135], v[216:219], v[76:79]
	v_mfma_f32_16x16x32_bf16 v[72:75], v[140:143], v[216:219], v[72:75]
	s_setprio 0
	s_setprio 1
	v_mfma_f32_16x16x32_bf16 v[116:119], v[144:147], v[180:183], 0
	v_mfma_f32_16x16x32_bf16 v[112:115], v[172:175], v[180:183], 0
	v_mfma_f32_16x16x32_bf16 v[100:103], v[144:147], v[196:199], 0
	v_mfma_f32_16x16x32_bf16 v[96:99], v[172:175], v[196:199], 0
	v_mfma_f32_16x16x32_bf16 v[84:87], v[144:147], v[204:207], 0
	v_mfma_f32_16x16x32_bf16 v[80:83], v[172:175], v[204:207], 0
	v_mfma_f32_16x16x32_bf16 v[68:71], v[144:147], v[212:215], 0
	v_mfma_f32_16x16x32_bf16 v[64:67], v[172:175], v[212:215], 0
	v_mfma_f32_16x16x32_bf16 v[116:119], v[148:151], v[192:195], v[116:119]
	v_mfma_f32_16x16x32_bf16 v[112:115], v[176:179], v[192:195], v[112:115]
	v_mfma_f32_16x16x32_bf16 v[100:103], v[148:151], v[200:203], v[100:103]
	v_mfma_f32_16x16x32_bf16 v[96:99], v[176:179], v[200:203], v[96:99]
	v_mfma_f32_16x16x32_bf16 v[84:87], v[148:151], v[208:211], v[84:87]
	v_mfma_f32_16x16x32_bf16 v[80:83], v[176:179], v[208:211], v[80:83]
	v_mfma_f32_16x16x32_bf16 v[68:71], v[148:151], v[216:219], v[68:71]
	v_mfma_f32_16x16x32_bf16 v[64:67], v[176:179], v[216:219], v[64:67]
	s_barrier
	s_setprio 0
	s_add_i32 s48, s68, s58
	v_lshl_add_u64 v[220:221], s[52:53], 0, v[154:155]
	s_mov_b32 m0, s48
	ds_read_b128 v[180:183], v190 offset:16384
	v_xor_b32_e32 v253, 64, v190
	ds_read_b128 v[192:195], v253 offset:16384
	ds_read_b128 v[196:199], v190 offset:18432
	ds_read_b128 v[200:203], v253 offset:18432
	ds_read_b128 v[204:207], v190 offset:20480
	ds_read_b128 v[208:211], v253 offset:20480
	ds_read_b128 v[212:215], v190 offset:22528
	ds_read_b128 v[216:219], v253 offset:22528
	global_load_lds_dwordx4 v[220:221], off
	s_add_i32 m0, s48, 0x2000
	s_add_u32 s48, s52, 0xb0000
	v_lshl_add_u64 v[222:223], s[52:53], 0, v[162:163]
	s_addc_u32 s49, s53, 0
	s_add_i32 s75, s69, s58
	global_load_lds_dwordx4 v[222:223], off
	v_lshl_add_u64 v[224:225], s[48:49], 0, v[154:155]
	s_mov_b32 m0, s75
	v_lshl_add_u64 v[226:227], s[54:55], 0, v[160:161]
	global_load_lds_dwordx4 v[224:225], off
	v_lshl_add_u64 v[224:225], s[48:49], 0, v[162:163]
	s_add_i32 m0, s75, 0x2000
	s_nop 0
	global_load_lds_dwordx4 v[224:225], off
	v_lshl_add_u64 v[224:225], s[54:55], 0, v[152:153]
	s_mov_b32 m0, s59
	s_nop 0
	global_load_lds_dwordx4 v[224:225], off
	s_mov_b32 m0, s60
	s_nop 0
	global_load_lds_dwordx4 v[226:227], off
	s_waitcnt vmcnt(24)
	s_waitcnt lgkmcnt(0)
	s_setprio 1
	s_barrier
	v_mfma_f32_16x16x32_bf16 v[60:63], v[128:131], v[180:183], 0
	v_mfma_f32_16x16x32_bf16 v[56:59], v[136:139], v[180:183], 0
	v_mfma_f32_16x16x32_bf16 v[44:47], v[128:131], v[196:199], 0
	v_mfma_f32_16x16x32_bf16 v[40:43], v[136:139], v[196:199], 0
	v_mfma_f32_16x16x32_bf16 v[28:31], v[128:131], v[204:207], 0
	v_mfma_f32_16x16x32_bf16 v[24:27], v[136:139], v[204:207], 0
	v_mfma_f32_16x16x32_bf16 v[12:15], v[128:131], v[212:215], 0
	v_mfma_f32_16x16x32_bf16 v[8:11], v[136:139], v[212:215], 0
	v_mfma_f32_16x16x32_bf16 v[60:63], v[132:135], v[192:195], v[60:63]
	v_mfma_f32_16x16x32_bf16 v[56:59], v[140:143], v[192:195], v[56:59]
	v_mfma_f32_16x16x32_bf16 v[44:47], v[132:135], v[200:203], v[44:47]
	v_mfma_f32_16x16x32_bf16 v[40:43], v[140:143], v[200:203], v[40:43]
	v_mfma_f32_16x16x32_bf16 v[28:31], v[132:135], v[208:211], v[28:31]
	v_mfma_f32_16x16x32_bf16 v[24:27], v[140:143], v[208:211], v[24:27]
	v_mfma_f32_16x16x32_bf16 v[12:15], v[132:135], v[216:219], v[12:15]
	v_mfma_f32_16x16x32_bf16 v[8:11], v[140:143], v[216:219], v[8:11]
	s_setprio 0
	s_setprio 1
	v_mfma_f32_16x16x32_bf16 v[52:55], v[144:147], v[180:183], 0
	v_mfma_f32_16x16x32_bf16 v[48:51], v[172:175], v[180:183], 0
	v_mfma_f32_16x16x32_bf16 v[36:39], v[144:147], v[196:199], 0
	v_mfma_f32_16x16x32_bf16 v[32:35], v[172:175], v[196:199], 0
	v_mfma_f32_16x16x32_bf16 v[20:23], v[144:147], v[204:207], 0
	v_mfma_f32_16x16x32_bf16 v[16:19], v[172:175], v[204:207], 0
	v_mfma_f32_16x16x32_bf16 v[4:7], v[144:147], v[212:215], 0
	v_mfma_f32_16x16x32_bf16 v[0:3], v[172:175], v[212:215], 0
	v_mfma_f32_16x16x32_bf16 v[52:55], v[148:151], v[192:195], v[52:55]
	v_mfma_f32_16x16x32_bf16 v[48:51], v[176:179], v[192:195], v[48:51]
	v_mfma_f32_16x16x32_bf16 v[36:39], v[148:151], v[200:203], v[36:39]
	v_mfma_f32_16x16x32_bf16 v[32:35], v[176:179], v[200:203], v[32:35]
	v_mfma_f32_16x16x32_bf16 v[20:23], v[148:151], v[208:211], v[20:23]
	v_mfma_f32_16x16x32_bf16 v[16:19], v[176:179], v[208:211], v[16:19]
	v_mfma_f32_16x16x32_bf16 v[4:7], v[148:151], v[216:219], v[4:7]
	v_mfma_f32_16x16x32_bf16 v[0:3], v[176:179], v[216:219], v[0:3]
	s_barrier
	s_setprio 0
	s_add_i32 s75, 0, 0x18000
	s_add_i32 s76, 0, 0x1c000
	v_add_u32_e32 v140, s75, v185
	v_add_u32_e32 v176, s76, v185
	ds_read_b128 v[128:131], v140
	v_xor_b32_e32 v253, 64, v140
	ds_read_b128 v[132:135], v253
	ds_read_b128 v[136:139], v140 offset:2048
	ds_read_b128 v[140:143], v253 offset:2048
	ds_read_b128 v[144:147], v176
	v_xor_b32_e32 v253, 64, v176
	ds_read_b128 v[148:151], v253
	ds_read_b128 v[172:175], v176 offset:2048
	ds_read_b128 v[176:179], v253 offset:2048
	s_add_u32 s48, s54, 0xb0000
	s_addc_u32 s49, s55, 0
	s_mov_b32 m0, s61
	v_lshl_add_u64 v[228:229], s[48:49], 0, v[152:153]
	ds_read_b128 v[180:183], v190 offset:32768
	v_xor_b32_e32 v253, 64, v190
	ds_read_b128 v[192:195], v253 offset:32768
	ds_read_b128 v[196:199], v190 offset:34816
	ds_read_b128 v[200:203], v253 offset:34816
	ds_read_b128 v[204:207], v190 offset:36864
	ds_read_b128 v[208:211], v253 offset:36864
	ds_read_b128 v[212:215], v190 offset:38912
	ds_read_b128 v[216:219], v253 offset:38912
	global_load_lds_dwordx4 v[228:229], off
	v_lshl_add_u64 v[228:229], s[48:49], 0, v[160:161]
	s_mov_b32 m0, s62
	s_nop 0
	global_load_lds_dwordx4 v[228:229], off
	s_waitcnt vmcnt(8)
	s_waitcnt lgkmcnt(0)
	s_setprio 1
	s_barrier
	v_mfma_f32_16x16x32_bf16 v[124:127], v[128:131], v[180:183], v[124:127]
	v_mfma_f32_16x16x32_bf16 v[124:127], v[132:135], v[192:195], v[124:127]
	v_mfma_f32_16x16x32_bf16 v[108:111], v[132:135], v[200:203], v[108:111]
	v_mfma_f32_16x16x32_bf16 v[108:111], v[128:131], v[196:199], v[108:111]
	v_mfma_f32_16x16x32_bf16 v[92:95], v[128:131], v[204:207], v[92:95]
	v_mfma_f32_16x16x32_bf16 v[92:95], v[132:135], v[208:211], v[92:95]
	v_mfma_f32_16x16x32_bf16 v[76:79], v[132:135], v[216:219], v[76:79]
	v_mfma_f32_16x16x32_bf16 v[76:79], v[128:131], v[212:215], v[76:79]
	v_mfma_f32_16x16x32_bf16 v[72:75], v[136:139], v[212:215], v[72:75]
	v_mfma_f32_16x16x32_bf16 v[72:75], v[140:143], v[216:219], v[72:75]
	v_mfma_f32_16x16x32_bf16 v[88:91], v[140:143], v[208:211], v[88:91]
	v_mfma_f32_16x16x32_bf16 v[88:91], v[136:139], v[204:207], v[88:91]
	v_mfma_f32_16x16x32_bf16 v[104:107], v[136:139], v[196:199], v[104:107]
	v_mfma_f32_16x16x32_bf16 v[104:107], v[140:143], v[200:203], v[104:107]
	v_mfma_f32_16x16x32_bf16 v[120:123], v[140:143], v[192:195], v[120:123]
	v_mfma_f32_16x16x32_bf16 v[120:123], v[136:139], v[180:183], v[120:123]
	s_setprio 0
	s_setprio 1
	v_mfma_f32_16x16x32_bf16 v[112:115], v[172:175], v[180:183], v[112:115]
	v_mfma_f32_16x16x32_bf16 v[112:115], v[176:179], v[192:195], v[112:115]
	v_mfma_f32_16x16x32_bf16 v[96:99], v[176:179], v[200:203], v[96:99]
	v_mfma_f32_16x16x32_bf16 v[96:99], v[172:175], v[196:199], v[96:99]
	v_mfma_f32_16x16x32_bf16 v[80:83], v[172:175], v[204:207], v[80:83]
	v_mfma_f32_16x16x32_bf16 v[80:83], v[176:179], v[208:211], v[80:83]
	v_mfma_f32_16x16x32_bf16 v[64:67], v[176:179], v[216:219], v[64:67]
	v_mfma_f32_16x16x32_bf16 v[64:67], v[172:175], v[212:215], v[64:67]
	v_mfma_f32_16x16x32_bf16 v[68:71], v[144:147], v[212:215], v[68:71]
	v_mfma_f32_16x16x32_bf16 v[68:71], v[148:151], v[216:219], v[68:71]
	v_mfma_f32_16x16x32_bf16 v[84:87], v[148:151], v[208:211], v[84:87]
	v_mfma_f32_16x16x32_bf16 v[84:87], v[144:147], v[204:207], v[84:87]
	v_mfma_f32_16x16x32_bf16 v[100:103], v[144:147], v[196:199], v[100:103]
	v_mfma_f32_16x16x32_bf16 v[100:103], v[148:151], v[200:203], v[100:103]
	v_mfma_f32_16x16x32_bf16 v[116:119], v[148:151], v[192:195], v[116:119]
	v_mfma_f32_16x16x32_bf16 v[116:119], v[144:147], v[180:183], v[116:119]
	s_barrier
	s_setprio 0
	s_add_i32 s48, s75, s58
	v_lshl_add_u64 v[220:221], v[220:221], 0, s[22:23]
	s_mov_b32 m0, s48
	ds_read_b128 v[180:183], v190 offset:49152
	v_xor_b32_e32 v253, 64, v190
	ds_read_b128 v[192:195], v253 offset:49152
	ds_read_b128 v[196:199], v190 offset:51200
	ds_read_b128 v[200:203], v253 offset:51200
	ds_read_b128 v[204:207], v190 offset:53248
	ds_read_b128 v[208:211], v253 offset:53248
	ds_read_b128 v[212:215], v190 offset:55296
	ds_read_b128 v[216:219], v253 offset:55296
	global_load_lds_dwordx4 v[220:221], off
	s_add_i32 m0, s48, 0x2000
	s_add_u32 s48, s52, 0xb0080
	v_lshl_add_u64 v[220:221], v[222:223], 0, s[22:23]
	s_addc_u32 s49, s53, 0
	s_add_i32 s52, s76, s58
	global_load_lds_dwordx4 v[220:221], off
	v_lshl_add_u64 v[220:221], s[48:49], 0, v[154:155]
	s_mov_b32 m0, s52
	s_nop 0
	global_load_lds_dwordx4 v[220:221], off
	v_lshl_add_u64 v[220:221], s[48:49], 0, v[162:163]
	s_add_i32 m0, s52, 0x2000
	s_nop 0
	global_load_lds_dwordx4 v[220:221], off
	v_lshl_add_u64 v[220:221], v[224:225], 0, s[22:23]
	s_mov_b32 m0, s3
	s_nop 0
	global_load_lds_dwordx4 v[220:221], off
	v_lshl_add_u64 v[220:221], v[226:227], 0, s[22:23]
	s_mov_b32 m0, s64
	s_nop 0
	global_load_lds_dwordx4 v[220:221], off
	s_waitcnt vmcnt(8)
	s_waitcnt lgkmcnt(0)
	s_setprio 1
	s_barrier
	v_mfma_f32_16x16x32_bf16 v[60:63], v[128:131], v[180:183], v[60:63]
	v_mfma_f32_16x16x32_bf16 v[60:63], v[132:135], v[192:195], v[60:63]
	v_mfma_f32_16x16x32_bf16 v[44:47], v[132:135], v[200:203], v[44:47]
	v_mfma_f32_16x16x32_bf16 v[44:47], v[128:131], v[196:199], v[44:47]
	v_mfma_f32_16x16x32_bf16 v[28:31], v[128:131], v[204:207], v[28:31]
	v_mfma_f32_16x16x32_bf16 v[28:31], v[132:135], v[208:211], v[28:31]
	v_mfma_f32_16x16x32_bf16 v[12:15], v[132:135], v[216:219], v[12:15]
	v_mfma_f32_16x16x32_bf16 v[12:15], v[128:131], v[212:215], v[12:15]
	v_mfma_f32_16x16x32_bf16 v[8:11], v[136:139], v[212:215], v[8:11]
	v_mfma_f32_16x16x32_bf16 v[8:11], v[140:143], v[216:219], v[8:11]
	v_mfma_f32_16x16x32_bf16 v[24:27], v[140:143], v[208:211], v[24:27]
	v_mfma_f32_16x16x32_bf16 v[24:27], v[136:139], v[204:207], v[24:27]
	v_mfma_f32_16x16x32_bf16 v[40:43], v[136:139], v[196:199], v[40:43]
	v_mfma_f32_16x16x32_bf16 v[40:43], v[140:143], v[200:203], v[40:43]
	v_mfma_f32_16x16x32_bf16 v[56:59], v[140:143], v[192:195], v[56:59]
	v_mfma_f32_16x16x32_bf16 v[56:59], v[136:139], v[180:183], v[56:59]
	s_setprio 0
	s_setprio 1
	v_mfma_f32_16x16x32_bf16 v[48:51], v[172:175], v[180:183], v[48:51]
	v_mfma_f32_16x16x32_bf16 v[48:51], v[176:179], v[192:195], v[48:51]
	v_mfma_f32_16x16x32_bf16 v[32:35], v[176:179], v[200:203], v[32:35]
	v_mfma_f32_16x16x32_bf16 v[32:35], v[172:175], v[196:199], v[32:35]
	v_mfma_f32_16x16x32_bf16 v[16:19], v[172:175], v[204:207], v[16:19]
	v_mfma_f32_16x16x32_bf16 v[16:19], v[176:179], v[208:211], v[16:19]
	v_mfma_f32_16x16x32_bf16 v[0:3], v[176:179], v[216:219], v[0:3]
	v_mfma_f32_16x16x32_bf16 v[0:3], v[172:175], v[212:215], v[0:3]
	v_mfma_f32_16x16x32_bf16 v[4:7], v[144:147], v[212:215], v[4:7]
	v_mfma_f32_16x16x32_bf16 v[4:7], v[148:151], v[216:219], v[4:7]
	v_mfma_f32_16x16x32_bf16 v[20:23], v[148:151], v[208:211], v[20:23]
	v_mfma_f32_16x16x32_bf16 v[20:23], v[144:147], v[204:207], v[20:23]
	v_mfma_f32_16x16x32_bf16 v[36:39], v[144:147], v[196:199], v[36:39]
	v_mfma_f32_16x16x32_bf16 v[36:39], v[148:151], v[200:203], v[36:39]
	v_mfma_f32_16x16x32_bf16 v[52:55], v[148:151], v[192:195], v[52:55]
	v_mfma_f32_16x16x32_bf16 v[52:55], v[144:147], v[180:183], v[52:55]
	s_barrier
	s_setprio 0
	s_add_i32 s74, s74, 2
	s_add_u32 s72, s72, 0x100
	s_addc_u32 s73, s73, 0
	s_cmp_gt_u32 s74, 41
	s_mov_b64 s[48:49], s[50:51]
	s_branch .LBB0_1181
.Lfa_11:
	ds_read_b128 v[128:131], v188
	v_xor_b32_e32 v253, 64, v188
	ds_read_b128 v[132:135], v253
	ds_read_b128 v[136:139], v188 offset:2048
	ds_read_b128 v[140:143], v253 offset:2048
	ds_read_b128 v[144:147], v189
	v_xor_b32_e32 v253, 64, v189
	ds_read_b128 v[148:151], v253
	ds_read_b128 v[172:175], v189 offset:2048
	ds_read_b128 v[176:179], v253 offset:2048
	s_add_u32 s50, s48, 0x100
	s_addc_u32 s51, s49, 0
	s_cmp_eq_u32 s74, 40
	s_cselect_b32 s55, s11, s51
	s_cselect_b32 s54, s10, s50
	s_cselect_b32 s53, s47, s73
	s_cselect_b32 s52, s46, s72
	v_lshl_add_u64 v[220:221], s[48:49], 0, v[166:167]
	s_add_i32 m0, s59, 0xc000
	ds_read_b128 v[180:183], v190
	v_xor_b32_e32 v253, 64, v190
	ds_read_b128 v[192:195], v253
	ds_read_b128 v[196:199], v190 offset:2048
	ds_read_b128 v[200:203], v253 offset:2048
	ds_read_b128 v[204:207], v190 offset:4096
	ds_read_b128 v[208:211], v253 offset:4096
	ds_read_b128 v[212:215], v190 offset:6144
	ds_read_b128 v[216:219], v253 offset:6144
	global_load_lds_dwordx4 v[220:221], off
	v_lshl_add_u64 v[220:221], s[48:49], 0, v[164:165]
	s_add_i32 m0, s59, 0xe000
	s_nop 0
	global_load_lds_dwordx4 v[220:221], off
	s_waitcnt vmcnt(8)
	s_waitcnt lgkmcnt(0)
	s_setprio 1
	s_barrier
	v_mfma_f32_16x16x32_bf16 v[124:127], v[128:131], v[180:183], 0
	v_mfma_f32_16x16x32_bf16 v[120:123], v[136:139], v[180:183], 0
	v_mfma_f32_16x16x32_bf16 v[108:111], v[128:131], v[196:199], 0
	v_mfma_f32_16x16x32_bf16 v[104:107], v[136:139], v[196:199], 0
	v_mfma_f32_16x16x32_bf16 v[92:95], v[128:131], v[204:207], 0
	v_mfma_f32_16x16x32_bf16 v[88:91], v[136:139], v[204:207], 0
	v_mfma_f32_16x16x32_bf16 v[76:79], v[128:131], v[212:215], 0
	v_mfma_f32_16x16x32_bf16 v[72:75], v[136:139], v[212:215], 0
	v_mfma_f32_16x16x32_bf16 v[124:127], v[132:135], v[192:195], v[124:127]
	v_mfma_f32_16x16x32_bf16 v[120:123], v[140:143], v[192:195], v[120:123]
	v_mfma_f32_16x16x32_bf16 v[108:111], v[132:135], v[200:203], v[108:111]
	v_mfma_f32_16x16x32_bf16 v[104:107], v[140:143], v[200:203], v[104:107]
	v_mfma_f32_16x16x32_bf16 v[92:95], v[132:135], v[208:211], v[92:95]
	v_mfma_f32_16x16x32_bf16 v[88:91], v[140:143], v[208:211], v[88:91]
	v_mfma_f32_16x16x32_bf16 v[76:79], v[132:135], v[216:219], v[76:79]
	v_mfma_f32_16x16x32_bf16 v[72:75], v[140:143], v[216:219], v[72:75]
	s_setprio 0
	s_setprio 1
	v_mfma_f32_16x16x32_bf16 v[116:119], v[144:147], v[180:183], 0
	v_mfma_f32_16x16x32_bf16 v[112:115], v[172:175], v[180:183], 0
	v_mfma_f32_16x16x32_bf16 v[100:103], v[144:147], v[196:199], 0
	v_mfma_f32_16x16x32_bf16 v[96:99], v[172:175], v[196:199], 0
	v_mfma_f32_16x16x32_bf16 v[84:87], v[144:147], v[204:207], 0
	v_mfma_f32_16x16x32_bf16 v[80:83], v[172:175], v[204:207], 0
	v_mfma_f32_16x16x32_bf16 v[68:71], v[144:147], v[212:215], 0
	v_mfma_f32_16x16x32_bf16 v[64:67], v[172:175], v[212:215], 0
	v_mfma_f32_16x16x32_bf16 v[116:119], v[148:151], v[192:195], v[116:119]
	v_mfma_f32_16x16x32_bf16 v[112:115], v[176:179], v[192:195], v[112:115]
	v_mfma_f32_16x16x32_bf16 v[100:103], v[148:151], v[200:203], v[100:103]
	v_mfma_f32_16x16x32_bf16 v[96:99], v[176:179], v[200:203], v[96:99]
	v_mfma_f32_16x16x32_bf16 v[84:87], v[148:151], v[208:211], v[84:87]
	v_mfma_f32_16x16x32_bf16 v[80:83], v[176:179], v[208:211], v[80:83]
	v_mfma_f32_16x16x32_bf16 v[68:71], v[148:151], v[216:219], v[68:71]
	v_mfma_f32_16x16x32_bf16 v[64:67], v[176:179], v[216:219], v[64:67]
	s_barrier
	s_setprio 0
	s_add_i32 s48, s68, s58
	v_lshl_add_u64 v[220:221], s[52:53], 0, v[154:155]
	s_mov_b32 m0, s48
	ds_read_b128 v[180:183], v190 offset:16384
	v_xor_b32_e32 v253, 64, v190
	ds_read_b128 v[192:195], v253 offset:16384
	ds_read_b128 v[196:199], v190 offset:18432
	ds_read_b128 v[200:203], v253 offset:18432
	ds_read_b128 v[204:207], v190 offset:20480
	ds_read_b128 v[208:211], v253 offset:20480
	ds_read_b128 v[212:215], v190 offset:22528
	ds_read_b128 v[216:219], v253 offset:22528
	global_load_lds_dwordx4 v[220:221], off
	s_add_i32 m0, s48, 0x2000
	s_add_u32 s48, s52, 0xb0000
	v_lshl_add_u64 v[222:223], s[52:53], 0, v[162:163]
	s_addc_u32 s49, s53, 0
	s_add_i32 s75, s69, s58
	global_load_lds_dwordx4 v[222:223], off
	v_lshl_add_u64 v[224:225], s[48:49], 0, v[154:155]
	s_mov_b32 m0, s75
	v_lshl_add_u64 v[226:227], s[54:55], 0, v[160:161]
	global_load_lds_dwordx4 v[224:225], off
	v_lshl_add_u64 v[224:225], s[48:49], 0, v[162:163]
	s_add_i32 m0, s75, 0x2000
	s_nop 0
	global_load_lds_dwordx4 v[224:225], off
	v_lshl_add_u64 v[224:225], s[54:55], 0, v[152:153]
	s_mov_b32 m0, s59
	s_nop 0
	global_load_lds_dwordx4 v[224:225], off
	s_mov_b32 m0, s60
	s_nop 0
	global_load_lds_dwordx4 v[226:227], off
	s_waitcnt vmcnt(8)
	s_waitcnt lgkmcnt(0)
	s_setprio 1
	s_barrier
	v_mfma_f32_16x16x32_bf16 v[60:63], v[128:131], v[180:183], 0
	v_mfma_f32_16x16x32_bf16 v[56:59], v[136:139], v[180:183], 0
	v_mfma_f32_16x16x32_bf16 v[44:47], v[128:131], v[196:199], 0
	v_mfma_f32_16x16x32_bf16 v[40:43], v[136:139], v[196:199], 0
	v_mfma_f32_16x16x32_bf16 v[28:31], v[128:131], v[204:207], 0
	v_mfma_f32_16x16x32_bf16 v[24:27], v[136:139], v[204:207], 0
	v_mfma_f32_16x16x32_bf16 v[12:15], v[128:131], v[212:215], 0
	v_mfma_f32_16x16x32_bf16 v[8:11], v[136:139], v[212:215], 0
	v_mfma_f32_16x16x32_bf16 v[60:63], v[132:135], v[192:195], v[60:63]
	v_mfma_f32_16x16x32_bf16 v[56:59], v[140:143], v[192:195], v[56:59]
	v_mfma_f32_16x16x32_bf16 v[44:47], v[132:135], v[200:203], v[44:47]
	v_mfma_f32_16x16x32_bf16 v[40:43], v[140:143], v[200:203], v[40:43]
	v_mfma_f32_16x16x32_bf16 v[28:31], v[132:135], v[208:211], v[28:31]
	v_mfma_f32_16x16x32_bf16 v[24:27], v[140:143], v[208:211], v[24:27]
	v_mfma_f32_16x16x32_bf16 v[12:15], v[132:135], v[216:219], v[12:15]
	v_mfma_f32_16x16x32_bf16 v[8:11], v[140:143], v[216:219], v[8:11]
	s_setprio 0
	s_setprio 1
	v_mfma_f32_16x16x32_bf16 v[52:55], v[144:147], v[180:183], 0
	v_mfma_f32_16x16x32_bf16 v[48:51], v[172:175], v[180:183], 0
	v_mfma_f32_16x16x32_bf16 v[36:39], v[144:147], v[196:199], 0
	v_mfma_f32_16x16x32_bf16 v[32:35], v[172:175], v[196:199], 0
	v_mfma_f32_16x16x32_bf16 v[20:23], v[144:147], v[204:207], 0
	v_mfma_f32_16x16x32_bf16 v[16:19], v[172:175], v[204:207], 0
	v_mfma_f32_16x16x32_bf16 v[4:7], v[144:147], v[212:215], 0
	v_mfma_f32_16x16x32_bf16 v[0:3], v[172:175], v[212:215], 0
	v_mfma_f32_16x16x32_bf16 v[52:55], v[148:151], v[192:195], v[52:55]
	v_mfma_f32_16x16x32_bf16 v[48:51], v[176:179], v[192:195], v[48:51]
	v_mfma_f32_16x16x32_bf16 v[36:39], v[148:151], v[200:203], v[36:39]
	v_mfma_f32_16x16x32_bf16 v[32:35], v[176:179], v[200:203], v[32:35]
	v_mfma_f32_16x16x32_bf16 v[20:23], v[148:151], v[208:211], v[20:23]
	v_mfma_f32_16x16x32_bf16 v[16:19], v[176:179], v[208:211], v[16:19]
	v_mfma_f32_16x16x32_bf16 v[4:7], v[148:151], v[216:219], v[4:7]
	v_mfma_f32_16x16x32_bf16 v[0:3], v[176:179], v[216:219], v[0:3]
	s_barrier
	s_setprio 0
	s_add_i32 s75, 0, 0x18000
	s_add_i32 s76, 0, 0x1c000
	v_add_u32_e32 v140, s75, v185
	v_add_u32_e32 v176, s76, v185
	ds_read_b128 v[128:131], v140
	v_xor_b32_e32 v253, 64, v140
	ds_read_b128 v[132:135], v253
	ds_read_b128 v[136:139], v140 offset:2048
	ds_read_b128 v[140:143], v253 offset:2048
	ds_read_b128 v[144:147], v176
	v_xor_b32_e32 v253, 64, v176
	ds_read_b128 v[148:151], v253
	ds_read_b128 v[172:175], v176 offset:2048
	ds_read_b128 v[176:179], v253 offset:2048
	s_add_u32 s48, s54, 0xb0000
	s_addc_u32 s49, s55, 0
	s_mov_b32 m0, s61
	v_lshl_add_u64 v[228:229], s[48:49], 0, v[152:153]
	ds_read_b128 v[180:183], v190 offset:32768
	v_xor_b32_e32 v253, 64, v190
	ds_read_b128 v[192:195], v253 offset:32768
	ds_read_b128 v[196:199], v190 offset:34816
	ds_read_b128 v[200:203], v253 offset:34816
	ds_read_b128 v[204:207], v190 offset:36864
	ds_read_b128 v[208:211], v253 offset:36864
	ds_read_b128 v[212:215], v190 offset:38912
	ds_read_b128 v[216:219], v253 offset:38912
	global_load_lds_dwordx4 v[228:229], off
	v_lshl_add_u64 v[228:229], s[48:49], 0, v[160:161]
	s_mov_b32 m0, s62
	s_nop 0
	global_load_lds_dwordx4 v[228:229], off
	s_waitcnt vmcnt(8)
	s_waitcnt lgkmcnt(0)
	s_setprio 1
	s_barrier
	v_mfma_f32_16x16x32_bf16 v[124:127], v[128:131], v[180:183], v[124:127]
	v_mfma_f32_16x16x32_bf16 v[124:127], v[132:135], v[192:195], v[124:127]
	v_mfma_f32_16x16x32_bf16 v[108:111], v[132:135], v[200:203], v[108:111]
	v_mfma_f32_16x16x32_bf16 v[108:111], v[128:131], v[196:199], v[108:111]
	v_mfma_f32_16x16x32_bf16 v[92:95], v[128:131], v[204:207], v[92:95]
	v_mfma_f32_16x16x32_bf16 v[92:95], v[132:135], v[208:211], v[92:95]
	v_mfma_f32_16x16x32_bf16 v[76:79], v[132:135], v[216:219], v[76:79]
	v_mfma_f32_16x16x32_bf16 v[76:79], v[128:131], v[212:215], v[76:79]
	v_mfma_f32_16x16x32_bf16 v[72:75], v[136:139], v[212:215], v[72:75]
	v_mfma_f32_16x16x32_bf16 v[72:75], v[140:143], v[216:219], v[72:75]
	v_mfma_f32_16x16x32_bf16 v[88:91], v[140:143], v[208:211], v[88:91]
	v_mfma_f32_16x16x32_bf16 v[88:91], v[136:139], v[204:207], v[88:91]
	v_mfma_f32_16x16x32_bf16 v[104:107], v[136:139], v[196:199], v[104:107]
	v_mfma_f32_16x16x32_bf16 v[104:107], v[140:143], v[200:203], v[104:107]
	v_mfma_f32_16x16x32_bf16 v[120:123], v[140:143], v[192:195], v[120:123]
	v_mfma_f32_16x16x32_bf16 v[120:123], v[136:139], v[180:183], v[120:123]
	s_setprio 0
	s_setprio 1
	v_mfma_f32_16x16x32_bf16 v[112:115], v[172:175], v[180:183], v[112:115]
	v_mfma_f32_16x16x32_bf16 v[112:115], v[176:179], v[192:195], v[112:115]
	v_mfma_f32_16x16x32_bf16 v[96:99], v[176:179], v[200:203], v[96:99]
	v_mfma_f32_16x16x32_bf16 v[96:99], v[172:175], v[196:199], v[96:99]
	v_mfma_f32_16x16x32_bf16 v[80:83], v[172:175], v[204:207], v[80:83]
	v_mfma_f32_16x16x32_bf16 v[80:83], v[176:179], v[208:211], v[80:83]
	v_mfma_f32_16x16x32_bf16 v[64:67], v[176:179], v[216:219], v[64:67]
	v_mfma_f32_16x16x32_bf16 v[64:67], v[172:175], v[212:215], v[64:67]
	v_mfma_f32_16x16x32_bf16 v[68:71], v[144:147], v[212:215], v[68:71]
	v_mfma_f32_16x16x32_bf16 v[68:71], v[148:151], v[216:219], v[68:71]
	v_mfma_f32_16x16x32_bf16 v[84:87], v[148:151], v[208:211], v[84:87]
	v_mfma_f32_16x16x32_bf16 v[84:87], v[144:147], v[204:207], v[84:87]
	v_mfma_f32_16x16x32_bf16 v[100:103], v[144:147], v[196:199], v[100:103]
	v_mfma_f32_16x16x32_bf16 v[100:103], v[148:151], v[200:203], v[100:103]
	v_mfma_f32_16x16x32_bf16 v[116:119], v[148:151], v[192:195], v[116:119]
	v_mfma_f32_16x16x32_bf16 v[116:119], v[144:147], v[180:183], v[116:119]
	s_barrier
	s_setprio 0
	s_add_i32 s48, s75, s58
	v_lshl_add_u64 v[220:221], v[220:221], 0, s[22:23]
	s_mov_b32 m0, s48
	ds_read_b128 v[180:183], v190 offset:49152
	v_xor_b32_e32 v253, 64, v190
	ds_read_b128 v[192:195], v253 offset:49152
	ds_read_b128 v[196:199], v190 offset:51200
	ds_read_b128 v[200:203], v253 offset:51200
	ds_read_b128 v[204:207], v190 offset:53248
	ds_read_b128 v[208:211], v253 offset:53248
	ds_read_b128 v[212:215], v190 offset:55296
	ds_read_b128 v[216:219], v253 offset:55296
	global_load_lds_dwordx4 v[220:221], off
	s_add_i32 m0, s48, 0x2000
	s_add_u32 s48, s52, 0xb0080
	v_lshl_add_u64 v[220:221], v[222:223], 0, s[22:23]
	s_addc_u32 s49, s53, 0
	s_add_i32 s52, s76, s58
	global_load_lds_dwordx4 v[220:221], off
	v_lshl_add_u64 v[220:221], s[48:49], 0, v[154:155]
	s_mov_b32 m0, s52
	s_nop 0
	global_load_lds_dwordx4 v[220:221], off
	v_lshl_add_u64 v[220:221], s[48:49], 0, v[162:163]
	s_add_i32 m0, s52, 0x2000
	s_nop 0
	global_load_lds_dwordx4 v[220:221], off
	v_lshl_add_u64 v[220:221], v[224:225], 0, s[22:23]
	s_mov_b32 m0, s3
	s_nop 0
	global_load_lds_dwordx4 v[220:221], off
	v_lshl_add_u64 v[220:221], v[226:227], 0, s[22:23]
	s_mov_b32 m0, s64
	s_nop 0
	global_load_lds_dwordx4 v[220:221], off
	s_waitcnt vmcnt(8)
	s_waitcnt lgkmcnt(0)
	s_setprio 1
	s_barrier
	v_mfma_f32_16x16x32_bf16 v[60:63], v[128:131], v[180:183], v[60:63]
	v_mfma_f32_16x16x32_bf16 v[60:63], v[132:135], v[192:195], v[60:63]
	v_mfma_f32_16x16x32_bf16 v[44:47], v[132:135], v[200:203], v[44:47]
	v_mfma_f32_16x16x32_bf16 v[44:47], v[128:131], v[196:199], v[44:47]
	v_mfma_f32_16x16x32_bf16 v[28:31], v[128:131], v[204:207], v[28:31]
	v_mfma_f32_16x16x32_bf16 v[28:31], v[132:135], v[208:211], v[28:31]
	v_mfma_f32_16x16x32_bf16 v[12:15], v[132:135], v[216:219], v[12:15]
	v_mfma_f32_16x16x32_bf16 v[12:15], v[128:131], v[212:215], v[12:15]
	v_mfma_f32_16x16x32_bf16 v[8:11], v[136:139], v[212:215], v[8:11]
	v_mfma_f32_16x16x32_bf16 v[8:11], v[140:143], v[216:219], v[8:11]
	v_mfma_f32_16x16x32_bf16 v[24:27], v[140:143], v[208:211], v[24:27]
	v_mfma_f32_16x16x32_bf16 v[24:27], v[136:139], v[204:207], v[24:27]
	v_mfma_f32_16x16x32_bf16 v[40:43], v[136:139], v[196:199], v[40:43]
	v_mfma_f32_16x16x32_bf16 v[40:43], v[140:143], v[200:203], v[40:43]
	v_mfma_f32_16x16x32_bf16 v[56:59], v[140:143], v[192:195], v[56:59]
	v_mfma_f32_16x16x32_bf16 v[56:59], v[136:139], v[180:183], v[56:59]
	s_setprio 0
	s_setprio 1
	v_mfma_f32_16x16x32_bf16 v[48:51], v[172:175], v[180:183], v[48:51]
	v_mfma_f32_16x16x32_bf16 v[48:51], v[176:179], v[192:195], v[48:51]
	v_mfma_f32_16x16x32_bf16 v[32:35], v[176:179], v[200:203], v[32:35]
	v_mfma_f32_16x16x32_bf16 v[32:35], v[172:175], v[196:199], v[32:35]
	v_mfma_f32_16x16x32_bf16 v[16:19], v[172:175], v[204:207], v[16:19]
	v_mfma_f32_16x16x32_bf16 v[16:19], v[176:179], v[208:211], v[16:19]
	v_mfma_f32_16x16x32_bf16 v[0:3], v[176:179], v[216:219], v[0:3]
	v_mfma_f32_16x16x32_bf16 v[0:3], v[172:175], v[212:215], v[0:3]
	v_mfma_f32_16x16x32_bf16 v[4:7], v[144:147], v[212:215], v[4:7]
	v_mfma_f32_16x16x32_bf16 v[4:7], v[148:151], v[216:219], v[4:7]
	v_mfma_f32_16x16x32_bf16 v[20:23], v[148:151], v[208:211], v[20:23]
	v_mfma_f32_16x16x32_bf16 v[20:23], v[144:147], v[204:207], v[20:23]
	v_mfma_f32_16x16x32_bf16 v[36:39], v[144:147], v[196:199], v[36:39]
	v_mfma_f32_16x16x32_bf16 v[36:39], v[148:151], v[200:203], v[36:39]
	v_mfma_f32_16x16x32_bf16 v[52:55], v[148:151], v[192:195], v[52:55]
	v_mfma_f32_16x16x32_bf16 v[52:55], v[144:147], v[180:183], v[52:55]
	s_barrier
	s_setprio 0
	s_add_i32 s74, s74, 2
	s_add_u32 s72, s72, 0x100
	s_addc_u32 s73, s73, 0
	s_cmp_gt_u32 s74, 41
	s_mov_b64 s[48:49], s[50:51]
.LBB0_1181:
	ds_read_b128 v[128:131], v188
	v_xor_b32_e32 v253, 64, v188
	ds_read_b128 v[132:135], v253
	ds_read_b128 v[136:139], v188 offset:2048
	ds_read_b128 v[140:143], v253 offset:2048
	ds_read_b128 v[144:147], v189
	v_xor_b32_e32 v253, 64, v189
	ds_read_b128 v[148:151], v253
	ds_read_b128 v[172:175], v189 offset:2048
	ds_read_b128 v[176:179], v253 offset:2048
	s_add_u32 s50, s48, 0x100
	s_addc_u32 s51, s49, 0
	s_cmp_eq_u32 s74, 40
	s_cselect_b32 s55, s11, s51
	s_cselect_b32 s54, s10, s50
	s_cselect_b32 s53, s47, s73
	s_cselect_b32 s52, s46, s72
	v_lshl_add_u64 v[220:221], s[48:49], 0, v[166:167]
	s_add_i32 m0, s59, 0xc000
	ds_read_b128 v[180:183], v190
	v_xor_b32_e32 v253, 64, v190
	ds_read_b128 v[192:195], v253
	ds_read_b128 v[196:199], v190 offset:2048
	ds_read_b128 v[200:203], v253 offset:2048
	ds_read_b128 v[204:207], v190 offset:4096
	ds_read_b128 v[208:211], v253 offset:4096
	ds_read_b128 v[212:215], v190 offset:6144
	ds_read_b128 v[216:219], v253 offset:6144
	global_load_lds_dwordx4 v[220:221], off
	v_lshl_add_u64 v[220:221], s[48:49], 0, v[164:165]
	s_add_i32 m0, s59, 0xe000
	s_nop 0
	global_load_lds_dwordx4 v[220:221], off
	s_waitcnt vmcnt(8)
	s_waitcnt lgkmcnt(0)
	s_setprio 1
	s_barrier
	v_mfma_f32_16x16x32_bf16 v[124:127], v[128:131], v[180:183], v[124:127]
	v_mfma_f32_16x16x32_bf16 v[124:127], v[132:135], v[192:195], v[124:127]
	v_mfma_f32_16x16x32_bf16 v[108:111], v[132:135], v[200:203], v[108:111]
	v_mfma_f32_16x16x32_bf16 v[108:111], v[128:131], v[196:199], v[108:111]
	v_mfma_f32_16x16x32_bf16 v[92:95], v[128:131], v[204:207], v[92:95]
	v_mfma_f32_16x16x32_bf16 v[92:95], v[132:135], v[208:211], v[92:95]
	v_mfma_f32_16x16x32_bf16 v[76:79], v[132:135], v[216:219], v[76:79]
	v_mfma_f32_16x16x32_bf16 v[76:79], v[128:131], v[212:215], v[76:79]
	v_mfma_f32_16x16x32_bf16 v[72:75], v[136:139], v[212:215], v[72:75]
	v_mfma_f32_16x16x32_bf16 v[72:75], v[140:143], v[216:219], v[72:75]
	v_mfma_f32_16x16x32_bf16 v[88:91], v[140:143], v[208:211], v[88:91]
	v_mfma_f32_16x16x32_bf16 v[88:91], v[136:139], v[204:207], v[88:91]
	v_mfma_f32_16x16x32_bf16 v[104:107], v[136:139], v[196:199], v[104:107]
	v_mfma_f32_16x16x32_bf16 v[104:107], v[140:143], v[200:203], v[104:107]
	v_mfma_f32_16x16x32_bf16 v[120:123], v[140:143], v[192:195], v[120:123]
	v_mfma_f32_16x16x32_bf16 v[120:123], v[136:139], v[180:183], v[120:123]
	s_setprio 0
	s_setprio 1
	v_mfma_f32_16x16x32_bf16 v[112:115], v[172:175], v[180:183], v[112:115]
	v_mfma_f32_16x16x32_bf16 v[112:115], v[176:179], v[192:195], v[112:115]
	v_mfma_f32_16x16x32_bf16 v[96:99], v[176:179], v[200:203], v[96:99]
	v_mfma_f32_16x16x32_bf16 v[96:99], v[172:175], v[196:199], v[96:99]
	v_mfma_f32_16x16x32_bf16 v[80:83], v[172:175], v[204:207], v[80:83]
	v_mfma_f32_16x16x32_bf16 v[80:83], v[176:179], v[208:211], v[80:83]
	v_mfma_f32_16x16x32_bf16 v[64:67], v[176:179], v[216:219], v[64:67]
	v_mfma_f32_16x16x32_bf16 v[64:67], v[172:175], v[212:215], v[64:67]
	v_mfma_f32_16x16x32_bf16 v[68:71], v[144:147], v[212:215], v[68:71]
	v_mfma_f32_16x16x32_bf16 v[68:71], v[148:151], v[216:219], v[68:71]
	v_mfma_f32_16x16x32_bf16 v[84:87], v[148:151], v[208:211], v[84:87]
	v_mfma_f32_16x16x32_bf16 v[84:87], v[144:147], v[204:207], v[84:87]
	v_mfma_f32_16x16x32_bf16 v[100:103], v[144:147], v[196:199], v[100:103]
	v_mfma_f32_16x16x32_bf16 v[100:103], v[148:151], v[200:203], v[100:103]
	v_mfma_f32_16x16x32_bf16 v[116:119], v[148:151], v[192:195], v[116:119]
	v_mfma_f32_16x16x32_bf16 v[116:119], v[144:147], v[180:183], v[116:119]
	s_barrier
	s_setprio 0
	s_add_i32 s48, s68, s58
	v_lshl_add_u64 v[220:221], s[52:53], 0, v[154:155]
	s_mov_b32 m0, s48
	ds_read_b128 v[180:183], v190 offset:16384
	v_xor_b32_e32 v253, 64, v190
	ds_read_b128 v[192:195], v253 offset:16384
	ds_read_b128 v[196:199], v190 offset:18432
	ds_read_b128 v[200:203], v253 offset:18432
	ds_read_b128 v[204:207], v190 offset:20480
	ds_read_b128 v[208:211], v253 offset:20480
	ds_read_b128 v[212:215], v190 offset:22528
	ds_read_b128 v[216:219], v253 offset:22528
	global_load_lds_dwordx4 v[220:221], off
	s_add_i32 m0, s48, 0x2000
	s_add_u32 s48, s52, 0xb0000
	v_lshl_add_u64 v[222:223], s[52:53], 0, v[162:163]
	s_addc_u32 s49, s53, 0
	s_add_i32 s75, s69, s58
	global_load_lds_dwordx4 v[222:223], off
	v_lshl_add_u64 v[224:225], s[48:49], 0, v[154:155]
	s_mov_b32 m0, s75
	v_lshl_add_u64 v[226:227], s[54:55], 0, v[160:161]
	global_load_lds_dwordx4 v[224:225], off
	v_lshl_add_u64 v[224:225], s[48:49], 0, v[162:163]
	s_add_i32 m0, s75, 0x2000
	s_nop 0
	global_load_lds_dwordx4 v[224:225], off
	v_lshl_add_u64 v[224:225], s[54:55], 0, v[152:153]
	s_mov_b32 m0, s59
	s_nop 0
	global_load_lds_dwordx4 v[224:225], off
	s_mov_b32 m0, s60
	s_nop 0
	global_load_lds_dwordx4 v[226:227], off
	s_waitcnt vmcnt(8)
	s_waitcnt lgkmcnt(0)
	s_setprio 1
	s_barrier
	v_mfma_f32_16x16x32_bf16 v[60:63], v[128:131], v[180:183], v[60:63]
	v_mfma_f32_16x16x32_bf16 v[60:63], v[132:135], v[192:195], v[60:63]
	v_mfma_f32_16x16x32_bf16 v[44:47], v[132:135], v[200:203], v[44:47]
	v_mfma_f32_16x16x32_bf16 v[44:47], v[128:131], v[196:199], v[44:47]
	v_mfma_f32_16x16x32_bf16 v[28:31], v[128:131], v[204:207], v[28:31]
	v_mfma_f32_16x16x32_bf16 v[28:31], v[132:135], v[208:211], v[28:31]
	v_mfma_f32_16x16x32_bf16 v[12:15], v[132:135], v[216:219], v[12:15]
	v_mfma_f32_16x16x32_bf16 v[12:15], v[128:131], v[212:215], v[12:15]
	v_mfma_f32_16x16x32_bf16 v[8:11], v[136:139], v[212:215], v[8:11]
	v_mfma_f32_16x16x32_bf16 v[8:11], v[140:143], v[216:219], v[8:11]
	v_mfma_f32_16x16x32_bf16 v[24:27], v[140:143], v[208:211], v[24:27]
	v_mfma_f32_16x16x32_bf16 v[24:27], v[136:139], v[204:207], v[24:27]
	v_mfma_f32_16x16x32_bf16 v[40:43], v[136:139], v[196:199], v[40:43]
	v_mfma_f32_16x16x32_bf16 v[40:43], v[140:143], v[200:203], v[40:43]
	v_mfma_f32_16x16x32_bf16 v[56:59], v[140:143], v[192:195], v[56:59]
	v_mfma_f32_16x16x32_bf16 v[56:59], v[136:139], v[180:183], v[56:59]
	s_setprio 0
	s_setprio 1
	v_mfma_f32_16x16x32_bf16 v[48:51], v[172:175], v[180:183], v[48:51]
	v_mfma_f32_16x16x32_bf16 v[48:51], v[176:179], v[192:195], v[48:51]
	v_mfma_f32_16x16x32_bf16 v[32:35], v[176:179], v[200:203], v[32:35]
	v_mfma_f32_16x16x32_bf16 v[32:35], v[172:175], v[196:199], v[32:35]
	v_mfma_f32_16x16x32_bf16 v[16:19], v[172:175], v[204:207], v[16:19]
	v_mfma_f32_16x16x32_bf16 v[16:19], v[176:179], v[208:211], v[16:19]
	v_mfma_f32_16x16x32_bf16 v[0:3], v[176:179], v[216:219], v[0:3]
	v_mfma_f32_16x16x32_bf16 v[0:3], v[172:175], v[212:215], v[0:3]
	v_mfma_f32_16x16x32_bf16 v[4:7], v[144:147], v[212:215], v[4:7]
	v_mfma_f32_16x16x32_bf16 v[4:7], v[148:151], v[216:219], v[4:7]
	v_mfma_f32_16x16x32_bf16 v[20:23], v[148:151], v[208:211], v[20:23]
	v_mfma_f32_16x16x32_bf16 v[20:23], v[144:147], v[204:207], v[20:23]
	v_mfma_f32_16x16x32_bf16 v[36:39], v[144:147], v[196:199], v[36:39]
	v_mfma_f32_16x16x32_bf16 v[36:39], v[148:151], v[200:203], v[36:39]
	v_mfma_f32_16x16x32_bf16 v[52:55], v[148:151], v[192:195], v[52:55]
	v_mfma_f32_16x16x32_bf16 v[52:55], v[144:147], v[180:183], v[52:55]
	s_barrier
	s_setprio 0
	s_add_i32 s75, 0, 0x18000
	s_add_i32 s76, 0, 0x1c000
	v_add_u32_e32 v140, s75, v185
	v_add_u32_e32 v176, s76, v185
	ds_read_b128 v[128:131], v140
	v_xor_b32_e32 v253, 64, v140
	ds_read_b128 v[132:135], v253
	ds_read_b128 v[136:139], v140 offset:2048
	ds_read_b128 v[140:143], v253 offset:2048
	ds_read_b128 v[144:147], v176
	v_xor_b32_e32 v253, 64, v176
	ds_read_b128 v[148:151], v253
	ds_read_b128 v[172:175], v176 offset:2048
	ds_read_b128 v[176:179], v253 offset:2048
	s_add_u32 s48, s54, 0xb0000
	s_addc_u32 s49, s55, 0
	s_mov_b32 m0, s61
	v_lshl_add_u64 v[228:229], s[48:49], 0, v[152:153]
	ds_read_b128 v[180:183], v190 offset:32768
	v_xor_b32_e32 v253, 64, v190
	ds_read_b128 v[192:195], v253 offset:32768
	ds_read_b128 v[196:199], v190 offset:34816
	ds_read_b128 v[200:203], v253 offset:34816
	ds_read_b128 v[204:207], v190 offset:36864
	ds_read_b128 v[208:211], v253 offset:36864
	ds_read_b128 v[212:215], v190 offset:38912
	ds_read_b128 v[216:219], v253 offset:38912
	global_load_lds_dwordx4 v[228:229], off
	v_lshl_add_u64 v[228:229], s[48:49], 0, v[160:161]
	s_mov_b32 m0, s62
	s_nop 0
	global_load_lds_dwordx4 v[228:229], off
	s_waitcnt vmcnt(8)
	s_waitcnt lgkmcnt(0)
	s_setprio 1
	s_barrier
	v_mfma_f32_16x16x32_bf16 v[124:127], v[128:131], v[180:183], v[124:127]
	v_mfma_f32_16x16x32_bf16 v[124:127], v[132:135], v[192:195], v[124:127]
	v_mfma_f32_16x16x32_bf16 v[108:111], v[132:135], v[200:203], v[108:111]
	v_mfma_f32_16x16x32_bf16 v[108:111], v[128:131], v[196:199], v[108:111]
	v_mfma_f32_16x16x32_bf16 v[92:95], v[128:131], v[204:207], v[92:95]
	v_mfma_f32_16x16x32_bf16 v[92:95], v[132:135], v[208:211], v[92:95]
	v_mfma_f32_16x16x32_bf16 v[76:79], v[132:135], v[216:219], v[76:79]
	v_mfma_f32_16x16x32_bf16 v[76:79], v[128:131], v[212:215], v[76:79]
	v_mfma_f32_16x16x32_bf16 v[72:75], v[136:139], v[212:215], v[72:75]
	v_mfma_f32_16x16x32_bf16 v[72:75], v[140:143], v[216:219], v[72:75]
	v_mfma_f32_16x16x32_bf16 v[88:91], v[140:143], v[208:211], v[88:91]
	v_mfma_f32_16x16x32_bf16 v[88:91], v[136:139], v[204:207], v[88:91]
	v_mfma_f32_16x16x32_bf16 v[104:107], v[136:139], v[196:199], v[104:107]
	v_mfma_f32_16x16x32_bf16 v[104:107], v[140:143], v[200:203], v[104:107]
	v_mfma_f32_16x16x32_bf16 v[120:123], v[140:143], v[192:195], v[120:123]
	v_mfma_f32_16x16x32_bf16 v[120:123], v[136:139], v[180:183], v[120:123]
	s_setprio 0
	s_setprio 1
	v_mfma_f32_16x16x32_bf16 v[112:115], v[172:175], v[180:183], v[112:115]
	v_mfma_f32_16x16x32_bf16 v[112:115], v[176:179], v[192:195], v[112:115]
	v_mfma_f32_16x16x32_bf16 v[96:99], v[176:179], v[200:203], v[96:99]
	v_mfma_f32_16x16x32_bf16 v[96:99], v[172:175], v[196:199], v[96:99]
	v_mfma_f32_16x16x32_bf16 v[80:83], v[172:175], v[204:207], v[80:83]
	v_mfma_f32_16x16x32_bf16 v[80:83], v[176:179], v[208:211], v[80:83]
	v_mfma_f32_16x16x32_bf16 v[64:67], v[176:179], v[216:219], v[64:67]
	v_mfma_f32_16x16x32_bf16 v[64:67], v[172:175], v[212:215], v[64:67]
	v_mfma_f32_16x16x32_bf16 v[68:71], v[144:147], v[212:215], v[68:71]
	v_mfma_f32_16x16x32_bf16 v[68:71], v[148:151], v[216:219], v[68:71]
	v_mfma_f32_16x16x32_bf16 v[84:87], v[148:151], v[208:211], v[84:87]
	v_mfma_f32_16x16x32_bf16 v[84:87], v[144:147], v[204:207], v[84:87]
	v_mfma_f32_16x16x32_bf16 v[100:103], v[144:147], v[196:199], v[100:103]
	v_mfma_f32_16x16x32_bf16 v[100:103], v[148:151], v[200:203], v[100:103]
	v_mfma_f32_16x16x32_bf16 v[116:119], v[148:151], v[192:195], v[116:119]
	v_mfma_f32_16x16x32_bf16 v[116:119], v[144:147], v[180:183], v[116:119]
	s_barrier
	s_setprio 0
	s_add_i32 s48, s75, s58
	v_lshl_add_u64 v[220:221], v[220:221], 0, s[22:23]
	s_mov_b32 m0, s48
	ds_read_b128 v[180:183], v190 offset:49152
	v_xor_b32_e32 v253, 64, v190
	ds_read_b128 v[192:195], v253 offset:49152
	ds_read_b128 v[196:199], v190 offset:51200
	ds_read_b128 v[200:203], v253 offset:51200
	ds_read_b128 v[204:207], v190 offset:53248
	ds_read_b128 v[208:211], v253 offset:53248
	ds_read_b128 v[212:215], v190 offset:55296
	ds_read_b128 v[216:219], v253 offset:55296
	global_load_lds_dwordx4 v[220:221], off
	s_add_i32 m0, s48, 0x2000
	s_add_u32 s48, s52, 0xb0080
	v_lshl_add_u64 v[220:221], v[222:223], 0, s[22:23]
	s_addc_u32 s49, s53, 0
	s_add_i32 s52, s76, s58
	global_load_lds_dwordx4 v[220:221], off
	v_lshl_add_u64 v[220:221], s[48:49], 0, v[154:155]
	s_mov_b32 m0, s52
	s_nop 0
	global_load_lds_dwordx4 v[220:221], off
	v_lshl_add_u64 v[220:221], s[48:49], 0, v[162:163]
	s_add_i32 m0, s52, 0x2000
	s_nop 0
	global_load_lds_dwordx4 v[220:221], off
	v_lshl_add_u64 v[220:221], v[224:225], 0, s[22:23]
	s_mov_b32 m0, s3
	s_nop 0
	global_load_lds_dwordx4 v[220:221], off
	v_lshl_add_u64 v[220:221], v[226:227], 0, s[22:23]
	s_mov_b32 m0, s64
	s_nop 0
	global_load_lds_dwordx4 v[220:221], off
	s_waitcnt vmcnt(8)
	s_waitcnt lgkmcnt(0)
	s_setprio 1
	s_barrier
	v_mfma_f32_16x16x32_bf16 v[60:63], v[128:131], v[180:183], v[60:63]
	v_mfma_f32_16x16x32_bf16 v[60:63], v[132:135], v[192:195], v[60:63]
	v_mfma_f32_16x16x32_bf16 v[44:47], v[132:135], v[200:203], v[44:47]
	v_mfma_f32_16x16x32_bf16 v[44:47], v[128:131], v[196:199], v[44:47]
	v_mfma_f32_16x16x32_bf16 v[28:31], v[128:131], v[204:207], v[28:31]
	v_mfma_f32_16x16x32_bf16 v[28:31], v[132:135], v[208:211], v[28:31]
	v_mfma_f32_16x16x32_bf16 v[12:15], v[132:135], v[216:219], v[12:15]
	v_mfma_f32_16x16x32_bf16 v[12:15], v[128:131], v[212:215], v[12:15]
	v_mfma_f32_16x16x32_bf16 v[8:11], v[136:139], v[212:215], v[8:11]
	v_mfma_f32_16x16x32_bf16 v[8:11], v[140:143], v[216:219], v[8:11]
	v_mfma_f32_16x16x32_bf16 v[24:27], v[140:143], v[208:211], v[24:27]
	v_mfma_f32_16x16x32_bf16 v[24:27], v[136:139], v[204:207], v[24:27]
	v_mfma_f32_16x16x32_bf16 v[40:43], v[136:139], v[196:199], v[40:43]
	v_mfma_f32_16x16x32_bf16 v[40:43], v[140:143], v[200:203], v[40:43]
	v_mfma_f32_16x16x32_bf16 v[56:59], v[140:143], v[192:195], v[56:59]
	v_mfma_f32_16x16x32_bf16 v[56:59], v[136:139], v[180:183], v[56:59]
	s_setprio 0
	s_setprio 1
	v_mfma_f32_16x16x32_bf16 v[48:51], v[172:175], v[180:183], v[48:51]
	v_mfma_f32_16x16x32_bf16 v[48:51], v[176:179], v[192:195], v[48:51]
	v_mfma_f32_16x16x32_bf16 v[32:35], v[176:179], v[200:203], v[32:35]
	v_mfma_f32_16x16x32_bf16 v[32:35], v[172:175], v[196:199], v[32:35]
	v_mfma_f32_16x16x32_bf16 v[16:19], v[172:175], v[204:207], v[16:19]
	v_mfma_f32_16x16x32_bf16 v[16:19], v[176:179], v[208:211], v[16:19]
	v_mfma_f32_16x16x32_bf16 v[0:3], v[176:179], v[216:219], v[0:3]
	v_mfma_f32_16x16x32_bf16 v[0:3], v[172:175], v[212:215], v[0:3]
	v_mfma_f32_16x16x32_bf16 v[4:7], v[144:147], v[212:215], v[4:7]
	v_mfma_f32_16x16x32_bf16 v[4:7], v[148:151], v[216:219], v[4:7]
	v_mfma_f32_16x16x32_bf16 v[20:23], v[148:151], v[208:211], v[20:23]
	v_mfma_f32_16x16x32_bf16 v[20:23], v[144:147], v[204:207], v[20:23]
	v_mfma_f32_16x16x32_bf16 v[36:39], v[144:147], v[196:199], v[36:39]
	v_mfma_f32_16x16x32_bf16 v[36:39], v[148:151], v[200:203], v[36:39]
	v_mfma_f32_16x16x32_bf16 v[52:55], v[148:151], v[192:195], v[52:55]
	v_mfma_f32_16x16x32_bf16 v[52:55], v[144:147], v[180:183], v[52:55]
	s_barrier
	s_setprio 0
	s_add_i32 s74, s74, 2
	s_add_u32 s72, s72, 0x100
	s_addc_u32 s73, s73, 0
	s_cmp_gt_u32 s74, 41
	s_mov_b64 s[48:49], s[50:51]
	s_cbranch_scc0 .LBB0_1181
	s_and_b64 vcc, exec, s[24:25]
	s_cbranch_vccz .LBB0_1184
	s_barrier
